# all flat loads/stores converted to global (same waits), on top of v25
# speedup vs baseline: 1.0085x; 1.0056x over previous
; DI void phase_prep(const Params& P, unsigned char* smem) {
;     ...
;   for (long i = (long)bid * 512 + tid; i < (long)MTOK * DM / 8; i += (long)nb * 512) {
;     long e = i * 8;
;     const float* s = (e < (long)NTP * DM) ? (P.x_p + e) : (P.x_s + (e - (long)NTP * DM));
;     const f32x4 a = __builtin_nontemporal_load((const f32x4*)s), b = __builtin_nontemporal_load((const f32x4*)(s + 4));
;     uint4 o = make_uint4(pack2(a[0], a[1]), pack2(a[2], a[3]), pack2(b[0], b[1]), pack2(b[2], b[3]));
;     *(uint4*)(xb + e) = o;
;   }
.LBB0_3:
	v_lshl_add_u64 v[14:15], s[4:5], 0, v[6:7]
	v_lshl_add_u64 v[16:17], s[6:7], 0, v[6:7]
	v_cmp_gt_i64_e32 vcc, s[42:43], v[12:13]
	v_lshl_add_u64 v[12:13], v[12:13], 0, s[34:35]
	v_lshl_add_u64 v[6:7], v[6:7], 0, s[36:37]
	v_cndmask_b32_e32 v19, v17, v15, vcc
	v_cndmask_b32_e32 v18, v16, v14, vcc
	global_load_dwordx4 v[14:17], v[18:19], off nt
	s_nop 0
	global_load_dwordx4 v[18:21], v[18:19], off offset:16 nt
	v_cmp_lt_i64_e32 vcc, s[44:45], v[12:13]
	s_or_b64 s[40:41], vcc, s[40:41]
	s_waitcnt vmcnt(0)
	v_cvt_pk_bf16_f32 v14, v14, v15
	v_cvt_pk_bf16_f32 v15, v16, v17
	s_waitcnt vmcnt(0)
	v_cvt_pk_bf16_f32 v16, v18, v19
	v_cvt_pk_bf16_f32 v17, v20, v21
	global_store_dwordx4 v[10:11], v[14:17], off
	v_lshl_add_u64 v[10:11], v[10:11], 0, s[38:39]
	s_andn2_b64 exec, exec, s[40:41]
	s_cbranch_execnz .LBB0_3

; DI void phase_prep(const Params& P, unsigned char* smem) {
;     ...
;     for (long i = (long)bid * 512 + tid; i < 8L * 4096 * 512 / 8; i += (long)nb * 512) {
;       long e = i * 8;
;       long b = e / (4096L * 512), r = e % (4096L * 512);
;       const float* s = P.cache_k + e;
;       const f32x4 a_ = __builtin_nontemporal_load((const f32x4*)s), c_ = __builtin_nontemporal_load((const f32x4*)(s + 4));
;       const float4 a = make_float4(a_[0], a_[1], a_[2], a_[3]), c = make_float4(c_[0], c_[1], c_[2], c_[3]);
;       *(uint4*)(sk + b * 4160L * 512 + kfrag_off((int)(r >> 9), (int)((r >> 6) & 7), (int)(r & 63))) =
;           make_uint4(pack2(a.x, a.y), pack2(a.z, a.w), pack2(c.x, c.y), pack2(c.z, c.w));
;     }
.LBB0_6:
	global_load_dwordx4 v[20:23], v[12:13], off offset:-16 nt
	global_load_dwordx4 v[24:27], v[12:13], off nt
	v_ashrrev_i32_e32 v1, 31, v19
	v_ashrrev_i32_e32 v3, 31, v15
	v_lshrrev_b32_e32 v10, 14, v1
	v_lshl_add_u64 v[28:29], v[18:19], 0, v[10:11]
	v_lshrrev_b32_e32 v10, 11, v3
	v_lshl_add_u64 v[18:19], v[18:19], 0, s[6:7]
	v_lshl_add_u64 v[30:31], v[14:15], 0, v[10:11]
	v_cmp_lt_i64_e32 vcc, s[38:39], v[18:19]
	v_and_b32_e32 v1, 0xffe00000, v30
	s_or_b64 s[36:37], vcc, s[36:37]
	v_sub_co_u32_e32 v1, vcc, v14, v1
	v_ashrrev_i64 v[28:29], 18, v[28:29]
	s_nop 0
	v_subb_co_u32_e32 v3, vcc, v15, v31, vcc
	v_alignbit_b32 v3, v3, v1, 9
	v_mad_u64_u32 v[32:33], s[40:41], v28, s33, v[16:17]
	v_ashrrev_i32_e32 v28, 5, v3
	v_mad_i32_i24 v33, v29, s33, v33
	v_lshrrev_b32_e32 v9, 4, v1
	v_ashrrev_i32_e32 v29, 31, v28
	v_bfe_u32 v7, v1, 4, 2
	v_and_b32_e32 v9, 28, v9
	v_lshlrev_b64 v[28:29], 5, v[28:29]
	v_or3_b32 v28, v28, v9, v7
	v_lshlrev_b32_e32 v1, 2, v1
	v_lshlrev_b64 v[28:29], 6, v[28:29]
	v_and_b32_e32 v3, 31, v3
	v_and_or_b32 v1, v1, 32, v28
	v_or_b32_e32 v28, v1, v3
	v_lshl_add_u64 v[12:13], v[12:13], 0, s[8:9]
	v_lshl_add_u64 v[14:15], v[14:15], 0, s[34:35]
	v_lshl_add_u64 v[28:29], v[28:29], 4, v[32:33]
	s_waitcnt vmcnt(0)
	v_cvt_pk_bf16_f32 v20, v20, v21
	v_cvt_pk_bf16_f32 v21, v22, v23
	v_cvt_pk_bf16_f32 v22, v24, v25
	v_cvt_pk_bf16_f32 v23, v26, v27
	global_store_dwordx4 v[28:29], v[20:23], off
	s_andn2_b64 exec, exec, s[36:37]
	s_cbranch_execnz .LBB0_6

; DI void phase_prep(const Params& P, unsigned char* smem) {
;     ...
;     for (long i = (long)bid * 512 + tid; i < 8L * 4096 * 64 / 8; i += (long)nb * 512) {
;       long e = i * 8;
;       long b = e / (4096L * 64), r = e % (4096L * 64);
;       const float* s = P.cache_ik + e;
;       const f32x4 a_ = __builtin_nontemporal_load((const f32x4*)s), c_ = __builtin_nontemporal_load((const f32x4*)(s + 4));
;       const float4 a = make_float4(a_[0], a_[1], a_[2], a_[3]), c = make_float4(c_[0], c_[1], c_[2], c_[3]);
;       *(uint4*)(ski + b * 4160L * 64 + kifrag_off((int)(r >> 6), (int)(r & 63))) =
;           make_uint4(pack2(a.x, a.y), pack2(a.z, a.w), pack2(c.x, c.y), pack2(c.z, c.w));
;     }
.LBB0_9:
	global_load_dwordx4 v[14:17], v[10:11], off offset:-16 nt
	global_load_dwordx4 v[18:21], v[10:11], off nt
	v_ashrrev_i32_e32 v1, 31, v5
	v_ashrrev_i32_e32 v9, 31, v7
	v_lshrrev_b32_e32 v2, 17, v1
	v_lshl_add_u64 v[22:23], v[4:5], 0, v[2:3]
	v_lshrrev_b32_e32 v2, 14, v9
	v_lshl_add_u64 v[4:5], v[4:5], 0, s[6:7]
	v_lshl_add_u64 v[24:25], v[6:7], 0, v[2:3]
	v_cmp_lt_i64_e32 vcc, s[36:37], v[4:5]
	v_and_b32_e32 v1, 0xfffc0000, v24
	s_or_b64 s[34:35], vcc, s[34:35]
	v_sub_co_u32_e32 v1, vcc, v6, v1
	v_ashrrev_i64 v[22:23], 15, v[22:23]
	s_nop 0
	v_subb_co_u32_e32 v2, vcc, v7, v25, vcc
	v_alignbit_b32 v2, v2, v1, 6
	v_mad_u64_u32 v[26:27], s[38:39], v22, s33, v[12:13]
	v_ashrrev_i32_e32 v22, 5, v2
	v_mad_i32_i24 v27, v23, s33, v27
	v_lshlrev_b32_e32 v1, 2, v1
	v_ashrrev_i32_e32 v23, 31, v22
	v_and_b32_e32 v9, 0xc0, v1
	v_and_b32_e32 v1, 32, v1
	v_lshlrev_b64 v[22:23], 8, v[22:23]
	v_and_b32_e32 v2, 31, v2
	v_or3_b32 v1, v22, v9, v1
	v_or_b32_e32 v22, v1, v2
	v_lshl_add_u64 v[10:11], v[10:11], 0, s[8:9]
	v_lshl_add_u64 v[6:7], v[6:7], 0, s[30:31]
	v_lshl_add_u64 v[22:23], v[22:23], 4, v[26:27]
	s_waitcnt vmcnt(0)
	v_cvt_pk_bf16_f32 v14, v14, v15
	v_cvt_pk_bf16_f32 v15, v16, v17
	v_cvt_pk_bf16_f32 v16, v18, v19
	v_cvt_pk_bf16_f32 v17, v20, v21
	global_store_dwordx4 v[22:23], v[14:17], off
	s_andn2_b64 exec, exec, s[34:35]
	s_cbranch_execnz .LBB0_9

; DI void phase_prep(const Params& P, unsigned char* smem) {
;     ...
;     for (int i = bid * 512 + tid; i < 8192 * 32; i += nb * 512) {
;       int pos = i >> 5, fi = i & 31;
;       float invf = powf(10000.0f, -(float)fi / 32.0f);
;       float ang = (float)pos * invf;
;       double a = (double)ang;
;       double kq = rint(a * 0.15915494309189535);
;       float r = (float)(a - kq * 6.283185307179586);
;       rot[i] = make_float2(cosf(r), sinf(r));
;     }
.LBB0_12:
	s_or_b64 exec, exec, s[4:5]
	v_mul_f32_e32 v18, v17, v17
	v_fmamk_f32 v19, v18, 0xb94c1982, v3
	v_fmaak_f32 v19, v18, v19, 0xbe2aaa9d
	v_mul_f32_e32 v19, v18, v19
	v_fmac_f32_e32 v17, v17, v19
	v_fmamk_f32 v19, v18, 0x37d75334, v9
	v_fmaak_f32 v19, v18, v19, 0x3d2aabf7
	v_fmaak_f32 v19, v18, v19, 0xbf000004
	v_fma_f32 v18, v18, v19, 1.0
	v_and_b32_e32 v19, 1, v16
	v_cmp_eq_u32_e32 vcc, 0, v19
	v_lshlrev_b32_e32 v16, 30, v16
	v_xor_b32_e32 v15, v15, v14
	v_cndmask_b32_e64 v17, -v17, v18, vcc
	v_bitop3_b32 v16, v16, v17, s57 bitop3:0x6c
	v_mul_f32_e32 v17, v20, v20
	v_fmamk_f32 v18, v17, 0xb94c1982, v3
	v_fmaak_f32 v18, v17, v18, 0xbe2aaa9d
	v_mul_f32_e32 v18, v17, v18
	v_fmac_f32_e32 v20, v20, v18
	v_fmamk_f32 v18, v17, 0x37d75334, v9
	v_fmaak_f32 v18, v17, v18, 0x3d2aabf7
	v_fmaak_f32 v18, v17, v18, 0xbf000004
	v_fma_f32 v17, v17, v18, 1.0
	v_and_b32_e32 v18, 1, v6
	v_lshlrev_b32_e32 v6, 30, v6
	v_cmp_eq_u32_e32 vcc, 0, v18
	v_and_b32_e32 v6, 0x80000000, v6
	v_xor_b32_e32 v6, v15, v6
	v_cndmask_b32_e32 v17, v17, v20, vcc
	v_xor_b32_e32 v6, v6, v17
	v_cmp_class_f32_e64 vcc, v14, s58
	v_add_u32_e32 v13, s34, v13
	s_nop 0
	v_cndmask_b32_e32 v14, v12, v16, vcc
	v_cndmask_b32_e32 v15, v12, v6, vcc
	v_add_co_u32_e32 v16, vcc, -4, v4
	s_nop 1
	v_addc_co_u32_e32 v17, vcc, -1, v5, vcc
	v_cmp_lt_i32_e32 vcc, s59, v13
	s_or_b64 s[38:39], vcc, s[38:39]
	v_lshl_add_u64 v[4:5], v[4:5], 0, s[36:37]
	global_store_dwordx2 v[16:17], v[14:15], off
	s_andn2_b64 exec, exec, s[38:39]
	s_cbranch_execz .LBB0_21

; DI void phase_prep(const Params& P, unsigned char* smem) {
;     ...
;     for (int i = bid * 512 + tid; i < 8 * T5N; i += nb * 512) {
;       int h = i / T5N, idx = i % T5N, rel = idx - T5OFF;
;       int n = rel < 0 ? -rel : rel;
;       int bucket;
;       if (n < 8) bucket = n;
;       else {
;         int lg = 8 + (int)(logf((float)n / 8.0f) / logf(128.0f) * 8.0f);
;         bucket = lg < 15 ? lg : 15;
;       }
;       if (rel > 0) bucket += 16;
;       t5t[i] = P.t5[bucket * 8 + h] * LOG2E;
;     }
.LBB0_23:
	s_or_b64 exec, exec, s[30:31]
	v_lshlrev_b32_e32 v7, 3, v7
	v_add_u32_e32 v9, 0x80, v7
	v_cmp_lt_i32_e32 vcc, s34, v6
	v_subrev_u32_e32 v1, s33, v1
	s_nop 0
	v_cndmask_b32_e32 v6, v7, v9, vcc
	v_add_u32_e32 v6, v6, v5
	v_ashrrev_i32_e32 v7, 31, v6
	v_lshl_add_u64 v[6:7], v[6:7], 2, s[26:27]
	global_load_dword v9, v[6:7], off
	v_ashrrev_i32_e32 v5, 31, v4
	v_lshl_add_u64 v[6:7], v[4:5], 2, s[6:7]
	v_add_u32_e32 v4, s33, v4
	v_cmp_lt_i32_e32 vcc, s41, v4
	s_or_b64 s[8:9], vcc, s[8:9]
	s_waitcnt vmcnt(0)
	v_mul_f32_e32 v5, 0x3fb8aa3b, v9
	global_store_dword v[6:7], v5, off
	s_andn2_b64 exec, exec, s[8:9]
	s_cbranch_execz .LBB0_26

; DI void phase_prep(const Params& P, unsigned char* smem) {
;     ...
;     if (bid == 0 && tid < 64) ((unsigned*)(P.ws + W_CTR))[tid] = 0u;
.LBB0_26:
	s_or_b64 exec, exec, s[4:5]
	s_cmp_eq_u32 s90, 0
	s_cselect_b64 s[4:5], -1, 0
	v_cmp_gt_u32_e32 vcc, 64, v8
	s_and_b64 s[6:7], s[4:5], vcc
	s_and_saveexec_b64 s[4:5], s[6:7]
	s_cbranch_execz .LBB0_28
	v_lshlrev_b32_e32 v4, 2, v8
	v_mov_b32_e32 v5, 0
	v_lshl_add_u64 v[6:7], s[22:23], 0, v[4:5]
	v_add_co_u32_e32 v6, vcc, 0x258a000, v6
	s_nop 1
	v_addc_co_u32_e32 v7, vcc, 0, v7, vcc
	global_store_dword v[6:7], v5, off offset:2048

; DI void phase_prep(const Params& P, unsigned char* smem) {
;     ...
;       for (int i = bid * 512 + tid; i < 8 * 16384; i += nb * 512) {
;         const long o = (long)(i >> 14) * 4160 * 512 + 129L * 16384 + (i & 16383);
;         svt[o] = 0; sk[o] = 0;
;       }
.LBB0_30:
	v_ashrrev_i32_e32 v6, 14, v3
	v_mul_i32_i24_e32 v6, 0x1040, v6
	v_ashrrev_i32_e32 v7, 31, v6
	v_lshlrev_b64 v[6:7], 9, v[6:7]
	v_and_or_b32 v6, v3, s21, v6
	v_add_u32_e32 v3, s20, v3
	v_lshl_add_u64 v[6:7], v[6:7], 1, v[4:5]
	v_cmp_lt_i32_e32 vcc, s26, v3
	v_lshl_add_u64 v[10:11], s[8:9], 0, v[6:7]
	s_or_b64 s[6:7], vcc, s[6:7]
	v_lshl_add_u64 v[6:7], s[28:29], 0, v[6:7]
	global_store_short v[10:11], v1, off
	global_store_short v[6:7], v1, off
	s_andn2_b64 exec, exec, s[6:7]
	s_cbranch_execnz .LBB0_30

; DI void phase_prep(const Params& P, unsigned char* smem) {
;     ...
;       u16* ski = (u16*)(P.ws + R_SKI);
;       for (int i = bid * 512 + tid; i < 8 * 2048; i += nb * 512) ski[(long)(i >> 11) * 4160 * 64 + 129L * 2048 + (i & 2047)] = 0;
.LBB0_34:
	v_ashrrev_i32_e32 v14, 11, v4
	v_ashrrev_i32_e32 v10, 11, v6
	v_ashrrev_i32_e32 v13, 11, v5
	v_and_b32_e32 v25, 0x7ff, v4
	v_mul_hi_i32_i24_e32 v15, 0x82000, v14
	v_mul_i32_i24_e32 v14, 0x82000, v14
	v_and_b32_e32 v24, 0x7ff, v5
	v_mul_hi_i32_i24_e32 v17, 0x82000, v13
	v_mul_i32_i24_e32 v16, 0x82000, v13
	v_mul_hi_i32_i24_e32 v19, 0x82000, v10
	v_mul_i32_i24_e32 v18, 0x82000, v10
	v_lshlrev_b32_e32 v10, 1, v25
	v_lshl_add_u64 v[14:15], s[20:21], 0, v[14:15]
	v_ashrrev_i32_e32 v3, 11, v7
	v_and_b32_e32 v23, 0x7ff, v6
	v_add_u32_e32 v12, -4, v12
	v_lshl_add_u64 v[16:17], s[20:21], 0, v[16:17]
	v_lshl_add_u64 v[14:15], v[14:15], 0, v[10:11]
	v_lshlrev_b32_e32 v10, 1, v24
	v_and_b32_e32 v22, 0x7ff, v7
	v_mul_hi_i32_i24_e32 v21, 0x82000, v3
	v_mul_i32_i24_e32 v20, 0x82000, v3
	v_cmp_eq_u32_e32 vcc, 0, v12
	v_lshl_add_u64 v[18:19], s[20:21], 0, v[18:19]
	v_lshl_add_u64 v[16:17], v[16:17], 0, v[10:11]
	v_lshlrev_b32_e32 v10, 1, v23
	v_add_u32_e32 v7, s33, v7
	v_add_u32_e32 v6, s31, v6
	v_add_u32_e32 v5, s30, v5
	v_add_u32_e32 v4, s29, v4
	v_lshl_add_u64 v[20:21], s[20:21], 0, v[20:21]
	s_or_b64 s[26:27], vcc, s[26:27]
	global_store_short v[14:15], v11, off
	v_lshl_add_u64 v[14:15], v[18:19], 0, v[10:11]
	v_lshlrev_b32_e32 v10, 1, v22
	global_store_short v[16:17], v11, off
	v_lshl_add_u64 v[16:17], v[20:21], 0, v[10:11]
	global_store_short v[14:15], v11, off
	global_store_short v[16:17], v11, off
	s_andn2_b64 exec, exec, s[26:27]
	s_cbranch_execnz .LBB0_34
	s_or_b64 exec, exec, s[26:27]
	v_mad_u64_u32 v[2:3], s[26:27], v9, s28, v[2:3]
	v_cmp_ne_u32_e32 vcc, v1, v9
	s_orn2_b64 s[26:27], vcc, exec

; DI void phase_prep(const Params& P, unsigned char* smem) {
;     ...
;       u16* ski = (u16*)(P.ws + R_SKI);
;       for (int i = bid * 512 + tid; i < 8 * 2048; i += nb * 512) ski[(long)(i >> 11) * 4160 * 64 + 129L * 2048 + (i & 2047)] = 0;
.LBB0_38:
	v_ashrrev_i32_e32 v1, 11, v2
	v_and_b32_e32 v3, 0x7ff, v2
	v_add_u32_e32 v2, s28, v2
	v_mul_hi_i32_i24_e32 v7, 0x82000, v1
	v_mul_i32_i24_e32 v6, 0x82000, v1
	v_lshlrev_b32_e32 v4, 1, v3
	v_cmp_lt_i32_e32 vcc, s26, v2
	v_lshl_add_u64 v[6:7], s[20:21], 0, v[6:7]
	s_or_b64 s[4:5], vcc, s[4:5]
	v_lshl_add_u64 v[6:7], v[6:7], 0, v[4:5]
	global_store_short v[6:7], v5, off
	s_andn2_b64 exec, exec, s[4:5]
	s_cbranch_execnz .LBB0_38

; DI u16 f2bf(float a) { return (u16)(pack2(a, 0.f) & 0xffffu); }
; template <int MODE>
; DI void transpose_tile(const float* __restrict__ src, const float* __restrict__ src2, long lds_, u16* __restrict__ dst,
;                        long ldd, int k0, int n0, float* tile) {
;     ...
;     for (int i = 0; i < 8; ++i) {
;       int kk = (tid >> 6) + 8 * i;
;       tile[kk * 65 + nn] = ok ? s[(long)(k0 + kk) * lds_ + col] : 0.f;
;     }
;   }
;   __syncthreads();
;   {
;     int kk = tid & 63;
;     for (int i = 0; i < 8; ++i) {
;       int nn = (tid >> 6) + 8 * i;
;       if (MODE == 3) dst[vfrag_off(k0 + kk, n0, nn)] = f2bf(tile[kk * 65 + nn]);
;       else dst[(long)(n0 + nn) * ldd + k0 + kk] = f2bf(tile[kk * 65 + nn]);
;     }
;   }
.LBB0_41:
	s_or_b64 exec, exec, s[16:17]
	ds_write_b32 v37, v2 offset:8320
	ds_write_b32 v37, v40 offset:10400
	ds_write_b32 v37, v41 offset:12480
	ds_write_b32 v37, v42 offset:14560
	s_waitcnt lgkmcnt(0)
	s_barrier
	ds_read2_b32 v[40:41], v29 offset1:8
	v_or_b32_e32 v44, s29, v9
	s_lshl_b32 s6, s6, 1
	v_ashrrev_i32_e32 v45, 31, v44
	v_lshl_add_u64 v[42:43], v[6:7], 0, s[6:7]
	v_lshlrev_b64 v[44:45], 11, v[44:45]
	s_waitcnt lgkmcnt(0)
	v_cvt_pk_bf16_f32 v2, v40, s0
	v_lshl_add_u64 v[44:45], v[42:43], 0, v[44:45]
	v_or_b32_e32 v40, s29, v20
	global_store_short v[44:45], v2, off
	v_cvt_pk_bf16_f32 v2, v41, s0
	v_ashrrev_i32_e32 v41, 31, v40
	ds_read2_b32 v[44:45], v29 offset0:16 offset1:24
	v_lshlrev_b64 v[40:41], 11, v[40:41]
	v_lshl_add_u64 v[40:41], v[42:43], 0, v[40:41]
	global_store_short v[40:41], v2, off
	v_or_b32_e32 v40, s29, v21
	v_ashrrev_i32_e32 v41, 31, v40
	v_lshlrev_b64 v[40:41], 11, v[40:41]
	s_waitcnt lgkmcnt(0)
	v_cvt_pk_bf16_f32 v2, v44, s0
	v_lshl_add_u64 v[40:41], v[42:43], 0, v[40:41]
	global_store_short v[40:41], v2, off
	v_or_b32_e32 v40, s29, v22
	v_ashrrev_i32_e32 v41, 31, v40
	v_cvt_pk_bf16_f32 v2, v45, s0
	ds_read2_b32 v[44:45], v29 offset0:32 offset1:40
	v_lshlrev_b64 v[40:41], 11, v[40:41]
	v_lshl_add_u64 v[40:41], v[42:43], 0, v[40:41]
	global_store_short v[40:41], v2, off
	v_or_b32_e32 v40, s29, v23
	v_ashrrev_i32_e32 v41, 31, v40
	v_lshlrev_b64 v[40:41], 11, v[40:41]
	s_waitcnt lgkmcnt(0)
	v_cvt_pk_bf16_f32 v2, v44, s0
	v_lshl_add_u64 v[40:41], v[42:43], 0, v[40:41]
	global_store_short v[40:41], v2, off
	v_or_b32_e32 v40, s29, v24
	v_ashrrev_i32_e32 v41, 31, v40
	v_cvt_pk_bf16_f32 v2, v45, s0
	ds_read2_b32 v[44:45], v29 offset0:48 offset1:56
	v_lshlrev_b64 v[40:41], 11, v[40:41]
	v_lshl_add_u64 v[40:41], v[42:43], 0, v[40:41]
	global_store_short v[40:41], v2, off
	v_or_b32_e32 v40, s29, v25
	v_ashrrev_i32_e32 v41, 31, v40
	v_lshlrev_b64 v[40:41], 11, v[40:41]
	s_waitcnt lgkmcnt(0)
	v_cvt_pk_bf16_f32 v2, v44, s0
	v_lshl_add_u64 v[40:41], v[42:43], 0, v[40:41]
	global_store_short v[40:41], v2, off
	v_add_u32_e32 v40, s29, v26
	v_ashrrev_i32_e32 v41, 31, v40
	v_lshlrev_b64 v[40:41], 11, v[40:41]
	v_cvt_pk_bf16_f32 v2, v45, s0
	v_lshl_add_u64 v[40:41], v[42:43], 0, v[40:41]
	global_store_short v[40:41], v2, off

; DI u16 f2bf(float a) { return (u16)(pack2(a, 0.f) & 0xffffu); }
; template <int MODE>
; DI void transpose_tile(const float* __restrict__ src, const float* __restrict__ src2, long lds_, u16* __restrict__ dst,
;                        long ldd, int k0, int n0, float* tile) {
;     ...
;     for (int i = 0; i < 8; ++i) {
;       int kk = (tid >> 6) + 8 * i;
;       tile[kk * 65 + nn] = ok ? s[(long)(k0 + kk) * lds_ + col] : 0.f;
;     }
;   }
;   __syncthreads();
;   {
;     int kk = tid & 63;
;     for (int i = 0; i < 8; ++i) {
;       int nn = (tid >> 6) + 8 * i;
;       if (MODE == 3) dst[vfrag_off(k0 + kk, n0, nn)] = f2bf(tile[kk * 65 + nn]);
;       else dst[(long)(n0 + nn) * ldd + k0 + kk] = f2bf(tile[kk * 65 + nn]);
;     }
;   }
; DI void phase_prep(const Params& P, unsigned char* smem) {
;     ...
;     {
;       int bh = q >> 6, tt = q & 63, b = bh >> 3, h = bh & 7;
;       transpose_tile<3>(P.cache_v + (long)b * 4096 * 512 + h * 64, nullptr, 512,
;                         (u16*)((unsigned char*)P.out + OB_SVT) + (long)b * 512 * 4160, 4160, tt * 64, h, tile);
;     }
.LBB0_43:
	s_cmpk_gt_i32 s28, 0x6ff
	s_mov_b64 s[4:5], -1
	s_cbranch_scc0 .LBB0_65
	s_cmpk_gt_u32 s28, 0x77f
	s_cbranch_scc0 .LBB0_62
	s_cmpk_gt_u32 s28, 0x87f
	s_cbranch_scc0 .LBB0_59
	s_cmpk_gt_u32 s28, 0x97f
	s_cbranch_scc0 .LBB0_56
	s_cmpk_gt_u32 s28, 0xeff
	s_cbranch_scc0 .LBB0_53
	s_cmpk_gt_u32 s28, 0x11bf
	s_cbranch_scc0 .LBB0_50
	s_add_i32 s4, s28, 0xffffee40
	s_lshr_b32 s6, s4, 9
	s_bfe_u32 s16, s4, 0x30006
	s_lshl_b64 s[4:5], s[6:7], 23
	s_add_u32 s4, s10, s4
	s_addc_u32 s5, s11, s5
	s_lshl_b32 s17, s16, 8
	s_add_u32 s4, s4, s17
	s_addc_u32 s5, s5, 0
	s_and_b32 s17, s18, 0xfc0
	v_or_b32_e32 v2, s17, v9
	v_lshl_or_b32 v2, v2, 9, v1
	v_lshl_add_u64 v[40:41], v[2:3], 2, s[4:5]
	v_or_b32_e32 v2, s17, v20
	v_lshl_or_b32 v2, v2, 9, v1
	v_lshl_add_u64 v[42:43], v[2:3], 2, s[4:5]
	v_or_b32_e32 v2, s17, v21
	v_lshl_or_b32 v2, v2, 9, v1
	v_lshl_add_u64 v[44:45], v[2:3], 2, s[4:5]
	v_or_b32_e32 v2, s17, v22
	v_lshl_or_b32 v2, v2, 9, v1
	v_lshl_add_u64 v[46:47], v[2:3], 2, s[4:5]
	v_or_b32_e32 v2, s17, v23
	v_lshl_or_b32 v2, v2, 9, v1
	v_lshl_add_u64 v[48:49], v[2:3], 2, s[4:5]
	v_or_b32_e32 v2, s17, v24
	v_lshl_or_b32 v2, v2, 9, v1
	v_lshl_add_u64 v[50:51], v[2:3], 2, s[4:5]
	v_or_b32_e32 v2, s17, v25
	v_lshl_or_b32 v2, v2, 9, v1
	v_lshl_add_u64 v[52:53], v[2:3], 2, s[4:5]
	v_add_u32_e32 v2, s17, v26
	v_lshl_or_b32 v2, v2, 9, v1
	s_waitcnt lgkmcnt(0)
	s_barrier
	v_lshl_add_u64 v[54:55], v[2:3], 2, s[4:5]
	global_load_dword v39, v[40:41], off
	global_load_dword v56, v[42:43], off
	global_load_dword v57, v[44:45], off
	global_load_dword v58, v[46:47], off
	global_load_dword v59, v[48:49], off
	global_load_dword v60, v[50:51], off
	global_load_dword v61, v[52:53], off
	global_load_dword v62, v[54:55], off
	v_add_u32_e32 v2, s18, v1
	v_mad_u64_u32 v[40:41], s[4:5], s6, v38, v[4:5]
	v_and_b32_e32 v2, 0xfe0, v2
	s_lshl_b32 s4, s16, 2
	v_or3_b32 v2, s4, v2, v27
	v_lshlrev_b32_e32 v42, 6, v2
	v_or_b32_e32 v48, v2, v30
	v_add_u32_e32 v64, v2, v33
	v_or_b32_e32 v2, v42, v28
	v_or_b32_e32 v50, v2, v9
	v_or_b32_e32 v44, v2, v20
	v_or_b32_e32 v46, v2, v21
	v_lshlrev_b32_e32 v2, 4, v50
	v_or_b32_e32 v52, v42, v31
	v_or_b32_e32 v54, v42, v32
	v_lshl_add_u64 v[42:43], v[40:41], 0, v[2:3]
	v_lshlrev_b32_e32 v2, 4, v44
	v_lshl_add_u64 v[44:45], v[40:41], 0, v[2:3]
	v_lshlrev_b32_e32 v2, 4, v46
	v_lshl_add_u64 v[46:47], v[40:41], 0, v[2:3]
	v_lshl_or_b32 v2, v48, 6, v35
	v_lshl_add_u64 v[48:49], v[2:3], 4, v[40:41]
	v_or_b32_e32 v2, 64, v50
	v_lshl_add_u64 v[50:51], v[2:3], 4, v[40:41]
	v_lshlrev_b32_e32 v2, 4, v52
	v_lshl_add_u64 v[52:53], v[40:41], 0, v[2:3]
	v_lshlrev_b32_e32 v2, 4, v54
	s_mov_b64 s[4:5], 0
	s_waitcnt vmcnt(0)
	ds_write_b32 v37, v39
	ds_write_b32 v37, v56 offset:2080
	ds_write_b32 v37, v57 offset:4160
	ds_write_b32 v37, v58 offset:6240
	ds_write_b32 v37, v59 offset:8320
	ds_write_b32 v37, v60 offset:10400
	ds_write_b32 v37, v61 offset:12480
	ds_write_b32 v37, v62 offset:14560
	s_waitcnt lgkmcnt(0)
	s_barrier
	ds_read2_b32 v[54:55], v29 offset1:8
	ds_read2_b32 v[58:59], v29 offset0:16 offset1:24
	ds_read2_b32 v[60:61], v29 offset0:32 offset1:40
	ds_read2_b32 v[62:63], v29 offset0:48 offset1:56
	v_lshl_add_u64 v[56:57], v[40:41], 0, v[2:3]
	s_waitcnt lgkmcnt(3)
	v_cvt_pk_bf16_f32 v2, v54, s0
	v_cvt_pk_bf16_f32 v39, v55, s0
	s_waitcnt lgkmcnt(2)
	v_cvt_pk_bf16_f32 v54, v58, s0
	v_cvt_pk_bf16_f32 v55, v59, s0
	s_waitcnt lgkmcnt(1)
	v_cvt_pk_bf16_f32 v58, v60, s0
	v_cvt_pk_bf16_f32 v59, v61, s0
	s_waitcnt lgkmcnt(0)
	v_cvt_pk_bf16_f32 v60, v62, s0
	global_store_short v[42:43], v2, off
	global_store_short v[44:45], v39, off
	global_store_short v[46:47], v54, off
	global_store_short v[48:49], v55, off
	global_store_short v[50:51], v58, off
	global_store_short v[52:53], v59, off
	global_store_short v[56:57], v60, off
	v_lshl_or_b32 v2, v64, 6, v36
	v_cvt_pk_bf16_f32 v61, v63, s0
	v_lshl_add_u64 v[40:41], v[2:3], 4, v[40:41]
	global_store_short v[40:41], v61, off
; DI u16 f2bf(float a) { return (u16)(pack2(a, 0.f) & 0xffffu); }
; template <int MODE>
; DI void transpose_tile(const float* __restrict__ src, const float* __restrict__ src2, long lds_, u16* __restrict__ dst,
;                        long ldd, int k0, int n0, float* tile) {
;     ...
;     for (int i = 0; i < 8; ++i) {
;       int kk = (tid >> 6) + 8 * i;
;       tile[kk * 65 + nn] = ok ? s[(long)(k0 + kk) * lds_ + col] : 0.f;
;     }
;   }
;   __syncthreads();
;   {
;     int kk = tid & 63;
;     for (int i = 0; i < 8; ++i) {
;       int nn = (tid >> 6) + 8 * i;
;       if (MODE == 3) dst[vfrag_off(k0 + kk, n0, nn)] = f2bf(tile[kk * 65 + nn]);
;       else dst[(long)(n0 + nn) * ldd + k0 + kk] = f2bf(tile[kk * 65 + nn]);
;     }
;   }
; DI void phase_prep(const Params& P, unsigned char* smem) {
;     ...
;     if (q < T_WDN) { transpose_tile<0>(P.w_down, nullptr, 1024, (u16*)(P.ws + W_WDN), DFF, (q % 44) * 64, (q / 44) * 64, tile); continue; }
.LBB0_50:
	s_andn2_b64 vcc, exec, s[4:5]
	s_cbranch_vccnz .LBB0_52
	s_add_i32 s4, s28, 0xf100
	s_and_b32 s5, s4, 0xffff
	s_mul_i32 s5, s5, 0xba2f
	s_lshr_b32 s5, s5, 21
	s_mul_i32 s6, s5, 44
	s_sub_i32 s4, s4, s6
	s_lshl_b32 s4, s4, 6
	s_and_b32 s4, s4, 0xffc0
	s_lshl_b32 s5, s5, 6
	v_or_b32_e32 v39, s5, v1
	v_or_b32_e32 v2, s4, v9
	v_lshl_add_u32 v2, v2, 10, v39
	v_lshl_add_u64 v[40:41], v[2:3], 2, s[24:25]
	v_or_b32_e32 v2, s4, v20
	v_lshl_add_u32 v2, v2, 10, v39
	v_lshl_add_u64 v[42:43], v[2:3], 2, s[24:25]
	v_or_b32_e32 v2, s4, v21
	v_lshl_add_u32 v2, v2, 10, v39
	v_lshl_add_u64 v[44:45], v[2:3], 2, s[24:25]
	v_or_b32_e32 v2, s4, v22
	v_lshl_add_u32 v2, v2, 10, v39
	v_lshl_add_u64 v[46:47], v[2:3], 2, s[24:25]
	v_or_b32_e32 v2, s4, v23
	v_lshl_add_u32 v2, v2, 10, v39
	v_lshl_add_u64 v[48:49], v[2:3], 2, s[24:25]
	v_or_b32_e32 v2, s4, v24
	v_lshl_add_u32 v2, v2, 10, v39
	v_lshl_add_u64 v[50:51], v[2:3], 2, s[24:25]
	v_or_b32_e32 v2, s4, v25
	v_lshl_add_u32 v2, v2, 10, v39
	v_lshl_add_u64 v[52:53], v[2:3], 2, s[24:25]
	v_add_u32_e32 v2, s4, v26
	v_lshl_add_u32 v2, v2, 10, v39
	s_waitcnt lgkmcnt(0)
	s_barrier
	v_lshl_add_u64 v[54:55], v[2:3], 2, s[24:25]
	global_load_dword v39, v[40:41], off
	global_load_dword v56, v[42:43], off
	global_load_dword v57, v[44:45], off
	global_load_dword v58, v[46:47], off
	global_load_dword v59, v[48:49], off
	global_load_dword v60, v[50:51], off
	global_load_dword v61, v[52:53], off
	global_load_dword v62, v[54:55], off
	v_or_b32_e32 v2, s5, v9
	s_lshl_b32 s6, s4, 1
	v_or_b32_e32 v44, s5, v20
	v_lshl_add_u64 v[40:41], v[10:11], 0, s[6:7]
	v_mul_u32_u24_e32 v2, 0xb00, v2
	v_or_b32_e32 v46, s5, v21
	v_lshl_add_u64 v[42:43], v[2:3], 1, v[40:41]
	v_mul_u32_u24_e32 v2, 0xb00, v44
	v_or_b32_e32 v48, s5, v22
	v_lshl_add_u64 v[44:45], v[2:3], 1, v[40:41]
	v_mul_u32_u24_e32 v2, 0xb00, v46
	v_or_b32_e32 v50, s5, v23
	v_lshl_add_u64 v[46:47], v[2:3], 1, v[40:41]
	v_mul_u32_u24_e32 v2, 0xb00, v48
	v_or_b32_e32 v52, s5, v24
	v_lshl_add_u64 v[48:49], v[2:3], 1, v[40:41]
	v_mul_u32_u24_e32 v2, 0xb00, v50
	v_or_b32_e32 v54, s5, v25
	v_lshl_add_u64 v[50:51], v[2:3], 1, v[40:41]
	v_mul_u32_u24_e32 v2, 0xb00, v52
	v_add_u32_e32 v63, s5, v26
	v_lshl_add_u64 v[52:53], v[2:3], 1, v[40:41]
	v_mul_u32_u24_e32 v2, 0xb00, v54
	v_lshl_add_u64 v[54:55], v[2:3], 1, v[40:41]
	v_mul_u32_u24_e32 v2, 0xb00, v63
	v_lshl_add_u64 v[40:41], v[2:3], 1, v[40:41]
	s_waitcnt vmcnt(0)
	ds_write_b32 v37, v39
	ds_write_b32 v37, v56 offset:2080
	ds_write_b32 v37, v57 offset:4160
	ds_write_b32 v37, v58 offset:6240
	ds_write_b32 v37, v59 offset:8320
	ds_write_b32 v37, v60 offset:10400
	ds_write_b32 v37, v61 offset:12480
	ds_write_b32 v37, v62 offset:14560
	s_waitcnt lgkmcnt(0)
	s_barrier
	ds_read2_b32 v[56:57], v29 offset1:8
	ds_read2_b32 v[58:59], v29 offset0:16 offset1:24
	ds_read2_b32 v[60:61], v29 offset0:32 offset1:40
	ds_read2_b32 v[62:63], v29 offset0:48 offset1:56
	s_waitcnt lgkmcnt(3)
	v_cvt_pk_bf16_f32 v2, v56, s0
	v_cvt_pk_bf16_f32 v39, v57, s0
	s_waitcnt lgkmcnt(2)
	v_cvt_pk_bf16_f32 v56, v58, s0
	v_cvt_pk_bf16_f32 v57, v59, s0
	s_waitcnt lgkmcnt(1)
	v_cvt_pk_bf16_f32 v58, v60, s0
	v_cvt_pk_bf16_f32 v59, v61, s0
	s_waitcnt lgkmcnt(0)
	v_cvt_pk_bf16_f32 v60, v62, s0
	v_cvt_pk_bf16_f32 v61, v63, s0
	global_store_short v[42:43], v2, off
	global_store_short v[44:45], v39, off
	global_store_short v[46:47], v56, off
	global_store_short v[48:49], v57, off
	global_store_short v[50:51], v58, off
	global_store_short v[52:53], v59, off
	global_store_short v[54:55], v60, off
	global_store_short v[40:41], v61, off

; DI u16 f2bf(float a) { return (u16)(pack2(a, 0.f) & 0xffffu); }
; template <int MODE>
; DI void transpose_tile(const float* __restrict__ src, const float* __restrict__ src2, long lds_, u16* __restrict__ dst,
;                        long ldd, int k0, int n0, float* tile) {
;     ...
;     } else if (MODE == 2) {
;       int grp = n >> 6, within = n & 63;
;       col = grp * 32 + (within & 31);
;       s = (within < 32) ? src : src2;
;     }
;     for (int i = 0; i < 8; ++i) {
;       int kk = (tid >> 6) + 8 * i;
;       tile[kk * 65 + nn] = ok ? s[(long)(k0 + kk) * lds_ + col] : 0.f;
;     }
;   }
;   __syncthreads();
;   {
;     int kk = tid & 63;
;     for (int i = 0; i < 8; ++i) {
;       int nn = (tid >> 6) + 8 * i;
;       if (MODE == 3) dst[vfrag_off(k0 + kk, n0, nn)] = f2bf(tile[kk * 65 + nn]);
;       else dst[(long)(n0 + nn) * ldd + k0 + kk] = f2bf(tile[kk * 65 + nn]);
;     }
;   }
; DI void phase_prep(const Params& P, unsigned char* smem) {
;     ...
;     if (q < T_WGU) { transpose_tile<2>(P.w_gate, P.w_up, DFF, (u16*)(P.ws + W_WGU), 1024, (q & 15) * 64, (q >> 4) * 64, tile); continue; }
.LBB0_53:
	s_andn2_b64 vcc, exec, s[4:5]
	s_cbranch_vccnz .LBB0_55
	s_and_b32 s5, s20, 0x3fc0
	s_addk_i32 s5, 0xda00
	s_lshr_b32 s6, s5, 1
	s_and_b32 s4, s18, 0x3c0
	s_and_b32 s6, s6, 0x1fe0
	v_or_b32_e32 v39, s6, v34
	v_or_b32_e32 v2, s4, v9
	v_mad_u32_u24 v2, v2, s26, v39
	v_lshl_add_u64 v[40:41], v[2:3], 2, v[12:13]
	v_or_b32_e32 v2, s4, v20
	v_mad_u32_u24 v2, v2, s26, v39
	v_lshl_add_u64 v[42:43], v[2:3], 2, v[12:13]
	v_or_b32_e32 v2, s4, v21
	v_mad_u32_u24 v2, v2, s26, v39
	v_lshl_add_u64 v[44:45], v[2:3], 2, v[12:13]
	v_or_b32_e32 v2, s4, v22
	v_mad_u32_u24 v2, v2, s26, v39
	v_lshl_add_u64 v[46:47], v[2:3], 2, v[12:13]
	v_or_b32_e32 v2, s4, v23
	v_mad_u32_u24 v2, v2, s26, v39
	v_lshl_add_u64 v[48:49], v[2:3], 2, v[12:13]
	v_or_b32_e32 v2, s4, v24
	v_mad_u32_u24 v2, v2, s26, v39
	v_lshl_add_u64 v[50:51], v[2:3], 2, v[12:13]
	v_or_b32_e32 v2, s4, v25
	v_mad_u32_u24 v2, v2, s26, v39
	v_lshl_add_u64 v[52:53], v[2:3], 2, v[12:13]
	v_add_u32_e32 v2, s4, v26
	v_mad_u32_u24 v2, v2, s26, v39
	s_waitcnt lgkmcnt(0)
	s_barrier
	v_lshl_add_u64 v[54:55], v[2:3], 2, v[12:13]
	global_load_dword v39, v[40:41], off
	global_load_dword v56, v[42:43], off
	global_load_dword v57, v[44:45], off
	global_load_dword v58, v[46:47], off
	global_load_dword v59, v[48:49], off
	global_load_dword v60, v[50:51], off
	global_load_dword v61, v[52:53], off
	global_load_dword v62, v[54:55], off
	v_or_b32_e32 v2, s4, v1
	v_or_b32_e32 v40, s5, v9
	v_lshlrev_b32_e32 v54, 1, v2
	v_or_b32_e32 v42, s5, v20
	v_lshl_or_b32 v2, v40, 11, v54
	v_or_b32_e32 v44, s5, v21
	v_lshl_add_u64 v[40:41], s[8:9], 0, v[2:3]
	v_lshl_or_b32 v2, v42, 11, v54
	v_or_b32_e32 v46, s5, v22
	v_lshl_add_u64 v[42:43], s[8:9], 0, v[2:3]
	v_lshl_or_b32 v2, v44, 11, v54
	v_or_b32_e32 v48, s5, v23
	v_lshl_add_u64 v[44:45], s[8:9], 0, v[2:3]
	v_lshl_or_b32 v2, v46, 11, v54
	v_or_b32_e32 v50, s5, v24
	v_lshl_add_u64 v[46:47], s[8:9], 0, v[2:3]
	v_lshl_or_b32 v2, v48, 11, v54
	v_or_b32_e32 v52, s5, v25
	v_lshl_add_u64 v[48:49], s[8:9], 0, v[2:3]
	v_lshl_or_b32 v2, v50, 11, v54
	v_add_u32_e32 v55, s5, v26
	v_lshl_add_u64 v[50:51], s[8:9], 0, v[2:3]
	v_lshl_or_b32 v2, v52, 11, v54
	v_lshl_add_u64 v[52:53], s[8:9], 0, v[2:3]
	v_lshl_or_b32 v2, v55, 11, v54
	s_waitcnt vmcnt(0)
	ds_write_b32 v37, v39
	ds_write_b32 v37, v56 offset:2080
	ds_write_b32 v37, v57 offset:4160
	ds_write_b32 v37, v58 offset:6240
	ds_write_b32 v37, v59 offset:8320
	ds_write_b32 v37, v60 offset:10400
	ds_write_b32 v37, v61 offset:12480
	ds_write_b32 v37, v62 offset:14560
	s_waitcnt lgkmcnt(0)
	s_barrier
	ds_read2_b32 v[54:55], v29 offset1:8
	ds_read2_b32 v[58:59], v29 offset0:16 offset1:24
	ds_read2_b32 v[60:61], v29 offset0:32 offset1:40
	ds_read2_b32 v[62:63], v29 offset0:48 offset1:56
	v_lshl_add_u64 v[56:57], s[8:9], 0, v[2:3]
	s_waitcnt lgkmcnt(3)
	v_cvt_pk_bf16_f32 v2, v54, s0
	v_cvt_pk_bf16_f32 v39, v55, s0
	s_waitcnt lgkmcnt(2)
	v_cvt_pk_bf16_f32 v54, v58, s0
	v_cvt_pk_bf16_f32 v55, v59, s0
	s_waitcnt lgkmcnt(1)
	v_cvt_pk_bf16_f32 v58, v60, s0
	v_cvt_pk_bf16_f32 v59, v61, s0
	s_waitcnt lgkmcnt(0)
	v_cvt_pk_bf16_f32 v60, v62, s0
	v_cvt_pk_bf16_f32 v61, v63, s0
	global_store_short v[40:41], v2, off
	global_store_short v[42:43], v39, off
	global_store_short v[44:45], v54, off
	global_store_short v[46:47], v55, off
	global_store_short v[48:49], v58, off
	global_store_short v[50:51], v59, off
	global_store_short v[52:53], v60, off
	global_store_short v[56:57], v61, off

; DI u16 f2bf(float a) { return (u16)(pack2(a, 0.f) & 0xffffu); }
; template <int MODE>
; DI void transpose_tile(const float* __restrict__ src, const float* __restrict__ src2, long lds_, u16* __restrict__ dst,
;                        long ldd, int k0, int n0, float* tile) {
;     ...
;     for (int i = 0; i < 8; ++i) {
;       int kk = (tid >> 6) + 8 * i;
;       tile[kk * 65 + nn] = ok ? s[(long)(k0 + kk) * lds_ + col] : 0.f;
;     }
;   }
;   __syncthreads();
;   {
;     int kk = tid & 63;
;     for (int i = 0; i < 8; ++i) {
;       int nn = (tid >> 6) + 8 * i;
;       if (MODE == 3) dst[vfrag_off(k0 + kk, n0, nn)] = f2bf(tile[kk * 65 + nn]);
;       else dst[(long)(n0 + nn) * ldd + k0 + kk] = f2bf(tile[kk * 65 + nn]);
;     }
;   }
; DI void phase_prep(const Params& P, unsigned char* smem) {
;     ...
;     if (q < T_WO) { transpose_tile<0>(P.w_o, nullptr, 1024, (u16*)(P.ws + W_WO), 1024, (q & 15) * 64, (q >> 4) * 64, tile); continue; }
.LBB0_56:
	s_andn2_b64 vcc, exec, s[4:5]
	s_cbranch_vccnz .LBB0_58
	s_and_b32 s5, s20, 0x3fc0
	s_and_b32 s4, s18, 0x3c0
	s_addk_i32 s5, 0xde00
	v_or_b32_e32 v39, s5, v1
	v_or_b32_e32 v2, s4, v9
	v_lshl_add_u32 v2, v2, 10, v39
	v_lshl_add_u64 v[40:41], v[2:3], 2, s[2:3]
	v_or_b32_e32 v2, s4, v20
	v_lshl_add_u32 v2, v2, 10, v39
	v_lshl_add_u64 v[42:43], v[2:3], 2, s[2:3]
	v_or_b32_e32 v2, s4, v21
	v_lshl_add_u32 v2, v2, 10, v39
	v_lshl_add_u64 v[44:45], v[2:3], 2, s[2:3]
	v_or_b32_e32 v2, s4, v22
	v_lshl_add_u32 v2, v2, 10, v39
	v_lshl_add_u64 v[46:47], v[2:3], 2, s[2:3]
	v_or_b32_e32 v2, s4, v23
	v_lshl_add_u32 v2, v2, 10, v39
	v_lshl_add_u64 v[48:49], v[2:3], 2, s[2:3]
	v_or_b32_e32 v2, s4, v24
	v_lshl_add_u32 v2, v2, 10, v39
	v_lshl_add_u64 v[50:51], v[2:3], 2, s[2:3]
	v_or_b32_e32 v2, s4, v25
	v_lshl_add_u32 v2, v2, 10, v39
	v_lshl_add_u64 v[52:53], v[2:3], 2, s[2:3]
	v_add_u32_e32 v2, s4, v26
	v_lshl_add_u32 v2, v2, 10, v39
	s_waitcnt lgkmcnt(0)
	s_barrier
	v_lshl_add_u64 v[54:55], v[2:3], 2, s[2:3]
	global_load_dword v39, v[40:41], off
	global_load_dword v58, v[42:43], off
	global_load_dword v59, v[44:45], off
	global_load_dword v60, v[46:47], off
	global_load_dword v61, v[48:49], off
	global_load_dword v62, v[50:51], off
	global_load_dword v63, v[52:53], off
	global_load_dword v64, v[54:55], off
	v_or_b32_e32 v2, s5, v9
	v_lshlrev_b64 v[42:43], 11, v[2:3]
	v_or_b32_e32 v2, s5, v20
	v_lshlrev_b64 v[44:45], 11, v[2:3]
	v_or_b32_e32 v2, s5, v21
	v_lshlrev_b64 v[46:47], 11, v[2:3]
	v_or_b32_e32 v2, s5, v22
	v_lshlrev_b64 v[48:49], 11, v[2:3]
	v_or_b32_e32 v2, s5, v23
	v_lshlrev_b64 v[50:51], 11, v[2:3]
	v_or_b32_e32 v2, s5, v24
	v_lshlrev_b64 v[52:53], 11, v[2:3]
	v_or_b32_e32 v2, s5, v25
	s_lshl_b32 s6, s4, 1
	v_lshlrev_b64 v[54:55], 11, v[2:3]
	v_add_u32_e32 v2, s5, v26
	v_lshl_add_u64 v[40:41], v[14:15], 0, s[6:7]
	v_lshlrev_b64 v[56:57], 11, v[2:3]
	v_lshl_add_u64 v[42:43], v[40:41], 0, v[42:43]
	v_lshl_add_u64 v[44:45], v[40:41], 0, v[44:45]
	v_lshl_add_u64 v[46:47], v[40:41], 0, v[46:47]
	v_lshl_add_u64 v[48:49], v[40:41], 0, v[48:49]
	v_lshl_add_u64 v[50:51], v[40:41], 0, v[50:51]
	v_lshl_add_u64 v[52:53], v[40:41], 0, v[52:53]
	v_lshl_add_u64 v[54:55], v[40:41], 0, v[54:55]
	v_lshl_add_u64 v[40:41], v[40:41], 0, v[56:57]
	s_waitcnt vmcnt(0)
	ds_write_b32 v37, v39
	ds_write_b32 v37, v58 offset:2080
	ds_write_b32 v37, v59 offset:4160
	ds_write_b32 v37, v60 offset:6240
	ds_write_b32 v37, v61 offset:8320
	ds_write_b32 v37, v62 offset:10400
	ds_write_b32 v37, v63 offset:12480
	ds_write_b32 v37, v64 offset:14560
	s_waitcnt lgkmcnt(0)
	s_barrier
	ds_read2_b32 v[58:59], v29 offset1:8
	ds_read2_b32 v[56:57], v29 offset0:16 offset1:24
	ds_read2_b32 v[60:61], v29 offset0:32 offset1:40
	ds_read2_b32 v[62:63], v29 offset0:48 offset1:56
	s_waitcnt lgkmcnt(2)
	v_cvt_pk_bf16_f32 v56, v56, s0
	v_cvt_pk_bf16_f32 v2, v58, s0
	v_cvt_pk_bf16_f32 v39, v59, s0
	v_cvt_pk_bf16_f32 v57, v57, s0
	s_waitcnt lgkmcnt(1)
	v_cvt_pk_bf16_f32 v58, v60, s0
	v_cvt_pk_bf16_f32 v59, v61, s0
	s_waitcnt lgkmcnt(0)
	v_cvt_pk_bf16_f32 v60, v62, s0
	v_cvt_pk_bf16_f32 v61, v63, s0
	global_store_short v[42:43], v2, off
	global_store_short v[44:45], v39, off
	global_store_short v[46:47], v56, off
	global_store_short v[48:49], v57, off
	global_store_short v[50:51], v58, off
	global_store_short v[52:53], v59, off
	global_store_short v[54:55], v60, off
	global_store_short v[40:41], v61, off

; DI u16 f2bf(float a) { return (u16)(pack2(a, 0.f) & 0xffffu); }
; template <int MODE>
; DI void transpose_tile(const float* __restrict__ src, const float* __restrict__ src2, long lds_, u16* __restrict__ dst,
;                        long ldd, int k0, int n0, float* tile) {
;     ...
;     for (int i = 0; i < 8; ++i) {
;       int kk = (tid >> 6) + 8 * i;
;       tile[kk * 65 + nn] = ok ? s[(long)(k0 + kk) * lds_ + col] : 0.f;
;     }
;   }
;   __syncthreads();
;   {
;     int kk = tid & 63;
;     for (int i = 0; i < 8; ++i) {
;       int nn = (tid >> 6) + 8 * i;
;       if (MODE == 3) dst[vfrag_off(k0 + kk, n0, nn)] = f2bf(tile[kk * 65 + nn]);
;       else dst[(long)(n0 + nn) * ldd + k0 + kk] = f2bf(tile[kk * 65 + nn]);
;     }
;   }
; DI void phase_prep(const Params& P, unsigned char* smem) {
;     ...
;     if (q < T_WPR) { transpose_tile<0>(P.w_pr, nullptr, 1024, (u16*)(P.ws + W_WPR), 1024, (q & 15) * 64, (q >> 4) * 64, tile); continue; }
.LBB0_59:
	s_andn2_b64 vcc, exec, s[4:5]
	s_cbranch_vccnz .LBB0_61
	s_and_b32 s5, s20, 0x3fc0
	s_and_b32 s4, s18, 0x3c0
	s_addk_i32 s5, 0xe200
	v_or_b32_e32 v39, s5, v1
	v_or_b32_e32 v2, s4, v9
	v_lshl_add_u32 v2, v2, 10, v39
	v_lshl_add_u64 v[40:41], v[2:3], 2, s[14:15]
	v_or_b32_e32 v2, s4, v20
	v_lshl_add_u32 v2, v2, 10, v39
	v_lshl_add_u64 v[42:43], v[2:3], 2, s[14:15]
	v_or_b32_e32 v2, s4, v21
	v_lshl_add_u32 v2, v2, 10, v39
	v_lshl_add_u64 v[44:45], v[2:3], 2, s[14:15]
	v_or_b32_e32 v2, s4, v22
	v_lshl_add_u32 v2, v2, 10, v39
	v_lshl_add_u64 v[46:47], v[2:3], 2, s[14:15]
	v_or_b32_e32 v2, s4, v23
	v_lshl_add_u32 v2, v2, 10, v39
	v_lshl_add_u64 v[48:49], v[2:3], 2, s[14:15]
	v_or_b32_e32 v2, s4, v24
	v_lshl_add_u32 v2, v2, 10, v39
	v_lshl_add_u64 v[50:51], v[2:3], 2, s[14:15]
	v_or_b32_e32 v2, s4, v25
	v_lshl_add_u32 v2, v2, 10, v39
	v_lshl_add_u64 v[52:53], v[2:3], 2, s[14:15]
	v_add_u32_e32 v2, s4, v26
	v_lshl_add_u32 v2, v2, 10, v39
	s_waitcnt lgkmcnt(0)
	s_barrier
	v_lshl_add_u64 v[54:55], v[2:3], 2, s[14:15]
	global_load_dword v39, v[40:41], off
	global_load_dword v58, v[42:43], off
	global_load_dword v59, v[44:45], off
	global_load_dword v60, v[46:47], off
	global_load_dword v61, v[48:49], off
	global_load_dword v62, v[50:51], off
	global_load_dword v63, v[52:53], off
	global_load_dword v64, v[54:55], off
	v_or_b32_e32 v2, s5, v9
	v_lshlrev_b64 v[42:43], 11, v[2:3]
	v_or_b32_e32 v2, s5, v20
	v_lshlrev_b64 v[44:45], 11, v[2:3]
	v_or_b32_e32 v2, s5, v21
	v_lshlrev_b64 v[46:47], 11, v[2:3]
	v_or_b32_e32 v2, s5, v22
	v_lshlrev_b64 v[48:49], 11, v[2:3]
	v_or_b32_e32 v2, s5, v23
	v_lshlrev_b64 v[50:51], 11, v[2:3]
	v_or_b32_e32 v2, s5, v24
	v_lshlrev_b64 v[52:53], 11, v[2:3]
	v_or_b32_e32 v2, s5, v25
	s_lshl_b32 s6, s4, 1
	v_lshlrev_b64 v[54:55], 11, v[2:3]
	v_add_u32_e32 v2, s5, v26
	v_lshl_add_u64 v[40:41], v[16:17], 0, s[6:7]
	v_lshlrev_b64 v[56:57], 11, v[2:3]
	v_lshl_add_u64 v[42:43], v[40:41], 0, v[42:43]
	v_lshl_add_u64 v[44:45], v[40:41], 0, v[44:45]
	v_lshl_add_u64 v[46:47], v[40:41], 0, v[46:47]
	v_lshl_add_u64 v[48:49], v[40:41], 0, v[48:49]
	v_lshl_add_u64 v[50:51], v[40:41], 0, v[50:51]
	v_lshl_add_u64 v[52:53], v[40:41], 0, v[52:53]
	v_lshl_add_u64 v[54:55], v[40:41], 0, v[54:55]
	v_lshl_add_u64 v[40:41], v[40:41], 0, v[56:57]
	s_waitcnt vmcnt(0)
	ds_write_b32 v37, v39
	ds_write_b32 v37, v58 offset:2080
	ds_write_b32 v37, v59 offset:4160
	ds_write_b32 v37, v60 offset:6240
	ds_write_b32 v37, v61 offset:8320
	ds_write_b32 v37, v62 offset:10400
	ds_write_b32 v37, v63 offset:12480
	ds_write_b32 v37, v64 offset:14560
	s_waitcnt lgkmcnt(0)
	s_barrier
	ds_read2_b32 v[58:59], v29 offset1:8
	ds_read2_b32 v[56:57], v29 offset0:16 offset1:24
	ds_read2_b32 v[60:61], v29 offset0:32 offset1:40
	ds_read2_b32 v[62:63], v29 offset0:48 offset1:56
	s_waitcnt lgkmcnt(2)
	v_cvt_pk_bf16_f32 v56, v56, s0
	v_cvt_pk_bf16_f32 v2, v58, s0
	v_cvt_pk_bf16_f32 v39, v59, s0
	v_cvt_pk_bf16_f32 v57, v57, s0
	s_waitcnt lgkmcnt(1)
	v_cvt_pk_bf16_f32 v58, v60, s0
	v_cvt_pk_bf16_f32 v59, v61, s0
	s_waitcnt lgkmcnt(0)
	v_cvt_pk_bf16_f32 v60, v62, s0
	v_cvt_pk_bf16_f32 v61, v63, s0
	global_store_short v[42:43], v2, off
	global_store_short v[44:45], v39, off
	global_store_short v[46:47], v56, off
	global_store_short v[48:49], v57, off
	global_store_short v[50:51], v58, off
	global_store_short v[52:53], v59, off
	global_store_short v[54:55], v60, off
	global_store_short v[40:41], v61, off

; DI u16 f2bf(float a) { return (u16)(pack2(a, 0.f) & 0xffffu); }
; template <int MODE>
; DI void transpose_tile(const float* __restrict__ src, const float* __restrict__ src2, long lds_, u16* __restrict__ dst,
;                        long ldd, int k0, int n0, float* tile) {
;     ...
;     for (int i = 0; i < 8; ++i) {
;       int kk = (tid >> 6) + 8 * i;
;       tile[kk * 65 + nn] = ok ? s[(long)(k0 + kk) * lds_ + col] : 0.f;
;     }
;   }
;   __syncthreads();
;   {
;     int kk = tid & 63;
;     for (int i = 0; i < 8; ++i) {
;       int nn = (tid >> 6) + 8 * i;
;       if (MODE == 3) dst[vfrag_off(k0 + kk, n0, nn)] = f2bf(tile[kk * 65 + nn]);
;       else dst[(long)(n0 + nn) * ldd + k0 + kk] = f2bf(tile[kk * 65 + nn]);
;     }
;   }
; DI void phase_prep(const Params& P, unsigned char* smem) {
;     ...
;     if (q < T_WPA) { transpose_tile<0>(P.w_pa, nullptr, 1024, (u16*)(P.ws + W_WPA), 512, (q & 7) * 64, (q >> 3) * 64, tile); continue; }
.LBB0_62:
	s_andn2_b64 vcc, exec, s[4:5]
	s_cbranch_vccnz .LBB0_64
	s_and_b32 s5, s22, 0x3fc0
	s_and_b32 s4, s18, 0x1c0
	s_addk_i32 s5, 0xc800
	v_or_b32_e32 v39, s5, v1
	v_or_b32_e32 v2, s4, v9
	v_lshl_add_u32 v2, v2, 10, v39
	v_lshl_add_u64 v[40:41], v[2:3], 2, s[12:13]
	v_or_b32_e32 v2, s4, v20
	v_lshl_add_u32 v2, v2, 10, v39
	v_lshl_add_u64 v[42:43], v[2:3], 2, s[12:13]
	v_or_b32_e32 v2, s4, v21
	v_lshl_add_u32 v2, v2, 10, v39
	v_lshl_add_u64 v[44:45], v[2:3], 2, s[12:13]
	v_or_b32_e32 v2, s4, v22
	v_lshl_add_u32 v2, v2, 10, v39
	v_lshl_add_u64 v[46:47], v[2:3], 2, s[12:13]
	v_or_b32_e32 v2, s4, v23
	v_lshl_add_u32 v2, v2, 10, v39
	v_lshl_add_u64 v[48:49], v[2:3], 2, s[12:13]
	v_or_b32_e32 v2, s4, v24
	v_lshl_add_u32 v2, v2, 10, v39
	v_lshl_add_u64 v[50:51], v[2:3], 2, s[12:13]
	v_or_b32_e32 v2, s4, v25
	v_lshl_add_u32 v2, v2, 10, v39
	v_lshl_add_u64 v[52:53], v[2:3], 2, s[12:13]
	v_add_u32_e32 v2, s4, v26
	v_lshl_add_u32 v2, v2, 10, v39
	s_waitcnt lgkmcnt(0)
	s_barrier
	v_lshl_add_u64 v[54:55], v[2:3], 2, s[12:13]
	global_load_dword v39, v[40:41], off
	global_load_dword v58, v[42:43], off
	global_load_dword v59, v[44:45], off
	global_load_dword v60, v[46:47], off
	global_load_dword v61, v[48:49], off
	global_load_dword v62, v[50:51], off
	global_load_dword v63, v[52:53], off
	global_load_dword v64, v[54:55], off
	v_or_b32_e32 v2, s5, v9
	v_lshlrev_b64 v[42:43], 10, v[2:3]
	v_or_b32_e32 v2, s5, v20
	v_lshlrev_b64 v[44:45], 10, v[2:3]
	v_or_b32_e32 v2, s5, v21
	v_lshlrev_b64 v[46:47], 10, v[2:3]
	v_or_b32_e32 v2, s5, v22
	v_lshlrev_b64 v[48:49], 10, v[2:3]
	v_or_b32_e32 v2, s5, v23
	v_lshlrev_b64 v[50:51], 10, v[2:3]
	v_or_b32_e32 v2, s5, v24
	v_lshlrev_b64 v[52:53], 10, v[2:3]
	v_or_b32_e32 v2, s5, v25
	s_lshl_b32 s6, s4, 1
	v_lshlrev_b64 v[54:55], 10, v[2:3]
	v_add_u32_e32 v2, s5, v26
	v_lshl_add_u64 v[40:41], v[18:19], 0, s[6:7]
	v_lshlrev_b64 v[56:57], 10, v[2:3]
	v_lshl_add_u64 v[42:43], v[40:41], 0, v[42:43]
	v_lshl_add_u64 v[44:45], v[40:41], 0, v[44:45]
	v_lshl_add_u64 v[46:47], v[40:41], 0, v[46:47]
	v_lshl_add_u64 v[48:49], v[40:41], 0, v[48:49]
	v_lshl_add_u64 v[50:51], v[40:41], 0, v[50:51]
	v_lshl_add_u64 v[52:53], v[40:41], 0, v[52:53]
	v_lshl_add_u64 v[54:55], v[40:41], 0, v[54:55]
	v_lshl_add_u64 v[40:41], v[40:41], 0, v[56:57]
	s_waitcnt vmcnt(0)
	ds_write_b32 v37, v39
	ds_write_b32 v37, v58 offset:2080
	ds_write_b32 v37, v59 offset:4160
	ds_write_b32 v37, v60 offset:6240
	ds_write_b32 v37, v61 offset:8320
	ds_write_b32 v37, v62 offset:10400
	ds_write_b32 v37, v63 offset:12480
	ds_write_b32 v37, v64 offset:14560
	s_waitcnt lgkmcnt(0)
	s_barrier
	ds_read2_b32 v[58:59], v29 offset1:8
	ds_read2_b32 v[56:57], v29 offset0:16 offset1:24
	ds_read2_b32 v[60:61], v29 offset0:32 offset1:40
	ds_read2_b32 v[62:63], v29 offset0:48 offset1:56
	s_waitcnt lgkmcnt(2)
	v_cvt_pk_bf16_f32 v56, v56, s0
	v_cvt_pk_bf16_f32 v2, v58, s0
	v_cvt_pk_bf16_f32 v39, v59, s0
	v_cvt_pk_bf16_f32 v57, v57, s0
	s_waitcnt lgkmcnt(1)
	v_cvt_pk_bf16_f32 v58, v60, s0
	v_cvt_pk_bf16_f32 v59, v61, s0
	s_waitcnt lgkmcnt(0)
	v_cvt_pk_bf16_f32 v60, v62, s0
	v_cvt_pk_bf16_f32 v61, v63, s0
	global_store_short v[42:43], v2, off
	global_store_short v[44:45], v39, off
	global_store_short v[46:47], v56, off
	global_store_short v[48:49], v57, off
	global_store_short v[50:51], v58, off
	global_store_short v[52:53], v59, off
	global_store_short v[54:55], v60, off
	global_store_short v[40:41], v61, off

; DI void epi_inproj(const Params& P, acc_t& acc, int ttile, int ftile, float* T) {
;     ...
;     __syncthreads();
;     {
;       float* Tw = T + wr * (256 * TLD);
; #pragma unroll
;       for (int bj = 0; bj < 2; ++bj)
; #pragma unroll
;         for (int m = 0; m < 4; ++m)
; #pragma unroll
;           for (int n = 0; n < 2; ++n)
;             *(f32x4*)(Tw + (bj * 128 + wc * 32 + n * 16 + fr) * TLD + m * 16 + fq * 4) = acc[ai][bj][m][n];
;     }
;     __syncthreads();
;     const int grp = __builtin_amdgcn_readfirstlane(tid_ >> 8), tl = tid_ & 255;
;     const int fg = ftile * 256 + ai * 128 + grp * 64;
;     float* Tr = T + grp * (256 * TLD) + tl * TLD;
;     const int tsub = tl >> 3, pj = tl & 7;
;     const float* Tgp = T + grp * (256 * TLD) + 8 * pj;
;     const long token = (long)ttile * 256 + tl;
;     int b, t, pos, nn, C;
;     if (!samp) { b = (int)(token >> 13); t = (int)(token & 8191); pos = t; nn = t & 63; C = 64; }
;     else { b = tl >> 5; t = tl & 31; pos = 4096 + t; nn = t; C = 32; }
;     ...
;     } else if (fg == F_WI) {
;       f32x4 a = *(const f32x4*)Tr;
;       *(f32x4*)((float*)(ws + R_WI) + token * 4) = a * 0.0625f;
.LBB0_96:
	v_mov_b32_e32 v160, v144
	s_cmpk_eq_i32 s6, 0x100
	s_cselect_b64 s[4:5], -1, 0
	v_and_b32_e32 v130, 15, v160
	s_cmpk_lg_i32 s6, 0x100
	v_lshrrev_b32_e32 v132, 1, v160
	s_movk_i32 s7, 0x60
	s_cselect_b64 s[56:57], -1, 0
	v_and_or_b32 v164, v132, s7, v130
	s_ashr_i32 s7, s6, 31
	s_lshl_b64 s[58:59], s[6:7], 8
	s_ashr_i32 s54, s6, 5
	s_lshl_b64 s[66:67], s[6:7], 19
	s_lshl_b64 s[64:65], s[6:7], 17
	s_add_u32 s26, s81, s66
	s_addc_u32 s44, s82, s67
	s_and_b64 s[24:25], s[4:5], exec
	s_cselect_b32 s53, s80, s44
	s_cselect_b32 s44, s51, s26
	s_lshl_b64 s[60:61], s[6:7], 18
	s_and_b32 s6, s60, 0xff800000
	s_add_u32 s62, s85, s6
	v_readfirstlane_b32 s6, v160
	v_lshrrev_b32_e32 v1, 8, v160
	v_and_b32_e32 v155, 0xff, v160
	s_addc_u32 s63, s86, s61
	s_ashr_i32 s25, s6, 8
	v_mul_i32_i24_e32 v1, 0x11000, v1
	v_and_b32_e32 v130, 48, v160
	v_or_b32_e32 v132, s58, v155
	v_mov_b32_e32 v133, s59
	s_lshl_b32 s6, s25, 6
	v_and_b32_e32 v163, 31, v160
	v_add3_u32 v162, 0, v1, v130
	v_lshlrev_b32_e32 v1, 3, v160
	v_lshl_add_u64 v[138:139], v[132:133], 4, s[2:3]
	v_lshlrev_b64 v[132:133], 8, v[132:133]
	s_add_i32 s70, s6, s8
	v_bfe_u32 v143, v160, 3, 5
	v_and_b32_e32 v153, 56, v1
	v_bitop3_b32 v1, s58, v148, v155 bitop3:0xc8
	v_bitop3_b32 v130, s58, 63, v155 bitop3:0xc8
	v_or_b32_e32 v140, 0x1000, v163
	v_lshl_add_u64 v[134:135], s[16:17], 0, v[132:133]
	v_lshlrev_b32_e32 v132, 8, v155
	v_mov_b32_e32 v133, v131
	v_lshlrev_b32_e32 v156, 5, v160
	s_and_b64 s[6:7], s[4:5], exec
	v_mul_u32_u24_e32 v161, 0x110, v155
	v_bfe_u32 v158, v160, 5, 3
	v_lshl_add_u64 v[136:137], s[18:19], 0, v[132:133]
	v_cndmask_b32_e64 v159, v130, v163, s[4:5]
	v_and_b32_e32 v133, 32, v156
	v_or_b32_e32 v154, 0x1000, v143
	v_mad_u32_u24 v130, v164, s94, v162
	s_mul_i32 s25, s25, 0x11000
	s_cselect_b32 s83, 31, 63
	v_cndmask_b32_e64 v157, v1, v140, s[4:5]
	s_cmpk_gt_i32 s70, 0x1ff
	s_mov_b64 s[6:7], -1
	s_waitcnt vmcnt(0)
	s_barrier
	ds_write_b128 v130, v[66:69]
	ds_write_b128 v130, v[70:73] offset:4352
	ds_write_b128 v130, v[74:77] offset:64
	ds_write_b128 v130, v[78:81] offset:4416
	ds_write_b128 v130, v[82:85] offset:128
	ds_write_b128 v130, v[86:89] offset:4480
	ds_write_b128 v130, v[90:93] offset:192
	ds_write_b128 v130, v[94:97] offset:4544
	ds_write_b128 v130, v[98:101] offset:34816
	ds_write_b128 v130, v[102:105] offset:39168
	ds_write_b128 v130, v[106:109] offset:34880
	ds_write_b128 v130, v[110:113] offset:39232
	ds_write_b128 v130, v[114:117] offset:34944
	ds_write_b128 v130, v[118:121] offset:39296
	ds_write_b128 v130, v[122:125] offset:35008
	ds_write_b128 v130, v[126:129] offset:39360
	s_waitcnt lgkmcnt(0)
	s_barrier
	s_cbranch_scc0 .LBB0_164
	s_cmpk_gt_u32 s70, 0x3ff
	s_cbranch_scc0 .LBB0_151
	s_cmpk_gt_u32 s70, 0x5ff
	s_cbranch_scc0 .LBB0_146
	s_cmpk_gt_u32 s70, 0x6ff
	s_cbranch_scc0 .LBB0_141
	s_add_i32 s6, s25, 0
	v_add_u32_e32 v165, s6, v161
	s_mov_b64 s[74:75], -1
	s_mov_b64 s[6:7], 0
	s_cmpk_lt_i32 s70, 0x740
	s_mov_b64 s[72:73], 0
	s_cbranch_scc1 .LBB0_128
	s_cmpk_eq_i32 s70, 0x740
	s_mov_b64 s[72:73], -1
	s_cbranch_scc0 .LBB0_103
	ds_read_b128 v[66:69], v165
	s_mov_b32 s24, 0x3d800000
	s_mov_b64 s[72:73], 0
	s_waitcnt lgkmcnt(0)
	v_pk_mul_f32 v[68:69], v[68:69], s[24:25] op_sel_hi:[1,0]
	v_pk_mul_f32 v[66:67], v[66:67], s[24:25] op_sel_hi:[1,0]
	global_store_dwordx4 v[138:139], v[66:69], off

; DI float sigmoidf_(float x) { return 1.0f / (1.0f + __expf(-x)); }
; DI uint4 pk8(f32x4 a, f32x4 b) { return make_uint4(pack2(a[0], a[1]), pack2(a[2], a[3]), pack2(b[0], b[1]), pack2(b[2], b[3])); }
; DI void epi_inproj(const Params& P, acc_t& acc, int ttile, int ftile, float* T) {
;     ...
;     } else if (fg < F_END) {
;       const bool isr = fg >= F_GRR;
;       u16* o = (u16*)(ws + (isr ? R_GRR : R_GA)) + (long)ttile * 256 * 1024 + (fg - (isr ? F_GRR : F_GA)) + 8 * pj;
; #pragma unroll 2
;       for (int it = 0; it < 8; ++it) {
;         const int tk = it * 32 + tsub;
;         f32x4 a = *(const f32x4*)(Tgp + tk * TLD), c = *(const f32x4*)(Tgp + tk * TLD + 4);
;         for (int j = 0; j < 4; ++j) { a[j] = sigmoidf_(a[j]); c[j] = sigmoidf_(c[j]); }
;         *(uint4*)(o + (long)tk * 1024) = pk8(a, c);
;       }
.LBB0_110:
	ds_read_b128 v[66:69], v1
	ds_read_b128 v[72:75], v1 offset:16
	s_waitcnt lgkmcnt(0)
	v_mul_f32_e32 v66, 0xbfb8aa3b, v66
	v_mul_f32_e32 v67, 0xbfb8aa3b, v67
	v_exp_f32_e32 v66, v66
	v_exp_f32_e32 v67, v67
	v_mul_f32_e32 v72, 0xbfb8aa3b, v72
	v_exp_f32_e32 v72, v72
	v_pk_add_f32 v[66:67], v[66:67], 1.0 op_sel_hi:[1,0]
	s_nop 0
	v_div_scale_f32 v76, s[72:73], v67, v67, 1.0
	v_rcp_f32_e32 v77, v76
	s_nop 0
	v_fma_f32 v78, -v76, v77, 1.0
	v_fmac_f32_e32 v77, v78, v77
	v_div_scale_f32 v78, vcc, 1.0, v67, 1.0
	v_mul_f32_e32 v79, v78, v77
	v_fma_f32 v80, -v76, v79, v78
	v_fmac_f32_e32 v79, v80, v77
	v_fma_f32 v76, -v76, v79, v78
	v_div_fmas_f32 v76, v76, v77, v79
	v_div_fixup_f32 v76, v76, v67, 1.0
	v_div_scale_f32 v67, s[72:73], v66, v66, 1.0
	v_rcp_f32_e32 v77, v67
	s_nop 0
	v_fma_f32 v78, -v67, v77, 1.0
	v_fmac_f32_e32 v77, v78, v77
	v_div_scale_f32 v78, vcc, 1.0, v66, 1.0
	v_mul_f32_e32 v79, v78, v77
	v_fma_f32 v80, -v67, v79, v78
	v_fmac_f32_e32 v79, v80, v77
	v_fma_f32 v67, -v67, v79, v78
	v_div_fmas_f32 v67, v67, v77, v79
	v_div_fixup_f32 v77, v67, v66, 1.0
	v_mul_f32_e32 v66, 0xbfb8aa3b, v73
	v_exp_f32_e32 v73, v66
	s_nop 0
	v_pk_add_f32 v[66:67], v[72:73], 1.0 op_sel_hi:[1,0]
	s_nop 0
	v_div_scale_f32 v72, s[72:73], v67, v67, 1.0
	v_rcp_f32_e32 v73, v72
	s_nop 0
	v_fma_f32 v78, -v72, v73, 1.0
	v_fmac_f32_e32 v73, v78, v73
	v_div_scale_f32 v78, vcc, 1.0, v67, 1.0
	v_mul_f32_e32 v79, v78, v73
	v_fma_f32 v80, -v72, v79, v78
	v_fmac_f32_e32 v79, v80, v73
	v_fma_f32 v72, -v72, v79, v78
	v_div_fmas_f32 v72, v72, v73, v79
	v_div_fixup_f32 v72, v72, v67, 1.0
	v_div_scale_f32 v67, s[72:73], v66, v66, 1.0
	v_rcp_f32_e32 v73, v67
	s_nop 0
	v_fma_f32 v78, -v67, v73, 1.0
	v_fmac_f32_e32 v73, v78, v73
	v_div_scale_f32 v78, vcc, 1.0, v66, 1.0
	v_mul_f32_e32 v79, v78, v73
	v_fma_f32 v80, -v67, v79, v78
	v_fmac_f32_e32 v79, v80, v73
	v_fma_f32 v67, -v67, v79, v78
	v_div_fmas_f32 v67, v67, v73, v79
	v_div_fixup_f32 v73, v67, v66, 1.0
	v_mul_f32_e32 v67, 0xbfb8aa3b, v74
	v_mul_f32_e32 v66, 0xbfb8aa3b, v68
	v_exp_f32_e32 v68, v67
	v_mul_f32_e32 v67, 0xbfb8aa3b, v69
	v_exp_f32_e32 v66, v66
	v_exp_f32_e32 v67, v67
	s_nop 0
	v_pk_add_f32 v[66:67], v[66:67], 1.0 op_sel_hi:[1,0]
	s_nop 0
	v_div_scale_f32 v69, s[72:73], v67, v67, 1.0
	v_rcp_f32_e32 v74, v69
	s_nop 0
	v_fma_f32 v78, -v69, v74, 1.0
	v_fmac_f32_e32 v74, v78, v74
	v_div_scale_f32 v78, vcc, 1.0, v67, 1.0
	v_mul_f32_e32 v79, v78, v74
	v_fma_f32 v80, -v69, v79, v78
	v_fmac_f32_e32 v79, v80, v74
	v_fma_f32 v69, -v69, v79, v78
	v_div_fmas_f32 v69, v69, v74, v79
	v_div_fixup_f32 v74, v69, v67, 1.0
	v_div_scale_f32 v67, s[72:73], v66, v66, 1.0
	v_rcp_f32_e32 v69, v67
	s_nop 0
	v_fma_f32 v78, -v67, v69, 1.0
	v_fmac_f32_e32 v69, v78, v69
	v_div_scale_f32 v78, vcc, 1.0, v66, 1.0
	v_mul_f32_e32 v79, v78, v69
	v_fma_f32 v80, -v67, v79, v78
	v_fmac_f32_e32 v79, v80, v69
	v_fma_f32 v67, -v67, v79, v78
	v_div_fmas_f32 v67, v67, v69, v79
	v_div_fixup_f32 v78, v67, v66, 1.0
	v_mul_f32_e32 v66, 0xbfb8aa3b, v75
	v_exp_f32_e32 v69, v66
	s_nop 0
	v_pk_add_f32 v[66:67], v[68:69], 1.0 op_sel_hi:[1,0]
	s_nop 0
	v_div_scale_f32 v68, s[72:73], v67, v67, 1.0
	v_rcp_f32_e32 v69, v68
	s_nop 0
	v_fma_f32 v75, -v68, v69, 1.0
	v_fmac_f32_e32 v69, v75, v69
	v_div_scale_f32 v75, vcc, 1.0, v67, 1.0
	v_mul_f32_e32 v79, v75, v69
	v_fma_f32 v80, -v68, v79, v75
	v_fmac_f32_e32 v79, v80, v69
	v_fma_f32 v68, -v68, v79, v75
	v_div_fmas_f32 v68, v68, v69, v79
	v_div_fixup_f32 v69, v68, v67, 1.0
	v_div_scale_f32 v67, s[72:73], v66, v66, 1.0
	v_rcp_f32_e32 v68, v67
	s_nop 0
	v_fma_f32 v75, -v67, v68, 1.0
	v_fmac_f32_e32 v68, v75, v68
	v_div_scale_f32 v75, vcc, 1.0, v66, 1.0
	v_mul_f32_e32 v79, v75, v68
	v_fma_f32 v80, -v67, v79, v75
	v_fmac_f32_e32 v79, v80, v68
	v_fma_f32 v67, -v67, v79, v75
	v_div_fmas_f32 v67, v67, v68, v79
	v_div_fixup_f32 v75, v67, v66, 1.0
	v_cvt_pk_bf16_f32 v66, v77, v76
	v_cvt_pk_bf16_f32 v67, v78, v74
	v_cvt_pk_bf16_f32 v68, v73, v72
	v_cvt_pk_bf16_f32 v69, v75, v69
	v_lshl_add_u64 v[76:77], v[70:71], 0, s[6:7]
	global_store_dwordx4 v[76:77], v[66:69], off
	ds_read_b128 v[66:69], v1 offset:8704
	ds_read_b128 v[72:75], v1 offset:8720
	s_add_u32 s6, s6, 0x20000
	s_addc_u32 s7, s7, 0
	v_add_u32_e32 v1, 0x4400, v1
	s_waitcnt lgkmcnt(0)
; DI float sigmoidf_(float x) { return 1.0f / (1.0f + __expf(-x)); }
; DI uint4 pk8(f32x4 a, f32x4 b) { return make_uint4(pack2(a[0], a[1]), pack2(a[2], a[3]), pack2(b[0], b[1]), pack2(b[2], b[3])); }
; DI void epi_inproj(const Params& P, acc_t& acc, int ttile, int ftile, float* T) {
;     ...
;     } else if (fg < F_END) {
;       const bool isr = fg >= F_GRR;
;       u16* o = (u16*)(ws + (isr ? R_GRR : R_GA)) + (long)ttile * 256 * 1024 + (fg - (isr ? F_GRR : F_GA)) + 8 * pj;
; #pragma unroll 2
;       for (int it = 0; it < 8; ++it) {
;         const int tk = it * 32 + tsub;
;         f32x4 a = *(const f32x4*)(Tgp + tk * TLD), c = *(const f32x4*)(Tgp + tk * TLD + 4);
;         for (int j = 0; j < 4; ++j) { a[j] = sigmoidf_(a[j]); c[j] = sigmoidf_(c[j]); }
;         *(uint4*)(o + (long)tk * 1024) = pk8(a, c);
;       }
	v_mul_f32_e32 v66, 0xbfb8aa3b, v66
	v_mul_f32_e32 v67, 0xbfb8aa3b, v67
	v_exp_f32_e32 v66, v66
	v_exp_f32_e32 v67, v67
	v_mul_f32_e32 v72, 0xbfb8aa3b, v72
	v_exp_f32_e32 v72, v72
	s_cmp_lg_u32 s6, 0x80000
	v_pk_add_f32 v[66:67], v[66:67], 1.0 op_sel_hi:[1,0]
	s_nop 0
	v_div_scale_f32 v78, s[72:73], v67, v67, 1.0
	v_rcp_f32_e32 v79, v78
	s_nop 0
	v_fma_f32 v80, -v78, v79, 1.0
	v_fmac_f32_e32 v79, v80, v79
	v_div_scale_f32 v80, vcc, 1.0, v67, 1.0
	v_mul_f32_e32 v81, v80, v79
	v_fma_f32 v82, -v78, v81, v80
	v_fmac_f32_e32 v81, v82, v79
	v_fma_f32 v78, -v78, v81, v80
	v_div_fmas_f32 v78, v78, v79, v81
	v_div_fixup_f32 v78, v78, v67, 1.0
	v_div_scale_f32 v67, s[72:73], v66, v66, 1.0
	v_rcp_f32_e32 v79, v67
	s_nop 0
	v_fma_f32 v80, -v67, v79, 1.0
	v_fmac_f32_e32 v79, v80, v79
	v_div_scale_f32 v80, vcc, 1.0, v66, 1.0
	v_mul_f32_e32 v81, v80, v79
	v_fma_f32 v82, -v67, v81, v80
	v_fmac_f32_e32 v81, v82, v79
	v_fma_f32 v67, -v67, v81, v80
	v_div_fmas_f32 v67, v67, v79, v81
	v_div_fixup_f32 v79, v67, v66, 1.0
	v_mul_f32_e32 v66, 0xbfb8aa3b, v73
	v_exp_f32_e32 v73, v66
	s_nop 0
	v_pk_add_f32 v[66:67], v[72:73], 1.0 op_sel_hi:[1,0]
	s_nop 0
	v_div_scale_f32 v72, s[72:73], v67, v67, 1.0
	v_rcp_f32_e32 v73, v72
	s_nop 0
	v_fma_f32 v80, -v72, v73, 1.0
	v_fmac_f32_e32 v73, v80, v73
	v_div_scale_f32 v80, vcc, 1.0, v67, 1.0
	v_mul_f32_e32 v81, v80, v73
	v_fma_f32 v82, -v72, v81, v80
	v_fmac_f32_e32 v81, v82, v73
	v_fma_f32 v72, -v72, v81, v80
	v_div_fmas_f32 v72, v72, v73, v81
	v_div_fixup_f32 v72, v72, v67, 1.0
	v_div_scale_f32 v67, s[72:73], v66, v66, 1.0
	v_rcp_f32_e32 v73, v67
	s_nop 0
	v_fma_f32 v80, -v67, v73, 1.0
	v_fmac_f32_e32 v73, v80, v73
	v_div_scale_f32 v80, vcc, 1.0, v66, 1.0
	v_mul_f32_e32 v81, v80, v73
	v_fma_f32 v82, -v67, v81, v80
	v_fmac_f32_e32 v81, v82, v73
	v_fma_f32 v67, -v67, v81, v80
	v_div_fmas_f32 v67, v67, v73, v81
	v_div_fixup_f32 v73, v67, v66, 1.0
	v_mul_f32_e32 v67, 0xbfb8aa3b, v74
	v_mul_f32_e32 v66, 0xbfb8aa3b, v68
	v_exp_f32_e32 v68, v67
	v_mul_f32_e32 v67, 0xbfb8aa3b, v69
	v_exp_f32_e32 v66, v66
	v_exp_f32_e32 v67, v67
	s_nop 0
	v_pk_add_f32 v[66:67], v[66:67], 1.0 op_sel_hi:[1,0]
	s_nop 0
	v_div_scale_f32 v69, s[72:73], v67, v67, 1.0
	v_rcp_f32_e32 v74, v69
	s_nop 0
	v_fma_f32 v80, -v69, v74, 1.0
	v_fmac_f32_e32 v74, v80, v74
	v_div_scale_f32 v80, vcc, 1.0, v67, 1.0
	v_mul_f32_e32 v81, v80, v74
	v_fma_f32 v82, -v69, v81, v80
	v_fmac_f32_e32 v81, v82, v74
	v_fma_f32 v69, -v69, v81, v80
	v_div_fmas_f32 v69, v69, v74, v81
	v_div_fixup_f32 v74, v69, v67, 1.0
	v_div_scale_f32 v67, s[72:73], v66, v66, 1.0
	v_rcp_f32_e32 v69, v67
	s_nop 0
	v_fma_f32 v80, -v67, v69, 1.0
	v_fmac_f32_e32 v69, v80, v69
	v_div_scale_f32 v80, vcc, 1.0, v66, 1.0
	v_mul_f32_e32 v81, v80, v69
	v_fma_f32 v82, -v67, v81, v80
	v_fmac_f32_e32 v81, v82, v69
	v_fma_f32 v67, -v67, v81, v80
	v_div_fmas_f32 v67, v67, v69, v81
	v_div_fixup_f32 v80, v67, v66, 1.0
	v_mul_f32_e32 v66, 0xbfb8aa3b, v75
	v_exp_f32_e32 v69, v66
	s_nop 0
	v_pk_add_f32 v[66:67], v[68:69], 1.0 op_sel_hi:[1,0]
	s_nop 0
	v_div_scale_f32 v68, s[72:73], v67, v67, 1.0
	v_rcp_f32_e32 v69, v68
	s_nop 0
	v_fma_f32 v75, -v68, v69, 1.0
	v_fmac_f32_e32 v69, v75, v69
	v_div_scale_f32 v75, vcc, 1.0, v67, 1.0
	v_mul_f32_e32 v81, v75, v69
	v_fma_f32 v82, -v68, v81, v75
	v_fmac_f32_e32 v81, v82, v69
	v_fma_f32 v68, -v68, v81, v75
	v_div_fmas_f32 v68, v68, v69, v81
	v_div_fixup_f32 v69, v68, v67, 1.0
	v_div_scale_f32 v67, s[72:73], v66, v66, 1.0
	v_rcp_f32_e32 v68, v67
	s_nop 0
	v_fma_f32 v75, -v67, v68, 1.0
	v_fmac_f32_e32 v68, v75, v68
	v_div_scale_f32 v75, vcc, 1.0, v66, 1.0
	v_mul_f32_e32 v81, v75, v68
	v_fma_f32 v82, -v67, v81, v75
	v_fmac_f32_e32 v81, v82, v68
	v_fma_f32 v67, -v67, v81, v75
	v_div_fmas_f32 v67, v67, v68, v81
	v_div_fixup_f32 v75, v67, v66, 1.0
	v_cvt_pk_bf16_f32 v68, v73, v72
	v_add_co_u32_e32 v72, vcc, s76, v76
	v_cvt_pk_bf16_f32 v66, v79, v78
	v_cvt_pk_bf16_f32 v67, v80, v74
	v_cvt_pk_bf16_f32 v69, v75, v69
	v_addc_co_u32_e32 v73, vcc, 0, v77, vcc
	global_store_dwordx4 v[72:73], v[66:69], off
	s_cbranch_scc1 .LBB0_110

; DI float siluf_(float x) { return x / (1.0f + __expf(-x)); }
; DI uint4 pk8(f32x4 a, f32x4 b) { return make_uint4(pack2(a[0], a[1]), pack2(a[2], a[3]), pack2(b[0], b[1]), pack2(b[2], b[3])); }
; DI void epi_inproj(const Params& P, acc_t& acc, int ttile, int ftile, float* T) {
;     ...
;     } else if (fg < F_GA) {
;       u16* o = (u16*)(ws + R_GR) + (long)ttile * 256 * 1024 + (fg - F_GR) + 8 * pj;
; #pragma unroll 2
;       for (int it = 0; it < 8; ++it) {
;         const int tk = it * 32 + tsub;
;         f32x4 a = *(const f32x4*)(Tgp + tk * TLD), c = *(const f32x4*)(Tgp + tk * TLD + 4);
;         for (int j = 0; j < 4; ++j) { a[j] = siluf_(a[j]); c[j] = siluf_(c[j]); }
;         *(uint4*)(o + (long)tk * 1024) = pk8(a, c);
;       }
.LBB0_114:
	ds_read_b128 v[66:69], v1
	ds_read_b128 v[72:75], v1 offset:16
	s_waitcnt lgkmcnt(0)
	v_mul_f32_e32 v76, 0xbfb8aa3b, v66
	v_mul_f32_e32 v77, 0xbfb8aa3b, v72
	v_exp_f32_e32 v78, v77
	v_mul_f32_e32 v77, 0xbfb8aa3b, v67
	v_exp_f32_e32 v76, v76
	v_exp_f32_e32 v77, v77
	s_nop 0
	v_pk_add_f32 v[76:77], v[76:77], 1.0 op_sel_hi:[1,0]
	s_nop 0
	v_div_scale_f32 v79, s[72:73], v77, v77, v67
	v_rcp_f32_e32 v80, v79
	s_nop 0
	v_fma_f32 v81, -v79, v80, 1.0
	v_fmac_f32_e32 v80, v81, v80
	v_div_scale_f32 v81, vcc, v67, v77, v67
	v_mul_f32_e32 v82, v81, v80
	v_fma_f32 v83, -v79, v82, v81
	v_fmac_f32_e32 v82, v83, v80
	v_fma_f32 v79, -v79, v82, v81
	v_div_fmas_f32 v79, v79, v80, v82
	v_div_fixup_f32 v77, v79, v77, v67
	v_div_scale_f32 v67, s[72:73], v76, v76, v66
	v_rcp_f32_e32 v79, v67
	s_nop 0
	v_fma_f32 v80, -v67, v79, 1.0
	v_fmac_f32_e32 v79, v80, v79
	v_div_scale_f32 v80, vcc, v66, v76, v66
	v_mul_f32_e32 v81, v80, v79
	v_fma_f32 v82, -v67, v81, v80
	v_fmac_f32_e32 v81, v82, v79
	v_fma_f32 v67, -v67, v81, v80
	v_div_fmas_f32 v67, v67, v79, v81
	v_div_fixup_f32 v76, v67, v76, v66
	v_mul_f32_e32 v66, 0xbfb8aa3b, v73
	v_exp_f32_e32 v79, v66
	s_nop 0
	v_pk_add_f32 v[66:67], v[78:79], 1.0 op_sel_hi:[1,0]
	s_nop 0
	v_div_scale_f32 v78, s[72:73], v67, v67, v73
	v_rcp_f32_e32 v79, v78
	s_nop 0
	v_fma_f32 v80, -v78, v79, 1.0
	v_fmac_f32_e32 v79, v80, v79
	v_div_scale_f32 v80, vcc, v73, v67, v73
	v_mul_f32_e32 v81, v80, v79
	v_fma_f32 v82, -v78, v81, v80
	v_fmac_f32_e32 v81, v82, v79
	v_fma_f32 v78, -v78, v81, v80
	v_div_fmas_f32 v78, v78, v79, v81
	v_div_fixup_f32 v78, v78, v67, v73
	v_div_scale_f32 v67, s[72:73], v66, v66, v72
	v_rcp_f32_e32 v73, v67
	s_nop 0
	v_fma_f32 v79, -v67, v73, 1.0
	v_fmac_f32_e32 v73, v79, v73
	v_div_scale_f32 v79, vcc, v72, v66, v72
	v_mul_f32_e32 v80, v79, v73
	v_fma_f32 v81, -v67, v80, v79
	v_fmac_f32_e32 v80, v81, v73
	v_fma_f32 v67, -v67, v80, v79
	v_div_fmas_f32 v67, v67, v73, v80
	v_div_fixup_f32 v79, v67, v66, v72
	v_mul_f32_e32 v67, 0xbfb8aa3b, v74
	v_mul_f32_e32 v66, 0xbfb8aa3b, v68
	v_exp_f32_e32 v72, v67
	v_mul_f32_e32 v67, 0xbfb8aa3b, v69
	v_exp_f32_e32 v66, v66
	v_exp_f32_e32 v67, v67
	s_nop 0
	v_pk_add_f32 v[66:67], v[66:67], 1.0 op_sel_hi:[1,0]
	s_nop 0
	v_div_scale_f32 v73, s[72:73], v67, v67, v69
	v_rcp_f32_e32 v80, v73
	s_nop 0
	v_fma_f32 v81, -v73, v80, 1.0
	v_fmac_f32_e32 v80, v81, v80
	v_div_scale_f32 v81, vcc, v69, v67, v69
	v_mul_f32_e32 v82, v81, v80
	v_fma_f32 v83, -v73, v82, v81
	v_fmac_f32_e32 v82, v83, v80
	v_fma_f32 v73, -v73, v82, v81
	v_div_fmas_f32 v73, v73, v80, v82
	v_div_fixup_f32 v69, v73, v67, v69
	v_div_scale_f32 v67, s[72:73], v66, v66, v68
	v_rcp_f32_e32 v73, v67
	s_nop 0
	v_fma_f32 v80, -v67, v73, 1.0
	v_fmac_f32_e32 v73, v80, v73
	v_div_scale_f32 v80, vcc, v68, v66, v68
	v_mul_f32_e32 v81, v80, v73
	v_fma_f32 v82, -v67, v81, v80
	v_fmac_f32_e32 v81, v82, v73
	v_fma_f32 v67, -v67, v81, v80
	v_div_fmas_f32 v67, v67, v73, v81
	v_div_fixup_f32 v68, v67, v66, v68
	v_mul_f32_e32 v66, 0xbfb8aa3b, v75
	v_exp_f32_e32 v73, v66
	s_nop 0
	v_pk_add_f32 v[66:67], v[72:73], 1.0 op_sel_hi:[1,0]
	s_nop 0
	v_div_scale_f32 v72, s[72:73], v67, v67, v75
	v_rcp_f32_e32 v73, v72
	s_nop 0
	v_fma_f32 v80, -v72, v73, 1.0
	v_fmac_f32_e32 v73, v80, v73
	v_div_scale_f32 v80, vcc, v75, v67, v75
	v_mul_f32_e32 v81, v80, v73
	v_fma_f32 v82, -v72, v81, v80
	v_fmac_f32_e32 v81, v82, v73
	v_fma_f32 v72, -v72, v81, v80
	v_div_fmas_f32 v72, v72, v73, v81
	v_div_fixup_f32 v72, v72, v67, v75
	v_div_scale_f32 v67, s[72:73], v66, v66, v74
	v_rcp_f32_e32 v73, v67
	s_nop 0
	v_fma_f32 v75, -v67, v73, 1.0
	v_fmac_f32_e32 v73, v75, v73
	v_div_scale_f32 v75, vcc, v74, v66, v74
	v_mul_f32_e32 v80, v75, v73
	v_fma_f32 v81, -v67, v80, v75
	v_fmac_f32_e32 v80, v81, v73
	v_fma_f32 v67, -v67, v80, v75
	v_div_fmas_f32 v67, v67, v73, v80
	v_div_fixup_f32 v73, v67, v66, v74
	v_cvt_pk_bf16_f32 v66, v76, v77
	v_lshl_add_u64 v[76:77], v[70:71], 0, s[6:7]
	v_cvt_pk_bf16_f32 v67, v68, v69
	v_cvt_pk_bf16_f32 v69, v73, v72
	v_add_co_u32_e32 v72, vcc, s77, v76
	v_cvt_pk_bf16_f32 v68, v79, v78
	s_nop 0
	v_addc_co_u32_e32 v73, vcc, 0, v77, vcc
	global_store_dwordx4 v[72:73], v[66:69], off offset:2560
	ds_read_b128 v[66:69], v1 offset:8704
	ds_read_b128 v[72:75], v1 offset:8720
	s_add_u32 s6, s6, 0x20000
	s_addc_u32 s7, s7, 0
	v_add_u32_e32 v1, 0x4400, v1
	s_waitcnt lgkmcnt(0)
; DI float siluf_(float x) { return x / (1.0f + __expf(-x)); }
; DI uint4 pk8(f32x4 a, f32x4 b) { return make_uint4(pack2(a[0], a[1]), pack2(a[2], a[3]), pack2(b[0], b[1]), pack2(b[2], b[3])); }
; DI void epi_inproj(const Params& P, acc_t& acc, int ttile, int ftile, float* T) {
;     ...
;     } else if (fg < F_GA) {
;       u16* o = (u16*)(ws + R_GR) + (long)ttile * 256 * 1024 + (fg - F_GR) + 8 * pj;
; #pragma unroll 2
;       for (int it = 0; it < 8; ++it) {
;         const int tk = it * 32 + tsub;
;         f32x4 a = *(const f32x4*)(Tgp + tk * TLD), c = *(const f32x4*)(Tgp + tk * TLD + 4);
;         for (int j = 0; j < 4; ++j) { a[j] = siluf_(a[j]); c[j] = siluf_(c[j]); }
;         *(uint4*)(o + (long)tk * 1024) = pk8(a, c);
;       }
	v_mul_f32_e32 v78, 0xbfb8aa3b, v66
	v_mul_f32_e32 v79, 0xbfb8aa3b, v72
	v_exp_f32_e32 v80, v79
	v_mul_f32_e32 v79, 0xbfb8aa3b, v67
	v_exp_f32_e32 v78, v78
	v_exp_f32_e32 v79, v79
	s_cmp_eq_u32 s6, 0x80000
	v_pk_add_f32 v[78:79], v[78:79], 1.0 op_sel_hi:[1,0]
	s_nop 0
	v_div_scale_f32 v81, s[72:73], v79, v79, v67
	v_rcp_f32_e32 v82, v81
	s_nop 0
	v_fma_f32 v83, -v81, v82, 1.0
	v_fmac_f32_e32 v82, v83, v82
	v_div_scale_f32 v83, vcc, v67, v79, v67
	v_mul_f32_e32 v84, v83, v82
	v_fma_f32 v85, -v81, v84, v83
	v_fmac_f32_e32 v84, v85, v82
	v_fma_f32 v81, -v81, v84, v83
	v_div_fmas_f32 v81, v81, v82, v84
	v_div_fixup_f32 v79, v81, v79, v67
	v_div_scale_f32 v67, s[72:73], v78, v78, v66
	v_rcp_f32_e32 v81, v67
	s_nop 0
	v_fma_f32 v82, -v67, v81, 1.0
	v_fmac_f32_e32 v81, v82, v81
	v_div_scale_f32 v82, vcc, v66, v78, v66
	v_mul_f32_e32 v83, v82, v81
	v_fma_f32 v84, -v67, v83, v82
	v_fmac_f32_e32 v83, v84, v81
	v_fma_f32 v67, -v67, v83, v82
	v_div_fmas_f32 v67, v67, v81, v83
	v_div_fixup_f32 v78, v67, v78, v66
	v_mul_f32_e32 v66, 0xbfb8aa3b, v73
	v_exp_f32_e32 v81, v66
	s_nop 0
	v_pk_add_f32 v[66:67], v[80:81], 1.0 op_sel_hi:[1,0]
	s_nop 0
	v_div_scale_f32 v80, s[72:73], v67, v67, v73
	v_rcp_f32_e32 v81, v80
	s_nop 0
	v_fma_f32 v82, -v80, v81, 1.0
	v_fmac_f32_e32 v81, v82, v81
	v_div_scale_f32 v82, vcc, v73, v67, v73
	v_mul_f32_e32 v83, v82, v81
	v_fma_f32 v84, -v80, v83, v82
	v_fmac_f32_e32 v83, v84, v81
	v_fma_f32 v80, -v80, v83, v82
	v_div_fmas_f32 v80, v80, v81, v83
	v_div_fixup_f32 v80, v80, v67, v73
	v_div_scale_f32 v67, s[72:73], v66, v66, v72
	v_rcp_f32_e32 v73, v67
	s_nop 0
	v_fma_f32 v81, -v67, v73, 1.0
	v_fmac_f32_e32 v73, v81, v73
	v_div_scale_f32 v81, vcc, v72, v66, v72
	v_mul_f32_e32 v82, v81, v73
	v_fma_f32 v83, -v67, v82, v81
	v_fmac_f32_e32 v82, v83, v73
	v_fma_f32 v67, -v67, v82, v81
	v_div_fmas_f32 v67, v67, v73, v82
	v_div_fixup_f32 v81, v67, v66, v72
	v_mul_f32_e32 v67, 0xbfb8aa3b, v74
	v_mul_f32_e32 v66, 0xbfb8aa3b, v68
	v_exp_f32_e32 v72, v67
	v_mul_f32_e32 v67, 0xbfb8aa3b, v69
	v_exp_f32_e32 v66, v66
	v_exp_f32_e32 v67, v67
	s_nop 0
	v_pk_add_f32 v[66:67], v[66:67], 1.0 op_sel_hi:[1,0]
	s_nop 0
	v_div_scale_f32 v73, s[72:73], v67, v67, v69
	v_rcp_f32_e32 v82, v73
	s_nop 0
	v_fma_f32 v83, -v73, v82, 1.0
	v_fmac_f32_e32 v82, v83, v82
	v_div_scale_f32 v83, vcc, v69, v67, v69
	v_mul_f32_e32 v84, v83, v82
	v_fma_f32 v85, -v73, v84, v83
	v_fmac_f32_e32 v84, v85, v82
	v_fma_f32 v73, -v73, v84, v83
	v_div_fmas_f32 v73, v73, v82, v84
	v_div_fixup_f32 v69, v73, v67, v69
	v_div_scale_f32 v67, s[72:73], v66, v66, v68
	v_rcp_f32_e32 v73, v67
	s_nop 0
	v_fma_f32 v82, -v67, v73, 1.0
	v_fmac_f32_e32 v73, v82, v73
	v_div_scale_f32 v82, vcc, v68, v66, v68
	v_mul_f32_e32 v83, v82, v73
	v_fma_f32 v84, -v67, v83, v82
	v_fmac_f32_e32 v83, v84, v73
	v_fma_f32 v67, -v67, v83, v82
	v_div_fmas_f32 v67, v67, v73, v83
	v_div_fixup_f32 v68, v67, v66, v68
	v_mul_f32_e32 v66, 0xbfb8aa3b, v75
	v_exp_f32_e32 v73, v66
	s_nop 0
	v_pk_add_f32 v[66:67], v[72:73], 1.0 op_sel_hi:[1,0]
	s_nop 0
	v_div_scale_f32 v72, s[72:73], v67, v67, v75
	v_rcp_f32_e32 v73, v72
	s_nop 0
	v_fma_f32 v82, -v72, v73, 1.0
	v_fmac_f32_e32 v73, v82, v73
	v_div_scale_f32 v82, vcc, v75, v67, v75
	v_mul_f32_e32 v83, v82, v73
	v_fma_f32 v84, -v72, v83, v82
	v_fmac_f32_e32 v83, v84, v73
	v_fma_f32 v72, -v72, v83, v82
	v_div_fmas_f32 v72, v72, v73, v83
	v_div_fixup_f32 v72, v72, v67, v75
	v_div_scale_f32 v67, s[72:73], v66, v66, v74
	v_rcp_f32_e32 v73, v67
	s_nop 0
	v_fma_f32 v75, -v67, v73, 1.0
	v_fmac_f32_e32 v73, v75, v73
	v_div_scale_f32 v75, vcc, v74, v66, v74
	v_mul_f32_e32 v82, v75, v73
	v_fma_f32 v83, -v67, v82, v75
	v_fmac_f32_e32 v82, v83, v73
	v_fma_f32 v67, -v67, v82, v75
	v_div_fmas_f32 v67, v67, v73, v82
	v_div_fixup_f32 v73, v67, v66, v74
	v_cvt_pk_bf16_f32 v67, v68, v69
	v_cvt_pk_bf16_f32 v69, v73, v72
	v_add_co_u32_e32 v72, vcc, s74, v76
	v_cvt_pk_bf16_f32 v66, v78, v79
	v_cvt_pk_bf16_f32 v68, v81, v80
	v_addc_co_u32_e32 v73, vcc, 0, v77, vcc
	global_store_dwordx4 v[72:73], v[66:69], off offset:2560
	s_cbranch_scc0 .LBB0_114

; DI float log_gamma_h(int h) { return log1pf(-exp2f(-5.0f - (float)h)); }
; DI uint4 pk8(f32x4 a, f32x4 b) { return make_uint4(pack2(a[0], a[1]), pack2(a[2], a[3]), pack2(b[0], b[1]), pack2(b[2], b[3])); }
; DI void epi_inproj(const Params& P, acc_t& acc, int ttile, int ftile, float* T) {
;     ...
;     } else if (fg < F_VR) {
;       const bool isk = fg >= F_KR;
;       const int h = ((isk ? fg - F_KR : fg - F_QR)) >> 6;
;       const float lg = log_gamma_h(h);
;       const float dec = isk ? (expf(lg * (float)(C - 1 - nn)) * 0.125f) : expf(lg * (float)(nn + 1));
;       const float* rot = (const float*)(ws + W_ROT) + ((long)pos * 32) * 2;
;       u16* nat = (u16*)(ws + (isk ? R_KR : R_QR)) + token * 512 + h * 64;
; #pragma unroll 2
;       for (int k = 0; k < 4; ++k) {
;         f32x4 xa = *(const f32x4*)(Tr + 8 * k), xb = *(const f32x4*)(Tr + 8 * k + 4);
;         f32x4 ya = *(const f32x4*)(Tr + 32 + 8 * k), yb = *(const f32x4*)(Tr + 32 + 8 * k + 4);
;         f32x4 r0 = *(const f32x4*)(rot + 16 * k), r1 = *(const f32x4*)(rot + 16 * k + 4);
;         f32x4 r2 = *(const f32x4*)(rot + 16 * k + 8), r3 = *(const f32x4*)(rot + 16 * k + 12);
;         f32x4 ca = {r0[0], r0[2], r1[0], r1[2]}, sa = {r0[1], r0[3], r1[1], r1[3]};
;         f32x4 cb = {r2[0], r2[2], r3[0], r3[2]}, sb = {r2[1], r2[3], r3[1], r3[3]};
;         f32x4 o1a = (xa * ca - ya * sa) * dec, o1b = (xb * cb - yb * sb) * dec;
;         f32x4 o2a = (xa * sa + ya * ca) * dec, o2b = (xb * sb + yb * cb) * dec;
;         *(uint4*)(nat + 8 * k) = pk8(o1a, o1b);
;         *(uint4*)(nat + 32 + 8 * k) = pk8(o2a, o2b);
;         if (isk) {
;           *(f32x4*)(Tr + 8 * k) = o1a; *(f32x4*)(Tr + 8 * k + 4) = o1b;
;           *(f32x4*)(Tr + 32 + 8 * k) = o2a; *(f32x4*)(Tr + 32 + 8 * k + 4) = o2b;
;         }
;       }
;       if (isk) ttype = 2;
.LBB0_124:
	v_lshl_add_u64 v[90:91], s[10:11], 0, v[88:89]
	v_add_co_u32_e32 v66, vcc, 0x2380000, v90
	v_add_u32_e32 v1, s24, v165
	s_nop 0
	v_addc_co_u32_e32 v67, vcc, 0, v91, vcc
	ds_read_b128 v[74:77], v1
	ds_read_b128 v[78:81], v1 offset:16
	ds_read_b128 v[92:95], v1 offset:128
	ds_read_b128 v[96:99], v1 offset:144
	global_load_dwordx4 v[100:103], v[66:67], off
	global_load_dwordx4 v[104:107], v[66:67], off offset:16
	global_load_dwordx4 v[108:111], v[66:67], off offset:32
	global_load_dwordx4 v[112:115], v[66:67], off offset:48
	s_andn2_b64 vcc, exec, s[72:73]
	s_waitcnt vmcnt(0) lgkmcnt(0)
	v_mov_b32_e32 v118, v101
	v_mov_b32_e32 v116, v105
	v_mov_b32_e32 v117, v107
	v_mov_b32_e32 v119, v103
	v_pk_mul_f32 v[66:67], v[94:95], v[116:117]
	v_pk_mul_f32 v[68:69], v[92:93], v[118:119]
	v_mov_b32_e32 v101, v102
	v_mov_b32_e32 v105, v106
	v_pk_fma_f32 v[70:71], v[74:75], v[100:101], v[68:69] neg_lo:[0,0,1] neg_hi:[0,0,1]
	v_pk_fma_f32 v[66:67], v[76:77], v[104:105], v[66:67] neg_lo:[0,0,1] neg_hi:[0,0,1]
	v_mov_b32_e32 v102, v113
	v_mov_b32_e32 v103, v115
	v_mov_b32_e32 v106, v109
	v_mov_b32_e32 v107, v111
	v_pk_mul_f32 v[68:69], v[84:85], v[66:67]
	v_pk_mul_f32 v[66:67], v[82:83], v[70:71]
	v_pk_mul_f32 v[70:71], v[98:99], v[102:103]
	v_pk_mul_f32 v[72:73], v[96:97], v[106:107]
	v_mov_b32_e32 v109, v110
	v_mov_b32_e32 v113, v114
	v_pk_mul_f32 v[94:95], v[94:95], v[104:105]
	v_pk_mul_f32 v[92:93], v[92:93], v[100:101]
	v_pk_fma_f32 v[110:111], v[78:79], v[108:109], v[72:73] neg_lo:[0,0,1] neg_hi:[0,0,1]
	v_pk_fma_f32 v[70:71], v[80:81], v[112:113], v[70:71] neg_lo:[0,0,1] neg_hi:[0,0,1]
	v_pk_fma_f32 v[74:75], v[74:75], v[118:119], v[92:93]
	v_pk_fma_f32 v[76:77], v[76:77], v[116:117], v[94:95]
	v_pk_mul_f32 v[92:93], v[98:99], v[112:113]
	v_pk_mul_f32 v[94:95], v[96:97], v[108:109]
	v_pk_mul_f32 v[72:73], v[84:85], v[70:71]
	v_pk_mul_f32 v[70:71], v[82:83], v[110:111]
	v_pk_fma_f32 v[78:79], v[78:79], v[106:107], v[94:95]
	v_pk_fma_f32 v[80:81], v[80:81], v[102:103], v[92:93]
	v_pk_mul_f32 v[76:77], v[84:85], v[76:77]
	v_pk_mul_f32 v[74:75], v[82:83], v[74:75]
	v_pk_mul_f32 v[80:81], v[84:85], v[80:81]
	v_pk_mul_f32 v[78:79], v[82:83], v[78:79]
	v_cvt_pk_bf16_f32 v94, v66, v67
	v_cvt_pk_bf16_f32 v95, v68, v69
	v_cvt_pk_bf16_f32 v96, v70, v71
	v_cvt_pk_bf16_f32 v97, v72, v73
	v_lshl_add_u64 v[92:93], s[10:11], 0, v[86:87]
	global_store_dwordx4 v[92:93], v[94:97], off
	s_nop 1
	v_cvt_pk_bf16_f32 v94, v74, v75
	v_cvt_pk_bf16_f32 v95, v76, v77
	v_cvt_pk_bf16_f32 v96, v78, v79
	v_cvt_pk_bf16_f32 v97, v80, v81
	global_store_dwordx4 v[92:93], v[94:97], off offset:64
	s_nop 1
	v_cndmask_b32_e64 v94, 0, 1, s[72:73]
	v_cmp_ne_u32_e64 s[6:7], 1, v94
	s_cbranch_vccnz .LBB0_126
	ds_write_b128 v1, v[66:69]
	ds_write_b128 v1, v[70:73] offset:16
	ds_write_b128 v1, v[74:77] offset:128
	ds_write_b128 v1, v[78:81] offset:144
.LBB0_126:
	v_add_co_u32_e32 v78, vcc, 0x2380000, v90
	s_nop 1
	v_addc_co_u32_e32 v79, vcc, 0, v91, vcc
	global_load_dwordx4 v[66:69], v[78:79], off offset:80
	global_load_dwordx4 v[70:73], v[78:79], off offset:64
	global_load_dwordx4 v[74:77], v[78:79], off offset:112
	s_nop 0
	global_load_dwordx4 v[78:81], v[78:79], off offset:96
	ds_read_b128 v[94:97], v1 offset:32
	ds_read_b128 v[98:101], v1 offset:48
	ds_read_b128 v[102:105], v1 offset:160
	ds_read_b128 v[106:109], v1 offset:176
	s_and_b64 vcc, exec, s[6:7]
	s_waitcnt vmcnt(0) lgkmcnt(0)
	v_mov_b32_e32 v90, v67
	v_mov_b32_e32 v91, v69
	v_mov_b32_e32 v110, v71
	v_mov_b32_e32 v111, v73
	v_mov_b32_e32 v71, v72
	v_mov_b32_e32 v67, v68
	v_mov_b32_e32 v68, v75
	v_mov_b32_e32 v69, v77
	v_mov_b32_e32 v72, v79
	v_mov_b32_e32 v73, v81
	v_mov_b32_e32 v79, v80
	v_mov_b32_e32 v75, v76
	v_pk_mul_f32 v[76:77], v[104:105], v[90:91]
	v_pk_mul_f32 v[80:81], v[102:103], v[110:111]
	v_pk_mul_f32 v[112:113], v[108:109], v[68:69]
	v_pk_mul_f32 v[114:115], v[106:107], v[72:73]
	v_pk_mul_f32 v[104:105], v[104:105], v[66:67]
	v_pk_mul_f32 v[102:103], v[102:103], v[70:71]
	v_pk_mul_f32 v[108:109], v[108:109], v[74:75]
	v_pk_mul_f32 v[106:107], v[106:107], v[78:79]
	v_pk_fma_f32 v[70:71], v[94:95], v[70:71], v[80:81] neg_lo:[0,0,1] neg_hi:[0,0,1]
	v_pk_fma_f32 v[66:67], v[96:97], v[66:67], v[76:77] neg_lo:[0,0,1] neg_hi:[0,0,1]
	v_pk_fma_f32 v[76:77], v[98:99], v[78:79], v[114:115] neg_lo:[0,0,1] neg_hi:[0,0,1]
	v_pk_fma_f32 v[74:75], v[100:101], v[74:75], v[112:113] neg_lo:[0,0,1] neg_hi:[0,0,1]
	v_pk_fma_f32 v[78:79], v[94:95], v[110:111], v[102:103]
	v_pk_fma_f32 v[80:81], v[96:97], v[90:91], v[104:105]
	v_pk_fma_f32 v[90:91], v[98:99], v[72:73], v[106:107]
	v_pk_fma_f32 v[94:95], v[100:101], v[68:69], v[108:109]
	v_pk_mul_f32 v[68:69], v[84:85], v[66:67]
	v_pk_mul_f32 v[66:67], v[82:83], v[70:71]
	v_pk_mul_f32 v[72:73], v[84:85], v[74:75]
	v_pk_mul_f32 v[70:71], v[82:83], v[76:77]
	v_pk_mul_f32 v[76:77], v[84:85], v[80:81]
	v_pk_mul_f32 v[74:75], v[82:83], v[78:79]
	v_pk_mul_f32 v[80:81], v[84:85], v[94:95]
	v_pk_mul_f32 v[78:79], v[82:83], v[90:91]
	v_cvt_pk_bf16_f32 v94, v66, v67
	v_cvt_pk_bf16_f32 v95, v68, v69
	v_cvt_pk_bf16_f32 v96, v70, v71
	v_cvt_pk_bf16_f32 v97, v72, v73
	v_cvt_pk_bf16_f32 v98, v74, v75
	v_cvt_pk_bf16_f32 v99, v76, v77
	v_cvt_pk_bf16_f32 v100, v78, v79
	v_cvt_pk_bf16_f32 v101, v80, v81
	global_store_dwordx4 v[92:93], v[94:97], off offset:16
	global_store_dwordx4 v[92:93], v[98:101], off offset:80
	s_cbranch_vccnz .LBB0_123
	ds_write_b128 v1, v[66:69] offset:32
	ds_write_b128 v1, v[70:73] offset:48
	ds_write_b128 v1, v[74:77] offset:160
	ds_write_b128 v1, v[78:81] offset:176
	s_branch .LBB0_123

; DI uint4 pk8(f32x4 a, f32x4 b) { return make_uint4(pack2(a[0], a[1]), pack2(a[2], a[3]), pack2(b[0], b[1]), pack2(b[2], b[3])); }
; DI void epi_inproj(const Params& P, acc_t& acc, int ttile, int ftile, float* T) {
;     ...
; #pragma unroll 2
;       for (int k = 0; k < 8; ++k) {
;         f32x4 a = *(const f32x4*)(Tr + 8 * k), c = *(const f32x4*)(Tr + 8 * k + 4);
;         f32x4 g0 = *(const f32x4*)(P.ikg + 8 * k), g1 = *(const f32x4*)(P.ikg + 8 * k + 4);
;         f32x4 b0 = *(const f32x4*)(P.ikb + 8 * k), b1 = *(const f32x4*)(P.ikb + 8 * k + 4);
;         a = (a - mean) * rstd * g0 + b0;
;         c = (c - mean) * rstd * g1 + b1;
;         *(f32x4*)(o + 8 * k) = a; *(f32x4*)(o + 8 * k + 4) = c;
;         *(uint4*)(kb + kifrag_off(keyi, 8 * k)) = pk8(a, c);
;       }
.LBB0_138:
	s_add_u32 s74, s12, s6
	s_addc_u32 s75, s13, s7
	s_add_u32 s72, s14, s6
	s_addc_u32 s73, s15, s7
	ds_read_b128 v[76:79], v165
	ds_read_b128 v[80:83], v165 offset:16
	global_load_dwordx4 v[84:87], v131, s[74:75] offset:16
	global_load_dwordx4 v[88:91], v131, s[74:75]
	global_load_dwordx4 v[92:95], v131, s[72:73] offset:16
	global_load_dwordx4 v[96:99], v131, s[72:73]
	s_add_i32 s26, s24, 0xffffff00
	s_waitcnt lgkmcnt(0)
	v_sub_f32_e32 v79, v79, v67
	v_sub_f32_e32 v78, v78, v66
	v_sub_f32_e32 v77, v77, v1
	v_sub_f32_e32 v76, v76, v142
	v_sub_f32_e32 v83, v83, v67
	v_sub_f32_e32 v82, v82, v66
	v_sub_f32_e32 v81, v81, v1
	v_sub_f32_e32 v80, v80, v142
	v_pk_mul_f32 v[76:77], v[68:69], v[76:77]
	v_pk_mul_f32 v[78:79], v[72:73], v[78:79]
	v_pk_mul_f32 v[80:81], v[68:69], v[80:81]
	v_pk_mul_f32 v[82:83], v[72:73], v[82:83]
	v_lshl_add_u64 v[100:101], v[70:71], 0, s[6:7]
	v_or_b32_e32 v130, s26, v74
	s_add_u32 s6, s6, 64
	s_addc_u32 s7, s7, 0
	s_waitcnt vmcnt(0)
	v_pk_fma_f32 v[82:83], v[82:83], v[86:87], v[94:95]
	v_pk_fma_f32 v[78:79], v[78:79], v[90:91], v[98:99]
	v_pk_fma_f32 v[76:77], v[76:77], v[88:89], v[96:97]
	v_pk_fma_f32 v[80:81], v[80:81], v[84:85], v[92:93]
	global_store_dwordx4 v[100:101], v[76:79], off
	global_store_dwordx4 v[100:101], v[80:83], off offset:16
	s_nop 0
	v_cvt_pk_bf16_f32 v76, v76, v77
	v_cvt_pk_bf16_f32 v77, v78, v79
	v_cvt_pk_bf16_f32 v78, v80, v81
	v_cvt_pk_bf16_f32 v79, v82, v83
	v_lshl_add_u64 v[80:81], v[130:131], 1, v[140:141]
	global_store_dwordx4 v[80:81], v[76:79], off
	ds_read_b128 v[76:79], v165 offset:32
	ds_read_b128 v[80:83], v165 offset:48
	global_load_dwordx4 v[84:87], v131, s[74:75] offset:48
	global_load_dwordx4 v[88:91], v131, s[74:75] offset:32
	global_load_dwordx4 v[92:95], v131, s[72:73] offset:48
	global_load_dwordx4 v[96:99], v131, s[72:73] offset:32
	v_or_b32_e32 v130, s24, v74
	s_addk_i32 s24, 0x200
	s_waitcnt lgkmcnt(0)
	v_sub_f32_e32 v79, v79, v67
	v_sub_f32_e32 v78, v78, v66
	v_sub_f32_e32 v77, v77, v1
	v_sub_f32_e32 v76, v76, v142
	v_sub_f32_e32 v83, v83, v67
	v_sub_f32_e32 v82, v82, v66
	v_sub_f32_e32 v81, v81, v1
	v_sub_f32_e32 v80, v80, v142
	v_pk_mul_f32 v[76:77], v[68:69], v[76:77]
	v_pk_mul_f32 v[78:79], v[72:73], v[78:79]
	v_pk_mul_f32 v[80:81], v[68:69], v[80:81]
	v_pk_mul_f32 v[82:83], v[72:73], v[82:83]
	v_add_u32_e32 v165, 64, v165
	s_cmpk_eq_i32 s6, 0x100
	s_waitcnt vmcnt(0)
	v_pk_fma_f32 v[82:83], v[82:83], v[86:87], v[94:95]
	v_pk_fma_f32 v[78:79], v[78:79], v[90:91], v[98:99]
	v_pk_fma_f32 v[76:77], v[76:77], v[88:89], v[96:97]
	v_pk_fma_f32 v[80:81], v[80:81], v[84:85], v[92:93]
	global_store_dwordx4 v[100:101], v[76:79], off offset:32
	global_store_dwordx4 v[100:101], v[80:83], off offset:48
	s_nop 0
	v_cvt_pk_bf16_f32 v76, v76, v77
	v_cvt_pk_bf16_f32 v77, v78, v79
	v_cvt_pk_bf16_f32 v78, v80, v81
	v_cvt_pk_bf16_f32 v79, v82, v83
	v_lshl_add_u64 v[80:81], v[130:131], 1, v[140:141]
	global_store_dwordx4 v[80:81], v[76:79], off
	s_cbranch_scc0 .LBB0_138
	s_mov_b32 s26, 0
	s_mov_b32 s74, 0x65d8000

; DI uint4 pk8(f32x4 a, f32x4 b) { return make_uint4(pack2(a[0], a[1]), pack2(a[2], a[3]), pack2(b[0], b[1]), pack2(b[2], b[3])); }
; DI void epi_inproj(const Params& P, acc_t& acc, int ttile, int ftile, float* T) {
;     ...
;     } else if (fg < F_KI) {
;       u16* o = (u16*)(ws + R_QI) + (long)ttile * 256 * 256 + (fg - F_QI) + 8 * pj;
; #pragma unroll 2
;       for (int it = 0; it < 8; ++it) {
;         const int tk = it * 32 + tsub;
;         f32x4 a = *(const f32x4*)(Tgp + tk * TLD), c = *(const f32x4*)(Tgp + tk * TLD + 4);
;         *(uint4*)(o + (long)tk * 256) = pk8(a, c);
;       }
.LBB0_143:
	ds_read_b128 v[68:71], v1
	ds_read_b128 v[72:75], v1 offset:16
	v_lshl_add_u64 v[76:77], v[66:67], 0, s[6:7]
	s_add_u32 s6, s6, 0x8000
	s_addc_u32 s7, s7, 0
	s_waitcnt lgkmcnt(0)
	v_cvt_pk_bf16_f32 v68, v68, v69
	v_cvt_pk_bf16_f32 v69, v70, v71
	v_cvt_pk_bf16_f32 v70, v72, v73
	v_add_co_u32_e32 v72, vcc, s33, v76
	v_cvt_pk_bf16_f32 v71, v74, v75
	s_nop 0
	v_addc_co_u32_e32 v73, vcc, 0, v77, vcc
	global_store_dwordx4 v[72:73], v[68:71], off offset:3328
	ds_read_b128 v[68:71], v1 offset:8704
	ds_read_b128 v[72:75], v1 offset:8720
	v_add_u32_e32 v1, 0x4400, v1
	s_cmp_eq_u32 s6, 0x20000
	s_waitcnt lgkmcnt(0)
	v_cvt_pk_bf16_f32 v68, v68, v69
	v_cvt_pk_bf16_f32 v69, v70, v71
	v_cvt_pk_bf16_f32 v70, v72, v73
	v_add_co_u32_e32 v72, vcc, s45, v76
	v_cvt_pk_bf16_f32 v71, v74, v75
	s_nop 0
	v_addc_co_u32_e32 v73, vcc, 0, v77, vcc
	global_store_dwordx4 v[72:73], v[68:71], off offset:3328
	s_cbranch_scc0 .LBB0_143
	s_mov_b32 s26, 0

; DI void epi_inproj(const Params& P, acc_t& acc, int ttile, int ftile, float* T) {
;     ...
;     } else if (fg < F_QI) {
;       const int c0 = fg - F_VA;
;       float* o = (samp ? (out + O_VS) : (out + O_VP + (long)ttile * 256 * 512)) + c0 + 8 * pj;
; #pragma unroll 2
;       for (int it = 0; it < 8; ++it) {
;         const int tk = it * 32 + tsub;
;         __builtin_nontemporal_store(*(const f32x4*)(Tgp + tk * TLD), (f32x4*)(o + (long)tk * 512));
;         __builtin_nontemporal_store(*(const f32x4*)(Tgp + tk * TLD + 4), (f32x4*)(o + (long)tk * 512 + 4));
;       }
;       ttype = 1;
.LBB0_148:
	ds_read_b128 v[68:71], v1
	v_lshl_add_u64 v[72:73], v[66:67], 0, s[6:7]
	v_add_co_u32_e32 v74, vcc, 0xfffff000, v72
	s_add_u32 s6, s6, 0x20000
	s_nop 0
	v_addc_co_u32_e32 v75, vcc, -1, v73, vcc
	s_waitcnt lgkmcnt(0)
	global_store_dwordx4 v[74:75], v[68:71], off nt
	ds_read_b128 v[68:71], v1 offset:16
	v_add_co_u32_e32 v74, vcc, 0xfffff010, v72
	s_addc_u32 s7, s7, 0
	s_nop 0
	v_addc_co_u32_e32 v75, vcc, -1, v73, vcc
	s_waitcnt lgkmcnt(0)
	global_store_dwordx4 v[74:75], v[68:71], off nt
	ds_read_b128 v[68:71], v1 offset:8704
	v_add_co_u32_e32 v72, vcc, 0xf000, v72
	s_cmp_eq_u32 s6, 0x80000
	s_nop 0
	v_addc_co_u32_e32 v73, vcc, 0, v73, vcc
	s_waitcnt lgkmcnt(0)
	global_store_dwordx4 v[72:73], v[68:71], off nt
	ds_read_b128 v[68:71], v1 offset:8720
	v_add_u32_e32 v1, 0x4400, v1
	s_waitcnt lgkmcnt(0)
	global_store_dwordx4 v[72:73], v[68:71], off offset:16 nt
	s_cbranch_scc0 .LBB0_148
	s_mov_b32 s26, 1

; DI uint4 pk8(f32x4 a, f32x4 b) { return make_uint4(pack2(a[0], a[1]), pack2(a[2], a[3]), pack2(b[0], b[1]), pack2(b[2], b[3])); }
; DI void epi_inproj(const Params& P, acc_t& acc, int ttile, int ftile, float* T) {
;     ...
;     } else if (fg < F_VA) {
;       const int c0 = fg - F_KA, hh_ = c0 >> 6;
; #pragma unroll 2
;       for (int it = 0; it < 8; ++it) {
;         const int tk = it * 32 + tsub;
;         f32x4 a = *(const f32x4*)(Tgp + tk * TLD), c = *(const f32x4*)(Tgp + tk * TLD + 4);
;         float* o; u16* kb; int keyi;
;         if (!samp) {
;           const long tok = (long)ttile * 256 + tk;
;           o = out + O_KP + tok * 512 + c0 + 8 * pj;
;           kb = (u16*)(ws + R_KA) + (tok >> 13) * (8192L * 512);
;           keyi = (int)(tok & 8191);
;         } else {
;           o = out + O_KS + (long)tk * 512 + c0 + 8 * pj;
;           kb = (u16*)(ws + R_SK) + (long)(tk >> 5) * 4160 * 512;
;           keyi = 4096 + (tk & 31);
;         }
;         __builtin_nontemporal_store(a, (f32x4*)o); __builtin_nontemporal_store(c, (f32x4*)(o + 4));
;         *(uint4*)(kb + kfrag_off(keyi, hh_, 8 * pj)) = pk8(a, c);
;       }
.LBB0_153:
	v_lshl_add_u64 v[78:79], v[80:81], 0, v[130:131]
	v_lshrrev_b32_e32 v130, 5, v84
	s_add_i32 s24, s24, 2
	s_waitcnt lgkmcnt(0)
	global_store_dwordx4 v[78:79], v[70:73], off nt
	global_store_dwordx4 v[78:79], v[66:69], off offset:16 nt
	s_add_u32 s74, s74, 0x20000
	v_cvt_pk_bf16_f32 v70, v70, v71
	v_cvt_pk_bf16_f32 v71, v72, v73
	v_cvt_pk_bf16_f32 v72, v66, v67
	v_lshlrev_b64 v[66:67], 11, v[130:131]
	v_lshl_add_u64 v[66:67], v[66:67], 0, v[74:75]
	s_addc_u32 s75, s75, 0
	v_and_or_b32 v66, v84, 31, v66
	s_add_u32 s76, s76, 0x820000
	v_or_b32_e32 v66, v66, v133
	s_addc_u32 s77, s77, 0
	v_cvt_pk_bf16_f32 v73, v68, v69
	v_lshl_add_u64 v[66:67], v[66:67], 4, s[6:7]
	v_add_u32_e32 v1, 64, v1
	s_cmp_eq_u32 s74, 0x80000
	v_add_u32_e32 v82, 0x4400, v82
	global_store_dwordx4 v[66:67], v[70:73], off
	s_cbranch_scc1 .LBB0_162

; DI uint4 pk8(f32x4 a, f32x4 b) { return make_uint4(pack2(a[0], a[1]), pack2(a[2], a[3]), pack2(b[0], b[1]), pack2(b[2], b[3])); }
; DI void epi_inproj(const Params& P, acc_t& acc, int ttile, int ftile, float* T) {
;     ...
;     } else if (fg < F_VA) {
;       const int c0 = fg - F_KA, hh_ = c0 >> 6;
; #pragma unroll 2
;       for (int it = 0; it < 8; ++it) {
;         const int tk = it * 32 + tsub;
;         f32x4 a = *(const f32x4*)(Tgp + tk * TLD), c = *(const f32x4*)(Tgp + tk * TLD + 4);
;         float* o; u16* kb; int keyi;
;         if (!samp) {
;           const long tok = (long)ttile * 256 + tk;
;           o = out + O_KP + tok * 512 + c0 + 8 * pj;
;           kb = (u16*)(ws + R_KA) + (tok >> 13) * (8192L * 512);
;           keyi = (int)(tok & 8191);
;         } else {
;           o = out + O_KS + (long)tk * 512 + c0 + 8 * pj;
;           kb = (u16*)(ws + R_SK) + (long)(tk >> 5) * 4160 * 512;
;           keyi = 4096 + (tk & 31);
;         }
;         __builtin_nontemporal_store(a, (f32x4*)o); __builtin_nontemporal_store(c, (f32x4*)(o + 4));
;         *(uint4*)(kb + kfrag_off(keyi, hh_, 8 * pj)) = pk8(a, c);
;       }
.LBB0_158:
	v_lshlrev_b32_e32 v130, 2, v153
	v_lshl_add_u64 v[80:81], v[80:81], 0, v[130:131]
	s_waitcnt lgkmcnt(0)
	global_store_dwordx4 v[80:81], v[70:73], off nt
	global_store_dwordx4 v[80:81], v[66:69], off offset:16 nt
	s_and_b64 vcc, exec, s[6:7]
	v_cvt_pk_bf16_f32 v70, v70, v71
	v_cvt_pk_bf16_f32 v71, v72, v73
	v_cvt_pk_bf16_f32 v72, v66, v67
	v_lshrrev_b32_e32 v66, 5, v84
	v_mov_b32_e32 v67, v131
	v_lshlrev_b64 v[66:67], 11, v[66:67]
	v_lshl_add_u64 v[66:67], v[66:67], 0, v[74:75]
	v_and_or_b32 v66, v84, 31, v66
	v_or_b32_e32 v66, v66, v133
	v_cvt_pk_bf16_f32 v73, v68, v69
	v_lshl_add_u64 v[66:67], v[66:67], 4, s[78:79]
	global_store_dwordx4 v[66:67], v[70:73], off
	ds_read_b128 v[70:73], v82 offset:8704
	ds_read_b128 v[66:69], v82 offset:8720
	s_mov_b64 s[6:7], -1
	s_cbranch_vccnz .LBB0_160
	v_add_u32_e32 v80, 32, v83
	v_or_b32_e32 v80, s58, v80
	v_mov_b32_e32 v81, s59
	v_lshlrev_b64 v[80:81], 11, v[80:81]
	v_add_u32_e32 v83, 32, v1
	v_lshl_add_u64 v[80:81], s[72:73], 0, v[80:81]
	v_and_b32_e32 v84, 0x1fff, v83
	s_mov_b64 s[6:7], 0

; DI uint4 pk8(f32x4 a, f32x4 b) { return make_uint4(pack2(a[0], a[1]), pack2(a[2], a[3]), pack2(b[0], b[1]), pack2(b[2], b[3])); }
; DI void epi_inproj(const Params& P, acc_t& acc, int ttile, int ftile, float* T) {
;     ...
;     if (fg < F_KA) {
;       u16* o = (u16*)(ws + R_QA) + (long)ttile * 256 * 512 + fg + 8 * pj;
; #pragma unroll 2
;       for (int it = 0; it < 8; ++it) {
;         const int tk = it * 32 + tsub;
;         f32x4 a = *(const f32x4*)(Tgp + tk * TLD), c = *(const f32x4*)(Tgp + tk * TLD + 4);
;         *(uint4*)(o + (long)tk * 512) = pk8(a * QSCALE, c * QSCALE);
;       }
.LBB0_166:
	ds_read_b128 v[68:71], v1
	ds_read_b128 v[74:77], v1 offset:16
	v_lshl_add_u64 v[78:79], v[66:67], 0, s[6:7]
	s_add_u32 s6, s6, 0x10000
	s_addc_u32 s7, s7, 0
	s_waitcnt lgkmcnt(0)
	v_pk_mul_f32 v[70:71], v[70:71], s[50:51] op_sel_hi:[1,0]
	v_pk_mul_f32 v[68:69], v[68:69], s[50:51] op_sel_hi:[1,0]
	v_pk_mul_f32 v[74:75], v[74:75], s[50:51] op_sel_hi:[1,0]
	v_pk_mul_f32 v[76:77], v[76:77], s[50:51] op_sel_hi:[1,0]
	v_cvt_pk_bf16_f32 v68, v68, v69
	v_cvt_pk_bf16_f32 v69, v70, v71
	v_cvt_pk_bf16_f32 v70, v74, v75
	v_add_co_u32_e32 v74, vcc, s89, v78
	v_cvt_pk_bf16_f32 v71, v76, v77
	s_nop 0
	v_addc_co_u32_e32 v75, vcc, 0, v79, vcc
	global_store_dwordx4 v[74:75], v[68:71], off offset:2304
	ds_read_b128 v[68:71], v1 offset:8704
	ds_read_b128 v[74:77], v1 offset:8720
	v_add_u32_e32 v1, 0x4400, v1
	s_cmp_eq_u32 s6, 0x40000
	s_waitcnt lgkmcnt(0)
	v_pk_mul_f32 v[70:71], v[70:71], s[50:51] op_sel_hi:[1,0]
	v_pk_mul_f32 v[68:69], v[68:69], s[50:51] op_sel_hi:[1,0]
	v_pk_mul_f32 v[74:75], v[74:75], s[50:51] op_sel_hi:[1,0]
	v_pk_mul_f32 v[76:77], v[76:77], s[50:51] op_sel_hi:[1,0]
	v_cvt_pk_bf16_f32 v68, v68, v69
	v_cvt_pk_bf16_f32 v69, v70, v71
	v_cvt_pk_bf16_f32 v70, v74, v75
	v_add_co_u32_e32 v74, vcc, s20, v78
	v_cvt_pk_bf16_f32 v71, v76, v77
	s_nop 0
	v_addc_co_u32_e32 v75, vcc, 0, v79, vcc
	global_store_dwordx4 v[74:75], v[68:71], off offset:2304
	s_cbranch_scc0 .LBB0_166
	s_mov_b32 s26, 0

; DI void epi_inproj(const Params& P, acc_t& acc, int ttile, int ftile, float* T) {
;     ...
;         if (ttype == 1) {
;           u16* vb = samp ? ((u16*)((unsigned char*)out + OB_SVT) + (long)bb * 512 * 4160) : ((u16*)((unsigned char*)out + OB_VAT) + (long)bb * 512 * 8192);
;           const int keyi = samp ? 4096 + tt0 : tt0, hh_ = (fg - F_VA) >> 6;
;           *(uint2*)(vb + vfrag_off(keyi, hh_, f)) = make_uint2(pack2(x[0], x[1]), pack2(x[2], x[3]));
;           *(uint2*)(vb + vfrag_off(keyi + 4, hh_, f)) = make_uint2(pack2(x[4], x[5]), pack2(x[6], x[7]));
.LBB0_170:
	s_bitset1_b32 s25, 12
	v_mov_b32_e32 v87, s25
	v_cndmask_b32_e64 v88, v86, v87, s[4:5]
	v_and_b32_e32 v130, 0x7fffffe0, v88
	v_lshrrev_b32_e32 v88, 3, v88
	v_lshl_add_u64 v[86:87], s[70:71], 0, v[130:131]
	v_and_b32_e32 v88, 2, v88
	v_or3_b32 v86, v88, v79, v86
	v_lshlrev_b64 v[86:87], 10, v[86:87]
	v_lshl_add_u64 v[76:77], v[76:77], 0, v[86:87]
	v_lshl_add_u64 v[76:77], v[76:77], 0, v[70:71]
	global_store_dwordx2 v[76:77], v[66:67], off offset:8
	global_store_dwordx2 v[76:77], v[68:69], off offset:520

; DI void epi_inproj(const Params& P, acc_t& acc, int ttile, int ftile, float* T) {
;     ...
;       for (int k = 0; k < 8; ++k) {
;         const int t0l = tb * 64 + k * 8;
;         int bb, tt0;
;         if (!samp) { bb = ttile >> 5; tt0 = (ttile & 31) * 256 + t0l; }
;         else { bb = t0l >> 5; tt0 = t0l & 31; }
;         float x[8];
;         for (int i2 = 0; i2 < 8; ++i2) x[i2] = Tg[(t0l + i2) * TLD];
;         if (ttype == 1) {
;           u16* vb = samp ? ((u16*)((unsigned char*)out + OB_SVT) + (long)bb * 512 * 4160) : ((u16*)((unsigned char*)out + OB_VAT) + (long)bb * 512 * 8192);
;           const int keyi = samp ? 4096 + tt0 : tt0, hh_ = (fg - F_VA) >> 6;
;           *(uint2*)(vb + vfrag_off(keyi, hh_, f)) = make_uint2(pack2(x[0], x[1]), pack2(x[2], x[3]));
;           *(uint2*)(vb + vfrag_off(keyi + 4, hh_, f)) = make_uint2(pack2(x[4], x[5]), pack2(x[6], x[7]));
;         } else
;         *(uint4*)(base + ((long)bb * rows_per_b + rowi) * ldt + tt0) =
;             make_uint4(pack2(x[0], x[1]), pack2(x[2], x[3]), pack2(x[4], x[5]), pack2(x[6], x[7]));
;       }
.LBB0_172:
	v_add_u32_e32 v86, 0x400, v73
	ds_read2_b32 v[66:67], v73 offset1:68
	ds_read2_b32 v[68:69], v73 offset0:136 offset1:204
	ds_read2_b32 v[76:77], v86 offset0:16 offset1:84
	ds_read2_b32 v[90:91], v86 offset0:152 offset1:220
	v_add_u32_e32 v87, s69, v78
	v_lshrrev_b32_e32 v88, 5, v87
	s_and_b32 s25, s69, 16
	v_add_u32_e32 v86, s69, v80
	s_mov_b64 s[76:77], -1
	s_and_b64 vcc, s[72:73], exec
	s_waitcnt lgkmcnt(0)
	v_cvt_pk_bf16_f32 v66, v66, v67
	v_cvt_pk_bf16_f32 v67, v68, v69
	v_cvt_pk_bf16_f32 v68, v76, v77
	v_cvt_pk_bf16_f32 v69, v90, v91
	s_cbranch_vccz .LBB0_174
	v_mov_b32_e32 v76, s54
	v_cndmask_b32_e64 v76, v76, v88, s[4:5]
	v_mov_b32_e32 v77, s25
	v_cndmask_b32_e64 v130, v86, v77, s[4:5]
	v_ashrrev_i32_e32 v77, 31, v76
	v_lshlrev_b64 v[76:77], s26, v[76:77]
	v_lshl_add_u64 v[76:77], v[76:77], 0, v[74:75]
	v_lshlrev_b64 v[76:77], s55, v[76:77]
	v_lshl_add_u64 v[76:77], v[76:77], 1, s[6:7]
	v_lshl_add_u64 v[76:77], v[130:131], 1, v[76:77]
	global_store_dwordx4 v[76:77], v[66:69], off
	s_mov_b64 s[76:77], 0

; DI void epi_inproj(const Params& P, acc_t& acc, int ttile, int ftile, float* T) {
;     ...
;       for (int k = 0; k < 8; ++k) {
;         const int t0l = tb * 64 + k * 8;
;         int bb, tt0;
;         if (!samp) { bb = ttile >> 5; tt0 = (ttile & 31) * 256 + t0l; }
;         else { bb = t0l >> 5; tt0 = t0l & 31; }
;         float x[8];
;         for (int i2 = 0; i2 < 8; ++i2) x[i2] = Tg[(t0l + i2) * TLD];
;         if (ttype == 1) {
;           u16* vb = samp ? ((u16*)((unsigned char*)out + OB_SVT) + (long)bb * 512 * 4160) : ((u16*)((unsigned char*)out + OB_VAT) + (long)bb * 512 * 8192);
;           const int keyi = samp ? 4096 + tt0 : tt0, hh_ = (fg - F_VA) >> 6;
;           *(uint2*)(vb + vfrag_off(keyi, hh_, f)) = make_uint2(pack2(x[0], x[1]), pack2(x[2], x[3]));
;           *(uint2*)(vb + vfrag_off(keyi + 4, hh_, f)) = make_uint2(pack2(x[4], x[5]), pack2(x[6], x[7]));
;         } else
;         *(uint4*)(base + ((long)bb * rows_per_b + rowi) * ldt + tt0) =
;             make_uint4(pack2(x[0], x[1]), pack2(x[2], x[3]), pack2(x[4], x[5]), pack2(x[6], x[7]));
;       }
.LBB0_177:
	s_bitset1_b32 s25, 12
	v_mov_b32_e32 v88, s25
	v_cndmask_b32_e64 v90, v86, v88, s[4:5]
	v_and_b32_e32 v130, 0x7fffffe0, v90
	v_lshrrev_b32_e32 v91, 3, v90
	v_lshl_add_u64 v[88:89], s[70:71], 0, v[130:131]
	v_and_b32_e32 v91, 2, v91
	v_or3_b32 v88, v91, v79, v88
	v_lshlrev_b64 v[88:89], 10, v[88:89]
	v_lshl_add_u64 v[76:77], v[76:77], 0, v[88:89]
	v_lshl_add_u64 v[76:77], v[76:77], 0, v[70:71]
	v_and_b32_e32 v130, 8, v90
	v_lshl_add_u64 v[76:77], v[76:77], 0, v[130:131]
	global_store_dwordx2 v[76:77], v[66:67], off
	global_store_dwordx2 v[76:77], v[68:69], off offset:512
.LBB0_178:
	v_add_u32_e32 v66, 8, v87
	v_add_u32_e32 v68, 0x800, v73
	v_add_u32_e32 v88, 0xc00, v73
	v_lshrrev_b32_e32 v87, 5, v66
	ds_read2_b32 v[66:67], v68 offset0:32 offset1:100
	ds_read2_b32 v[68:69], v68 offset0:168 offset1:236
	ds_read2_b32 v[76:77], v88 offset0:48 offset1:116
	ds_read2_b32 v[88:89], v88 offset0:184 offset1:252
	s_add_i32 s25, s69, 8
	s_and_b32 s25, s25, 24
	v_add_u32_e32 v86, 8, v86
	s_mov_b64 s[76:77], -1
	s_andn2_b64 vcc, exec, s[72:73]
	s_waitcnt lgkmcnt(0)
	v_cvt_pk_bf16_f32 v66, v66, v67
	v_cvt_pk_bf16_f32 v67, v68, v69
	v_cvt_pk_bf16_f32 v68, v76, v77
	v_cvt_pk_bf16_f32 v69, v88, v89
	s_cbranch_vccnz .LBB0_180
	v_mov_b32_e32 v76, s54
	v_cndmask_b32_e64 v76, v76, v87, s[4:5]
	v_mov_b32_e32 v77, s25
	v_cndmask_b32_e64 v130, v86, v77, s[4:5]
	v_ashrrev_i32_e32 v77, 31, v76
	v_lshlrev_b64 v[76:77], s26, v[76:77]
	v_lshl_add_u64 v[76:77], v[76:77], 0, v[74:75]
	v_lshlrev_b64 v[76:77], s55, v[76:77]
	v_lshl_add_u64 v[76:77], v[76:77], 1, s[6:7]
	v_lshl_add_u64 v[76:77], v[130:131], 1, v[76:77]
	global_store_dwordx4 v[76:77], v[66:69], off
	s_cbranch_execnz .LBB0_171
	s_branch .LBB0_181

; DI void epi_inproj(const Params& P, acc_t& acc, int ttile, int ftile, float* T) {
;     ...
;     __syncthreads();
;     {
;       float* Tw = T + wr * (256 * TLD);
; #pragma unroll
;       for (int bj = 0; bj < 2; ++bj)
; #pragma unroll
;         for (int m = 0; m < 4; ++m)
; #pragma unroll
;           for (int n = 0; n < 2; ++n)
;             *(f32x4*)(Tw + (bj * 128 + wc * 32 + n * 16 + fr) * TLD + m * 16 + fq * 4) = acc[ai][bj][m][n];
;     }
;     __syncthreads();
;     const int grp = __builtin_amdgcn_readfirstlane(tid_ >> 8), tl = tid_ & 255;
;     const int fg = ftile * 256 + ai * 128 + grp * 64;
;     float* Tr = T + grp * (256 * TLD) + tl * TLD;
;     const int tsub = tl >> 3, pj = tl & 7;
;     const float* Tgp = T + grp * (256 * TLD) + 8 * pj;
;     const long token = (long)ttile * 256 + tl;
;     int b, t, pos, nn, C;
;     if (!samp) { b = (int)(token >> 13); t = (int)(token & 8191); pos = t; nn = t & 63; C = 64; }
;     else { b = tl >> 5; t = tl & 31; pos = 4096 + t; nn = t; C = 32; }
;     ...
;     } else if (fg == F_WI) {
;       f32x4 a = *(const f32x4*)Tr;
;       *(f32x4*)((float*)(ws + R_WI) + token * 4) = a * 0.0625f;
.LBB0_184:
	v_readfirstlane_b32 s6, v160
	s_ashr_i32 s25, s6, 8
	s_lshl_b32 s72, s25, 6
	s_add_i32 s26, s72, s68
	v_add_u32_e32 v1, v162, v1
	s_mul_i32 s25, s25, 0x11000
	s_cmpk_lt_i32 s26, 0x200
	s_mov_b64 s[6:7], -1
	s_waitcnt lgkmcnt(0)
	s_barrier
	ds_write_b128 v1, v[2:5]
	ds_write_b128 v1, v[6:9] offset:4352
	ds_write_b128 v1, v[10:13] offset:64
	ds_write_b128 v1, v[14:17] offset:4416
	ds_write_b128 v1, v[18:21] offset:128
	ds_write_b128 v1, v[22:25] offset:4480
	ds_write_b128 v1, v[26:29] offset:192
	ds_write_b128 v1, v[30:33] offset:4544
	ds_write_b128 v1, v[34:37] offset:34816
	ds_write_b128 v1, v[38:41] offset:39168
	ds_write_b128 v1, v[42:45] offset:34880
	ds_write_b128 v1, v[46:49] offset:39232
	ds_write_b128 v1, v[50:53] offset:34944
	ds_write_b128 v1, v[54:57] offset:39296
	ds_write_b128 v1, v[58:61] offset:35008
	ds_write_b128 v1, v[62:65] offset:39360
	s_waitcnt lgkmcnt(0)
	s_barrier
	s_cbranch_scc1 .LBB0_252
	s_cmpk_lt_u32 s26, 0x400
	s_cbranch_scc1 .LBB0_239
	s_cmpk_lt_u32 s26, 0x600
	s_cbranch_scc1 .LBB0_234
	s_cmpk_lt_u32 s26, 0x700
	s_cbranch_scc1 .LBB0_229
	s_add_i32 s6, s25, 0
	v_add_u32_e32 v69, s6, v161
	s_mov_b64 s[70:71], -1
	s_mov_b64 s[6:7], 0
	s_cmpk_lt_i32 s26, 0x740
	s_mov_b64 s[68:69], 0
	s_cbranch_scc1 .LBB0_216
	s_cmpk_eq_i32 s26, 0x740
	s_mov_b64 s[68:69], -1
	s_cbranch_scc0 .LBB0_191
	ds_read_b128 v[2:5], v69
	s_mov_b32 s68, 0x3d800000
	s_waitcnt lgkmcnt(0)
	v_pk_mul_f32 v[4:5], v[4:5], s[68:69] op_sel_hi:[1,0]
	v_pk_mul_f32 v[2:3], v[2:3], s[68:69] op_sel_hi:[1,0]
	global_store_dwordx4 v[138:139], v[2:5], off
	s_mov_b64 s[68:69], 0

; DI float sigmoidf_(float x) { return 1.0f / (1.0f + __expf(-x)); }
; DI uint4 pk8(f32x4 a, f32x4 b) { return make_uint4(pack2(a[0], a[1]), pack2(a[2], a[3]), pack2(b[0], b[1]), pack2(b[2], b[3])); }
; DI void epi_inproj(const Params& P, acc_t& acc, int ttile, int ftile, float* T) {
;     ...
;     } else if (fg < F_END) {
;       const bool isr = fg >= F_GRR;
;       u16* o = (u16*)(ws + (isr ? R_GRR : R_GA)) + (long)ttile * 256 * 1024 + (fg - (isr ? F_GRR : F_GA)) + 8 * pj;
; #pragma unroll 2
;       for (int it = 0; it < 8; ++it) {
;         const int tk = it * 32 + tsub;
;         f32x4 a = *(const f32x4*)(Tgp + tk * TLD), c = *(const f32x4*)(Tgp + tk * TLD + 4);
;         for (int j = 0; j < 4; ++j) { a[j] = sigmoidf_(a[j]); c[j] = sigmoidf_(c[j]); }
;         *(uint4*)(o + (long)tk * 1024) = pk8(a, c);
;       }
.LBB0_198:
	ds_read_b128 v[2:5], v1
	ds_read_b128 v[8:11], v1 offset:16
	s_waitcnt lgkmcnt(0)
	v_mul_f32_e32 v2, 0xbfb8aa3b, v2
	v_mul_f32_e32 v3, 0xbfb8aa3b, v3
	v_exp_f32_e32 v2, v2
	v_exp_f32_e32 v3, v3
	v_mul_f32_e32 v8, 0xbfb8aa3b, v8
	v_exp_f32_e32 v8, v8
	v_pk_add_f32 v[2:3], v[2:3], 1.0 op_sel_hi:[1,0]
	s_nop 0
	v_div_scale_f32 v12, s[68:69], v3, v3, 1.0
	v_rcp_f32_e32 v13, v12
	s_nop 0
	v_fma_f32 v14, -v12, v13, 1.0
	v_fmac_f32_e32 v13, v14, v13
	v_div_scale_f32 v14, vcc, 1.0, v3, 1.0
	v_mul_f32_e32 v15, v14, v13
	v_fma_f32 v16, -v12, v15, v14
	v_fmac_f32_e32 v15, v16, v13
	v_fma_f32 v12, -v12, v15, v14
	v_div_fmas_f32 v12, v12, v13, v15
	v_div_fixup_f32 v12, v12, v3, 1.0
	v_div_scale_f32 v3, s[68:69], v2, v2, 1.0
	v_rcp_f32_e32 v13, v3
	s_nop 0
	v_fma_f32 v14, -v3, v13, 1.0
	v_fmac_f32_e32 v13, v14, v13
	v_div_scale_f32 v14, vcc, 1.0, v2, 1.0
	v_mul_f32_e32 v15, v14, v13
	v_fma_f32 v16, -v3, v15, v14
	v_fmac_f32_e32 v15, v16, v13
	v_fma_f32 v3, -v3, v15, v14
	v_div_fmas_f32 v3, v3, v13, v15
	v_div_fixup_f32 v13, v3, v2, 1.0
	v_mul_f32_e32 v2, 0xbfb8aa3b, v9
	v_exp_f32_e32 v9, v2
	s_nop 0
	v_pk_add_f32 v[2:3], v[8:9], 1.0 op_sel_hi:[1,0]
	s_nop 0
	v_div_scale_f32 v8, s[68:69], v3, v3, 1.0
	v_rcp_f32_e32 v9, v8
	s_nop 0
	v_fma_f32 v14, -v8, v9, 1.0
	v_fmac_f32_e32 v9, v14, v9
	v_div_scale_f32 v14, vcc, 1.0, v3, 1.0
	v_mul_f32_e32 v15, v14, v9
	v_fma_f32 v16, -v8, v15, v14
	v_fmac_f32_e32 v15, v16, v9
	v_fma_f32 v8, -v8, v15, v14
	v_div_fmas_f32 v8, v8, v9, v15
	v_div_fixup_f32 v8, v8, v3, 1.0
	v_div_scale_f32 v3, s[68:69], v2, v2, 1.0
	v_rcp_f32_e32 v9, v3
	s_nop 0
	v_fma_f32 v14, -v3, v9, 1.0
	v_fmac_f32_e32 v9, v14, v9
	v_div_scale_f32 v14, vcc, 1.0, v2, 1.0
	v_mul_f32_e32 v15, v14, v9
	v_fma_f32 v16, -v3, v15, v14
	v_fmac_f32_e32 v15, v16, v9
	v_fma_f32 v3, -v3, v15, v14
	v_div_fmas_f32 v3, v3, v9, v15
	v_div_fixup_f32 v9, v3, v2, 1.0
	v_mul_f32_e32 v3, 0xbfb8aa3b, v10
	v_mul_f32_e32 v2, 0xbfb8aa3b, v4
	v_exp_f32_e32 v4, v3
	v_mul_f32_e32 v3, 0xbfb8aa3b, v5
	v_exp_f32_e32 v2, v2
	v_exp_f32_e32 v3, v3
	s_nop 0
	v_pk_add_f32 v[2:3], v[2:3], 1.0 op_sel_hi:[1,0]
	s_nop 0
	v_div_scale_f32 v5, s[68:69], v3, v3, 1.0
	v_rcp_f32_e32 v10, v5
	s_nop 0
	v_fma_f32 v14, -v5, v10, 1.0
	v_fmac_f32_e32 v10, v14, v10
	v_div_scale_f32 v14, vcc, 1.0, v3, 1.0
	v_mul_f32_e32 v15, v14, v10
	v_fma_f32 v16, -v5, v15, v14
	v_fmac_f32_e32 v15, v16, v10
	v_fma_f32 v5, -v5, v15, v14
	v_div_fmas_f32 v5, v5, v10, v15
	v_div_fixup_f32 v10, v5, v3, 1.0
	v_div_scale_f32 v3, s[68:69], v2, v2, 1.0
	v_rcp_f32_e32 v5, v3
	s_nop 0
	v_fma_f32 v14, -v3, v5, 1.0
	v_fmac_f32_e32 v5, v14, v5
	v_div_scale_f32 v14, vcc, 1.0, v2, 1.0
	v_mul_f32_e32 v15, v14, v5
	v_fma_f32 v16, -v3, v15, v14
	v_fmac_f32_e32 v15, v16, v5
	v_fma_f32 v3, -v3, v15, v14
	v_div_fmas_f32 v3, v3, v5, v15
	v_div_fixup_f32 v14, v3, v2, 1.0
	v_mul_f32_e32 v2, 0xbfb8aa3b, v11
	v_exp_f32_e32 v5, v2
	s_nop 0
	v_pk_add_f32 v[2:3], v[4:5], 1.0 op_sel_hi:[1,0]
	s_nop 0
	v_div_scale_f32 v4, s[68:69], v3, v3, 1.0
	v_rcp_f32_e32 v5, v4
	s_nop 0
	v_fma_f32 v11, -v4, v5, 1.0
	v_fmac_f32_e32 v5, v11, v5
	v_div_scale_f32 v11, vcc, 1.0, v3, 1.0
	v_mul_f32_e32 v15, v11, v5
	v_fma_f32 v16, -v4, v15, v11
	v_fmac_f32_e32 v15, v16, v5
	v_fma_f32 v4, -v4, v15, v11
	v_div_fmas_f32 v4, v4, v5, v15
	v_div_fixup_f32 v5, v4, v3, 1.0
	v_div_scale_f32 v3, s[68:69], v2, v2, 1.0
	v_rcp_f32_e32 v4, v3
	s_nop 0
	v_fma_f32 v11, -v3, v4, 1.0
	v_fmac_f32_e32 v4, v11, v4
	v_div_scale_f32 v11, vcc, 1.0, v2, 1.0
	v_mul_f32_e32 v15, v11, v4
	v_fma_f32 v16, -v3, v15, v11
	v_fmac_f32_e32 v15, v16, v4
	v_fma_f32 v3, -v3, v15, v11
	v_div_fmas_f32 v3, v3, v4, v15
	v_div_fixup_f32 v11, v3, v2, 1.0
	v_cvt_pk_bf16_f32 v2, v13, v12
	v_cvt_pk_bf16_f32 v3, v14, v10
	v_cvt_pk_bf16_f32 v4, v9, v8
	v_cvt_pk_bf16_f32 v5, v11, v5
	v_lshl_add_u64 v[12:13], v[6:7], 0, s[6:7]
	global_store_dwordx4 v[12:13], v[2:5], off offset:256
	ds_read_b128 v[2:5], v1 offset:8704
	ds_read_b128 v[8:11], v1 offset:8720
	s_add_u32 s6, s6, 0x20000
	s_addc_u32 s7, s7, 0
	v_add_u32_e32 v1, 0x4400, v1
	s_waitcnt lgkmcnt(0)
; DI float sigmoidf_(float x) { return 1.0f / (1.0f + __expf(-x)); }
; DI uint4 pk8(f32x4 a, f32x4 b) { return make_uint4(pack2(a[0], a[1]), pack2(a[2], a[3]), pack2(b[0], b[1]), pack2(b[2], b[3])); }
; DI void epi_inproj(const Params& P, acc_t& acc, int ttile, int ftile, float* T) {
;     ...
;     } else if (fg < F_END) {
;       const bool isr = fg >= F_GRR;
;       u16* o = (u16*)(ws + (isr ? R_GRR : R_GA)) + (long)ttile * 256 * 1024 + (fg - (isr ? F_GRR : F_GA)) + 8 * pj;
; #pragma unroll 2
;       for (int it = 0; it < 8; ++it) {
;         const int tk = it * 32 + tsub;
;         f32x4 a = *(const f32x4*)(Tgp + tk * TLD), c = *(const f32x4*)(Tgp + tk * TLD + 4);
;         for (int j = 0; j < 4; ++j) { a[j] = sigmoidf_(a[j]); c[j] = sigmoidf_(c[j]); }
;         *(uint4*)(o + (long)tk * 1024) = pk8(a, c);
;       }
	v_mul_f32_e32 v2, 0xbfb8aa3b, v2
	v_mul_f32_e32 v3, 0xbfb8aa3b, v3
	v_exp_f32_e32 v2, v2
	v_exp_f32_e32 v3, v3
	v_mul_f32_e32 v8, 0xbfb8aa3b, v8
	v_exp_f32_e32 v8, v8
	s_cmp_eq_u32 s6, 0x80000
	v_pk_add_f32 v[2:3], v[2:3], 1.0 op_sel_hi:[1,0]
	s_nop 0
	v_div_scale_f32 v14, s[68:69], v3, v3, 1.0
	v_rcp_f32_e32 v15, v14
	s_nop 0
	v_fma_f32 v16, -v14, v15, 1.0
	v_fmac_f32_e32 v15, v16, v15
	v_div_scale_f32 v16, vcc, 1.0, v3, 1.0
	v_mul_f32_e32 v17, v16, v15
	v_fma_f32 v18, -v14, v17, v16
	v_fmac_f32_e32 v17, v18, v15
	v_fma_f32 v14, -v14, v17, v16
	v_div_fmas_f32 v14, v14, v15, v17
	v_div_fixup_f32 v14, v14, v3, 1.0
	v_div_scale_f32 v3, s[68:69], v2, v2, 1.0
	v_rcp_f32_e32 v15, v3
	s_nop 0
	v_fma_f32 v16, -v3, v15, 1.0
	v_fmac_f32_e32 v15, v16, v15
	v_div_scale_f32 v16, vcc, 1.0, v2, 1.0
	v_mul_f32_e32 v17, v16, v15
	v_fma_f32 v18, -v3, v17, v16
	v_fmac_f32_e32 v17, v18, v15
	v_fma_f32 v3, -v3, v17, v16
	v_div_fmas_f32 v3, v3, v15, v17
	v_div_fixup_f32 v15, v3, v2, 1.0
	v_mul_f32_e32 v2, 0xbfb8aa3b, v9
	v_exp_f32_e32 v9, v2
	s_nop 0
	v_pk_add_f32 v[2:3], v[8:9], 1.0 op_sel_hi:[1,0]
	s_nop 0
	v_div_scale_f32 v8, s[68:69], v3, v3, 1.0
	v_rcp_f32_e32 v9, v8
	s_nop 0
	v_fma_f32 v16, -v8, v9, 1.0
	v_fmac_f32_e32 v9, v16, v9
	v_div_scale_f32 v16, vcc, 1.0, v3, 1.0
	v_mul_f32_e32 v17, v16, v9
	v_fma_f32 v18, -v8, v17, v16
	v_fmac_f32_e32 v17, v18, v9
	v_fma_f32 v8, -v8, v17, v16
	v_div_fmas_f32 v8, v8, v9, v17
	v_div_fixup_f32 v8, v8, v3, 1.0
	v_div_scale_f32 v3, s[68:69], v2, v2, 1.0
	v_rcp_f32_e32 v9, v3
	s_nop 0
	v_fma_f32 v16, -v3, v9, 1.0
	v_fmac_f32_e32 v9, v16, v9
	v_div_scale_f32 v16, vcc, 1.0, v2, 1.0
	v_mul_f32_e32 v17, v16, v9
	v_fma_f32 v18, -v3, v17, v16
	v_fmac_f32_e32 v17, v18, v9
	v_fma_f32 v3, -v3, v17, v16
	v_div_fmas_f32 v3, v3, v9, v17
	v_div_fixup_f32 v9, v3, v2, 1.0
	v_mul_f32_e32 v3, 0xbfb8aa3b, v10
	v_mul_f32_e32 v2, 0xbfb8aa3b, v4
	v_exp_f32_e32 v4, v3
	v_mul_f32_e32 v3, 0xbfb8aa3b, v5
	v_exp_f32_e32 v2, v2
	v_exp_f32_e32 v3, v3
	s_nop 0
	v_pk_add_f32 v[2:3], v[2:3], 1.0 op_sel_hi:[1,0]
	s_nop 0
	v_div_scale_f32 v5, s[68:69], v3, v3, 1.0
	v_rcp_f32_e32 v10, v5
	s_nop 0
	v_fma_f32 v16, -v5, v10, 1.0
	v_fmac_f32_e32 v10, v16, v10
	v_div_scale_f32 v16, vcc, 1.0, v3, 1.0
	v_mul_f32_e32 v17, v16, v10
	v_fma_f32 v18, -v5, v17, v16
	v_fmac_f32_e32 v17, v18, v10
	v_fma_f32 v5, -v5, v17, v16
	v_div_fmas_f32 v5, v5, v10, v17
	v_div_fixup_f32 v10, v5, v3, 1.0
	v_div_scale_f32 v3, s[68:69], v2, v2, 1.0
	v_rcp_f32_e32 v5, v3
	s_nop 0
	v_fma_f32 v16, -v3, v5, 1.0
	v_fmac_f32_e32 v5, v16, v5
	v_div_scale_f32 v16, vcc, 1.0, v2, 1.0
	v_mul_f32_e32 v17, v16, v5
	v_fma_f32 v18, -v3, v17, v16
	v_fmac_f32_e32 v17, v18, v5
	v_fma_f32 v3, -v3, v17, v16
	v_div_fmas_f32 v3, v3, v5, v17
	v_div_fixup_f32 v16, v3, v2, 1.0
	v_mul_f32_e32 v2, 0xbfb8aa3b, v11
	v_exp_f32_e32 v5, v2
	s_nop 0
	v_pk_add_f32 v[2:3], v[4:5], 1.0 op_sel_hi:[1,0]
	s_nop 0
	v_div_scale_f32 v4, s[68:69], v3, v3, 1.0
	v_rcp_f32_e32 v5, v4
	s_nop 0
	v_fma_f32 v11, -v4, v5, 1.0
	v_fmac_f32_e32 v5, v11, v5
	v_div_scale_f32 v11, vcc, 1.0, v3, 1.0
	v_mul_f32_e32 v17, v11, v5
	v_fma_f32 v18, -v4, v17, v11
	v_fmac_f32_e32 v17, v18, v5
	v_fma_f32 v4, -v4, v17, v11
	v_div_fmas_f32 v4, v4, v5, v17
	v_div_fixup_f32 v5, v4, v3, 1.0
	v_div_scale_f32 v3, s[68:69], v2, v2, 1.0
	v_rcp_f32_e32 v4, v3
	s_nop 0
	v_fma_f32 v11, -v3, v4, 1.0
	v_fmac_f32_e32 v4, v11, v4
	v_div_scale_f32 v11, vcc, 1.0, v2, 1.0
	v_mul_f32_e32 v17, v11, v4
	v_fma_f32 v18, -v3, v17, v11
	v_fmac_f32_e32 v17, v18, v4
	v_fma_f32 v3, -v3, v17, v11
	v_div_fmas_f32 v3, v3, v4, v17
	v_div_fixup_f32 v11, v3, v2, 1.0
	v_cvt_pk_bf16_f32 v4, v9, v8
	v_add_co_u32_e32 v8, vcc, s76, v12
	v_cvt_pk_bf16_f32 v2, v15, v14
	v_cvt_pk_bf16_f32 v3, v16, v10
	v_cvt_pk_bf16_f32 v5, v11, v5
	v_addc_co_u32_e32 v9, vcc, 0, v13, vcc
	global_store_dwordx4 v[8:9], v[2:5], off offset:256
	s_cbranch_scc0 .LBB0_198

; DI float siluf_(float x) { return x / (1.0f + __expf(-x)); }
; DI uint4 pk8(f32x4 a, f32x4 b) { return make_uint4(pack2(a[0], a[1]), pack2(a[2], a[3]), pack2(b[0], b[1]), pack2(b[2], b[3])); }
; DI void epi_inproj(const Params& P, acc_t& acc, int ttile, int ftile, float* T) {
;     ...
;     } else if (fg < F_GA) {
;       u16* o = (u16*)(ws + R_GR) + (long)ttile * 256 * 1024 + (fg - F_GR) + 8 * pj;
; #pragma unroll 2
;       for (int it = 0; it < 8; ++it) {
;         const int tk = it * 32 + tsub;
;         f32x4 a = *(const f32x4*)(Tgp + tk * TLD), c = *(const f32x4*)(Tgp + tk * TLD + 4);
;         for (int j = 0; j < 4; ++j) { a[j] = siluf_(a[j]); c[j] = siluf_(c[j]); }
;         *(uint4*)(o + (long)tk * 1024) = pk8(a, c);
;       }
.LBB0_202:
	ds_read_b128 v[2:5], v1
	ds_read_b128 v[8:11], v1 offset:16
	s_waitcnt lgkmcnt(0)
	v_mul_f32_e32 v12, 0xbfb8aa3b, v2
	v_mul_f32_e32 v13, 0xbfb8aa3b, v8
	v_exp_f32_e32 v14, v13
	v_mul_f32_e32 v13, 0xbfb8aa3b, v3
	v_exp_f32_e32 v12, v12
	v_exp_f32_e32 v13, v13
	s_nop 0
	v_pk_add_f32 v[12:13], v[12:13], 1.0 op_sel_hi:[1,0]
	s_nop 0
	v_div_scale_f32 v15, s[66:67], v13, v13, v3
	v_rcp_f32_e32 v16, v15
	s_nop 0
	v_fma_f32 v17, -v15, v16, 1.0
	v_fmac_f32_e32 v16, v17, v16
	v_div_scale_f32 v17, vcc, v3, v13, v3
	v_mul_f32_e32 v18, v17, v16
	v_fma_f32 v19, -v15, v18, v17
	v_fmac_f32_e32 v18, v19, v16
	v_fma_f32 v15, -v15, v18, v17
	v_div_fmas_f32 v15, v15, v16, v18
	v_div_fixup_f32 v13, v15, v13, v3
	v_div_scale_f32 v3, s[66:67], v12, v12, v2
	v_rcp_f32_e32 v15, v3
	s_nop 0
	v_fma_f32 v16, -v3, v15, 1.0
	v_fmac_f32_e32 v15, v16, v15
	v_div_scale_f32 v16, vcc, v2, v12, v2
	v_mul_f32_e32 v17, v16, v15
	v_fma_f32 v18, -v3, v17, v16
	v_fmac_f32_e32 v17, v18, v15
	v_fma_f32 v3, -v3, v17, v16
	v_div_fmas_f32 v3, v3, v15, v17
	v_div_fixup_f32 v12, v3, v12, v2
	v_mul_f32_e32 v2, 0xbfb8aa3b, v9
	v_exp_f32_e32 v15, v2
	s_nop 0
	v_pk_add_f32 v[2:3], v[14:15], 1.0 op_sel_hi:[1,0]
	s_nop 0
	v_div_scale_f32 v14, s[66:67], v3, v3, v9
	v_rcp_f32_e32 v15, v14
	s_nop 0
	v_fma_f32 v16, -v14, v15, 1.0
	v_fmac_f32_e32 v15, v16, v15
	v_div_scale_f32 v16, vcc, v9, v3, v9
	v_mul_f32_e32 v17, v16, v15
	v_fma_f32 v18, -v14, v17, v16
	v_fmac_f32_e32 v17, v18, v15
	v_fma_f32 v14, -v14, v17, v16
	v_div_fmas_f32 v14, v14, v15, v17
	v_div_fixup_f32 v14, v14, v3, v9
	v_div_scale_f32 v3, s[66:67], v2, v2, v8
	v_rcp_f32_e32 v9, v3
	s_nop 0
	v_fma_f32 v15, -v3, v9, 1.0
	v_fmac_f32_e32 v9, v15, v9
	v_div_scale_f32 v15, vcc, v8, v2, v8
	v_mul_f32_e32 v16, v15, v9
	v_fma_f32 v17, -v3, v16, v15
	v_fmac_f32_e32 v16, v17, v9
	v_fma_f32 v3, -v3, v16, v15
	v_div_fmas_f32 v3, v3, v9, v16
	v_div_fixup_f32 v15, v3, v2, v8
	v_mul_f32_e32 v3, 0xbfb8aa3b, v10
	v_mul_f32_e32 v2, 0xbfb8aa3b, v4
	v_exp_f32_e32 v8, v3
	v_mul_f32_e32 v3, 0xbfb8aa3b, v5
	v_exp_f32_e32 v2, v2
	v_exp_f32_e32 v3, v3
	s_nop 0
	v_pk_add_f32 v[2:3], v[2:3], 1.0 op_sel_hi:[1,0]
	s_nop 0
	v_div_scale_f32 v9, s[66:67], v3, v3, v5
	v_rcp_f32_e32 v16, v9
	s_nop 0
	v_fma_f32 v17, -v9, v16, 1.0
	v_fmac_f32_e32 v16, v17, v16
	v_div_scale_f32 v17, vcc, v5, v3, v5
	v_mul_f32_e32 v18, v17, v16
	v_fma_f32 v19, -v9, v18, v17
	v_fmac_f32_e32 v18, v19, v16
	v_fma_f32 v9, -v9, v18, v17
	v_div_fmas_f32 v9, v9, v16, v18
	v_div_fixup_f32 v5, v9, v3, v5
	v_div_scale_f32 v3, s[66:67], v2, v2, v4
	v_rcp_f32_e32 v9, v3
	s_nop 0
	v_fma_f32 v16, -v3, v9, 1.0
	v_fmac_f32_e32 v9, v16, v9
	v_div_scale_f32 v16, vcc, v4, v2, v4
	v_mul_f32_e32 v17, v16, v9
	v_fma_f32 v18, -v3, v17, v16
	v_fmac_f32_e32 v17, v18, v9
	v_fma_f32 v3, -v3, v17, v16
	v_div_fmas_f32 v3, v3, v9, v17
	v_div_fixup_f32 v4, v3, v2, v4
	v_mul_f32_e32 v2, 0xbfb8aa3b, v11
	v_exp_f32_e32 v9, v2
	s_nop 0
	v_pk_add_f32 v[2:3], v[8:9], 1.0 op_sel_hi:[1,0]
	s_nop 0
	v_div_scale_f32 v8, s[66:67], v3, v3, v11
	v_rcp_f32_e32 v9, v8
	s_nop 0
	v_fma_f32 v16, -v8, v9, 1.0
	v_fmac_f32_e32 v9, v16, v9
	v_div_scale_f32 v16, vcc, v11, v3, v11
	v_mul_f32_e32 v17, v16, v9
	v_fma_f32 v18, -v8, v17, v16
	v_fmac_f32_e32 v17, v18, v9
	v_fma_f32 v8, -v8, v17, v16
	v_div_fmas_f32 v8, v8, v9, v17
	v_div_fixup_f32 v8, v8, v3, v11
	v_div_scale_f32 v3, s[66:67], v2, v2, v10
	v_rcp_f32_e32 v9, v3
	s_nop 0
	v_fma_f32 v11, -v3, v9, 1.0
	v_fmac_f32_e32 v9, v11, v9
	v_div_scale_f32 v11, vcc, v10, v2, v10
	v_mul_f32_e32 v16, v11, v9
	v_fma_f32 v17, -v3, v16, v11
	v_fmac_f32_e32 v16, v17, v9
	v_fma_f32 v3, -v3, v16, v11
	v_div_fmas_f32 v3, v3, v9, v16
	v_div_fixup_f32 v9, v3, v2, v10
	v_cvt_pk_bf16_f32 v2, v12, v13
	v_lshl_add_u64 v[12:13], v[6:7], 0, s[6:7]
	v_cvt_pk_bf16_f32 v3, v4, v5
	v_cvt_pk_bf16_f32 v5, v9, v8
	v_add_co_u32_e32 v8, vcc, s77, v12
	v_cvt_pk_bf16_f32 v4, v15, v14
	s_nop 0
	v_addc_co_u32_e32 v9, vcc, 0, v13, vcc
	global_store_dwordx4 v[8:9], v[2:5], off offset:2560
	ds_read_b128 v[2:5], v1 offset:8704
	ds_read_b128 v[8:11], v1 offset:8720
	s_add_u32 s6, s6, 0x20000
	s_addc_u32 s7, s7, 0
	v_add_u32_e32 v1, 0x4400, v1
	s_waitcnt lgkmcnt(0)
; DI float siluf_(float x) { return x / (1.0f + __expf(-x)); }
; DI uint4 pk8(f32x4 a, f32x4 b) { return make_uint4(pack2(a[0], a[1]), pack2(a[2], a[3]), pack2(b[0], b[1]), pack2(b[2], b[3])); }
; DI void epi_inproj(const Params& P, acc_t& acc, int ttile, int ftile, float* T) {
;     ...
;     } else if (fg < F_GA) {
;       u16* o = (u16*)(ws + R_GR) + (long)ttile * 256 * 1024 + (fg - F_GR) + 8 * pj;
; #pragma unroll 2
;       for (int it = 0; it < 8; ++it) {
;         const int tk = it * 32 + tsub;
;         f32x4 a = *(const f32x4*)(Tgp + tk * TLD), c = *(const f32x4*)(Tgp + tk * TLD + 4);
;         for (int j = 0; j < 4; ++j) { a[j] = siluf_(a[j]); c[j] = siluf_(c[j]); }
;         *(uint4*)(o + (long)tk * 1024) = pk8(a, c);
;       }
	v_mul_f32_e32 v14, 0xbfb8aa3b, v2
	v_mul_f32_e32 v15, 0xbfb8aa3b, v8
	v_exp_f32_e32 v16, v15
	v_mul_f32_e32 v15, 0xbfb8aa3b, v3
	v_exp_f32_e32 v14, v14
	v_exp_f32_e32 v15, v15
	s_cmp_eq_u32 s6, 0x80000
	v_pk_add_f32 v[14:15], v[14:15], 1.0 op_sel_hi:[1,0]
	s_nop 0
	v_div_scale_f32 v17, s[66:67], v15, v15, v3
	v_rcp_f32_e32 v18, v17
	s_nop 0
	v_fma_f32 v19, -v17, v18, 1.0
	v_fmac_f32_e32 v18, v19, v18
	v_div_scale_f32 v19, vcc, v3, v15, v3
	v_mul_f32_e32 v20, v19, v18
	v_fma_f32 v21, -v17, v20, v19
	v_fmac_f32_e32 v20, v21, v18
	v_fma_f32 v17, -v17, v20, v19
	v_div_fmas_f32 v17, v17, v18, v20
	v_div_fixup_f32 v15, v17, v15, v3
	v_div_scale_f32 v3, s[66:67], v14, v14, v2
	v_rcp_f32_e32 v17, v3
	s_nop 0
	v_fma_f32 v18, -v3, v17, 1.0
	v_fmac_f32_e32 v17, v18, v17
	v_div_scale_f32 v18, vcc, v2, v14, v2
	v_mul_f32_e32 v19, v18, v17
	v_fma_f32 v20, -v3, v19, v18
	v_fmac_f32_e32 v19, v20, v17
	v_fma_f32 v3, -v3, v19, v18
	v_div_fmas_f32 v3, v3, v17, v19
	v_div_fixup_f32 v14, v3, v14, v2
	v_mul_f32_e32 v2, 0xbfb8aa3b, v9
	v_exp_f32_e32 v17, v2
	s_nop 0
	v_pk_add_f32 v[2:3], v[16:17], 1.0 op_sel_hi:[1,0]
	s_nop 0
	v_div_scale_f32 v16, s[66:67], v3, v3, v9
	v_rcp_f32_e32 v17, v16
	s_nop 0
	v_fma_f32 v18, -v16, v17, 1.0
	v_fmac_f32_e32 v17, v18, v17
	v_div_scale_f32 v18, vcc, v9, v3, v9
	v_mul_f32_e32 v19, v18, v17
	v_fma_f32 v20, -v16, v19, v18
	v_fmac_f32_e32 v19, v20, v17
	v_fma_f32 v16, -v16, v19, v18
	v_div_fmas_f32 v16, v16, v17, v19
	v_div_fixup_f32 v16, v16, v3, v9
	v_div_scale_f32 v3, s[66:67], v2, v2, v8
	v_rcp_f32_e32 v9, v3
	s_nop 0
	v_fma_f32 v17, -v3, v9, 1.0
	v_fmac_f32_e32 v9, v17, v9
	v_div_scale_f32 v17, vcc, v8, v2, v8
	v_mul_f32_e32 v18, v17, v9
	v_fma_f32 v19, -v3, v18, v17
	v_fmac_f32_e32 v18, v19, v9
	v_fma_f32 v3, -v3, v18, v17
	v_div_fmas_f32 v3, v3, v9, v18
	v_div_fixup_f32 v17, v3, v2, v8
	v_mul_f32_e32 v3, 0xbfb8aa3b, v10
	v_mul_f32_e32 v2, 0xbfb8aa3b, v4
	v_exp_f32_e32 v8, v3
	v_mul_f32_e32 v3, 0xbfb8aa3b, v5
	v_exp_f32_e32 v2, v2
	v_exp_f32_e32 v3, v3
	s_nop 0
	v_pk_add_f32 v[2:3], v[2:3], 1.0 op_sel_hi:[1,0]
	s_nop 0
	v_div_scale_f32 v9, s[66:67], v3, v3, v5
	v_rcp_f32_e32 v18, v9
	s_nop 0
	v_fma_f32 v19, -v9, v18, 1.0
	v_fmac_f32_e32 v18, v19, v18
	v_div_scale_f32 v19, vcc, v5, v3, v5
	v_mul_f32_e32 v20, v19, v18
	v_fma_f32 v21, -v9, v20, v19
	v_fmac_f32_e32 v20, v21, v18
	v_fma_f32 v9, -v9, v20, v19
	v_div_fmas_f32 v9, v9, v18, v20
	v_div_fixup_f32 v5, v9, v3, v5
	v_div_scale_f32 v3, s[66:67], v2, v2, v4
	v_rcp_f32_e32 v9, v3
	s_nop 0
	v_fma_f32 v18, -v3, v9, 1.0
	v_fmac_f32_e32 v9, v18, v9
	v_div_scale_f32 v18, vcc, v4, v2, v4
	v_mul_f32_e32 v19, v18, v9
	v_fma_f32 v20, -v3, v19, v18
	v_fmac_f32_e32 v19, v20, v9
	v_fma_f32 v3, -v3, v19, v18
	v_div_fmas_f32 v3, v3, v9, v19
	v_div_fixup_f32 v4, v3, v2, v4
	v_mul_f32_e32 v2, 0xbfb8aa3b, v11
	v_exp_f32_e32 v9, v2
	s_nop 0
	v_pk_add_f32 v[2:3], v[8:9], 1.0 op_sel_hi:[1,0]
	s_nop 0
	v_div_scale_f32 v8, s[66:67], v3, v3, v11
	v_rcp_f32_e32 v9, v8
	s_nop 0
	v_fma_f32 v18, -v8, v9, 1.0
	v_fmac_f32_e32 v9, v18, v9
	v_div_scale_f32 v18, vcc, v11, v3, v11
	v_mul_f32_e32 v19, v18, v9
	v_fma_f32 v20, -v8, v19, v18
	v_fmac_f32_e32 v19, v20, v9
	v_fma_f32 v8, -v8, v19, v18
	v_div_fmas_f32 v8, v8, v9, v19
	v_div_fixup_f32 v8, v8, v3, v11
	v_div_scale_f32 v3, s[66:67], v2, v2, v10
	v_rcp_f32_e32 v9, v3
	s_nop 0
	v_fma_f32 v11, -v3, v9, 1.0
	v_fmac_f32_e32 v9, v11, v9
	v_div_scale_f32 v11, vcc, v10, v2, v10
	v_mul_f32_e32 v18, v11, v9
	v_fma_f32 v19, -v3, v18, v11
	v_fmac_f32_e32 v18, v19, v9
	v_fma_f32 v3, -v3, v18, v11
	v_div_fmas_f32 v3, v3, v9, v18
	v_div_fixup_f32 v9, v3, v2, v10
	v_cvt_pk_bf16_f32 v3, v4, v5
	v_cvt_pk_bf16_f32 v5, v9, v8
	v_add_co_u32_e32 v8, vcc, s74, v12
	v_cvt_pk_bf16_f32 v2, v14, v15
	v_cvt_pk_bf16_f32 v4, v17, v16
	v_addc_co_u32_e32 v9, vcc, 0, v13, vcc
	global_store_dwordx4 v[8:9], v[2:5], off offset:2560
	s_cbranch_scc0 .LBB0_202

; DI float log_gamma_h(int h) { return log1pf(-exp2f(-5.0f - (float)h)); }
; DI uint4 pk8(f32x4 a, f32x4 b) { return make_uint4(pack2(a[0], a[1]), pack2(a[2], a[3]), pack2(b[0], b[1]), pack2(b[2], b[3])); }
; DI void epi_inproj(const Params& P, acc_t& acc, int ttile, int ftile, float* T) {
;     ...
;     } else if (fg < F_VR) {
;       const bool isk = fg >= F_KR;
;       const int h = ((isk ? fg - F_KR : fg - F_QR)) >> 6;
;       const float lg = log_gamma_h(h);
;       const float dec = isk ? (expf(lg * (float)(C - 1 - nn)) * 0.125f) : expf(lg * (float)(nn + 1));
;       const float* rot = (const float*)(ws + W_ROT) + ((long)pos * 32) * 2;
;       u16* nat = (u16*)(ws + (isk ? R_KR : R_QR)) + token * 512 + h * 64;
; #pragma unroll 2
;       for (int k = 0; k < 4; ++k) {
;         f32x4 xa = *(const f32x4*)(Tr + 8 * k), xb = *(const f32x4*)(Tr + 8 * k + 4);
;         f32x4 ya = *(const f32x4*)(Tr + 32 + 8 * k), yb = *(const f32x4*)(Tr + 32 + 8 * k + 4);
;         f32x4 r0 = *(const f32x4*)(rot + 16 * k), r1 = *(const f32x4*)(rot + 16 * k + 4);
;         f32x4 r2 = *(const f32x4*)(rot + 16 * k + 8), r3 = *(const f32x4*)(rot + 16 * k + 12);
;         f32x4 ca = {r0[0], r0[2], r1[0], r1[2]}, sa = {r0[1], r0[3], r1[1], r1[3]};
;         f32x4 cb = {r2[0], r2[2], r3[0], r3[2]}, sb = {r2[1], r2[3], r3[1], r3[3]};
;         f32x4 o1a = (xa * ca - ya * sa) * dec, o1b = (xb * cb - yb * sb) * dec;
;         f32x4 o2a = (xa * sa + ya * ca) * dec, o2b = (xb * sb + yb * cb) * dec;
;         *(uint4*)(nat + 8 * k) = pk8(o1a, o1b);
;         *(uint4*)(nat + 32 + 8 * k) = pk8(o2a, o2b);
;         if (isk) {
;           *(f32x4*)(Tr + 8 * k) = o1a; *(f32x4*)(Tr + 8 * k + 4) = o1b;
;           *(f32x4*)(Tr + 32 + 8 * k) = o2a; *(f32x4*)(Tr + 32 + 8 * k + 4) = o2b;
;         }
;       }
;       if (isk) ttype = 2;
.LBB0_212:
	v_lshl_add_u64 v[26:27], s[10:11], 0, v[24:25]
	v_add_co_u32_e32 v2, vcc, 0x2380000, v26
	v_add_u32_e32 v1, s55, v69
	s_nop 0
	v_addc_co_u32_e32 v3, vcc, 0, v27, vcc
	ds_read_b128 v[10:13], v1
	ds_read_b128 v[14:17], v1 offset:16
	ds_read_b128 v[28:31], v1 offset:128
	ds_read_b128 v[32:35], v1 offset:144
	global_load_dwordx4 v[36:39], v[2:3], off
	global_load_dwordx4 v[40:43], v[2:3], off offset:16
	global_load_dwordx4 v[44:47], v[2:3], off offset:32
	global_load_dwordx4 v[48:51], v[2:3], off offset:48
	s_andn2_b64 vcc, exec, s[66:67]
	s_waitcnt vmcnt(0) lgkmcnt(0)
	v_mov_b32_e32 v54, v37
	v_mov_b32_e32 v52, v41
	v_mov_b32_e32 v53, v43
	v_mov_b32_e32 v55, v39
	v_pk_mul_f32 v[2:3], v[30:31], v[52:53]
	v_pk_mul_f32 v[4:5], v[28:29], v[54:55]
	v_mov_b32_e32 v37, v38
	v_mov_b32_e32 v41, v42
	v_pk_fma_f32 v[6:7], v[10:11], v[36:37], v[4:5] neg_lo:[0,0,1] neg_hi:[0,0,1]
	v_pk_fma_f32 v[2:3], v[12:13], v[40:41], v[2:3] neg_lo:[0,0,1] neg_hi:[0,0,1]
	v_mov_b32_e32 v38, v49
	v_mov_b32_e32 v39, v51
	v_mov_b32_e32 v42, v45
	v_mov_b32_e32 v43, v47
	v_pk_mul_f32 v[4:5], v[20:21], v[2:3]
	v_pk_mul_f32 v[2:3], v[18:19], v[6:7]
	v_pk_mul_f32 v[6:7], v[34:35], v[38:39]
	v_pk_mul_f32 v[8:9], v[32:33], v[42:43]
	v_mov_b32_e32 v45, v46
	v_mov_b32_e32 v49, v50
	v_pk_mul_f32 v[30:31], v[30:31], v[40:41]
	v_pk_mul_f32 v[28:29], v[28:29], v[36:37]
	v_pk_fma_f32 v[46:47], v[14:15], v[44:45], v[8:9] neg_lo:[0,0,1] neg_hi:[0,0,1]
	v_pk_fma_f32 v[6:7], v[16:17], v[48:49], v[6:7] neg_lo:[0,0,1] neg_hi:[0,0,1]
	v_pk_fma_f32 v[10:11], v[10:11], v[54:55], v[28:29]
	v_pk_fma_f32 v[12:13], v[12:13], v[52:53], v[30:31]
	v_pk_mul_f32 v[28:29], v[34:35], v[48:49]
	v_pk_mul_f32 v[30:31], v[32:33], v[44:45]
	v_pk_mul_f32 v[8:9], v[20:21], v[6:7]
	v_pk_mul_f32 v[6:7], v[18:19], v[46:47]
	v_pk_fma_f32 v[14:15], v[14:15], v[42:43], v[30:31]
	v_pk_fma_f32 v[16:17], v[16:17], v[38:39], v[28:29]
	v_pk_mul_f32 v[12:13], v[20:21], v[12:13]
	v_pk_mul_f32 v[10:11], v[18:19], v[10:11]
	v_pk_mul_f32 v[16:17], v[20:21], v[16:17]
	v_pk_mul_f32 v[14:15], v[18:19], v[14:15]
	v_cvt_pk_bf16_f32 v30, v2, v3
	v_cvt_pk_bf16_f32 v31, v4, v5
	v_cvt_pk_bf16_f32 v32, v6, v7
	v_cvt_pk_bf16_f32 v33, v8, v9
	v_lshl_add_u64 v[28:29], s[10:11], 0, v[22:23]
	global_store_dwordx4 v[28:29], v[30:33], off offset:256
	s_nop 1
	v_cvt_pk_bf16_f32 v30, v10, v11
	v_cvt_pk_bf16_f32 v31, v12, v13
	v_cvt_pk_bf16_f32 v32, v14, v15
	v_cvt_pk_bf16_f32 v33, v16, v17
	global_store_dwordx4 v[28:29], v[30:33], off offset:320
	s_nop 1
	v_cndmask_b32_e64 v30, 0, 1, s[66:67]
	v_cmp_ne_u32_e64 s[6:7], 1, v30
	s_cbranch_vccnz .LBB0_214
	ds_write_b128 v1, v[2:5]
	ds_write_b128 v1, v[6:9] offset:16
	ds_write_b128 v1, v[10:13] offset:128
	ds_write_b128 v1, v[14:17] offset:144
.LBB0_214:
	v_add_co_u32_e32 v14, vcc, 0x2380000, v26
	s_nop 1
	v_addc_co_u32_e32 v15, vcc, 0, v27, vcc
	global_load_dwordx4 v[2:5], v[14:15], off offset:80
	global_load_dwordx4 v[6:9], v[14:15], off offset:64
	global_load_dwordx4 v[10:13], v[14:15], off offset:112
	s_nop 0
	global_load_dwordx4 v[14:17], v[14:15], off offset:96
	ds_read_b128 v[30:33], v1 offset:32
	ds_read_b128 v[34:37], v1 offset:48
	ds_read_b128 v[38:41], v1 offset:160
	ds_read_b128 v[42:45], v1 offset:176
	s_and_b64 vcc, exec, s[6:7]
	s_waitcnt vmcnt(0) lgkmcnt(0)
	v_mov_b32_e32 v26, v3
	v_mov_b32_e32 v27, v5
	v_mov_b32_e32 v46, v7
	v_mov_b32_e32 v47, v9
	v_mov_b32_e32 v7, v8
	v_mov_b32_e32 v3, v4
	v_mov_b32_e32 v4, v11
	v_mov_b32_e32 v5, v13
	v_mov_b32_e32 v8, v15
	v_mov_b32_e32 v9, v17
	v_mov_b32_e32 v15, v16
	v_mov_b32_e32 v11, v12
	v_pk_mul_f32 v[12:13], v[40:41], v[26:27]
	v_pk_mul_f32 v[16:17], v[38:39], v[46:47]
	v_pk_mul_f32 v[48:49], v[44:45], v[4:5]
	v_pk_mul_f32 v[50:51], v[42:43], v[8:9]
	v_pk_mul_f32 v[40:41], v[40:41], v[2:3]
	v_pk_mul_f32 v[38:39], v[38:39], v[6:7]
	v_pk_mul_f32 v[44:45], v[44:45], v[10:11]
	v_pk_mul_f32 v[42:43], v[42:43], v[14:15]
	v_pk_fma_f32 v[6:7], v[30:31], v[6:7], v[16:17] neg_lo:[0,0,1] neg_hi:[0,0,1]
	v_pk_fma_f32 v[2:3], v[32:33], v[2:3], v[12:13] neg_lo:[0,0,1] neg_hi:[0,0,1]
	v_pk_fma_f32 v[12:13], v[34:35], v[14:15], v[50:51] neg_lo:[0,0,1] neg_hi:[0,0,1]
	v_pk_fma_f32 v[10:11], v[36:37], v[10:11], v[48:49] neg_lo:[0,0,1] neg_hi:[0,0,1]
	v_pk_fma_f32 v[14:15], v[30:31], v[46:47], v[38:39]
	v_pk_fma_f32 v[16:17], v[32:33], v[26:27], v[40:41]
	v_pk_fma_f32 v[26:27], v[34:35], v[8:9], v[42:43]
	v_pk_fma_f32 v[30:31], v[36:37], v[4:5], v[44:45]
	v_pk_mul_f32 v[4:5], v[20:21], v[2:3]
	v_pk_mul_f32 v[2:3], v[18:19], v[6:7]
	v_pk_mul_f32 v[8:9], v[20:21], v[10:11]
	v_pk_mul_f32 v[6:7], v[18:19], v[12:13]
	v_pk_mul_f32 v[12:13], v[20:21], v[16:17]
	v_pk_mul_f32 v[10:11], v[18:19], v[14:15]
	v_pk_mul_f32 v[16:17], v[20:21], v[30:31]
	v_pk_mul_f32 v[14:15], v[18:19], v[26:27]
	v_cvt_pk_bf16_f32 v30, v2, v3
	v_cvt_pk_bf16_f32 v31, v4, v5
	v_cvt_pk_bf16_f32 v32, v6, v7
	v_cvt_pk_bf16_f32 v33, v8, v9
	v_cvt_pk_bf16_f32 v34, v10, v11
	v_cvt_pk_bf16_f32 v35, v12, v13
	v_cvt_pk_bf16_f32 v36, v14, v15
	v_cvt_pk_bf16_f32 v37, v16, v17
	global_store_dwordx4 v[28:29], v[30:33], off offset:272
	global_store_dwordx4 v[28:29], v[34:37], off offset:336
	s_cbranch_vccnz .LBB0_211
	ds_write_b128 v1, v[2:5] offset:32
	ds_write_b128 v1, v[6:9] offset:48
	ds_write_b128 v1, v[10:13] offset:160
	ds_write_b128 v1, v[14:17] offset:176
	s_branch .LBB0_211

; DI uint4 pk8(f32x4 a, f32x4 b) { return make_uint4(pack2(a[0], a[1]), pack2(a[2], a[3]), pack2(b[0], b[1]), pack2(b[2], b[3])); }
; DI void epi_inproj(const Params& P, acc_t& acc, int ttile, int ftile, float* T) {
;     ...
; #pragma unroll 2
;       for (int k = 0; k < 8; ++k) {
;         f32x4 a = *(const f32x4*)(Tr + 8 * k), c = *(const f32x4*)(Tr + 8 * k + 4);
;         f32x4 g0 = *(const f32x4*)(P.ikg + 8 * k), g1 = *(const f32x4*)(P.ikg + 8 * k + 4);
;         f32x4 b0 = *(const f32x4*)(P.ikb + 8 * k), b1 = *(const f32x4*)(P.ikb + 8 * k + 4);
;         a = (a - mean) * rstd * g0 + b0;
;         c = (c - mean) * rstd * g1 + b1;
;         *(f32x4*)(o + 8 * k) = a; *(f32x4*)(o + 8 * k + 4) = c;
;         *(uint4*)(kb + kifrag_off(keyi, 8 * k)) = pk8(a, c);
;       }
.LBB0_226:
	s_add_u32 s68, s12, s6
	s_addc_u32 s69, s13, s7
	s_add_u32 s66, s14, s6
	s_addc_u32 s67, s15, s7
	ds_read_b128 v[12:15], v69
	ds_read_b128 v[16:19], v69 offset:16
	global_load_dwordx4 v[20:23], v131, s[68:69] offset:16
	global_load_dwordx4 v[24:27], v131, s[68:69]
	global_load_dwordx4 v[28:31], v131, s[66:67] offset:16
	global_load_dwordx4 v[32:35], v131, s[66:67]
	s_add_i32 s70, s55, 0xffffff00
	s_waitcnt lgkmcnt(0)
	v_sub_f32_e32 v15, v15, v3
	v_sub_f32_e32 v14, v14, v2
	v_sub_f32_e32 v13, v13, v1
	v_sub_f32_e32 v12, v12, v68
	v_sub_f32_e32 v19, v19, v3
	v_sub_f32_e32 v18, v18, v2
	v_sub_f32_e32 v17, v17, v1
	v_sub_f32_e32 v16, v16, v68
	v_pk_mul_f32 v[12:13], v[4:5], v[12:13]
	v_pk_mul_f32 v[14:15], v[8:9], v[14:15]
	v_pk_mul_f32 v[16:17], v[4:5], v[16:17]
	v_pk_mul_f32 v[18:19], v[8:9], v[18:19]
	v_lshl_add_u64 v[36:37], v[6:7], 0, s[6:7]
	v_or_b32_e32 v130, s70, v10
	s_add_u32 s6, s6, 64
	s_addc_u32 s7, s7, 0
	s_waitcnt vmcnt(0)
	v_pk_fma_f32 v[18:19], v[18:19], v[22:23], v[30:31]
	v_pk_fma_f32 v[14:15], v[14:15], v[26:27], v[34:35]
	v_pk_fma_f32 v[12:13], v[12:13], v[24:25], v[32:33]
	v_pk_fma_f32 v[16:17], v[16:17], v[20:21], v[28:29]
	global_store_dwordx4 v[36:37], v[12:15], off
	global_store_dwordx4 v[36:37], v[16:19], off offset:16
	s_nop 0
	v_cvt_pk_bf16_f32 v12, v12, v13
	v_cvt_pk_bf16_f32 v13, v14, v15
	v_cvt_pk_bf16_f32 v14, v16, v17
	v_cvt_pk_bf16_f32 v15, v18, v19
	v_lshl_add_u64 v[16:17], v[130:131], 1, v[66:67]
	global_store_dwordx4 v[16:17], v[12:15], off
	ds_read_b128 v[12:15], v69 offset:32
	ds_read_b128 v[16:19], v69 offset:48
	global_load_dwordx4 v[20:23], v131, s[68:69] offset:48
	global_load_dwordx4 v[24:27], v131, s[68:69] offset:32
	global_load_dwordx4 v[28:31], v131, s[66:67] offset:48
	global_load_dwordx4 v[32:35], v131, s[66:67] offset:32
	v_or_b32_e32 v130, s55, v10
	s_addk_i32 s55, 0x200
	s_waitcnt lgkmcnt(0)
	v_sub_f32_e32 v15, v15, v3
	v_sub_f32_e32 v14, v14, v2
	v_sub_f32_e32 v13, v13, v1
	v_sub_f32_e32 v12, v12, v68
	v_sub_f32_e32 v19, v19, v3
	v_sub_f32_e32 v18, v18, v2
	v_sub_f32_e32 v17, v17, v1
	v_sub_f32_e32 v16, v16, v68
	v_pk_mul_f32 v[12:13], v[4:5], v[12:13]
	v_pk_mul_f32 v[14:15], v[8:9], v[14:15]
	v_pk_mul_f32 v[16:17], v[4:5], v[16:17]
	v_pk_mul_f32 v[18:19], v[8:9], v[18:19]
	v_add_u32_e32 v69, 64, v69
	s_cmpk_eq_i32 s6, 0x100
	s_waitcnt vmcnt(0)
	v_pk_fma_f32 v[18:19], v[18:19], v[22:23], v[30:31]
	v_pk_fma_f32 v[14:15], v[14:15], v[26:27], v[34:35]
	v_pk_fma_f32 v[12:13], v[12:13], v[24:25], v[32:33]
	v_pk_fma_f32 v[16:17], v[16:17], v[20:21], v[28:29]
	global_store_dwordx4 v[36:37], v[12:15], off offset:32
	global_store_dwordx4 v[36:37], v[16:19], off offset:48
	s_nop 0
	v_cvt_pk_bf16_f32 v12, v12, v13
	v_cvt_pk_bf16_f32 v13, v14, v15
	v_cvt_pk_bf16_f32 v14, v16, v17
	v_cvt_pk_bf16_f32 v15, v18, v19
	v_lshl_add_u64 v[16:17], v[130:131], 1, v[66:67]
	global_store_dwordx4 v[16:17], v[12:15], off
	s_cbranch_scc0 .LBB0_226
	s_mov_b32 s55, 0

; DI uint4 pk8(f32x4 a, f32x4 b) { return make_uint4(pack2(a[0], a[1]), pack2(a[2], a[3]), pack2(b[0], b[1]), pack2(b[2], b[3])); }
; DI void epi_inproj(const Params& P, acc_t& acc, int ttile, int ftile, float* T) {
;     ...
;     } else if (fg < F_KI) {
;       u16* o = (u16*)(ws + R_QI) + (long)ttile * 256 * 256 + (fg - F_QI) + 8 * pj;
; #pragma unroll 2
;       for (int it = 0; it < 8; ++it) {
;         const int tk = it * 32 + tsub;
;         f32x4 a = *(const f32x4*)(Tgp + tk * TLD), c = *(const f32x4*)(Tgp + tk * TLD + 4);
;         *(uint4*)(o + (long)tk * 256) = pk8(a, c);
;       }
.LBB0_231:
	ds_read_b128 v[4:7], v1
	ds_read_b128 v[8:11], v1 offset:16
	v_lshl_add_u64 v[12:13], v[2:3], 0, s[6:7]
	s_add_u32 s6, s6, 0x8000
	s_addc_u32 s7, s7, 0
	s_waitcnt lgkmcnt(0)
	v_cvt_pk_bf16_f32 v4, v4, v5
	v_cvt_pk_bf16_f32 v5, v6, v7
	v_cvt_pk_bf16_f32 v6, v8, v9
	v_add_co_u32_e32 v8, vcc, s33, v12
	v_cvt_pk_bf16_f32 v7, v10, v11
	s_nop 0
	v_addc_co_u32_e32 v9, vcc, 0, v13, vcc
	global_store_dwordx4 v[8:9], v[4:7], off offset:3328
	ds_read_b128 v[4:7], v1 offset:8704
	ds_read_b128 v[8:11], v1 offset:8720
	v_add_u32_e32 v1, 0x4400, v1
	s_cmp_eq_u32 s6, 0x20000
	s_waitcnt lgkmcnt(0)
	v_cvt_pk_bf16_f32 v4, v4, v5
	v_cvt_pk_bf16_f32 v5, v6, v7
	v_cvt_pk_bf16_f32 v6, v8, v9
	v_add_co_u32_e32 v8, vcc, s45, v12
	v_cvt_pk_bf16_f32 v7, v10, v11
	s_nop 0
	v_addc_co_u32_e32 v9, vcc, 0, v13, vcc
	global_store_dwordx4 v[8:9], v[4:7], off offset:3328
	s_cbranch_scc0 .LBB0_231
	s_mov_b32 s55, 0

; DI void epi_inproj(const Params& P, acc_t& acc, int ttile, int ftile, float* T) {
;     ...
;     } else if (fg < F_QI) {
;       const int c0 = fg - F_VA;
;       float* o = (samp ? (out + O_VS) : (out + O_VP + (long)ttile * 256 * 512)) + c0 + 8 * pj;
; #pragma unroll 2
;       for (int it = 0; it < 8; ++it) {
;         const int tk = it * 32 + tsub;
;         __builtin_nontemporal_store(*(const f32x4*)(Tgp + tk * TLD), (f32x4*)(o + (long)tk * 512));
;         __builtin_nontemporal_store(*(const f32x4*)(Tgp + tk * TLD + 4), (f32x4*)(o + (long)tk * 512 + 4));
;       }
;       ttype = 1;
.LBB0_236:
	ds_read_b128 v[4:7], v1
	v_lshl_add_u64 v[8:9], v[2:3], 0, s[6:7]
	v_add_co_u32_e32 v10, vcc, 0xfffff000, v8
	s_add_u32 s6, s6, 0x20000
	s_nop 0
	v_addc_co_u32_e32 v11, vcc, -1, v9, vcc
	s_waitcnt lgkmcnt(0)
	global_store_dwordx4 v[10:11], v[4:7], off nt
	ds_read_b128 v[4:7], v1 offset:16
	v_add_co_u32_e32 v10, vcc, 0xfffff010, v8
	s_addc_u32 s7, s7, 0
	s_nop 0
	v_addc_co_u32_e32 v11, vcc, -1, v9, vcc
	s_waitcnt lgkmcnt(0)
	global_store_dwordx4 v[10:11], v[4:7], off nt
	ds_read_b128 v[4:7], v1 offset:8704
	v_add_co_u32_e32 v8, vcc, 0xf000, v8
	s_cmp_eq_u32 s6, 0x80000
	s_nop 0
	v_addc_co_u32_e32 v9, vcc, 0, v9, vcc
	s_waitcnt lgkmcnt(0)
	global_store_dwordx4 v[8:9], v[4:7], off nt
	ds_read_b128 v[4:7], v1 offset:8720
	v_add_u32_e32 v1, 0x4400, v1
	s_waitcnt lgkmcnt(0)
	global_store_dwordx4 v[8:9], v[4:7], off offset:16 nt
	s_cbranch_scc0 .LBB0_236
	s_mov_b32 s55, 1

; DI uint4 pk8(f32x4 a, f32x4 b) { return make_uint4(pack2(a[0], a[1]), pack2(a[2], a[3]), pack2(b[0], b[1]), pack2(b[2], b[3])); }
; DI void epi_inproj(const Params& P, acc_t& acc, int ttile, int ftile, float* T) {
;     ...
;     } else if (fg < F_VA) {
;       const int c0 = fg - F_KA, hh_ = c0 >> 6;
; #pragma unroll 2
;       for (int it = 0; it < 8; ++it) {
;         const int tk = it * 32 + tsub;
;         f32x4 a = *(const f32x4*)(Tgp + tk * TLD), c = *(const f32x4*)(Tgp + tk * TLD + 4);
;         float* o; u16* kb; int keyi;
;         if (!samp) {
;           const long tok = (long)ttile * 256 + tk;
;           o = out + O_KP + tok * 512 + c0 + 8 * pj;
;           kb = (u16*)(ws + R_KA) + (tok >> 13) * (8192L * 512);
;           keyi = (int)(tok & 8191);
;         } else {
;           o = out + O_KS + (long)tk * 512 + c0 + 8 * pj;
;           kb = (u16*)(ws + R_SK) + (long)(tk >> 5) * 4160 * 512;
;           keyi = 4096 + (tk & 31);
;         }
;         __builtin_nontemporal_store(a, (f32x4*)o); __builtin_nontemporal_store(c, (f32x4*)(o + 4));
;         *(uint4*)(kb + kfrag_off(keyi, hh_, 8 * pj)) = pk8(a, c);
;       }
.LBB0_241:
	v_lshl_add_u64 v[14:15], v[16:17], 0, v[130:131]
	v_lshrrev_b32_e32 v130, 5, v20
	s_add_i32 s44, s44, 2
	s_waitcnt lgkmcnt(0)
	global_store_dwordx4 v[14:15], v[6:9], off nt
	global_store_dwordx4 v[14:15], v[2:5], off offset:16 nt
	s_add_u32 s52, s52, 0x20000
	v_cvt_pk_bf16_f32 v6, v6, v7
	v_cvt_pk_bf16_f32 v7, v8, v9
	v_cvt_pk_bf16_f32 v8, v2, v3
	v_lshlrev_b64 v[2:3], 11, v[130:131]
	v_lshl_add_u64 v[2:3], v[2:3], 0, v[10:11]
	s_addc_u32 s53, s53, 0
	v_and_or_b32 v2, v20, 31, v2
	s_add_u32 s66, s66, 0x820000
	v_or_b32_e32 v2, v2, v133
	s_addc_u32 s67, s67, 0
	v_cvt_pk_bf16_f32 v9, v4, v5
	v_lshl_add_u64 v[2:3], v[2:3], 4, s[6:7]
	v_add_u32_e32 v1, 64, v1
	s_cmp_eq_u32 s52, 0x80000
	v_add_u32_e32 v18, 0x4400, v18
	global_store_dwordx4 v[2:3], v[6:9], off
	s_cbranch_scc1 .LBB0_250

; DI uint4 pk8(f32x4 a, f32x4 b) { return make_uint4(pack2(a[0], a[1]), pack2(a[2], a[3]), pack2(b[0], b[1]), pack2(b[2], b[3])); }
; DI void epi_inproj(const Params& P, acc_t& acc, int ttile, int ftile, float* T) {
;     ...
;     } else if (fg < F_VA) {
;       const int c0 = fg - F_KA, hh_ = c0 >> 6;
; #pragma unroll 2
;       for (int it = 0; it < 8; ++it) {
;         const int tk = it * 32 + tsub;
;         f32x4 a = *(const f32x4*)(Tgp + tk * TLD), c = *(const f32x4*)(Tgp + tk * TLD + 4);
;         float* o; u16* kb; int keyi;
;         if (!samp) {
;           const long tok = (long)ttile * 256 + tk;
;           o = out + O_KP + tok * 512 + c0 + 8 * pj;
;           kb = (u16*)(ws + R_KA) + (tok >> 13) * (8192L * 512);
;           keyi = (int)(tok & 8191);
;         } else {
;           o = out + O_KS + (long)tk * 512 + c0 + 8 * pj;
;           kb = (u16*)(ws + R_SK) + (long)(tk >> 5) * 4160 * 512;
;           keyi = 4096 + (tk & 31);
;         }
;         __builtin_nontemporal_store(a, (f32x4*)o); __builtin_nontemporal_store(c, (f32x4*)(o + 4));
;         *(uint4*)(kb + kfrag_off(keyi, hh_, 8 * pj)) = pk8(a, c);
;       }
.LBB0_246:
	v_lshlrev_b32_e32 v130, 2, v153
	v_lshl_add_u64 v[16:17], v[16:17], 0, v[130:131]
	s_waitcnt lgkmcnt(0)
	global_store_dwordx4 v[16:17], v[6:9], off nt
	global_store_dwordx4 v[16:17], v[2:5], off offset:16 nt
	s_and_b64 vcc, exec, s[6:7]
	v_cvt_pk_bf16_f32 v6, v6, v7
	v_cvt_pk_bf16_f32 v7, v8, v9
	v_cvt_pk_bf16_f32 v8, v2, v3
	v_lshrrev_b32_e32 v2, 5, v20
	v_mov_b32_e32 v3, v131
	v_lshlrev_b64 v[2:3], 11, v[2:3]
	v_lshl_add_u64 v[2:3], v[2:3], 0, v[10:11]
	v_and_or_b32 v2, v20, 31, v2
	v_or_b32_e32 v2, v2, v133
	v_cvt_pk_bf16_f32 v9, v4, v5
	v_lshl_add_u64 v[2:3], v[2:3], 4, s[68:69]
	global_store_dwordx4 v[2:3], v[6:9], off
	ds_read_b128 v[6:9], v18 offset:8704
	ds_read_b128 v[2:5], v18 offset:8720
	s_mov_b64 s[6:7], -1
	s_cbranch_vccnz .LBB0_248
	v_add_u32_e32 v16, 32, v19
	v_or_b32_e32 v16, s58, v16
	v_mov_b32_e32 v17, s59
	v_lshlrev_b64 v[16:17], 11, v[16:17]
	v_add_u32_e32 v19, 32, v1
	v_lshl_add_u64 v[16:17], s[64:65], 0, v[16:17]
	v_and_b32_e32 v20, 0x1fff, v19
	s_mov_b64 s[6:7], 0

; DI uint4 pk8(f32x4 a, f32x4 b) { return make_uint4(pack2(a[0], a[1]), pack2(a[2], a[3]), pack2(b[0], b[1]), pack2(b[2], b[3])); }
; DI void epi_inproj(const Params& P, acc_t& acc, int ttile, int ftile, float* T) {
;     ...
;     if (fg < F_KA) {
;       u16* o = (u16*)(ws + R_QA) + (long)ttile * 256 * 512 + fg + 8 * pj;
; #pragma unroll 2
;       for (int it = 0; it < 8; ++it) {
;         const int tk = it * 32 + tsub;
;         f32x4 a = *(const f32x4*)(Tgp + tk * TLD), c = *(const f32x4*)(Tgp + tk * TLD + 4);
;         *(uint4*)(o + (long)tk * 512) = pk8(a * QSCALE, c * QSCALE);
;       }
.LBB0_254:
	ds_read_b128 v[4:7], v1
	ds_read_b128 v[8:11], v1 offset:16
	v_lshl_add_u64 v[12:13], v[2:3], 0, s[6:7]
	s_add_u32 s6, s6, 0x10000
	s_addc_u32 s7, s7, 0
	s_waitcnt lgkmcnt(0)
	v_pk_mul_f32 v[6:7], v[6:7], s[50:51] op_sel_hi:[1,0]
	v_pk_mul_f32 v[4:5], v[4:5], s[50:51] op_sel_hi:[1,0]
	v_pk_mul_f32 v[8:9], v[8:9], s[50:51] op_sel_hi:[1,0]
	v_pk_mul_f32 v[10:11], v[10:11], s[50:51] op_sel_hi:[1,0]
	v_cvt_pk_bf16_f32 v4, v4, v5
	v_cvt_pk_bf16_f32 v5, v6, v7
	v_cvt_pk_bf16_f32 v6, v8, v9
	v_add_co_u32_e32 v8, vcc, s89, v12
	v_cvt_pk_bf16_f32 v7, v10, v11
	s_nop 0
	v_addc_co_u32_e32 v9, vcc, 0, v13, vcc
	global_store_dwordx4 v[8:9], v[4:7], off offset:2560
	ds_read_b128 v[4:7], v1 offset:8704
	ds_read_b128 v[8:11], v1 offset:8720
	v_add_u32_e32 v1, 0x4400, v1
	s_cmp_eq_u32 s6, 0x40000
	s_waitcnt lgkmcnt(0)
	v_pk_mul_f32 v[6:7], v[6:7], s[50:51] op_sel_hi:[1,0]
	v_pk_mul_f32 v[4:5], v[4:5], s[50:51] op_sel_hi:[1,0]
	v_pk_mul_f32 v[8:9], v[8:9], s[50:51] op_sel_hi:[1,0]
	v_pk_mul_f32 v[10:11], v[10:11], s[50:51] op_sel_hi:[1,0]
	v_cvt_pk_bf16_f32 v4, v4, v5
	v_cvt_pk_bf16_f32 v5, v6, v7
	v_cvt_pk_bf16_f32 v6, v8, v9
	v_add_co_u32_e32 v8, vcc, s20, v12
	v_cvt_pk_bf16_f32 v7, v10, v11
	s_nop 0
	v_addc_co_u32_e32 v9, vcc, 0, v13, vcc
	global_store_dwordx4 v[8:9], v[4:7], off offset:2560
	s_cbranch_scc0 .LBB0_254
	s_mov_b32 s55, 0

; DI long vfrag_off(int key, int h, int d) {
;   const int kb = key >> 5, k5 = key & 31, sx = k5 >> 4, r = k5 & 15, g = (r >> 2) & 1, e = (r & 3) + 4 * (r >> 3);
;   return ((((long)kb * 8 + h) * 4 + (sx * 2 + (d >> 5))) * 64 + g * 32 + (d & 31)) * 8 + e;
; DI void epi_inproj(const Params& P, acc_t& acc, int ttile, int ftile, float* T) {
;     ...
;         if (ttype == 1) {
;           u16* vb = samp ? ((u16*)((unsigned char*)out + OB_SVT) + (long)bb * 512 * 4160) : ((u16*)((unsigned char*)out + OB_VAT) + (long)bb * 512 * 8192);
;           const int keyi = samp ? 4096 + tt0 : tt0, hh_ = (fg - F_VA) >> 6;
;           *(uint2*)(vb + vfrag_off(keyi, hh_, f)) = make_uint2(pack2(x[0], x[1]), pack2(x[2], x[3]));
;           *(uint2*)(vb + vfrag_off(keyi + 4, hh_, f)) = make_uint2(pack2(x[4], x[5]), pack2(x[6], x[7]));
.LBB0_258:
	s_or_b32 s6, s25, 0x1000
	v_mov_b32_e32 v11, s6
	v_cndmask_b32_e64 v12, v10, v11, s[4:5]
	v_and_b32_e32 v130, 0x7fffffe0, v12
	v_lshrrev_b32_e32 v12, 3, v12
	v_lshl_add_u64 v[10:11], s[58:59], 0, v[130:131]
	v_and_b32_e32 v12, 2, v12
	v_or3_b32 v10, v12, v79, v10
	v_lshlrev_b64 v[10:11], 10, v[10:11]
	v_lshl_add_u64 v[8:9], v[8:9], 0, v[10:11]
	v_lshl_add_u64 v[8:9], v[8:9], 0, v[70:71]
	global_store_dwordx2 v[8:9], v[2:3], off offset:8
	global_store_dwordx2 v[8:9], v[4:5], off offset:520

; DI void epi_inproj(const Params& P, acc_t& acc, int ttile, int ftile, float* T) {
;     ...
; #pragma unroll 2
;       for (int k = 0; k < 8; ++k) {
;         const int t0l = tb * 64 + k * 8;
;         int bb, tt0;
;         if (!samp) { bb = ttile >> 5; tt0 = (ttile & 31) * 256 + t0l; }
;         else { bb = t0l >> 5; tt0 = t0l & 31; }
;         float x[8];
;         for (int i2 = 0; i2 < 8; ++i2) x[i2] = Tg[(t0l + i2) * TLD];
;         if (ttype == 1) {
;           u16* vb = samp ? ((u16*)((unsigned char*)out + OB_SVT) + (long)bb * 512 * 4160) : ((u16*)((unsigned char*)out + OB_VAT) + (long)bb * 512 * 8192);
;           const int keyi = samp ? 4096 + tt0 : tt0, hh_ = (fg - F_VA) >> 6;
;           *(uint2*)(vb + vfrag_off(keyi, hh_, f)) = make_uint2(pack2(x[0], x[1]), pack2(x[2], x[3]));
;           *(uint2*)(vb + vfrag_off(keyi + 4, hh_, f)) = make_uint2(pack2(x[4], x[5]), pack2(x[6], x[7]));
;         } else
;         *(uint4*)(base + ((long)bb * rows_per_b + rowi) * ldt + tt0) =
;             make_uint4(pack2(x[0], x[1]), pack2(x[2], x[3]), pack2(x[4], x[5]), pack2(x[6], x[7]));
.LBB0_260:
	v_add_u32_e32 v10, 0x400, v1
	ds_read2_b32 v[2:3], v1 offset1:68
	ds_read2_b32 v[4:5], v1 offset0:136 offset1:204
	ds_read2_b32 v[8:9], v10 offset0:16 offset1:84
	ds_read2_b32 v[14:15], v10 offset0:152 offset1:220
	v_add_u32_e32 v11, s44, v78
	v_cndmask_b32_e64 v13, 0, 1, s[56:57]
	v_lshrrev_b32_e32 v12, 5, v11
	s_and_b32 s25, s44, 16
	v_add_u32_e32 v10, s44, v80
	s_mov_b64 s[8:9], -1
	v_cmp_ne_u32_e64 s[6:7], 1, v13
	s_andn2_b64 vcc, exec, s[56:57]
	s_waitcnt lgkmcnt(0)
	v_cvt_pk_bf16_f32 v2, v2, v3
	v_cvt_pk_bf16_f32 v3, v4, v5
	v_cvt_pk_bf16_f32 v4, v8, v9
	v_cvt_pk_bf16_f32 v5, v14, v15
	s_cbranch_vccnz .LBB0_262
	v_mov_b32_e32 v8, s54
	v_cndmask_b32_e64 v8, v8, v12, s[4:5]
	v_mov_b32_e32 v9, s25
	v_cndmask_b32_e64 v130, v10, v9, s[4:5]
	v_ashrrev_i32_e32 v9, 31, v8
	v_lshlrev_b64 v[8:9], s24, v[8:9]
	v_lshl_add_u64 v[8:9], v[8:9], 0, v[6:7]
	v_lshlrev_b64 v[8:9], s26, v[8:9]
	v_lshl_add_u64 v[8:9], v[8:9], 1, s[52:53]
	v_lshl_add_u64 v[8:9], v[130:131], 1, v[8:9]
	s_mov_b64 s[8:9], 0
	global_store_dwordx4 v[8:9], v[2:5], off

; DI void epi_inproj(const Params& P, acc_t& acc, int ttile, int ftile, float* T) {
;     ...
; #pragma unroll 2
;       for (int k = 0; k < 8; ++k) {
;         const int t0l = tb * 64 + k * 8;
;         int bb, tt0;
;         if (!samp) { bb = ttile >> 5; tt0 = (ttile & 31) * 256 + t0l; }
;         else { bb = t0l >> 5; tt0 = t0l & 31; }
;         float x[8];
;         for (int i2 = 0; i2 < 8; ++i2) x[i2] = Tg[(t0l + i2) * TLD];
;         if (ttype == 1) {
;           u16* vb = samp ? ((u16*)((unsigned char*)out + OB_SVT) + (long)bb * 512 * 4160) : ((u16*)((unsigned char*)out + OB_VAT) + (long)bb * 512 * 8192);
;           const int keyi = samp ? 4096 + tt0 : tt0, hh_ = (fg - F_VA) >> 6;
;           *(uint2*)(vb + vfrag_off(keyi, hh_, f)) = make_uint2(pack2(x[0], x[1]), pack2(x[2], x[3]));
;           *(uint2*)(vb + vfrag_off(keyi + 4, hh_, f)) = make_uint2(pack2(x[4], x[5]), pack2(x[6], x[7]));
;         } else
;         *(uint4*)(base + ((long)bb * rows_per_b + rowi) * ldt + tt0) =
;             make_uint4(pack2(x[0], x[1]), pack2(x[2], x[3]), pack2(x[4], x[5]), pack2(x[6], x[7]));
.LBB0_265:
	s_bitset1_b32 s25, 12
	v_mov_b32_e32 v12, s25
	v_cndmask_b32_e64 v14, v10, v12, s[4:5]
	v_and_b32_e32 v130, 0x7fffffe0, v14
	v_lshrrev_b32_e32 v15, 3, v14
	v_lshl_add_u64 v[12:13], s[58:59], 0, v[130:131]
	v_and_b32_e32 v15, 2, v15
	v_or3_b32 v12, v15, v79, v12
	v_lshlrev_b64 v[12:13], 10, v[12:13]
	v_lshl_add_u64 v[8:9], v[8:9], 0, v[12:13]
	v_lshl_add_u64 v[8:9], v[8:9], 0, v[70:71]
	v_and_b32_e32 v130, 8, v14
	v_lshl_add_u64 v[8:9], v[8:9], 0, v[130:131]
	global_store_dwordx2 v[8:9], v[2:3], off
	global_store_dwordx2 v[8:9], v[4:5], off offset:512
.LBB0_266:
	v_add_u32_e32 v2, 8, v11
	v_add_u32_e32 v4, 0x800, v1
	v_add_u32_e32 v12, 0xc00, v1
	v_lshrrev_b32_e32 v11, 5, v2
	ds_read2_b32 v[2:3], v4 offset0:32 offset1:100
	ds_read2_b32 v[4:5], v4 offset0:168 offset1:236
	ds_read2_b32 v[8:9], v12 offset0:48 offset1:116
	ds_read2_b32 v[12:13], v12 offset0:184 offset1:252
	s_add_i32 s25, s44, 8
	s_and_b32 s25, s25, 24
	v_add_u32_e32 v10, 8, v10
	s_mov_b64 s[62:63], -1
	s_and_b64 vcc, exec, s[6:7]
	s_waitcnt lgkmcnt(0)
	v_cvt_pk_bf16_f32 v2, v2, v3
	v_cvt_pk_bf16_f32 v3, v4, v5
	v_cvt_pk_bf16_f32 v4, v8, v9
	v_cvt_pk_bf16_f32 v5, v12, v13
	s_cbranch_vccnz .LBB0_268
	v_mov_b32_e32 v8, s54
	v_cndmask_b32_e64 v8, v8, v11, s[4:5]
	v_mov_b32_e32 v9, s25
	v_cndmask_b32_e64 v130, v10, v9, s[4:5]
	v_ashrrev_i32_e32 v9, 31, v8
	v_lshlrev_b64 v[8:9], s24, v[8:9]
	v_lshl_add_u64 v[8:9], v[8:9], 0, v[6:7]
	v_lshlrev_b64 v[8:9], s26, v[8:9]
	v_lshl_add_u64 v[8:9], v[8:9], 1, s[52:53]
	v_lshl_add_u64 v[8:9], v[130:131], 1, v[8:9]
	global_store_dwordx4 v[8:9], v[2:5], off
	s_cbranch_execnz .LBB0_259
	s_branch .LBB0_269

; DI int crow(int r, int g) { return (r & 3) + 8 * (r >> 2) + 4 * g; }
; DI void ret_item(const Params& P, unsigned char* smem, bool samp, int b, int h) {
;     ...
;   float* so = P.out + (samp ? O_SS : O_SP) + (long)(b * 8 + h) * 64 * 128;
;   for (int r = 0; r < 16; ++r) so[(long)(dh * 32 + crow(r, g)) * 128 + eb * 32 + l32] = S[r];
.LBB0_287:
	s_lshl_b64 s[0:1], s[8:9], 15
	v_readlane_b32 s2, v250, 22
	s_add_u32 s0, s2, s0
	v_readlane_b32 s2, v250, 25
	s_addc_u32 s1, s2, s1
	s_lshl_b32 s2, s18, 2
	v_or_b32_e32 v20, s17, v101
	s_add_u32 s0, s0, s2
	s_addc_u32 s1, s1, 0
	v_lshlrev_b32_e32 v2, 2, v100
	v_ashrrev_i32_e32 v21, 31, v20
	v_lshl_add_u64 v[22:23], s[0:1], 0, v[2:3]
	v_lshlrev_b64 v[24:25], 9, v[20:21]
	v_lshl_add_u64 v[24:25], v[22:23], 0, v[24:25]
	global_store_dword v[24:25], v4, off
	v_or_b32_e32 v24, 1, v20
	v_ashrrev_i32_e32 v25, 31, v24
	v_lshlrev_b64 v[24:25], 9, v[24:25]
	v_lshl_add_u64 v[24:25], v[22:23], 0, v[24:25]
	v_or_b32_e32 v4, 2, v20
	global_store_dword v[24:25], v5, off
	v_ashrrev_i32_e32 v5, 31, v4
	v_lshlrev_b64 v[4:5], 9, v[4:5]
	v_lshl_add_u64 v[4:5], v[22:23], 0, v[4:5]
	global_store_dword v[4:5], v6, off
	v_or_b32_e32 v4, 3, v20
	v_ashrrev_i32_e32 v5, 31, v4
	v_lshlrev_b64 v[4:5], 9, v[4:5]
	v_lshl_add_u64 v[4:5], v[22:23], 0, v[4:5]
	global_store_dword v[4:5], v7, off
	v_or_b32_e32 v4, 8, v20
	v_ashrrev_i32_e32 v5, 31, v4
	v_lshlrev_b64 v[4:5], 9, v[4:5]
	v_lshl_add_u64 v[4:5], v[22:23], 0, v[4:5]
	global_store_dword v[4:5], v8, off
	v_or_b32_e32 v4, 9, v20
	v_ashrrev_i32_e32 v5, 31, v4
	v_lshlrev_b64 v[4:5], 9, v[4:5]
	v_lshl_add_u64 v[4:5], v[22:23], 0, v[4:5]
	global_store_dword v[4:5], v9, off
	v_or_b32_e32 v4, 10, v20
	v_ashrrev_i32_e32 v5, 31, v4
	v_lshlrev_b64 v[4:5], 9, v[4:5]
	v_lshl_add_u64 v[4:5], v[22:23], 0, v[4:5]
	global_store_dword v[4:5], v10, off
	v_or_b32_e32 v4, 11, v20
	v_ashrrev_i32_e32 v5, 31, v4
	v_lshlrev_b64 v[4:5], 9, v[4:5]
	v_lshl_add_u64 v[4:5], v[22:23], 0, v[4:5]
	global_store_dword v[4:5], v11, off
	v_or_b32_e32 v4, 16, v20
	v_ashrrev_i32_e32 v5, 31, v4
	v_lshlrev_b64 v[4:5], 9, v[4:5]
	v_lshl_add_u64 v[4:5], v[22:23], 0, v[4:5]
	global_store_dword v[4:5], v12, off
	v_or_b32_e32 v4, 17, v20
	v_ashrrev_i32_e32 v5, 31, v4
	v_lshlrev_b64 v[4:5], 9, v[4:5]
	v_lshl_add_u64 v[4:5], v[22:23], 0, v[4:5]
	global_store_dword v[4:5], v13, off
	v_or_b32_e32 v4, 18, v20
	v_ashrrev_i32_e32 v5, 31, v4
	v_lshlrev_b64 v[4:5], 9, v[4:5]
	v_lshl_add_u64 v[4:5], v[22:23], 0, v[4:5]
	global_store_dword v[4:5], v14, off
	v_or_b32_e32 v4, 19, v20
	v_ashrrev_i32_e32 v5, 31, v4
	v_lshlrev_b64 v[4:5], 9, v[4:5]
	v_lshl_add_u64 v[4:5], v[22:23], 0, v[4:5]
	global_store_dword v[4:5], v15, off
	v_or_b32_e32 v4, 24, v20
	v_ashrrev_i32_e32 v5, 31, v4
	v_lshlrev_b64 v[4:5], 9, v[4:5]
	v_lshl_add_u64 v[4:5], v[22:23], 0, v[4:5]
	global_store_dword v[4:5], v16, off
	v_or_b32_e32 v4, 25, v20
	v_ashrrev_i32_e32 v5, 31, v4
	v_lshlrev_b64 v[4:5], 9, v[4:5]
	v_lshl_add_u64 v[4:5], v[22:23], 0, v[4:5]
	global_store_dword v[4:5], v17, off
	v_or_b32_e32 v4, 26, v20
	v_ashrrev_i32_e32 v5, 31, v4
	v_lshlrev_b64 v[4:5], 9, v[4:5]
	v_lshl_add_u64 v[4:5], v[22:23], 0, v[4:5]
	global_store_dword v[4:5], v18, off
	v_or_b32_e32 v4, 27, v20
	v_ashrrev_i32_e32 v5, 31, v4
	v_lshlrev_b64 v[4:5], 9, v[4:5]
	v_lshl_add_u64 v[4:5], v[22:23], 0, v[4:5]
	global_store_dword v[4:5], v19, off

; DI void attn_item(const Params& P, unsigned char* smem, bool samp, int b, int c) {
;     ...
;   const int nq = samp ? 32 : 64;
;   const long qrow0 = samp ? (NTP + b * 32) : ((long)b * 8192 + c * 64);
;   const int nkeys = samp ? 4128 : (c + 1) * 64;
;   const int ntiles = (nkeys + 63) >> 6;
;   const int qpos0 = samp ? 4096 : c * 64;
;   const u16* Kb = samp ? ((const u16*)(ws + R_SK) + (long)b * 4160 * 512) : ((const u16*)(ws + R_KA) + (long)b * 8192 * 512);
;   const u16* VTb = samp ? ((const u16*)((unsigned char*)P.out + OB_SVT) + (long)b * 512 * 4160)
;                         : ((const u16*)((unsigned char*)P.out + OB_VAT) + (long)b * 512 * 8192);
;   const long ldv = samp ? 4160 : 8192;
;   const u16* KIb = samp ? ((const u16*)(ws + R_SKI) + (long)b * 4160 * 64) : ((const u16*)(ws + R_KI) + (long)b * 8192 * 64);
;   unsigned* hist = (unsigned*)(smem + L_HIST) + wid * 2048;
;   unsigned* maskl = (unsigned*)(smem + L_HIST);
;   const float* t5l = (const float*)(smem + L_T5) + wid * T5N;
;   int* resl = (int*)(smem + L_RES) + wid * 32;
;   unsigned* cl = (unsigned*)(smem + L_CL) + wid * 1024;
;   uint2* lst = (uint2*)(smem + L_LIST) + wid * (8 * CAND_CAP);
;   unsigned* ccnt = (unsigned*)(smem + L_WV) + wid * 8;
;   const bool all_sel = (nkeys <= 256);
;   if (all_sel) {
;     for (int i = lane; i < ntiles * 16; i += 64) {
;       const int kt = i >> 4, r = i & 15;
;       maskl[(kt * 64 + 8 * wid + (r >> 1)) * 2 + (r & 1)] = 0xffffffffu;
;     }
;   } else {
;     bf16x8 iq[4];
;     {
;       int ql = 8 * wid + (l32 >> 2);
;       if (ql > nq - 1) ql = nq - 1;
;       const u16* p = (const u16*)(ws + R_QI) + (qrow0 + ql) * 256 + (l32 & 3) * 64 + g * 8;
;       for (int ks = 0; ks < 4; ++ks) iq[ks] = ld16(p + ks * 16);
;     }
;     f32x4 wv[4];
;     float scl[4];
;     for (int i = 0; i < 4; ++i) {
;       int ql = 8 * wid + g + 2 * i;
;       if (ql > nq - 1) ql = nq - 1;
; DI void phase_mixers(const Params& P, unsigned char* smem) {
;     ...
;       __syncthreads();
;       if (threadIdx.x == 0) itl[0] = (int)atomicAdd(ctr + b, 1u);
;       __syncthreads();
;       const int it = itl[0];
;       if (it >= ITEMS_PER_Q) break;
;       if (it < 8) ret_item(P, smem, false, b, it);
;       else if (it >= 137) ret_item(P, smem, true, b, it - 137);
;       else attn_item(P, smem, it == 8, b, it == 8 ? 0 : 127 - (it - 9));
.LBB0_292:
	s_or_b64 exec, exec, s[0:1]
	s_waitcnt lgkmcnt(0)
	s_barrier
	ds_read_b32 v1, v186
	s_movk_i32 s0, 0x90
	s_waitcnt lgkmcnt(0)
	v_cmp_lt_i32_e32 vcc, s0, v1
	v_readfirstlane_b32 s94, v1
	s_mov_b64 s[0:1], -1
	s_cbranch_vccnz .LBB0_289
	s_cmp_gt_i32 s94, 7
	s_cbranch_scc0 .LBB0_725
	s_cmpk_lt_u32 s94, 0x89
	s_cbranch_scc0 .LBB0_714
	v_mov_b32_e32 v112, v182
	s_mov_b64 s[86:87], s[38:39]
	v_readfirstlane_b32 s0, v112
	s_ashr_i32 s6, s0, 6
	v_bfe_u32 v178, v112, 5, 1
	v_writelane_b32 v250, s0, 53
	s_lshl_b32 s0, s94, 6
	s_sub_i32 s2, 0x2200, s0
	v_readlane_b32 s1, v250, 41
	v_writelane_b32 v250, s2, 54
	s_add_i32 s2, s2, s1
	s_sub_i32 s3, 0x2240, s0
	s_cmp_eq_u32 s94, 8
	s_cselect_b64 s[0:1], -1, 0
	v_writelane_b32 v250, s0, 55
	v_and_b32_e32 v110, 63, v112
	v_and_b32_e32 v195, 31, v112
	v_writelane_b32 v250, s1, 56
	s_and_b64 s[0:1], s[0:1], exec
	s_cselect_b32 s0, 32, 64
	v_writelane_b32 v250, s0, 9
	s_cselect_b32 s0, 0x1020, s3
	v_readlane_b32 s1, v250, 45
	s_cselect_b32 s2, s1, s2
	v_writelane_b32 v250, s2, 57
	s_add_i32 s1, s0, 63
	s_lshr_b32 s95, s1, 6
	v_writelane_b32 v250, s3, 58
	s_mov_b32 s2, s6
	v_writelane_b32 v250, s2, 14
	s_lshl_b32 s97, s6, 3
	s_cmpk_gt_u32 s0, 0x100
	v_writelane_b32 v250, s3, 15
	s_mov_b64 s[2:3], -1
	v_lshlrev_b32_e32 v108, 4, v178
	s_cbranch_scc0 .LBB0_683
	v_readlane_b32 s2, v250, 14
	s_lshl_b32 s1, s2, 13
	v_lshrrev_b32_e32 v1, 2, v195
	v_readlane_b32 s2, v250, 9
	v_readlane_b32 s8, v250, 57
	v_or_b32_e32 v1, s97, v1
	s_add_i32 s6, s2, -1
	v_readlane_b32 s9, v250, 58
	v_min_i32_e32 v4, s6, v1
	s_mov_b32 s9, s91
	v_ashrrev_i32_e32 v5, 31, v4
	v_lshl_add_u64 v[4:5], v[4:5], 0, s[8:9]
	v_lshlrev_b64 v[4:5], 9, v[4:5]
	v_lshlrev_b32_e32 v1, 7, v112
	v_lshl_add_u64 v[4:5], s[86:87], 0, v[4:5]
	v_and_b32_e32 v2, 0x180, v1
	v_readlane_b32 s3, v250, 15
	v_lshl_add_u64 v[4:5], v[4:5], 0, v[2:3]
	v_mov_b32_e32 v109, v3
	v_lshl_add_u64 v[4:5], v[4:5], 0, v[108:109]
	s_mov_b64 s[2:3], 0x247ca900
	v_lshl_add_u64 v[6:7], v[4:5], 0, s[2:3]
	s_mov_b32 s2, 0x247ca000
	v_add_co_u32_e32 v4, vcc, s2, v4
	v_or_b32_e32 v1, s97, v178
	s_nop 0
	v_addc_co_u32_e32 v5, vcc, 0, v5, vcc
	global_load_dwordx4 v[36:39], v[6:7], off offset:32
	global_load_dwordx4 v[40:43], v[6:7], off offset:64
	global_load_dwordx4 v[44:47], v[4:5], off offset:2304
	global_load_dwordx4 v[48:51], v[6:7], off offset:96
	v_min_i32_e32 v4, s6, v1
	v_or_b32_e32 v2, 2, v1
	s_add_u32 s2, s86, 0x273fa900
	v_ashrrev_i32_e32 v5, 31, v4
	v_min_i32_e32 v6, s6, v2
	s_addc_u32 s3, s87, 0
	v_lshl_add_u64 v[4:5], v[4:5], 0, s[8:9]
	v_ashrrev_i32_e32 v7, 31, v6
	v_lshl_add_u64 v[4:5], v[4:5], 4, s[2:3]
	v_lshl_add_u64 v[6:7], v[6:7], 0, s[8:9]
	v_or_b32_e32 v2, 4, v1
	v_lshl_add_u64 v[6:7], v[6:7], 4, s[2:3]
	global_load_dwordx4 v[52:55], v[4:5], off
	global_load_dwordx4 v[56:59], v[6:7], off
	v_min_i32_e32 v4, s6, v2
	v_or_b32_e32 v1, 6, v1
	v_ashrrev_i32_e32 v5, 31, v4
	v_min_i32_e32 v6, s6, v1
	v_lshl_add_u64 v[4:5], v[4:5], 0, s[8:9]
	v_ashrrev_i32_e32 v7, 31, v6
	v_lshl_add_u64 v[4:5], v[4:5], 4, s[2:3]
	v_lshl_add_u64 v[6:7], v[6:7], 0, s[8:9]
	v_lshl_add_u64 v[6:7], v[6:7], 4, s[2:3]
	global_load_dwordx4 v[60:63], v[4:5], off
	global_load_dwordx4 v[64:67], v[6:7], off
	s_mov_b32 s6, s8
	v_or_b32_e32 v109, 0xffffffc0, v110
	v_lshlrev_b32_e32 v1, 2, v110
	s_add_i32 s12, s1, 0
	v_writelane_b32 v250, s6, 57
	v_lshlrev_b32_e32 v113, 3, v178
	v_add_u32_e32 v2, s12, v1
	s_mov_b64 s[2:3], 0
	v_mov_b32_e32 v4, v109
	v_writelane_b32 v250, s7, 58
; #define IDX_PIPE_BEGIN() bf16x8 nk0[4], nk1[4]; IDX_LOAD(0, nk0, nk1);
; DI void attn_item(const Params& P, unsigned char* smem, bool samp, int b, int c) {
;     ...
;     for (int i = 0; i < 4; ++i) {
;       int ql = 8 * wid + g + 2 * i;
;       if (ql > nq - 1) ql = nq - 1;
;       wv[i] = *(const f32x4*)((const float*)(ws + R_WI) + (qrow0 + ql) * 4);
;       const float s2 = 32.0f * (wv[i][0] * wv[i][0] + wv[i][1] * wv[i][1] + wv[i][2] * wv[i][2] + wv[i][3] * wv[i][3]);
;       scl[i] = rsqrtf(s2 + 1e-30f);
;     }
;     ...
;     for (int i = lane; i < 2048; i += 64) hist[i] = 0u;
;     { IDX_PIPE_BEGIN();
.LBB0_297:
	v_add_u32_e32 v4, 64, v4
	s_movk_i32 s1, 0x7bf
	v_cmp_lt_u32_e32 vcc, s1, v4
	ds_write_b32 v2, v3
	s_or_b64 s[2:3], vcc, s[2:3]
	v_add_u32_e32 v2, 0x100, v2
	s_andn2_b64 exec, exec, s[2:3]
	s_cbranch_execnz .LBB0_297
	s_or_b64 exec, exec, s[2:3]
	v_readlane_b32 s2, v250, 55
	v_readlane_b32 s3, v250, 56
	s_and_b64 s[2:3], s[2:3], exec
	v_readlane_b32 s1, v250, 43
	v_readlane_b32 s2, v250, 44
	s_cselect_b32 s59, s2, s1
	s_mov_b32 s1, 0x26fea900
	s_cselect_b32 s58, s1, 0x267ea900
	s_add_u32 s1, s86, s58
	s_addc_u32 s3, s87, 0
	s_lshl_b32 s2, s59, 1
	s_add_u32 s2, s1, s2
	s_addc_u32 s3, s3, 0
	v_lshlrev_b32_e32 v2, 4, v110
	v_lshl_add_u64 v[114:115], s[2:3], 0, v[2:3]
	s_movk_i32 s1, 0x1000
	v_add_co_u32_e32 v4, vcc, s1, v114
	s_waitcnt vmcnt(0) lgkmcnt(0)
	v_mov_b32_e32 v122, v57
	v_addc_co_u32_e32 v5, vcc, 0, v115, vcc
	global_load_dwordx4 v[76:79], v[4:5], off offset:3072
	global_load_dwordx4 v[88:91], v[4:5], off offset:2048
	global_load_dwordx4 v[96:99], v[114:115], off offset:3072
	global_load_dwordx4 v[80:83], v[114:115], off offset:2048
	global_load_dwordx4 v[72:75], v[4:5], off offset:1024
	global_load_dwordx4 v[84:87], v[4:5], off
	global_load_dwordx4 v[92:95], v[114:115], off offset:1024
	global_load_dwordx4 v[68:71], v[114:115], off
	v_mov_b32_e32 v123, v53
	v_mov_b32_e32 v120, v56
	v_mov_b32_e32 v121, v52
	v_pk_mul_f32 v[4:5], v[122:123], v[122:123]
	v_mov_b32_e32 v124, v58
	v_pk_fma_f32 v[4:5], v[120:121], v[120:121], v[4:5]
	v_mov_b32_e32 v125, v54
	v_pk_fma_f32 v[4:5], v[124:125], v[124:125], v[4:5]
	v_mov_b32_e32 v126, v59
	v_mov_b32_e32 v127, v55
	s_mov_b32 s2, 0xda24260
	v_pk_fma_f32 v[4:5], v[126:127], v[126:127], v[4:5]
	v_mov_b64_e32 v[6:7], s[2:3]
	s_mov_b32 s2, 0x42000000
	v_pk_fma_f32 v[4:5], v[4:5], s[2:3], v[6:7] op_sel_hi:[1,0,0]
	v_mov_b32_e32 v130, v65
	v_mul_f32_e32 v8, 0x4b800000, v5
	v_cmp_gt_f32_e32 vcc, s33, v5
	v_cmp_gt_f32_e64 s[6:7], s33, v4
	v_mov_b32_e32 v131, v61
	v_cndmask_b32_e32 v5, v5, v8, vcc
	v_mul_f32_e32 v8, 0x4b800000, v4
	v_cndmask_b32_e64 v4, v4, v8, s[6:7]
	v_mov_b32_e32 v128, v64
	v_mov_b32_e32 v129, v60
	v_pk_mul_f32 v[8:9], v[130:131], v[130:131]
	v_mov_b32_e32 v132, v66
	v_pk_fma_f32 v[8:9], v[128:129], v[128:129], v[8:9]
	v_mov_b32_e32 v133, v62
	v_pk_fma_f32 v[8:9], v[132:133], v[132:133], v[8:9]
	v_mov_b32_e32 v134, v67
	v_mov_b32_e32 v135, v63
	v_pk_fma_f32 v[8:9], v[134:135], v[134:135], v[8:9]
	v_rsq_f32_e32 v5, v5
	v_pk_fma_f32 v[6:7], v[8:9], s[2:3], v[6:7] op_sel_hi:[1,0,0]
	v_rsq_f32_e32 v4, v4
	v_mul_f32_e32 v8, 0x4b800000, v7
	v_cmp_gt_f32_e64 s[8:9], s33, v7
	v_cmp_gt_f32_e64 s[10:11], s33, v6
	s_mov_b32 s2, 0x45800000
	v_cndmask_b32_e64 v7, v7, v8, s[8:9]
	v_mul_f32_e32 v8, 0x4b800000, v6
	v_cndmask_b32_e64 v6, v6, v8, s[10:11]
	v_rsq_f32_e32 v7, v7
	v_rsq_f32_e32 v6, v6
	v_pk_mul_f32 v[8:9], v[4:5], s[2:3] op_sel_hi:[1,0]
	s_mov_b32 s13, 0
	s_mov_b32 s14, 1
	v_pk_mul_f32 v[10:11], v[6:7], s[2:3] op_sel_hi:[1,0]
	s_mov_b64 s[2:3], 0x1000
	v_lshl_add_u64 v[116:117], v[114:115], 0, s[2:3]
	s_mov_b64 s[2:3], 0x1400
	v_lshl_add_u64 v[118:119], v[114:115], 0, s[2:3]
	s_mov_b64 s[2:3], 0x1800
	v_lshl_add_u64 v[104:105], v[114:115], 0, s[2:3]
	s_mov_b64 s[2:3], 0x1c00
	v_lshl_add_u64 v[100:101], v[114:115], 0, s[2:3]
	s_lshl_b32 s2, s0, 7
	s_addk_i32 s2, 0x1f80
	v_cndmask_b32_e32 v103, v5, v9, vcc
	v_cndmask_b32_e64 v102, v4, v8, s[6:7]
	v_cndmask_b32_e64 v107, v7, v11, s[8:9]
	v_cndmask_b32_e64 v106, v6, v10, s[10:11]
	v_lshlrev_b32_e32 v111, 3, v110
	s_sub_i32 s1, s0, 64
	v_lshl_add_u32 v136, v178, 10, s12
	s_and_b32 s10, s2, 0x3fe000
	s_mov_b64 s[2:3], 0
	s_branch .LBB0_300

.LBB0_300:
	s_waitcnt vmcnt(0) lgkmcnt(0)
	v_mfma_f32_32x32x16_bf16 v[20:35], v[44:47], v[68:71], 0
	s_cmp_ge_u32 s14, s95
	v_mfma_f32_32x32x16_bf16 v[4:19], v[44:47], v[84:87], 0
	v_mfma_f32_32x32x16_bf16 v[20:35], v[36:39], v[92:95], v[20:35]
	v_mfma_f32_32x32x16_bf16 v[4:19], v[36:39], v[72:75], v[4:19]
	v_mfma_f32_32x32x16_bf16 v[20:35], v[40:43], v[80:83], v[20:35]
	v_mfma_f32_32x32x16_bf16 v[4:19], v[40:43], v[88:91], v[4:19]
	v_mfma_f32_32x32x16_bf16 v[20:35], v[48:51], v[96:99], v[20:35]
	v_mfma_f32_32x32x16_bf16 v[4:19], v[48:51], v[76:79], v[4:19]
	s_cbranch_scc1 .LBB0_302
	v_lshl_add_u64 v[68:69], v[114:115], 0, s[2:3]
	v_add_co_u32_e32 v76, vcc, 0x2000, v68
	s_nop 1
	v_addc_co_u32_e32 v77, vcc, 0, v69, vcc
	v_add_co_u32_e32 v78, vcc, 0x3000, v68
	s_nop 1
	v_addc_co_u32_e32 v79, vcc, 0, v69, vcc
	global_load_dwordx4 v[68:71], v[76:77], off
	global_load_dwordx4 v[92:95], v[76:77], off offset:1024
	global_load_dwordx4 v[84:87], v[78:79], off
	global_load_dwordx4 v[72:75], v[78:79], off offset:1024
	global_load_dwordx4 v[80:83], v[76:77], off offset:2048
	global_load_dwordx4 v[96:99], v[76:77], off offset:3072
	global_load_dwordx4 v[88:91], v[78:79], off offset:2048
	s_nop 0
	global_load_dwordx4 v[76:79], v[78:79], off offset:3072

; DI void attn_item(const Params& P, unsigned char* smem, bool samp, int b, int c) {
;     ...
;         for (int kt = 0; kt < ntiles; ++kt) {
;           float sc[4][2];
;           IDX_SCORES(kt, sc);
;           for (int hf = 0; hf < 2; ++hf) {
;             const bool valid = (kt * 64 + hf * 32 + l32) < nkeys;
;             for (int i = 0; i < 4; ++i) {
;               const unsigned key = mono_key(sc[i][hf]);
;               const bool inb = valid && (pass == 0 || ((key >> (shift + 8)) == tau[i]));
;               const unsigned dg = (key >> shift) & 255u;
;               if (inb) atomicAdd(&cl[(g + 2 * i) * 128 + (dg >> 1)], 1u << (16 * (dg & 1)));
;             }
.LBB0_548:
	global_load_dwordx4 v[4:7], v[86:87], off
	global_load_dwordx4 v[128:131], v[86:87], off offset:1024
	v_add_co_u32_e32 v20, vcc, 0xfffff000, v86
	s_nop 1
	v_addc_co_u32_e32 v21, vcc, -1, v87, vcc
	global_load_dwordx4 v[20:23], v[20:21], off
	v_add_co_u32_e32 v132, vcc, 0xfffff400, v86
	s_waitcnt vmcnt(0) lgkmcnt(0)
	v_mfma_f32_32x32x16_bf16 v[4:19], v[44:47], v[4:7], 0
	v_addc_co_u32_e32 v133, vcc, -1, v87, vcc
	v_mfma_f32_32x32x16_bf16 v[4:19], v[36:39], v[128:131], v[4:19]
	global_load_dwordx4 v[128:131], v[132:133], off
	v_add_co_u32_e32 v132, vcc, 0xfffff800, v86
	s_nop 1
	v_addc_co_u32_e32 v133, vcc, -1, v87, vcc
	v_mfma_f32_32x32x16_bf16 v[20:35], v[44:47], v[20:23], 0
	s_waitcnt vmcnt(0) lgkmcnt(0)
	v_mfma_f32_32x32x16_bf16 v[20:35], v[36:39], v[128:131], v[20:35]
	global_load_dwordx4 v[128:131], v[86:87], off offset:2048
	s_waitcnt vmcnt(0) lgkmcnt(0)
	v_mfma_f32_32x32x16_bf16 v[4:19], v[40:43], v[128:131], v[4:19]
	global_load_dwordx4 v[128:131], v[132:133], off
	v_add_co_u32_e32 v132, vcc, 0xfffffc00, v86
	s_nop 1
	v_addc_co_u32_e32 v133, vcc, -1, v87, vcc
	v_cmp_gt_u32_e32 vcc, s0, v76
	s_waitcnt vmcnt(0) lgkmcnt(0)
	v_mfma_f32_32x32x16_bf16 v[20:35], v[40:43], v[128:131], v[20:35]
	global_load_dwordx4 v[128:131], v[132:133], off
	s_waitcnt vmcnt(0) lgkmcnt(0)
	v_mfma_f32_32x32x16_bf16 v[20:35], v[48:51], v[128:131], v[20:35]
	global_load_dwordx4 v[128:131], v[86:87], off offset:3072
	s_waitcnt vmcnt(0) lgkmcnt(0)
	v_mfma_f32_32x32x16_bf16 v[4:19], v[48:51], v[128:131], v[4:19]
	s_and_saveexec_b64 s[24:25], vcc
	s_cbranch_execz .LBB0_557
	s_nop 6
	v_med3_f32 v20, v20, 0, v187
	v_med3_f32 v21, v21, 0, v187
	v_mul_f32_e32 v20, v52, v20
	v_med3_f32 v22, v22, 0, v187
	v_fmac_f32_e32 v20, v53, v21
	v_med3_f32 v23, v23, 0, v187
	v_fmac_f32_e32 v20, v54, v22
	v_fmac_f32_e32 v20, v55, v23
	v_not_b32_e32 v21, v20
	v_or_b32_e32 v22, 0x80000000, v20
	v_cmp_gt_i32_e32 vcc, 0, v20
	s_nop 1
	v_cndmask_b32_e32 v20, v22, v21, vcc
	v_lshrrev_b32_e32 v21, s21, v20
	v_cmp_eq_u32_e32 vcc, v21, v97
	s_or_b64 s[34:35], s[2:3], vcc
	s_and_saveexec_b64 s[26:27], s[34:35]
	s_cbranch_execz .LBB0_551
	v_lshrrev_b32_e32 v20, s20, v20
	v_lshlrev_b32_e32 v21, 1, v20
	v_and_b32_e32 v21, 0x1fc, v21
	v_lshlrev_b32_e32 v20, 4, v20
	v_add_u32_e32 v21, v99, v21
	v_lshlrev_b32_e64 v20, v20, 1
	ds_add_u32 v21, v20

; DI void attn_item(const Params& P, unsigned char* smem, bool samp, int b, int c) {
;     ...
;       for (int kt = 0; kt < ntiles; ++kt) {
;         float sc[4][2];
;         IDX_SCORES(kt, sc);
;         for (int hf = 0; hf < 2; ++hf) {
;           const bool valid = (kt * 64 + hf * 32 + l32) < nkeys;
;           for (int i = 0; i < 4; ++i) {
;             const unsigned key = mono_key(sc[i][hf]);
;             const bool eq = valid && (key == tau[i]);
;             const unsigned long long bal = __ballot(eq);
;             const unsigned mym = g ? (unsigned)(bal >> 32) : (unsigned)bal;
;             const int rank = __popc(mym & ((1u << l32) - 1u));
;             const bool tsel = eq && (seen[i] + rank < need[i]);
;             seen[i] += __popc(mym);
;             const bool sel = (valid && key > tau[i]) || tsel;
;             const unsigned long long sb = __ballot(sel);
;             if (lane == 0) {
;               maskl[(kt * 64 + 8 * wid + 2 * i) * 2 + hf] = (unsigned)sb;
;               maskl[(kt * 64 + 8 * wid + 2 * i + 1) * 2 + hf] = (unsigned)(sb >> 32);
;             }
;           }
.LBB0_599:
	v_add_co_u32_e32 v4, vcc, 0xfffff000, v84
	s_nop 1
	v_addc_co_u32_e32 v5, vcc, -1, v85, vcc
	global_load_dwordx4 v[4:7], v[4:5], off
	s_nop 0
	global_load_dwordx4 v[8:11], v[84:85], off
	v_add_co_u32_e32 v12, vcc, 0xfffff400, v84
	s_waitcnt vmcnt(0) lgkmcnt(0)
	v_mfma_f32_32x32x16_bf16 v[20:35], v[44:47], v[4:7], 0
	v_addc_co_u32_e32 v13, vcc, -1, v85, vcc
	global_load_dwordx4 v[90:93], v[12:13], off
	global_load_dwordx4 v[128:131], v[84:85], off offset:1024
	v_add_co_u32_e32 v12, vcc, 0xfffff800, v84
	s_nop 1
	v_addc_co_u32_e32 v13, vcc, -1, v85, vcc
	global_load_dwordx4 v[132:135], v[12:13], off
	global_load_dwordx4 v[136:139], v[84:85], off offset:2048
	v_add_co_u32_e32 v12, vcc, 0xfffffc00, v84
	s_waitcnt vmcnt(0) lgkmcnt(0)
	v_mfma_f32_32x32x16_bf16 v[20:35], v[36:39], v[90:93], v[20:35]
	v_addc_co_u32_e32 v13, vcc, -1, v85, vcc
	global_load_dwordx4 v[140:143], v[12:13], off
	global_load_dwordx4 v[144:147], v[84:85], off offset:3072
	v_cmp_gt_u32_e32 vcc, s0, v80
	v_mfma_f32_32x32x16_bf16 v[20:35], v[40:43], v[132:135], v[20:35]
	v_mfma_f32_32x32x16_bf16 v[4:19], v[44:47], v[8:11], 0
	s_waitcnt vmcnt(0) lgkmcnt(0)
	v_mfma_f32_32x32x16_bf16 v[20:35], v[48:51], v[140:143], v[20:35]
	s_nop 11
	v_med3_f32 v20, v20, 0, v187
	v_mfma_f32_32x32x16_bf16 v[4:19], v[36:39], v[128:131], v[4:19]
	v_mul_f32_e32 v20, v52, v20
	v_med3_f32 v21, v21, 0, v187
	v_fmac_f32_e32 v20, v53, v21
	v_med3_f32 v21, v22, 0, v187
	v_fmac_f32_e32 v20, v54, v21
	v_med3_f32 v21, v23, 0, v187
	v_fmac_f32_e32 v20, v55, v21
	v_mfma_f32_32x32x16_bf16 v[4:19], v[40:43], v[136:139], v[4:19]
	v_not_b32_e32 v21, v20
	v_or_b32_e32 v22, 0x80000000, v20
	v_cmp_gt_i32_e64 s[8:9], 0, v20
	s_nop 1
	v_cndmask_b32_e64 v22, v22, v21, s[8:9]
	v_cmp_eq_u32_e64 s[8:9], v22, v97
	s_and_b64 s[2:3], vcc, s[8:9]
	v_cndmask_b32_e64 v20, 0, 1, s[2:3]
	v_cmp_ne_u32_e64 s[8:9], 0, v20
	v_mfma_f32_32x32x16_bf16 v[4:19], v[48:51], v[144:147], v[4:19]
	s_nop 0
	v_lshrrev_b64 v[20:21], v76, s[8:9]
	v_and_b32_e32 v21, v20, v78
	v_bcnt_u32_b32 v21, v21, v88
	v_cmp_lt_i32_e64 s[8:9], v21, v81
	s_and_b64 s[2:3], s[2:3], s[8:9]
	v_cmp_gt_u32_e64 s[8:9], v22, v97
	s_and_b64 s[8:9], vcc, s[8:9]
	s_or_b64 s[2:3], s[8:9], s[2:3]
	v_cndmask_b32_e64 v21, 0, 1, s[2:3]
	v_cmp_ne_u32_e64 s[8:9], 0, v21
	s_and_saveexec_b64 s[2:3], s[6:7]
	v_mov_b32_e32 v21, s10
	v_mov_b32_e32 v22, s8
	v_mov_b32_e32 v23, s9
	ds_write2_b32 v21, v22, v23 offset1:2
	s_or_b64 exec, exec, s[2:3]
	v_med3_f32 v21, v24, 0, v187
	v_mul_f32_e32 v21, v56, v21
	v_med3_f32 v22, v25, 0, v187
	v_fmac_f32_e32 v21, v57, v22
	v_med3_f32 v22, v26, 0, v187
	v_fmac_f32_e32 v21, v58, v22
	v_med3_f32 v22, v27, 0, v187
	v_fmac_f32_e32 v21, v59, v22
	v_not_b32_e32 v22, v21
	v_or_b32_e32 v23, 0x80000000, v21
	v_cmp_gt_i32_e64 s[8:9], 0, v21
	s_nop 1
	v_cndmask_b32_e64 v21, v23, v22, s[8:9]
	v_cmp_eq_u32_e64 s[8:9], v21, v96
	s_and_b64 s[2:3], vcc, s[8:9]
	v_cndmask_b32_e64 v22, 0, 1, s[2:3]
	v_cmp_ne_u32_e64 s[8:9], 0, v22
	s_nop 1
	v_lshrrev_b64 v[26:27], v76, s[8:9]
	v_and_b32_e32 v22, v26, v78
	v_bcnt_u32_b32 v22, v22, v87
	v_cmp_lt_i32_e64 s[8:9], v22, v83
	s_and_b64 s[2:3], s[2:3], s[8:9]
	v_cmp_gt_u32_e64 s[8:9], v21, v96
	s_and_b64 s[8:9], vcc, s[8:9]
	s_or_b64 s[2:3], s[8:9], s[2:3]
	v_cndmask_b32_e64 v21, 0, 1, s[2:3]
	v_cmp_ne_u32_e64 s[8:9], 0, v21
	s_and_saveexec_b64 s[2:3], s[6:7]
	v_mov_b32_e32 v21, s10
	v_mov_b32_e32 v22, s8
	v_mov_b32_e32 v23, s9
	ds_write2_b32 v21, v22, v23 offset0:4 offset1:6
	s_or_b64 exec, exec, s[2:3]
	v_med3_f32 v21, v28, 0, v187
	v_mul_f32_e32 v21, v60, v21
	v_med3_f32 v22, v29, 0, v187
	v_fmac_f32_e32 v21, v61, v22
	v_med3_f32 v22, v30, 0, v187
	v_fmac_f32_e32 v21, v62, v22
	v_med3_f32 v22, v31, 0, v187
	v_fmac_f32_e32 v21, v63, v22
	v_not_b32_e32 v22, v21
	v_or_b32_e32 v23, 0x80000000, v21
	v_cmp_gt_i32_e64 s[8:9], 0, v21
	s_nop 1
	v_cndmask_b32_e64 v21, v23, v22, s[8:9]
	v_cmp_eq_u32_e64 s[8:9], v21, v95
	s_and_b64 s[2:3], vcc, s[8:9]
	v_cndmask_b32_e64 v22, 0, 1, s[2:3]
	v_cmp_ne_u32_e64 s[8:9], 0, v22
	s_nop 1
	v_lshrrev_b64 v[24:25], v76, s[8:9]
	v_and_b32_e32 v22, v24, v78
	v_bcnt_u32_b32 v22, v22, v86
	v_cmp_lt_i32_e64 s[8:9], v22, v77
	s_and_b64 s[2:3], s[2:3], s[8:9]
	v_cmp_gt_u32_e64 s[8:9], v21, v95
	s_and_b64 s[8:9], vcc, s[8:9]
	s_or_b64 s[2:3], s[8:9], s[2:3]
	v_cndmask_b32_e64 v21, 0, 1, s[2:3]
	v_cmp_ne_u32_e64 s[8:9], 0, v21
	s_and_saveexec_b64 s[2:3], s[6:7]
	v_mov_b32_e32 v21, s10
	v_mov_b32_e32 v22, s8
	v_mov_b32_e32 v23, s9
	ds_write2_b32 v21, v22, v23 offset0:8 offset1:10
	s_or_b64 exec, exec, s[2:3]
	v_med3_f32 v21, v32, 0, v187
	v_mul_f32_e32 v21, v64, v21
	v_med3_f32 v22, v33, 0, v187
	v_fmac_f32_e32 v21, v65, v22
	v_med3_f32 v22, v34, 0, v187
	v_fmac_f32_e32 v21, v66, v22
	v_med3_f32 v22, v35, 0, v187
	v_fmac_f32_e32 v21, v67, v22
	v_not_b32_e32 v22, v21
	v_or_b32_e32 v23, 0x80000000, v21
	v_cmp_gt_i32_e64 s[8:9], 0, v21
	s_nop 1
	v_cndmask_b32_e64 v21, v23, v22, s[8:9]
; DI void attn_item(const Params& P, unsigned char* smem, bool samp, int b, int c) {
;     ...
;         for (int hf = 0; hf < 2; ++hf) {
;           const bool valid = (kt * 64 + hf * 32 + l32) < nkeys;
;           for (int i = 0; i < 4; ++i) {
;             const unsigned key = mono_key(sc[i][hf]);
;             const bool eq = valid && (key == tau[i]);
;             const unsigned long long bal = __ballot(eq);
;             const unsigned mym = g ? (unsigned)(bal >> 32) : (unsigned)bal;
;             const int rank = __popc(mym & ((1u << l32) - 1u));
;             const bool tsel = eq && (seen[i] + rank < need[i]);
;             seen[i] += __popc(mym);
;             const bool sel = (valid && key > tau[i]) || tsel;
;             const unsigned long long sb = __ballot(sel);
;             if (lane == 0) {
;               maskl[(kt * 64 + 8 * wid + 2 * i) * 2 + hf] = (unsigned)sb;
;               maskl[(kt * 64 + 8 * wid + 2 * i + 1) * 2 + hf] = (unsigned)(sb >> 32);
;             }
;           }
	v_cmp_eq_u32_e64 s[8:9], v21, v94
	s_and_b64 s[2:3], vcc, s[8:9]
	v_cndmask_b32_e64 v22, 0, 1, s[2:3]
	v_cmp_ne_u32_e64 s[8:9], 0, v22
	s_nop 1
	v_lshrrev_b64 v[22:23], v76, s[8:9]
	v_and_b32_e32 v23, v22, v78
	v_bcnt_u32_b32 v23, v23, v82
	v_cmp_lt_i32_e64 s[8:9], v23, v79
	s_and_b64 s[2:3], s[2:3], s[8:9]
	v_cmp_gt_u32_e64 s[8:9], v21, v94
	s_and_b64 s[8:9], vcc, s[8:9]
	s_or_b64 s[2:3], s[8:9], s[2:3]
	v_cndmask_b32_e64 v21, 0, 1, s[2:3]
	v_cmp_ne_u32_e32 vcc, 0, v21
	s_and_saveexec_b64 s[2:3], s[6:7]
	v_mov_b32_e32 v21, s10
	v_mov_b32_e32 v23, vcc_lo
	v_mov_b32_e32 v25, vcc_hi
	ds_write2_b32 v21, v23, v25 offset0:12 offset1:14
	s_or_b64 exec, exec, s[2:3]
	v_med3_f32 v4, v4, 0, v187
	v_mul_f32_e32 v4, v52, v4
	v_med3_f32 v5, v5, 0, v187
	v_fmac_f32_e32 v4, v53, v5
	v_med3_f32 v5, v6, 0, v187
	v_fmac_f32_e32 v4, v54, v5
	v_med3_f32 v5, v7, 0, v187
	v_fmac_f32_e32 v4, v55, v5
	v_add_u32_e32 v5, 32, v80
	v_cmp_gt_u32_e32 vcc, s0, v5
	v_not_b32_e32 v5, v4
	v_or_b32_e32 v6, 0x80000000, v4
	v_cmp_gt_i32_e64 s[8:9], 0, v4
	v_bcnt_u32_b32 v20, v20, v88
	s_nop 0
	v_cndmask_b32_e64 v6, v6, v5, s[8:9]
	v_cmp_eq_u32_e64 s[8:9], v6, v97
	s_and_b64 s[2:3], vcc, s[8:9]
	v_cndmask_b32_e64 v4, 0, 1, s[2:3]
	v_cmp_ne_u32_e64 s[8:9], 0, v4
	s_nop 1
	v_lshrrev_b64 v[4:5], v76, s[8:9]
	v_and_b32_e32 v5, v4, v78
	v_bcnt_u32_b32 v5, v5, v20
	v_cmp_lt_i32_e64 s[8:9], v5, v81
	s_and_b64 s[2:3], s[2:3], s[8:9]
	v_cmp_gt_u32_e64 s[8:9], v6, v97
	s_and_b64 s[8:9], vcc, s[8:9]
	s_or_b64 s[2:3], s[8:9], s[2:3]
	v_cndmask_b32_e64 v5, 0, 1, s[2:3]
	v_cmp_ne_u32_e64 s[8:9], 0, v5
	s_and_saveexec_b64 s[2:3], s[6:7]
	v_mov_b32_e32 v5, s10
	v_mov_b32_e32 v6, s8
	v_mov_b32_e32 v7, s9
	ds_write2_b32 v5, v6, v7 offset0:1 offset1:3
	s_or_b64 exec, exec, s[2:3]
	v_med3_f32 v6, v8, 0, v187
	v_mul_f32_e32 v6, v56, v6
	v_med3_f32 v7, v9, 0, v187
	v_fmac_f32_e32 v6, v57, v7
	v_med3_f32 v7, v10, 0, v187
	v_fmac_f32_e32 v6, v58, v7
	v_med3_f32 v7, v11, 0, v187
	v_fmac_f32_e32 v6, v59, v7
	v_not_b32_e32 v7, v6
	v_or_b32_e32 v8, 0x80000000, v6
	v_cmp_gt_i32_e64 s[8:9], 0, v6
	v_bcnt_u32_b32 v5, v26, v87
	s_nop 0
	v_cndmask_b32_e64 v8, v8, v7, s[8:9]
	v_cmp_eq_u32_e64 s[8:9], v8, v96
	s_and_b64 s[2:3], vcc, s[8:9]
	v_cndmask_b32_e64 v6, 0, 1, s[2:3]
	v_cmp_ne_u32_e64 s[8:9], 0, v6
	s_nop 1
	v_lshrrev_b64 v[6:7], v76, s[8:9]
	v_and_b32_e32 v7, v6, v78
	v_bcnt_u32_b32 v7, v7, v5
	v_cmp_lt_i32_e64 s[8:9], v7, v83
	s_and_b64 s[2:3], s[2:3], s[8:9]
	v_cmp_gt_u32_e64 s[8:9], v8, v96
	s_and_b64 s[8:9], vcc, s[8:9]
	s_or_b64 s[2:3], s[8:9], s[2:3]
	v_cndmask_b32_e64 v7, 0, 1, s[2:3]
	v_cmp_ne_u32_e64 s[8:9], 0, v7
	s_and_saveexec_b64 s[2:3], s[6:7]
	v_mov_b32_e32 v7, s10
	v_mov_b32_e32 v8, s8
	v_mov_b32_e32 v9, s9
	ds_write2_b32 v7, v8, v9 offset0:5 offset1:7
	s_or_b64 exec, exec, s[2:3]
	v_med3_f32 v8, v12, 0, v187
	v_mul_f32_e32 v8, v60, v8
	v_med3_f32 v9, v13, 0, v187
	v_fmac_f32_e32 v8, v61, v9
	v_med3_f32 v9, v14, 0, v187
	v_fmac_f32_e32 v8, v62, v9
	v_med3_f32 v9, v15, 0, v187
	v_fmac_f32_e32 v8, v63, v9
	v_not_b32_e32 v9, v8
	v_or_b32_e32 v10, 0x80000000, v8
	v_cmp_gt_i32_e64 s[8:9], 0, v8
	v_bcnt_u32_b32 v7, v24, v86
	s_nop 0
	v_cndmask_b32_e64 v10, v10, v9, s[8:9]
	v_cmp_eq_u32_e64 s[8:9], v10, v95
	s_and_b64 s[2:3], vcc, s[8:9]
	v_cndmask_b32_e64 v8, 0, 1, s[2:3]
	v_cmp_ne_u32_e64 s[8:9], 0, v8
	s_nop 1
	v_lshrrev_b64 v[8:9], v76, s[8:9]
	v_and_b32_e32 v9, v8, v78
	v_bcnt_u32_b32 v9, v9, v7
	v_cmp_lt_i32_e64 s[8:9], v9, v77
	s_and_b64 s[2:3], s[2:3], s[8:9]
	v_cmp_gt_u32_e64 s[8:9], v10, v95
	s_and_b64 s[8:9], vcc, s[8:9]
	s_or_b64 s[2:3], s[8:9], s[2:3]
	v_cndmask_b32_e64 v9, 0, 1, s[2:3]
	v_cmp_ne_u32_e64 s[8:9], 0, v9
	s_and_saveexec_b64 s[2:3], s[6:7]
	v_mov_b32_e32 v9, s10
	v_mov_b32_e32 v10, s8
	v_mov_b32_e32 v11, s9
	ds_write2_b32 v9, v10, v11 offset0:9 offset1:11
	s_or_b64 exec, exec, s[2:3]
	v_med3_f32 v10, v16, 0, v187
	v_mul_f32_e32 v10, v64, v10
	v_med3_f32 v11, v17, 0, v187
	v_fmac_f32_e32 v10, v65, v11
	v_med3_f32 v11, v18, 0, v187
	v_fmac_f32_e32 v10, v66, v11
	v_med3_f32 v11, v19, 0, v187
	v_fmac_f32_e32 v10, v67, v11
	v_not_b32_e32 v11, v10
	v_or_b32_e32 v12, 0x80000000, v10
	v_cmp_gt_i32_e64 s[8:9], 0, v10
	v_bcnt_u32_b32 v9, v22, v82
	s_nop 0
	v_cndmask_b32_e64 v12, v12, v11, s[8:9]
	v_cmp_eq_u32_e64 s[8:9], v12, v94
	s_and_b64 s[2:3], vcc, s[8:9]
	v_cndmask_b32_e64 v10, 0, 1, s[2:3]
	v_cmp_ne_u32_e64 s[8:9], 0, v10
	s_nop 1
	v_lshrrev_b64 v[10:11], v76, s[8:9]
	v_and_b32_e32 v11, v10, v78
	v_bcnt_u32_b32 v11, v11, v9
	v_cmp_lt_i32_e64 s[8:9], v11, v79
	s_and_b64 s[2:3], s[2:3], s[8:9]
	v_cmp_gt_u32_e64 s[8:9], v12, v94
	s_and_b64 s[8:9], vcc, s[8:9]
	s_or_b64 s[2:3], s[8:9], s[2:3]
	v_cndmask_b32_e64 v11, 0, 1, s[2:3]
	v_cmp_ne_u32_e32 vcc, 0, v11
	s_and_saveexec_b64 s[2:3], s[6:7]
	s_cbranch_execz .LBB0_598
	v_mov_b32_e32 v11, s10
	v_mov_b32_e32 v12, vcc_lo
	v_mov_b32_e32 v13, vcc_hi
	ds_write2_b32 v11, v12, v13 offset0:13 offset1:15
	s_branch .LBB0_598

; #define IDX_PIPE_BEGIN() bf16x8 nk0[4], nk1[4]; IDX_LOAD(0, nk0, nk1);
; DI void attn_item(const Params& P, unsigned char* smem, bool samp, int b, int c) {
;     ...
;     if (!wave_ovf) {
;       int seen[4] = {0, 0, 0, 0};
;       int cbase[4] = {0, 0, 0, 0};
;       const unsigned ltmask = (1u << l32) - 1u;
;       const bool anyzb = __ballot(bst[0] == 255 || bst[1] == 255 || bst[2] == 255 || bst[3] == 255) != 0ull;
;       IDX_PIPE_BEGIN();
; #pragma unroll 1
;       for (int kt = 0; kt < ntiles; ++kt) {
;     ...
;             mv = (lane == (2 * i) * 2 + hf) ? (unsigned)sb : mv;
;             mv = (lane == (2 * i + 1) * 2 + hf) ? (unsigned)(sb >> 32) : mv;
.LBB0_616:
	global_load_dwordx4 v[100:103], v[100:101], off
	s_nop 0
	global_load_dwordx4 v[96:99], v[104:105], off
	s_nop 0
	global_load_dwordx4 v[104:107], v[114:115], off offset:3072
	global_load_dwordx4 v[92:95], v[114:115], off offset:2048
	global_load_dwordx4 v[84:87], v[118:119], off
	global_load_dwordx4 v[80:83], v[116:117], off
	global_load_dwordx4 v[88:91], v[114:115], off offset:1024
	global_load_dwordx4 v[76:79], v[114:115], off
	v_readlane_b32 s2, v250, 14
	s_mov_b32 s60, s2
	s_mulk_i32 s2, 0x1700
	s_movk_i32 s16, 0xff
	v_readlane_b32 s3, v250, 15
	v_writelane_b32 v250, s2, 61
	s_add_i32 s2, s2, 0
	v_cmp_eq_u32_e64 s[8:9], s16, v122
	v_writelane_b32 v250, s2, 62
	s_add_i32 s20, s2, 0x18540
	s_or_b64 s[2:3], s[18:19], s[8:9]
	v_cmp_eq_u32_e64 s[12:13], s16, v124
	v_cmp_ne_u32_e64 s[6:7], s16, v122
	v_cmp_ne_u32_e64 s[10:11], s16, v124
	s_or_b64 s[2:3], s[2:3], s[12:13]
	v_cmp_ne_u32_e64 s[14:15], s16, v126
	v_cmp_eq_u32_e64 s[16:17], s16, v126
	s_or_b64 s[2:3], s[2:3], s[16:17]
	v_cndmask_b32_e64 v5, 0, 1, s[2:3]
	v_cmp_ne_u32_e32 vcc, 0, v5
	s_cmp_lg_u64 vcc, 0
	s_cselect_b64 s[88:89], -1, 0
	s_lshl_b32 s60, s60, 6
	s_xor_b64 s[2:3], s[18:19], -1
	s_add_i32 s60, s60, 0
	s_lshl_b32 s59, s59, 1
	s_add_u32 s59, s86, s59
	v_add_u32_e32 v118, s60, v1
	s_addc_u32 s60, s87, 0
	v_lshlrev_b32_e64 v4, v195, -1
	s_add_u32 s58, s59, s58
	v_not_b32_e32 v109, v4
	v_mov_b32_e32 v4, s20
	s_movk_i32 s24, 0x2e0
	s_addc_u32 s59, s60, 0
	v_mad_u32_u24 v111, v178, s24, v4
	v_lshl_add_u64 v[4:5], s[58:59], 0, v[2:3]
	s_mov_b64 s[58:59], 0x3c00
	s_mov_b32 s21, 0
	v_and_b32_e32 v114, 32, v112
	v_cmp_eq_u32_e64 s[24:25], 0, v110
	v_cmp_eq_u32_e64 s[26:27], 2, v110
	v_cmp_eq_u32_e64 s[28:29], 4, v110
	v_cmp_eq_u32_e64 s[30:31], 6, v110
	v_cmp_eq_u32_e64 s[34:35], 8, v110
	v_cmp_eq_u32_e64 s[36:37], 10, v110
	v_cmp_eq_u32_e64 s[38:39], 12, v110
	v_cmp_eq_u32_e64 s[40:41], 14, v110
	v_cmp_eq_u32_e64 s[42:43], 1, v110
	v_cmp_eq_u32_e64 s[44:45], 3, v110
	v_cmp_eq_u32_e64 s[46:47], 5, v110
	v_cmp_eq_u32_e64 s[48:49], 7, v110
	v_cmp_eq_u32_e64 s[50:51], 9, v110
	v_cmp_eq_u32_e64 s[52:53], 11, v110
	v_cmp_eq_u32_e64 s[54:55], 15, v110
	v_cmp_eq_u32_e64 s[56:57], 13, v110
	v_lshl_add_u64 v[116:117], v[4:5], 0, s[58:59]
	v_mov_b32_e32 v1, 0
	v_mov_b32_e32 v2, 0
	v_mov_b32_e32 v113, 0
	v_mov_b32_e32 v115, 0
	v_mov_b32_e32 v119, 0
	v_mov_b32_e32 v120, 0
	v_mov_b32_e32 v122, 0
	v_mov_b32_e32 v124, 0
	s_mov_b32 s96, 0
	s_branch .LBB0_618

; DI void attn_item(const Params& P, unsigned char* smem, bool samp, int b, int c) {
;     ...
;       for (int kt = 0; kt < ntiles; ++kt) {
;         float sc[4][2];
;         IDX_PIPE_STEP(kt, sc);
.LBB0_618:
	s_waitcnt vmcnt(0) lgkmcnt(0)
	v_mfma_f32_32x32x16_bf16 v[20:35], v[44:47], v[76:79], 0
	s_add_i32 s96, s96, 1
	s_cmp_ge_u32 s96, s95
	v_mfma_f32_32x32x16_bf16 v[4:19], v[44:47], v[80:83], 0
	v_mfma_f32_32x32x16_bf16 v[20:35], v[36:39], v[88:91], v[20:35]
	v_mfma_f32_32x32x16_bf16 v[4:19], v[36:39], v[84:87], v[4:19]
	v_mfma_f32_32x32x16_bf16 v[20:35], v[40:43], v[92:95], v[20:35]
	v_mfma_f32_32x32x16_bf16 v[4:19], v[40:43], v[96:99], v[4:19]
	v_mfma_f32_32x32x16_bf16 v[20:35], v[48:51], v[104:107], v[20:35]
	v_mfma_f32_32x32x16_bf16 v[4:19], v[48:51], v[100:103], v[4:19]
	s_cbranch_scc1 .LBB0_620
	v_add_co_u32_e32 v76, vcc, 0xffffe400, v116
	s_nop 1
	v_addc_co_u32_e32 v77, vcc, -1, v117, vcc
	v_add_co_u32_e32 v80, vcc, 0xfffff400, v116
	s_nop 1
	v_addc_co_u32_e32 v81, vcc, -1, v117, vcc
	v_add_co_u32_e32 v84, vcc, 0xffffe800, v116
	global_load_dwordx4 v[76:79], v[76:77], off
	s_nop 0
	global_load_dwordx4 v[80:83], v[80:81], off
	v_addc_co_u32_e32 v85, vcc, -1, v117, vcc
	v_add_co_u32_e32 v86, vcc, 0xfffff800, v116
	s_nop 1
	v_addc_co_u32_e32 v87, vcc, -1, v117, vcc
	v_add_co_u32_e32 v92, vcc, 0xffffec00, v116
	global_load_dwordx4 v[88:91], v[84:85], off
	s_nop 0
	global_load_dwordx4 v[84:87], v[86:87], off
	v_addc_co_u32_e32 v93, vcc, -1, v117, vcc
	v_add_co_u32_e32 v96, vcc, 0xfffffc00, v116
	s_nop 1
	v_addc_co_u32_e32 v97, vcc, -1, v117, vcc
	v_add_co_u32_e32 v100, vcc, 0xfffff000, v116
	global_load_dwordx4 v[92:95], v[92:93], off
	s_nop 0
	global_load_dwordx4 v[96:99], v[96:97], off
	v_addc_co_u32_e32 v101, vcc, -1, v117, vcc
	global_load_dwordx4 v[104:107], v[100:101], off
	s_nop 0
	global_load_dwordx4 v[100:103], v[116:117], off

; DI void attn_item(const Params& P, unsigned char* smem, bool samp, int b, int c) {
;     ...
;   const int h = wid;
;   bf16x8 qf[2][4];
;   for (int qh = 0; qh < 2; ++qh) {
;     int ql = qh * 32 + l32;
;     if (ql > nq - 1) ql = nq - 1;
;     const u16* p = (const u16*)(ws + R_QA) + (qrow0 + ql) * 512 + h * 64 + g * 8;
;     for (int ks = 0; ks < 4; ++ks) qf[qh][ks] = ld16(p + ks * 16);
;   }
;   f32x16 oacc[2][2];
;   for (int a = 0; a < 2; ++a) for (int q = 0; q < 2; ++q) for (int r = 0; r < 16; ++r) oacc[a][q][r] = 0.f;
;   float mrun[2] = {-1e30f, -1e30f}, lrun[2] = {0.f, 0.f};
;   const u16* kbase = Kb + (long)h * 2048 + lane * 8;
;   const u16* vbase = VTb + (long)h * 2048 + lane * 8;
;   bf16x8 kfN[4], vfN[2][2];
;   for (int ks = 0; ks < 4; ++ks) kfN[ks] = ld16(kbase + ks * 512);
;   for (int dh = 0; dh < 2; ++dh)
;     for (int s = 0; s < 2; ++s) vfN[dh][s] = ld16(vbase + (s * 2 + dh) * 512);
;   const int nhalf = ntiles * 2;
.LBB0_696:
	s_or_b64 exec, exec, s[2:3]
	v_readlane_b32 s0, v250, 2
	v_readlane_b32 s8, v250, 55
	v_readlane_b32 s1, v250, 3
	v_readlane_b32 s9, v250, 56
	s_load_dwordx2 s[96:97], s[0:1], 0xb8
	s_and_b64 s[0:1], s[8:9], exec
	v_readlane_b32 s0, v250, 54
	s_cselect_b32 s11, 0x1000, s0
	v_readlane_b32 s0, v250, 51
	v_readlane_b32 s1, v250, 42
	s_cselect_b32 s0, s1, s0
	s_mov_b32 s1, 0x2274a900
	s_cselect_b32 s12, s1, 0x1e74a900
	s_add_u32 s1, s86, s12
	s_addc_u32 s2, s87, 0
	s_lshl_b32 s90, s0, 1
	s_add_u32 s6, s1, s90
	s_addc_u32 s7, s2, 0
	s_and_b64 s[0:1], s[8:9], exec
	s_mov_b32 s0, 0xc080000
	s_cselect_b32 s13, s0, 0x8080000
	v_readlane_b32 s16, v250, 23
	v_readlane_b32 s17, v250, 24
	s_add_u32 s0, s16, s13
	s_addc_u32 s1, s17, 0
	s_add_u32 s8, s0, s90
	v_readlane_b32 s0, v250, 9
	s_addc_u32 s9, s1, 0
	s_add_i32 s2, s0, -1
	v_readlane_b32 s0, v250, 53
	s_andn2_b32 s0, s0, 63
	s_ashr_i32 s1, s0, 31
	s_lshl_b64 s[0:1], s[0:1], 1
	s_add_u32 s0, s86, s0
	s_addc_u32 s1, s87, s1
	v_readlane_b32 s14, v250, 57
	s_add_u32 s0, s0, 0x258a900
	v_min_u32_e32 v1, s2, v195
	s_mov_b32 s18, s14
	s_addc_u32 s1, s1, 0
	v_mov_b32_e32 v109, v3
	v_or_b32_e32 v1, s18, v1
	v_lshl_add_u64 v[4:5], s[0:1], 0, v[108:109]
	v_lshlrev_b32_e32 v2, 10, v1
	v_or_b32_e32 v1, 32, v195
	v_readlane_b32 s15, v250, 58
	v_lshl_add_u64 v[6:7], v[4:5], 0, v[2:3]
	v_min_u32_e32 v2, s2, v1
	v_readlane_b32 s2, v250, 14
	v_readlane_b32 s3, v250, 15
	s_mov_b32 s14, s2
	s_ashr_i32 s15, s2, 31
	s_lshl_b64 s[2:3], s[14:15], 12
	v_add_lshl_u32 v2, v2, s18, 10
	s_add_u32 s6, s6, s2
	v_lshl_add_u64 v[4:5], v[4:5], 0, v[2:3]
	s_addc_u32 s7, s7, s3
	v_lshlrev_b32_e32 v2, 4, v110
	s_waitcnt lgkmcnt(0)
	s_barrier
	global_load_dwordx4 v[114:117], v[6:7], off
	global_load_dwordx4 v[118:121], v[6:7], off offset:32
	global_load_dwordx4 v[122:125], v[6:7], off offset:64
	global_load_dwordx4 v[126:129], v[6:7], off offset:96
	global_load_dwordx4 v[130:133], v[4:5], off
	global_load_dwordx4 v[134:137], v[4:5], off offset:32
	global_load_dwordx4 v[138:141], v[4:5], off offset:64
	global_load_dwordx4 v[142:145], v[4:5], off offset:96
	v_lshl_add_u64 v[4:5], s[6:7], 0, v[2:3]
	s_add_u32 s6, s8, s2
	s_addc_u32 s7, s9, s3
	v_lshl_add_u64 v[6:7], s[6:7], 0, v[2:3]
	s_waitcnt vmcnt(0)
	global_load_dwordx4 v[146:149], v[6:7], off offset:3072
	global_load_dwordx4 v[158:161], v[6:7], off offset:2048
	global_load_dwordx4 v[154:157], v[6:7], off offset:1024
	global_load_dwordx4 v[150:153], v[6:7], off
	global_load_dwordx4 v[162:165], v[4:5], off offset:3072
	global_load_dwordx4 v[166:169], v[4:5], off offset:2048
	global_load_dwordx4 v[170:173], v[4:5], off offset:1024
	global_load_dwordx4 v[174:177], v[4:5], off
	s_lshl_b32 s9, s95, 1
	s_add_i32 s10, s11, 0xfffffb43
	s_add_u32 s6, s13, s2
	s_addc_u32 s7, 0, s3
	s_add_u32 s6, s16, s6
	s_addc_u32 s7, s17, s7
	v_and_b32_e32 v5, 64, v190
	s_add_u32 s2, s12, s2
	v_xor_b32_e32 v4, 32, v190
	v_add_u32_e32 v5, 64, v5
	s_addc_u32 s3, 0, s3
	v_cmp_lt_i32_e32 vcc, v4, v5
	s_add_u32 s2, s86, s2
	s_mulk_i32 s14, 0x1500
	v_cndmask_b32_e32 v4, v190, v4, vcc
	s_addc_u32 s3, s87, s3
	v_lshlrev_b32_e32 v198, 2, v178
	v_lshlrev_b32_e32 v196, 2, v4
	v_lshl_add_u64 v[178:179], s[6:7], 0, v[2:3]
	v_lshl_add_u64 v[180:181], s[2:3], 0, v[2:3]
	v_or_b32_e32 v2, s14, v108
	v_add_lshl_u32 v4, s11, v195, 2
	v_sub_u32_e32 v2, v2, v4
	v_readlane_b32 s2, v250, 26
	v_mov_b32_e32 v16, v3
	v_mov_b32_e32 v17, v3
	v_add_u32_e32 v199, s2, v2
	v_mov_b32_e32 v2, v3
	v_mov_b32_e32 v4, v3
	v_mov_b32_e32 v5, v3
	v_mov_b32_e32 v6, v3
	v_mov_b32_e32 v7, v3
	v_mov_b32_e32 v8, v3
	v_mov_b32_e32 v9, v3
	v_mov_b32_e32 v10, v3
	v_mov_b32_e32 v11, v3
	v_mov_b32_e32 v12, v3
	v_mov_b32_e32 v13, v3
	v_mov_b32_e32 v14, v3
	v_mov_b32_e32 v15, v3
	v_mov_b64_e32 v[32:33], v[16:17]
	v_mov_b64_e32 v[64:65], v[16:17]
	v_mov_b64_e32 v[48:49], v[16:17]
	s_waitcnt vmcnt(0)
	v_mov_b64_e32 v[80:81], v[16:17]
	v_readlane_b32 s28, v250, 33
	s_mov_b32 s8, 0
	s_mov_b32 s16, s18
	v_lshlrev_b32_e32 v200, 3, v195
	v_mov_b32_e32 v197, 0
	v_mov_b32_e32 v201, 0xf149f2ca
	v_mov_b64_e32 v[30:31], v[14:15]
	v_mov_b64_e32 v[28:29], v[12:13]
	v_mov_b64_e32 v[26:27], v[10:11]
	v_mov_b64_e32 v[24:25], v[8:9]
	v_mov_b64_e32 v[22:23], v[6:7]
	v_mov_b64_e32 v[20:21], v[4:5]
	v_mov_b64_e32 v[18:19], v[2:3]
	v_mov_b64_e32 v[62:63], v[14:15]
	v_mov_b64_e32 v[60:61], v[12:13]
	v_mov_b64_e32 v[58:59], v[10:11]
	v_mov_b64_e32 v[56:57], v[8:9]
	v_mov_b64_e32 v[54:55], v[6:7]
	v_mov_b64_e32 v[52:53], v[4:5]
	v_mov_b64_e32 v[50:51], v[2:3]
	v_mov_b64_e32 v[46:47], v[14:15]
	v_mov_b64_e32 v[44:45], v[12:13]
	v_mov_b64_e32 v[42:43], v[10:11]
	v_mov_b64_e32 v[40:41], v[8:9]
	v_mov_b64_e32 v[38:39], v[6:7]
	v_mov_b64_e32 v[36:37], v[4:5]
	v_mov_b64_e32 v[34:35], v[2:3]
	v_mov_b64_e32 v[78:79], v[14:15]
	v_mov_b64_e32 v[76:77], v[12:13]
	v_mov_b64_e32 v[74:75], v[10:11]
	v_mov_b64_e32 v[72:73], v[8:9]
	v_mov_b64_e32 v[70:71], v[6:7]
	v_mov_b64_e32 v[68:69], v[4:5]
	v_mov_b64_e32 v[66:67], v[2:3]
	v_mov_b32_e32 v2, 0xf149f2ca
	v_mov_b32_e32 v4, 0
	s_mov_b32 s2, 0
	v_readlane_b32 s29, v250, 34

; DI uint2 pack4(float a, float b, float c, float d) { return make_uint2(pack2(a, b), pack2(c, d)); }
; DI void attn_item(const Params& P, unsigned char* smem, bool samp, int b, int c) {
;     ...
;   for (int qh = 0; qh < 2; ++qh) {
;     float lt = lrun[qh] + __shfl_xor(lrun[qh], 32);
;     const float inv = 1.0f / lt;
;     const int ql = qh * 32 + l32;
;     if (ql < nq) {
;       u16* ap = (u16*)(ws + R_QA) + (qrow0 + ql) * 512 + h * 64;
;       for (int dh = 0; dh < 2; ++dh)
;         for (int i = 0; i < 4; ++i) {
;           const int d = dh * 32 + 4 * g + 8 * i;
;           *(uint2*)(ap + d) = pack4(oacc[dh][qh][4 * i] * inv, oacc[dh][qh][4 * i + 1] * inv, oacc[dh][qh][4 * i + 2] * inv,
;                                     oacc[dh][qh][4 * i + 3] * inv);
;         }
;     }
;   }
.LBB0_711:
	s_waitcnt vmcnt(0)
	ds_bpermute_b32 v5, v196, v4
	v_or_b32_e32 v2, s16, v195
	v_lshlrev_b32_e32 v2, 10, v2
	s_waitcnt lgkmcnt(0)
	v_add_f32_e32 v6, v4, v5
	v_div_scale_f32 v7, s[2:3], v6, v6, 1.0
	v_rcp_f32_e32 v8, v7
	v_lshl_add_u64 v[4:5], s[0:1], 0, v[2:3]
	v_div_scale_f32 v2, vcc, 1.0, v6, 1.0
	v_fma_f32 v9, -v7, v8, 1.0
	v_fmac_f32_e32 v8, v9, v8
	v_mul_f32_e32 v9, v2, v8
	v_fma_f32 v10, -v7, v9, v2
	v_fmac_f32_e32 v9, v10, v8
	v_fma_f32 v2, -v7, v9, v2
	v_div_fmas_f32 v2, v2, v8, v9
	v_div_fixup_f32 v6, v2, v6, 1.0
	v_pk_mul_f32 v[8:9], v[66:67], v[6:7] op_sel_hi:[1,0]
	v_pk_mul_f32 v[10:11], v[68:69], v[6:7] op_sel_hi:[1,0]
	v_lshlrev_b32_e32 v2, 1, v198
	v_cvt_pk_bf16_f32 v8, v8, v9
	v_cvt_pk_bf16_f32 v9, v10, v11
	v_lshl_add_u64 v[10:11], v[4:5], 0, v[2:3]
	global_store_dwordx2 v[10:11], v[8:9], off
	v_pk_mul_f32 v[4:5], v[70:71], v[6:7] op_sel_hi:[1,0]
	v_pk_mul_f32 v[8:9], v[72:73], v[6:7] op_sel_hi:[1,0]
	v_cvt_pk_bf16_f32 v4, v4, v5
	v_cvt_pk_bf16_f32 v5, v8, v9
	global_store_dwordx2 v[10:11], v[4:5], off offset:16
	v_pk_mul_f32 v[4:5], v[74:75], v[6:7] op_sel_hi:[1,0]
	v_pk_mul_f32 v[8:9], v[76:77], v[6:7] op_sel_hi:[1,0]
	v_cvt_pk_bf16_f32 v4, v4, v5
	v_cvt_pk_bf16_f32 v5, v8, v9
	global_store_dwordx2 v[10:11], v[4:5], off offset:32
	v_pk_mul_f32 v[4:5], v[78:79], v[6:7] op_sel_hi:[1,0]
	v_pk_mul_f32 v[8:9], v[80:81], v[6:7] op_sel_hi:[1,0]
	v_cvt_pk_bf16_f32 v4, v4, v5
	v_cvt_pk_bf16_f32 v5, v8, v9
	global_store_dwordx2 v[10:11], v[4:5], off offset:48
	v_pk_mul_f32 v[4:5], v[50:51], v[6:7] op_sel_hi:[1,0]
	v_pk_mul_f32 v[8:9], v[52:53], v[6:7] op_sel_hi:[1,0]
	v_cvt_pk_bf16_f32 v4, v4, v5
	v_cvt_pk_bf16_f32 v5, v8, v9
	global_store_dwordx2 v[10:11], v[4:5], off offset:64
	v_pk_mul_f32 v[4:5], v[54:55], v[6:7] op_sel_hi:[1,0]
	v_pk_mul_f32 v[8:9], v[56:57], v[6:7] op_sel_hi:[1,0]
	v_cvt_pk_bf16_f32 v4, v4, v5
	v_cvt_pk_bf16_f32 v5, v8, v9
	global_store_dwordx2 v[10:11], v[4:5], off offset:80
	v_pk_mul_f32 v[4:5], v[58:59], v[6:7] op_sel_hi:[1,0]
	v_pk_mul_f32 v[8:9], v[60:61], v[6:7] op_sel_hi:[1,0]
	v_cvt_pk_bf16_f32 v4, v4, v5
	v_cvt_pk_bf16_f32 v5, v8, v9
	global_store_dwordx2 v[10:11], v[4:5], off offset:96
	ds_bpermute_b32 v4, v196, v197
	v_pk_mul_f32 v[8:9], v[62:63], v[6:7] op_sel_hi:[1,0]
	v_pk_mul_f32 v[6:7], v[64:65], v[6:7] op_sel_hi:[1,0]
	v_readlane_b32 s2, v250, 9
	v_cvt_pk_bf16_f32 v8, v8, v9
	v_cvt_pk_bf16_f32 v9, v6, v7
	v_cmp_gt_u32_e32 vcc, s2, v1
	global_store_dwordx2 v[10:11], v[8:9], off offset:112
	s_and_saveexec_b64 s[2:3], vcc
	s_xor_b64 s[2:3], exec, s[2:3]
	s_cbranch_execz .LBB0_713
	s_waitcnt lgkmcnt(0)
	v_add_f32_e32 v4, v197, v4
	v_div_scale_f32 v5, s[6:7], v4, v4, 1.0
	v_rcp_f32_e32 v6, v5
	v_div_scale_f32 v7, vcc, 1.0, v4, 1.0
	v_fma_f32 v8, -v5, v6, 1.0
	v_fmac_f32_e32 v6, v8, v6
	v_mul_f32_e32 v8, v7, v6
	v_fma_f32 v9, -v5, v8, v7
	v_fmac_f32_e32 v8, v9, v6
	v_fma_f32 v5, -v5, v8, v7
	v_div_fmas_f32 v5, v5, v6, v8
	v_div_fixup_f32 v4, v5, v4, 1.0
	v_add_lshl_u32 v6, v1, s16, 10
	v_mov_b32_e32 v7, v3
	v_lshl_add_u64 v[6:7], s[0:1], 0, v[6:7]
	v_pk_mul_f32 v[8:9], v[34:35], v[4:5] op_sel_hi:[1,0]
	v_pk_mul_f32 v[10:11], v[36:37], v[4:5] op_sel_hi:[1,0]
	v_cvt_pk_bf16_f32 v8, v8, v9
	v_cvt_pk_bf16_f32 v9, v10, v11
	v_lshl_add_u64 v[6:7], v[6:7], 0, v[2:3]
	global_store_dwordx2 v[6:7], v[8:9], off
	v_pk_mul_f32 v[8:9], v[38:39], v[4:5] op_sel_hi:[1,0]
	v_pk_mul_f32 v[10:11], v[40:41], v[4:5] op_sel_hi:[1,0]
	v_cvt_pk_bf16_f32 v8, v8, v9
	v_cvt_pk_bf16_f32 v9, v10, v11
	global_store_dwordx2 v[6:7], v[8:9], off offset:16
	v_pk_mul_f32 v[8:9], v[42:43], v[4:5] op_sel_hi:[1,0]
	v_pk_mul_f32 v[10:11], v[44:45], v[4:5] op_sel_hi:[1,0]
	v_cvt_pk_bf16_f32 v8, v8, v9
	v_cvt_pk_bf16_f32 v9, v10, v11
	global_store_dwordx2 v[6:7], v[8:9], off offset:32
	v_pk_mul_f32 v[8:9], v[46:47], v[4:5] op_sel_hi:[1,0]
	v_pk_mul_f32 v[10:11], v[48:49], v[4:5] op_sel_hi:[1,0]
	v_cvt_pk_bf16_f32 v8, v8, v9
	v_cvt_pk_bf16_f32 v9, v10, v11
	global_store_dwordx2 v[6:7], v[8:9], off offset:48
	v_pk_mul_f32 v[8:9], v[18:19], v[4:5] op_sel_hi:[1,0]
	v_pk_mul_f32 v[10:11], v[20:21], v[4:5] op_sel_hi:[1,0]
	v_cvt_pk_bf16_f32 v8, v8, v9
	v_cvt_pk_bf16_f32 v9, v10, v11
	global_store_dwordx2 v[6:7], v[8:9], off offset:64
	v_pk_mul_f32 v[8:9], v[22:23], v[4:5] op_sel_hi:[1,0]
	v_pk_mul_f32 v[10:11], v[24:25], v[4:5] op_sel_hi:[1,0]
	v_cvt_pk_bf16_f32 v8, v8, v9
	v_cvt_pk_bf16_f32 v9, v10, v11
	global_store_dwordx2 v[6:7], v[8:9], off offset:80
	v_pk_mul_f32 v[8:9], v[26:27], v[4:5] op_sel_hi:[1,0]
	v_pk_mul_f32 v[10:11], v[28:29], v[4:5] op_sel_hi:[1,0]
	v_cvt_pk_bf16_f32 v8, v8, v9
	v_cvt_pk_bf16_f32 v9, v10, v11
	global_store_dwordx2 v[6:7], v[8:9], off offset:96
	v_pk_mul_f32 v[8:9], v[30:31], v[4:5] op_sel_hi:[1,0]
	v_pk_mul_f32 v[4:5], v[32:33], v[4:5] op_sel_hi:[1,0]
	v_cvt_pk_bf16_f32 v8, v8, v9
	v_cvt_pk_bf16_f32 v9, v4, v5
	global_store_dwordx2 v[6:7], v[8:9], off offset:112

; DI uint2 pack4(float a, float b, float c, float d) { return make_uint2(pack2(a, b), pack2(c, d)); }
; DI float log_gamma_h(int h) { return log1pf(-exp2f(-5.0f - (float)h)); }
; DI int crow(int r, int g) { return (r & 3) + 8 * (r >> 2) + 4 * g; }
; DI void ret_item(const Params& P, unsigned char* smem, bool samp, int b, int h) {
;   const int tid_ = launder_tid();
;   const int wid = __builtin_amdgcn_readfirstlane(tid_ >> 6), lane = tid_ & 63, l32 = lane & 31, g = lane >> 5;
;   unsigned char* ws = P.ws;
;   asm volatile("" : "+s"(ws));
;   const int C = samp ? 32 : 64, nchunks = samp ? 1 : 128;
;   const long row0 = samp ? (NTP + b * 32) : (long)b * 8192;
;   const u16* qb = (const u16*)(ws + R_QR) + row0 * 512 + h * 64;
;   const u16* kb = (const u16*)(ws + R_KR) + row0 * 512 + h * 64;
;   const long ldt = samp ? 32 : 8192;
;   const u16* krt = samp ? ((const u16*)(ws + R_SKRT) + (long)(b * 8 + h) * 64 * 32) : ((const u16*)(ws + R_KRT) + (long)(b * 8 + h) * 64 * 8192);
;   const u16* vrt = samp ? ((const u16*)(ws + R_SVRT) + (long)(b * 8 + h) * 128 * 32) : ((const u16*)(ws + R_VRT) + (long)(b * 8 + h) * 128 * 8192);
;   u16* grp = (u16*)(ws + R_GR) + row0 * 1024 + h * 128;
;   u16* sbuf = (u16*)(smem + L_SBUF);
;   float2* stat = (float2*)(smem + L_STAT);
;   const int nh = wid >> 2, eb = wid & 3;
;   const int dh = nh;
;   const float lg = log_gamma_h(h);
;   const float gC = expf(lg * (float)C), ginvC = expf(-lg * (float)C);
;   f32x16 S;
;   for (int r = 0; r < 16; ++r)
;     S[r] = samp ? P.state[((long)(b * 8 + h) * 64 + dh * 32 + crow(r, g)) * 128 + eb * 32 + l32] : 0.f;
;   int cur = 0;
;   __syncthreads();
;   for (int i = 0; i < 4; ++i) {
;     const int d0 = dh * 32 + 4 * g + 8 * i;
;     *(uint2*)(sbuf + (eb * 32 + l32) * SLD + d0) = pack4(S[4 * i], S[4 * i + 1], S[4 * i + 2], S[4 * i + 3]);
;   }
;   __syncthreads();
.LBB0_714:
	s_and_b64 vcc, exec, s[0:1]
	s_cbranch_vccz .LBB0_736
	s_add_i32 s20, s94, 0xffffff77
	v_cvt_f32_u32_e32 v1, s20
	v_readlane_b32 s2, v250, 10
	s_add_i32 s90, s20, s2
	s_mov_b32 s8, 0xc2fc0000
	v_sub_f32_e32 v1, 0xc0a00000, v1
	v_mov_b32_e32 v20, v182
	s_mov_b64 s[0:1], s[38:39]
	s_lshl_b64 s[2:3], s[90:91], 12
	v_cmp_gt_f32_e32 vcc, s8, v1
	s_add_u32 s2, s0, s2
	s_addc_u32 s3, s1, s3
	v_cndmask_b32_e32 v2, 0, v191, vcc
	s_lshl_b64 s[6:7], s[90:91], 13
	v_add_f32_e32 v1, v1, v2
	v_readfirstlane_b32 s10, v20
	s_add_u32 s6, s0, s6
	v_exp_f32_e32 v1, v1
	s_addc_u32 s7, s1, s7
	s_ashr_i32 s23, s10, 8
	s_and_b64 s[8:9], vcc, exec
	s_cselect_b32 s8, 0xffffffc0, 0
	s_lshl_b32 s18, s23, 5
	v_ldexp_f32 v18, v1, s8
	s_lshl_b64 s[8:9], s[90:91], 6
	s_ashr_i32 s24, s18, 31
	s_add_u32 s11, s8, s18
	v_sub_f32_e32 v1, 1.0, v18
	s_addc_u32 s12, s9, s24
	s_lshr_b32 s8, s10, 1
	v_add_f32_e32 v2, -1.0, v1
	s_and_b32 s21, s8, 0x60
	v_bfe_u32 v109, v20, 5, 1
	s_waitcnt lgkmcnt(0)
	v_sub_f32_e32 v4, v2, v1
	s_lshl_b32 s19, s21, 2
	v_and_b32_e32 v108, 31, v20
	v_add_f32_e32 v4, 1.0, v4
	v_sub_f32_e64 v2, -v18, v2
	v_lshlrev_b32_e32 v106, 2, v109
	s_add_u32 s8, s36, s19
	v_add_f32_e32 v21, v2, v4
	s_addc_u32 s9, s37, 0
	v_lshlrev_b32_e32 v2, 2, v108
	v_or_b32_e32 v6, s11, v106
	v_mov_b32_e32 v7, s12
	v_lshl_add_u64 v[4:5], s[8:9], 0, v[2:3]
	v_lshlrev_b64 v[8:9], 9, v[6:7]
	v_or_b32_e32 v10, 1, v6
	v_mov_b32_e32 v11, s12
	v_or_b32_e32 v12, 2, v6
	v_mov_b32_e32 v13, s12
	v_or_b32_e32 v14, 3, v6
	v_mov_b32_e32 v15, s12
	v_or_b32_e32 v16, 8, v6
	v_mov_b32_e32 v17, s12
	v_or_b32_e32 v22, 9, v6
	v_mov_b32_e32 v23, s12
	v_or_b32_e32 v24, 10, v6
	v_mov_b32_e32 v25, s12
	v_or_b32_e32 v26, 11, v6
	v_mov_b32_e32 v27, s12
	v_lshl_add_u64 v[8:9], v[4:5], 0, v[8:9]
	v_lshlrev_b64 v[10:11], 9, v[10:11]
	v_lshlrev_b64 v[12:13], 9, v[12:13]
	v_lshlrev_b64 v[14:15], 9, v[14:15]
	v_lshlrev_b64 v[16:17], 9, v[16:17]
	v_lshlrev_b64 v[22:23], 9, v[22:23]
	v_lshlrev_b64 v[24:25], 9, v[24:25]
	v_lshlrev_b64 v[26:27], 9, v[26:27]
	v_lshl_add_u64 v[10:11], v[4:5], 0, v[10:11]
	v_lshl_add_u64 v[12:13], v[4:5], 0, v[12:13]
	v_lshl_add_u64 v[14:15], v[4:5], 0, v[14:15]
	v_lshl_add_u64 v[16:17], v[4:5], 0, v[16:17]
	v_lshl_add_u64 v[22:23], v[4:5], 0, v[22:23]
	v_lshl_add_u64 v[24:25], v[4:5], 0, v[24:25]
	v_lshl_add_u64 v[26:27], v[4:5], 0, v[26:27]
	global_load_dword v68, v[8:9], off
	global_load_dword v69, v[10:11], off
	global_load_dword v70, v[12:13], off
	global_load_dword v71, v[14:15], off
	global_load_dword v72, v[16:17], off
	global_load_dword v73, v[22:23], off
	global_load_dword v74, v[24:25], off
	global_load_dword v75, v[26:27], off
	v_or_b32_e32 v8, 16, v6
	v_mov_b32_e32 v9, s12
	v_lshlrev_b64 v[8:9], 9, v[8:9]
	v_or_b32_e32 v10, 17, v6
	v_mov_b32_e32 v11, s12
	v_or_b32_e32 v12, 18, v6
	v_mov_b32_e32 v13, s12
	v_or_b32_e32 v14, 19, v6
	v_mov_b32_e32 v15, s12
	v_or_b32_e32 v16, 24, v6
	v_mov_b32_e32 v17, s12
	v_or_b32_e32 v22, 25, v6
	v_mov_b32_e32 v23, s12
	v_or_b32_e32 v24, 26, v6
	v_mov_b32_e32 v25, s12
	v_or_b32_e32 v6, 27, v6
	v_lshl_add_u64 v[8:9], v[4:5], 0, v[8:9]
	v_lshlrev_b64 v[10:11], 9, v[10:11]
	v_lshlrev_b64 v[12:13], 9, v[12:13]
	v_lshlrev_b64 v[14:15], 9, v[14:15]
	v_lshlrev_b64 v[16:17], 9, v[16:17]
	v_lshlrev_b64 v[22:23], 9, v[22:23]
	v_lshlrev_b64 v[24:25], 9, v[24:25]
	v_lshlrev_b64 v[6:7], 9, v[6:7]
	v_lshl_add_u64 v[10:11], v[4:5], 0, v[10:11]
	v_lshl_add_u64 v[12:13], v[4:5], 0, v[12:13]
	v_lshl_add_u64 v[14:15], v[4:5], 0, v[14:15]
	v_lshl_add_u64 v[16:17], v[4:5], 0, v[16:17]
	v_lshl_add_u64 v[22:23], v[4:5], 0, v[22:23]
	v_lshl_add_u64 v[24:25], v[4:5], 0, v[24:25]
	v_lshl_add_u64 v[4:5], v[4:5], 0, v[6:7]
	global_load_dword v76, v[8:9], off
	global_load_dword v77, v[10:11], off
	global_load_dword v78, v[12:13], off
	global_load_dword v79, v[14:15], off
	global_load_dword v80, v[16:17], off
	global_load_dword v81, v[22:23], off
	global_load_dword v82, v[24:25], off
	global_load_dword v83, v[4:5], off
	v_frexp_mant_f32_e32 v28, v1
	v_cvt_f64_f32_e32 v[4:5], v1
	s_mov_b32 s8, 0x3f2aaaab
	v_frexp_exp_i32_f64_e32 v4, v[4:5]
	v_cmp_gt_f32_e32 vcc, s8, v28
	s_mov_b32 s8, 0x3f317218
	v_lshlrev_b32_e32 v112, 3, v109
	v_subbrev_co_u32_e32 v4, vcc, 0, v4, vcc
	v_sub_u32_e32 v5, 0, v4
	v_ldexp_f32 v1, v1, v5
	v_add_f32_e32 v6, -1.0, v1
	v_add_f32_e32 v9, 1.0, v1
	v_add_f32_e32 v7, 1.0, v6
	v_add_f32_e32 v10, -1.0, v9
	v_ldexp_f32 v5, v21, v5
	v_sub_f32_e32 v7, v1, v7
	v_sub_f32_e32 v1, v1, v10
	v_add_f32_e32 v1, v5, v1
	v_add_f32_e32 v7, v5, v7
	v_add_f32_e32 v5, v9, v1
	v_rcp_f32_e32 v10, v5
	v_add_f32_e32 v8, v6, v7
	v_sub_f32_e32 v6, v8, v6
	v_sub_f32_e32 v6, v7, v6
	v_sub_f32_e32 v7, v5, v9
	v_sub_f32_e32 v1, v1, v7
	v_mul_f32_e32 v7, v8, v10
	v_mul_f32_e32 v9, v5, v7
	v_fma_f32 v11, v7, v5, -v9
	v_fmac_f32_e32 v11, v7, v1
	v_add_f32_e32 v12, v9, v11
	v_sub_f32_e32 v13, v8, v12
	v_sub_f32_e32 v8, v8, v13
	v_sub_f32_e32 v9, v12, v9
	v_sub_f32_e32 v8, v8, v12
	v_add_f32_e32 v6, v6, v8
	v_sub_f32_e32 v8, v9, v11
	v_add_f32_e32 v6, v8, v6
	v_add_f32_e32 v8, v13, v6
	v_mul_f32_e32 v9, v10, v8
	v_mul_f32_e32 v11, v5, v9
	v_fma_f32 v5, v9, v5, -v11
	v_fmac_f32_e32 v5, v9, v1
	v_sub_f32_e32 v1, v13, v8
	v_add_f32_e32 v1, v6, v1
	v_add_f32_e32 v6, v11, v5
	v_sub_f32_e32 v12, v8, v6
	v_sub_f32_e32 v8, v8, v12
	v_sub_f32_e32 v11, v6, v11
	v_sub_f32_e32 v6, v8, v6
	v_add_f32_e32 v1, v1, v6
	v_sub_f32_e32 v5, v11, v5
	v_add_f32_e32 v1, v5, v1
	v_add_f32_e32 v1, v12, v1
	v_add_f32_e32 v12, v7, v9
	v_sub_f32_e32 v5, v12, v7
	v_mul_f32_e32 v1, v10, v1
	v_sub_f32_e32 v5, v9, v5
	v_cvt_f32_i32_e32 v15, v4
	v_add_f32_e32 v13, v5, v1
	v_add_f32_e32 v14, v12, v13
	v_mul_f32_e32 v16, v14, v14
	v_fmamk_f32 v1, v16, 0x3e9b6dac, v185
	v_mul_f32_e32 v21, 0x3f317218, v15
	v_fmaak_f32 v17, v16, v1, 0x3f2aaada
	v_fma_f32 v22, v15, s8, -v21
	v_or_b32_e32 v1, s21, v108
	s_movk_i32 s8, 0x90
	v_mad_u32_u24 v111, v1, s8, 0
	v_lshl_add_u32 v4, s23, 6, v111
	v_add_u32_e32 v107, v4, v112
	s_waitcnt vmcnt(0)
	v_cvt_pk_bf16_f32 v4, v68, v69
	v_cvt_pk_bf16_f32 v5, v70, v71
	v_cvt_pk_bf16_f32 v6, v72, v73
	v_cvt_pk_bf16_f32 v7, v74, v75
	v_or_b32_e32 v96, s18, v108
	s_barrier
; DI uint2 pack4(float a, float b, float c, float d) { return make_uint2(pack2(a, b), pack2(c, d)); }
; DI void ret_item(const Params& P, unsigned char* smem, bool samp, int b, int h) {
;     ...
;   __syncthreads();
;   for (int i = 0; i < 4; ++i) {
;     const int d0 = dh * 32 + 4 * g + 8 * i;
;     *(uint2*)(sbuf + (eb * 32 + l32) * SLD + d0) = pack4(S[4 * i], S[4 * i + 1], S[4 * i + 2], S[4 * i + 3]);
;   }
;   __syncthreads();
;   const bool act = !(samp && nh == 1);
; #pragma unroll 1
;   for (int c = 0; c < nchunks; ++c) {
;     const long t0 = (long)c * 64;
;     f32x16 oT = {};
;     bf16x8 uaf[4], ubf[4];
;     for (int ks = 0; ks < 4; ++ks)
;       if (ks < C / 16) {
;         uaf[ks] = ld16(krt + (long)(dh * 32 + l32) * ldt + t0 + ks * 16 + g * 8);
;         ubf[ks] = ld16(vrt + (long)(eb * 32 + l32) * ldt + t0 + ks * 16 + g * 8);
;       }
;     uint2 sgv[4];
;     if (act) {
;       const u16* rp0 = grp + (t0 + nh * 32 + l32) * 1024 + eb * 32;
;       for (int i = 0; i < 4; ++i) sgv[i] = *(const uint2*)(rp0 + 4 * g + 8 * i);
;     }
;     if (act) {
;       bf16x8 qf[4];
;       {
;         const u16* p = qb + (t0 + nh * 32 + l32) * 512 + g * 8;
;         for (int ks = 0; ks < 4; ++ks) qf[ks] = ld16(p + ks * 16);
;       }
;       for (int mh = 0; mh <= nh; ++mh) {
;         bf16x8 kf[4];
;         const u16* p = kb + (t0 + mh * 32 + l32) * 512 + g * 8;
;         for (int ks = 0; ks < 4; ++ks) kf[ks] = ld16(p + ks * 16);
	ds_write2_b64 v107, v[4:5], v[6:7] offset1:2
	v_cvt_pk_bf16_f32 v4, v76, v77
	v_cvt_pk_bf16_f32 v5, v78, v79
	v_cvt_pk_bf16_f32 v6, v80, v81
	v_cvt_pk_bf16_f32 v7, v82, v83
	v_ashrrev_i32_e32 v97, 31, v96
	ds_write2_b64 v107, v[4:5], v[6:7] offset0:4 offset1:6
	v_lshlrev_b64 v[4:5], 6, v[96:97]
	v_lshl_add_u64 v[4:5], s[2:3], 0, v[4:5]
	v_lshlrev_b32_e32 v6, 4, v109
	v_mov_b32_e32 v7, v3
	v_lshl_add_u64 v[4:5], v[4:5], 0, v[6:7]
	s_mov_b64 s[2:3], 0x3357b900
	v_lshlrev_b32_e32 v10, 6, v1
	v_mov_b32_e32 v11, v3
	v_lshl_add_u64 v[8:9], v[4:5], 0, s[2:3]
	v_lshl_add_u64 v[10:11], s[6:7], 0, v[10:11]
	v_add_co_u32_e32 v4, vcc, 0x3357b000, v4
	v_lshl_add_u64 v[6:7], v[10:11], 0, v[6:7]
	s_mov_b64 s[2:3], 0x3b5bb900
	v_addc_co_u32_e32 v5, vcc, 0, v5, vcc
	v_lshl_add_u64 v[10:11], v[6:7], 0, s[2:3]
	v_add_co_u32_e32 v6, vcc, 0x3b5bb000, v6
	s_waitcnt lgkmcnt(0)
	s_barrier
	v_addc_co_u32_e32 v7, vcc, 0, v7, vcc
	global_load_dwordx4 v[44:47], v[4:5], off offset:2304
	global_load_dwordx4 v[48:51], v[6:7], off offset:2304
	global_load_dwordx4 v[36:39], v[8:9], off offset:32
	global_load_dwordx4 v[40:43], v[10:11], off offset:32
	v_mul_f32_e32 v8, v14, v16
	v_ldexp_f32 v7, v14, 1
	v_mul_f32_e32 v8, v8, v17
	v_sub_f32_e32 v4, v14, v12
	v_add_f32_e32 v9, v7, v8
	v_sub_f32_e32 v4, v13, v4
	v_sub_f32_e32 v7, v9, v7
	v_ldexp_f32 v4, v4, 1
	v_sub_f32_e32 v7, v8, v7
	v_add_f32_e32 v4, v4, v7
	v_fmac_f32_e32 v22, 0xb102e308, v15
	v_add_f32_e32 v7, v9, v4
	v_add_f32_e32 v5, v21, v22
	v_sub_f32_e32 v8, v7, v9
	v_sub_f32_e32 v4, v4, v8
	v_add_f32_e32 v8, v5, v7
	v_sub_f32_e32 v9, v8, v5
	v_sub_f32_e32 v6, v5, v21
	v_sub_f32_e32 v10, v8, v9
	v_sub_f32_e32 v6, v22, v6
	v_sub_f32_e32 v5, v5, v10
	v_sub_f32_e32 v7, v7, v9
	v_add_f32_e32 v5, v7, v5
	v_add_f32_e32 v7, v6, v4
	v_sub_f32_e32 v9, v7, v6
	v_sub_f32_e32 v10, v7, v9
	v_sub_f32_e32 v6, v6, v10
	v_sub_f32_e32 v4, v4, v9
	v_add_f32_e32 v5, v7, v5
	v_add_f32_e32 v4, v4, v6
	v_add_f32_e32 v6, v8, v5
	v_sub_f32_e32 v7, v6, v8
	v_sub_f32_e32 v5, v5, v7
	v_add_f32_e32 v4, v4, v5
	v_add_f32_e32 v4, v6, v4
	v_cmp_nlt_f32_e32 vcc, 1.0, v18
	s_mov_b32 s2, 0x33800000
	s_mov_b32 s11, 0xc2ce8ed0
	v_cndmask_b32_e32 v4, v192, v4, vcc
	v_cmp_neq_f32_e32 vcc, 1.0, v18
	s_mov_b32 s12, 0x42b17218
	v_mov_b32_e32 v97, s24
	v_cndmask_b32_e32 v4, v193, v4, vcc
	v_cmp_gt_f32_e32 vcc, s2, v18
	v_readlane_b32 s2, v250, 46
	s_add_u32 s2, s0, s2
	s_addc_u32 s3, s1, 0
	s_lshl_b32 s10, s20, 8
	s_add_u32 s2, s2, s10
	s_addc_u32 s3, s3, 0
	s_cmp_lg_u32 s23, 1
	s_cselect_b64 s[16:17], -1, 0
	s_lshl_b32 s14, s21, 1
	s_add_u32 s2, s2, s14
	s_addc_u32 s3, s3, 0
	v_cndmask_b32_e64 v4, v4, -v18, vcc
	s_add_u32 s14, s2, 0x65ca900
	v_mul_f32_e32 v110, 0x42000000, v4
	v_mul_f32_e32 v21, 0xc2000000, v4
	s_addc_u32 s15, s3, 0
	s_lshl_b32 s22, s23, 10
	v_mov_b32_e32 v19, 0
	v_cmp_ngt_f32_e64 s[6:7], s11, v110
	v_cmp_nlt_f32_e64 s[8:9], s12, v110
	v_cmp_ngt_f32_e64 s[10:11], s11, v21
	v_cmp_nlt_f32_e64 s[12:13], s12, v21
	s_cmp_eq_u32 s23, 1
	v_lshlrev_b64 v[94:95], 11, v[96:97]
	v_lshlrev_b32_e32 v90, 1, v106
	v_mov_b32_e32 v18, 0
	v_mov_b32_e32 v17, 0
	v_mov_b32_e32 v16, 0
	v_mov_b32_e32 v15, 0
	v_mov_b32_e32 v14, 0
	v_mov_b32_e32 v13, 0
	v_mov_b32_e32 v12, 0
	v_mov_b32_e32 v11, 0
	v_mov_b32_e32 v10, 0
	v_mov_b32_e32 v9, 0
	v_mov_b32_e32 v8, 0
	v_mov_b32_e32 v7, 0
	v_mov_b32_e32 v6, 0
	v_mov_b32_e32 v5, 0
	v_mov_b32_e32 v4, 0
	s_cbranch_scc1 .LBB0_722
	s_lshl_b32 s2, s20, 6
	v_readlane_b32 s24, v250, 50
	s_mov_b32 s3, s91
	s_add_u32 s26, s0, s24
	s_addc_u32 s27, s1, 0
	s_lshl_b64 s[24:25], s[2:3], 1
	v_mov_b32_e32 v91, v3
	s_add_u32 s24, s26, s24
	v_lshl_add_u64 v[6:7], s[14:15], 0, v[90:91]
	s_addc_u32 s25, s27, s25
	v_lshlrev_b32_e32 v4, 1, v112
	v_mov_b32_e32 v5, v3
	v_lshl_add_u64 v[6:7], v[6:7], 0, v[94:95]
	v_lshl_add_u64 v[4:5], s[24:25], 0, v[4:5]
	global_load_dwordx2 v[92:93], v[6:7], off
	global_load_dwordx2 v[88:89], v[6:7], off offset:16
	global_load_dwordx2 v[86:87], v[6:7], off offset:32
	global_load_dwordx2 v[84:85], v[6:7], off offset:48
	v_lshlrev_b64 v[6:7], 10, v[96:97]
	v_lshl_add_u64 v[4:5], v[4:5], 0, v[6:7]
	s_mov_b64 s[24:25], 0x274fb900
	v_lshl_add_u64 v[6:7], v[4:5], 0, s[24:25]
	v_add_co_u32_e32 v4, vcc, 0x274fb000, v4
	v_mov_b32_e32 v19, 0
	s_nop 0
	v_addc_co_u32_e32 v5, vcc, 0, v5, vcc
	global_load_dwordx4 v[60:63], v[6:7], off offset:32
	global_load_dwordx4 v[56:59], v[6:7], off offset:64
	global_load_dwordx4 v[64:67], v[4:5], off offset:2304
	global_load_dwordx4 v[52:55], v[6:7], off offset:96
	s_cmp_lt_i32 s23, 0
	v_mov_b32_e32 v18, v19
	v_mov_b32_e32 v17, v19
	v_mov_b32_e32 v16, v19
	v_mov_b32_e32 v15, v19
	v_mov_b32_e32 v14, v19
	v_mov_b32_e32 v13, v19
	v_mov_b32_e32 v12, v19
	v_mov_b32_e32 v11, v19
	v_mov_b32_e32 v10, v19
	v_mov_b32_e32 v9, v19
	v_mov_b32_e32 v8, v19
	v_mov_b32_e32 v7, v19
	v_mov_b32_e32 v6, v19
	v_mov_b32_e32 v5, v19
	v_mov_b32_e32 v4, v19
	s_cbranch_scc1 .LBB0_719
	v_mul_f32_e32 v4, 0x3fb8aa3b, v21
	s_mov_b32 s24, 0x3fb8aa3b
	v_fma_f32 v5, v21, s24, -v4
	v_rndne_f32_e32 v6, v4
	v_fmac_f32_e32 v5, 0x32a5705f, v21
	v_sub_f32_e32 v4, v4, v6
	v_add_f32_e32 v4, v4, v5
	v_cvt_i32_f32_e32 v5, v6
	v_exp_f32_e32 v4, v4
	v_lshlrev_b32_e32 v6, 5, v1
	v_lshlrev_b32_e32 v6, 1, v6
	v_mov_b32_e32 v7, v3
	v_ldexp_f32 v4, v4, v5
	v_cndmask_b32_e64 v4, 0, v4, s[10:11]
	v_readlane_b32 s11, v250, 49
	v_cndmask_b32_e64 v98, v194, v4, s[12:13]
	s_add_i32 s12, s11, s94
	s_mov_b32 s13, s91
	s_lshl_b64 s[12:13], s[12:13], 13
	v_mov_b32_e32 v5, s13
	v_or_b32_e32 v4, s12, v112
	v_readlane_b32 s12, v250, 38
	v_lshl_add_u64 v[100:101], v[4:5], 0, v[6:7]
	v_lshlrev_b32_e32 v4, 10, v108
	v_mov_b32_e32 v5, v3
	v_readlane_b32 s13, v250, 39
	v_lshrrev_b32_e32 v6, 1, v20
	v_and_b32_e32 v6, 16, v6
	v_lshl_add_u64 v[4:5], s[12:13], 0, v[4:5]
	v_lshl_add_u64 v[4:5], v[4:5], 0, v[6:7]
	v_lshl_add_u64 v[102:103], s[2:3], 1, v[4:5]
	v_mov_b32_e32 v4, 0
	v_mov_b32_e32 v1, v96
	v_mov_b32_e32 v99, v98
	s_add_i32 s10, s23, 1
	v_mov_b32_e32 v91, v106
	v_mov_b32_e32 v5, v4
	v_mov_b32_e32 v6, v4
	v_mov_b32_e32 v7, v4
	v_mov_b32_e32 v8, v4
	v_mov_b32_e32 v9, v4
	v_mov_b32_e32 v10, v4
	v_mov_b32_e32 v11, v4
	v_mov_b32_e32 v12, v4
	v_mov_b32_e32 v13, v4
	v_mov_b32_e32 v14, v4
	v_mov_b32_e32 v15, v4
	v_mov_b32_e32 v16, v4
	v_mov_b32_e32 v17, v4
	v_mov_b32_e32 v18, v4
	v_mov_b32_e32 v19, v4
; DI int crow(int r, int g) { return (r & 3) + 8 * (r >> 2) + 4 * g; }
; #define MFMA32(a, b, c) __builtin_amdgcn_mfma_f32_32x32x16_bf16((a), (b), (c), 0, 0, 0)
; DI void ret_item(const Params& P, unsigned char* smem, bool samp, int b, int h) {
;     ...
;       for (int mh = 0; mh <= nh; ++mh) {
;         bf16x8 kf[4];
;         const u16* p = kb + (t0 + mh * 32 + l32) * 512 + g * 8;
;         for (int ks = 0; ks < 4; ++ks) kf[ks] = ld16(p + ks * 16);
;         f32x16 inn = {};
;         for (int ks = 0; ks < 4; ++ks) inn = MFMA32(kf[ks], qf[ks], inn);
;         const int ncol = nh * 32 + l32;
;         for (int r = 0; r < 16; ++r) {
;           const int m = mh * 32 + crow(r, g);
;           inn[r] = (ncol >= m) ? inn[r] * ginvC : 0.f;
;         }
;         for (int s = 0; s < 2; ++s) {
;           const u16* vp = vrt + (long)(eb * 32 + l32) * ldt + t0 + mh * 32 + 16 * s + 4 * g;
;           bf16x8 vf = ld8x2(vp, vp + 8);
;           oT = MFMA32(vf, packacc8(inn, s), oT);
;         }
;       }
.LBB0_718:
	v_lshl_add_u64 v[20:21], s[0:1], 0, v[102:103]
	s_mov_b32 s2, 0x2f53b000
	v_add_co_u32_e32 v24, vcc, s2, v20
	s_mov_b32 s2, 0x3b5bb000
	s_nop 0
	v_addc_co_u32_e32 v25, vcc, 0, v21, vcc
	global_load_dwordx4 v[20:23], v[24:25], off offset:2304
	global_load_dwordx4 v[114:117], v[24:25], off offset:2336
	global_load_dwordx4 v[118:121], v[24:25], off offset:2368
	global_load_dwordx4 v[122:125], v[24:25], off offset:2400
	v_cmp_ge_i32_e32 vcc, v96, v91
	v_or_b32_e32 v127, 10, v91
	v_or_b32_e32 v126, 11, v91
	v_or_b32_e32 v129, 16, v91
	v_or_b32_e32 v128, 17, v91
	v_or_b32_e32 v131, 18, v91
	v_or_b32_e32 v130, 19, v91
	v_or_b32_e32 v132, 24, v91
	v_or_b32_e32 v133, 26, v91
	s_add_i32 s10, s10, -1
	v_lshl_add_u64 v[102:103], v[102:103], 0, s[82:83]
	s_cmp_eq_u32 s10, 0
	s_waitcnt vmcnt(0) lgkmcnt(0)
	v_mfma_f32_32x32x16_bf16 v[20:35], v[20:23], v[64:67], 0
	v_mfma_f32_32x32x16_bf16 v[20:35], v[114:117], v[60:63], v[20:35]
	v_mfma_f32_32x32x16_bf16 v[20:35], v[118:121], v[56:59], v[20:35]
	v_mfma_f32_32x32x16_bf16 v[20:35], v[122:125], v[52:55], v[20:35]
	v_or_b32_e32 v123, 2, v91
	v_or_b32_e32 v122, 3, v91
	v_or_b32_e32 v125, 8, v91
	v_or_b32_e32 v124, 9, v91
	s_nop 7
	v_mul_f32_e32 v20, v98, v20
	v_cndmask_b32_e32 v97, 0, v20, vcc
	v_cmp_gt_i32_e32 vcc, v96, v91
	v_mul_f32_e32 v20, v98, v21
	v_pk_mul_f32 v[114:115], v[98:99], v[22:23]
	v_cndmask_b32_e32 v113, 0, v20, vcc
	v_lshl_add_u64 v[20:21], s[0:1], 0, v[100:101]
	v_add_co_u32_e32 v120, vcc, s2, v20
	v_pk_mul_f32 v[118:119], v[98:99], v[26:27]
	s_nop 0
	v_addc_co_u32_e32 v121, vcc, 0, v21, vcc
	global_load_dwordx2 v[20:21], v[120:121], off offset:2304
	global_load_dwordx2 v[22:23], v[120:121], off offset:2320
	v_pk_mul_f32 v[26:27], v[98:99], v[32:33]
	v_cvt_pk_bf16_f32 v33, v114, v115
	v_cmp_ge_i32_e32 vcc, v96, v123
	v_pk_mul_f32 v[116:117], v[98:99], v[24:25]
	v_pk_mul_f32 v[24:25], v[98:99], v[34:35]
	v_cndmask_b32_e32 v34, 0, v33, vcc
	v_lshrrev_b32_e32 v33, 16, v33
	v_cmp_ge_i32_e32 vcc, v1, v122
	v_cvt_pk_bf16_f32 v32, v97, v113
	v_pk_mul_f32 v[104:105], v[98:99], v[28:29]
	v_cndmask_b32_e32 v33, 0, v33, vcc
	v_perm_b32 v33, v33, v34, s5
	v_cvt_pk_bf16_f32 v34, v116, v117
	v_cmp_ge_i32_e32 vcc, v96, v125
	v_pk_mul_f32 v[28:29], v[98:99], v[30:31]
	v_or_b32_e32 v31, 25, v91
	v_cndmask_b32_e32 v35, 0, v34, vcc
	v_lshrrev_b32_e32 v34, 16, v34
	v_cmp_ge_i32_e32 vcc, v1, v124
	v_cvt_pk_bf16_f32 v28, v28, v29
	v_cvt_pk_bf16_f32 v26, v26, v27
	v_cndmask_b32_e32 v34, 0, v34, vcc
	v_perm_b32 v34, v34, v35, s5
	v_cvt_pk_bf16_f32 v35, v118, v119
	v_cmp_ge_i32_e32 vcc, v96, v127
	v_or_b32_e32 v30, 27, v91
	v_cvt_pk_bf16_f32 v24, v24, v25
	v_cndmask_b32_e32 v97, 0, v35, vcc
	v_lshrrev_b32_e32 v35, 16, v35
	v_cmp_ge_i32_e32 vcc, v1, v126
	v_add_u32_e32 v91, 32, v91
	v_lshl_add_u64 v[100:101], v[100:101], 0, 64
	v_cndmask_b32_e32 v35, 0, v35, vcc
	v_perm_b32 v35, v35, v97, s5
	v_cmp_ge_i32_e32 vcc, v96, v129
	s_waitcnt vmcnt(0) lgkmcnt(0)
	v_mfma_f32_32x32x16_bf16 v[4:19], v[20:23], v[32:35], v[4:19]
	global_load_dwordx2 v[20:21], v[120:121], off offset:2336
	global_load_dwordx2 v[22:23], v[120:121], off offset:2352
	v_cvt_pk_bf16_f32 v32, v104, v105
	v_cndmask_b32_e32 v33, 0, v32, vcc
	v_lshrrev_b32_e32 v32, 16, v32
	v_cmp_ge_i32_e32 vcc, v1, v128
	s_nop 1
	v_cndmask_b32_e32 v32, 0, v32, vcc
	v_cmp_ge_i32_e32 vcc, v96, v131
	v_perm_b32 v32, v32, v33, s5
	s_nop 0
	v_cndmask_b32_e32 v29, 0, v28, vcc
	v_lshrrev_b32_e32 v28, 16, v28
	v_cmp_ge_i32_e32 vcc, v1, v130
	s_nop 1
	v_cndmask_b32_e32 v28, 0, v28, vcc
	v_cmp_ge_i32_e32 vcc, v96, v132
	v_perm_b32 v33, v28, v29, s5
	s_nop 0
	v_cndmask_b32_e32 v27, 0, v26, vcc
	v_lshrrev_b32_e32 v26, 16, v26
	v_cmp_ge_i32_e32 vcc, v1, v31
	s_nop 1
	v_cndmask_b32_e32 v26, 0, v26, vcc
	v_cmp_ge_i32_e32 vcc, v96, v133
	v_perm_b32 v34, v26, v27, s5
	s_nop 0
	v_cndmask_b32_e32 v25, 0, v24, vcc
	v_lshrrev_b32_e32 v24, 16, v24
	v_cmp_ge_i32_e32 vcc, v1, v30
	s_nop 1
	v_cndmask_b32_e32 v24, 0, v24, vcc
	v_perm_b32 v35, v24, v25, s5
	s_waitcnt vmcnt(0) lgkmcnt(0)
	s_nop 0
	v_mfma_f32_32x32x16_bf16 v[4:19], v[20:23], v[32:35], v[4:19]
	s_cbranch_scc0 .LBB0_718

; DI float bflo(unsigned u) { return __uint_as_float(u << 16); }
; DI float bfhi(unsigned u) { return __uint_as_float(u & 0xffff0000u); }
; DI uint2 pack4(float a, float b, float c, float d) { return make_uint2(pack2(a, b), pack2(c, d)); }
; DI void ret_item(const Params& P, unsigned char* smem, bool samp, int b, int h) {
;     ...
;     __syncthreads();
;     if (act) {
;       float s1 = 0.f, s2 = 0.f;
;       for (int e = 0; e < 4; ++e) { float2 v = stat[(nh * 4 + e) * 32 + l32]; s1 += v.x; s2 += v.y; }
;       const float mean = s1 * (1.0f / 128.0f);
;       const float var = fmaxf(s2 * (1.0f / 128.0f) - mean * mean, 0.f);
;       const float rstd = rsqrtf(var + 1e-6f);
;       u16* rp = grp + (t0 + nh * 32 + l32) * 1024 + eb * 32;
;       const float* gg = P.gng + h * 128 + eb * 32;
;       for (int i = 0; i < 4; ++i) {
;         const int e = 4 * g + 8 * i;
;         const uint2 sg = sgv[i];
;         f32x4 gv = *(const f32x4*)(gg + e);
;         float r0 = (oT[4 * i] - mean) * rstd * gv[0], r1 = (oT[4 * i + 1] - mean) * rstd * gv[1];
;         float r2 = (oT[4 * i + 2] - mean) * rstd * gv[2], r3 = (oT[4 * i + 3] - mean) * rstd * gv[3];
;         *(uint2*)(rp + e) = pack4(r0 * bflo(sg.x), r1 * bfhi(sg.x), r2 * bflo(sg.y), r3 * bfhi(sg.y));
;       }
;     }
.LBB0_722:
	v_mul_f32_e32 v1, 0x3fb8aa3b, v110
	s_mov_b32 s0, 0x3fb8aa3b
	v_fma_f32 v20, v110, s0, -v1
	v_rndne_f32_e32 v21, v1
	v_fmac_f32_e32 v20, 0x32a5705f, v110
	v_sub_f32_e32 v1, v1, v21
	v_add_f32_e32 v1, v1, v20
	v_exp_f32_e32 v1, v1
	v_cvt_i32_f32_e32 v20, v21
	s_lshl_b32 s0, s20, 7
	s_andn2_b64 vcc, exec, s[16:17]
	s_waitcnt lgkmcnt(0)
	v_ldexp_f32 v1, v1, v20
	v_cndmask_b32_e64 v1, 0, v1, s[6:7]
	v_cndmask_b32_e64 v20, v194, v1, s[8:9]
	s_barrier
	s_cbranch_vccnz .LBB0_724
	s_mov_b32 s1, s91
	s_add_i32 s22, s22, 0
	s_lshl_b64 s[0:1], s[0:1], 2
	s_add_u32 s0, s28, s0
	s_addc_u32 s1, s29, s1
	s_add_u32 s0, s0, s19
	s_addc_u32 s1, s1, 0
	v_lshlrev_b32_e32 v1, 2, v106
	global_load_dwordx4 v[22:25], v1, s[0:1]
	v_lshl_add_u32 v21, v108, 3, s22
	v_add_u32_e32 v21, 0x9000, v21
	ds_read2_b64 v[26:29], v21 offset1:32
	ds_read2_b64 v[30:33], v21 offset0:64 offset1:96
	v_lshlrev_b32_e32 v52, 16, v92
	v_and_b32_e32 v53, 0xffff0000, v92
	v_lshlrev_b32_e32 v54, 16, v93
	s_waitcnt lgkmcnt(0)
	v_pk_add_f32 v[26:27], v[26:27], 0 op_sel_hi:[1,0]
	v_and_b32_e32 v55, 0xffff0000, v93
	v_pk_add_f32 v[26:27], v[26:27], v[28:29]
	v_lshl_add_u64 v[34:35], s[14:15], 0, v[94:95]
	v_pk_add_f32 v[26:27], v[26:27], v[30:31]
	v_mov_b32_e32 v91, v3
	v_pk_add_f32 v[26:27], v[26:27], v[32:33]
	s_nop 0
	v_pk_mul_f32 v[26:27], v[26:27], s[84:85] op_sel_hi:[1,0]
	s_nop 0
	v_fma_f32 v21, -v26, v26, v27
	v_max_f32_e32 v21, 0, v21
	v_add_f32_e32 v21, 0x358637bd, v21
	v_mul_f32_e32 v28, 0x4b800000, v21
	v_cmp_gt_f32_e32 vcc, s33, v21
	v_pk_add_f32 v[4:5], v[4:5], v[26:27] op_sel_hi:[1,0] neg_lo:[0,1] neg_hi:[0,1]
	v_pk_add_f32 v[6:7], v[6:7], v[26:27] op_sel_hi:[1,0] neg_lo:[0,1] neg_hi:[0,1]
	v_cndmask_b32_e32 v21, v21, v28, vcc
	v_rsq_f32_e32 v21, v21
	v_lshl_add_u64 v[28:29], v[34:35], 0, v[90:91]
	v_pk_add_f32 v[8:9], v[8:9], v[26:27] op_sel_hi:[1,0] neg_lo:[0,1] neg_hi:[0,1]
	v_pk_add_f32 v[10:11], v[10:11], v[26:27] op_sel_hi:[1,0] neg_lo:[0,1] neg_hi:[0,1]
	v_mul_f32_e32 v30, 0x45800000, v21
	v_cndmask_b32_e32 v30, v21, v30, vcc
	v_pk_mul_f32 v[4:5], v[4:5], v[30:31] op_sel_hi:[1,0]
	v_pk_mul_f32 v[6:7], v[6:7], v[30:31] op_sel_hi:[1,0]
	v_pk_mul_f32 v[8:9], v[8:9], v[30:31] op_sel_hi:[1,0]
	v_pk_mul_f32 v[10:11], v[10:11], v[30:31] op_sel_hi:[1,0]
	v_pk_add_f32 v[12:13], v[12:13], v[26:27] op_sel_hi:[1,0] neg_lo:[0,1] neg_hi:[0,1]
	v_pk_add_f32 v[14:15], v[14:15], v[26:27] op_sel_hi:[1,0] neg_lo:[0,1] neg_hi:[0,1]
	v_pk_mul_f32 v[12:13], v[12:13], v[30:31] op_sel_hi:[1,0]
	v_pk_mul_f32 v[14:15], v[14:15], v[30:31] op_sel_hi:[1,0]
	s_waitcnt vmcnt(0)
	v_pk_mul_f32 v[4:5], v[22:23], v[4:5]
	v_pk_mul_f32 v[6:7], v[24:25], v[6:7]
	v_pk_mul_f32 v[4:5], v[4:5], v[52:53]
	v_pk_mul_f32 v[6:7], v[6:7], v[54:55]
	v_cvt_pk_bf16_f32 v4, v4, v5
	v_cvt_pk_bf16_f32 v5, v6, v7
	global_store_dwordx2 v[28:29], v[4:5], off
	global_load_dwordx4 v[4:7], v1, s[0:1] offset:32
	v_lshlrev_b32_e32 v22, 16, v88
	v_and_b32_e32 v23, 0xffff0000, v88
	v_lshlrev_b32_e32 v24, 16, v89
	v_and_b32_e32 v25, 0xffff0000, v89
	s_waitcnt vmcnt(0)
	v_pk_mul_f32 v[4:5], v[4:5], v[8:9]
	v_pk_mul_f32 v[6:7], v[6:7], v[10:11]
	v_pk_mul_f32 v[4:5], v[4:5], v[22:23]
	v_pk_mul_f32 v[6:7], v[6:7], v[24:25]
	v_cvt_pk_bf16_f32 v4, v4, v5
	v_cvt_pk_bf16_f32 v5, v6, v7
	global_store_dwordx2 v[28:29], v[4:5], off offset:16
	global_load_dwordx4 v[4:7], v1, s[0:1] offset:64
	v_lshlrev_b32_e32 v8, 16, v86
	v_and_b32_e32 v9, 0xffff0000, v86
	v_lshlrev_b32_e32 v10, 16, v87
	v_and_b32_e32 v11, 0xffff0000, v87
	s_waitcnt vmcnt(0)
	v_pk_mul_f32 v[4:5], v[4:5], v[12:13]
	v_pk_mul_f32 v[6:7], v[6:7], v[14:15]
	v_pk_mul_f32 v[4:5], v[4:5], v[8:9]
	v_pk_mul_f32 v[6:7], v[6:7], v[10:11]
	v_cvt_pk_bf16_f32 v4, v4, v5
	v_cvt_pk_bf16_f32 v5, v6, v7
	global_store_dwordx2 v[28:29], v[4:5], off offset:32
	global_load_dwordx4 v[4:7], v1, s[0:1] offset:96
	v_pk_add_f32 v[12:13], v[16:17], v[26:27] op_sel_hi:[1,0] neg_lo:[0,1] neg_hi:[0,1]
	v_pk_add_f32 v[14:15], v[18:19], v[26:27] op_sel_hi:[1,0] neg_lo:[0,1] neg_hi:[0,1]
	v_pk_mul_f32 v[12:13], v[12:13], v[30:31] op_sel_hi:[1,0]
	v_pk_mul_f32 v[14:15], v[14:15], v[30:31] op_sel_hi:[1,0]
	v_lshlrev_b32_e32 v8, 16, v84
	v_and_b32_e32 v9, 0xffff0000, v84
	v_lshlrev_b32_e32 v10, 16, v85
	v_and_b32_e32 v11, 0xffff0000, v85
	s_waitcnt vmcnt(0)
	v_pk_mul_f32 v[4:5], v[12:13], v[4:5]
	v_pk_mul_f32 v[6:7], v[14:15], v[6:7]
	v_pk_mul_f32 v[4:5], v[4:5], v[8:9]
	v_pk_mul_f32 v[6:7], v[6:7], v[10:11]
	v_cvt_pk_bf16_f32 v4, v4, v5
	v_cvt_pk_bf16_f32 v5, v6, v7
	global_store_dwordx2 v[28:29], v[4:5], off offset:48
; DI uint2 pack4(float a, float b, float c, float d) { return make_uint2(pack2(a, b), pack2(c, d)); }
; DI int crow(int r, int g) { return (r & 3) + 8 * (r >> 2) + 4 * g; }
; #define MFMA32(a, b, c) __builtin_amdgcn_mfma_f32_32x32x16_bf16((a), (b), (c), 0, 0, 0)
; DI void ret_item(const Params& P, unsigned char* smem, bool samp, int b, int h) {
;     ...
;     for (int r = 0; r < 16; ++r) S[r] *= gC;
;     for (int ks = 0; ks < 4; ++ks)
;       if (ks < C / 16) S = MFMA32(uaf[ks], ubf[ks], S);
;     {
;       u16* sn = sbuf + (cur ^ 1) * (128 * SLD);
;       for (int i = 0; i < 4; ++i) {
;         const int d0 = dh * 32 + 4 * g + 8 * i;
;         *(uint2*)(sn + (eb * 32 + l32) * SLD + d0) = pack4(S[4 * i], S[4 * i + 1], S[4 * i + 2], S[4 * i + 3]);
;       }
;     }
;     __syncthreads();
;     cur ^= 1;
;   }
;   float* so = P.out + (samp ? O_SS : O_SP) + (long)(b * 8 + h) * 64 * 128;
;   for (int r = 0; r < 16; ++r) so[(long)(dh * 32 + crow(r, g)) * 128 + eb * 32 + l32] = S[r];
.LBB0_724:
	v_pk_mul_f32 v[18:19], v[20:21], v[82:83] op_sel_hi:[0,1]
	v_pk_mul_f32 v[16:17], v[20:21], v[80:81] op_sel_hi:[0,1]
	v_pk_mul_f32 v[14:15], v[20:21], v[78:79] op_sel_hi:[0,1]
	v_pk_mul_f32 v[12:13], v[20:21], v[76:77] op_sel_hi:[0,1]
	v_pk_mul_f32 v[10:11], v[20:21], v[74:75] op_sel_hi:[0,1]
	v_pk_mul_f32 v[8:9], v[20:21], v[72:73] op_sel_hi:[0,1]
	v_pk_mul_f32 v[6:7], v[20:21], v[70:71] op_sel_hi:[0,1]
	v_pk_mul_f32 v[4:5], v[20:21], v[68:69] op_sel_hi:[0,1]
	s_lshl_b64 s[0:1], s[90:91], 15
	v_readlane_b32 s2, v250, 20
	s_waitcnt vmcnt(0)
	v_mfma_f32_32x32x16_bf16 v[4:19], v[44:47], v[48:51], v[4:19]
	s_add_u32 s0, s2, s0
	v_readlane_b32 s2, v250, 21
	v_add_u32_e32 v1, 0x4800, v107
	s_addc_u32 s1, s2, s1
	s_add_u32 s0, s0, s19
	s_addc_u32 s1, s1, 0
	v_mfma_f32_32x32x16_bf16 v[4:19], v[36:39], v[40:43], v[4:19]
	s_nop 11
	v_cvt_pk_bf16_f32 v20, v4, v5
	v_cvt_pk_bf16_f32 v21, v6, v7
	v_cvt_pk_bf16_f32 v22, v8, v9
	v_cvt_pk_bf16_f32 v23, v10, v11
	ds_write2_b64 v1, v[20:21], v[22:23] offset1:2
	v_or_b32_e32 v20, s18, v106
	v_cvt_pk_bf16_f32 v24, v12, v13
	v_cvt_pk_bf16_f32 v25, v14, v15
	v_cvt_pk_bf16_f32 v26, v16, v17
	v_cvt_pk_bf16_f32 v27, v18, v19
	v_ashrrev_i32_e32 v21, 31, v20
	ds_write2_b64 v1, v[24:25], v[26:27] offset0:4 offset1:6
	v_lshl_add_u64 v[22:23], s[0:1], 0, v[2:3]
	v_lshlrev_b64 v[24:25], 9, v[20:21]
	v_lshl_add_u64 v[24:25], v[22:23], 0, v[24:25]
	s_waitcnt lgkmcnt(0)
	s_barrier
	global_store_dword v[24:25], v4, off
	v_or_b32_e32 v24, 1, v20
	v_ashrrev_i32_e32 v25, 31, v24
	v_lshlrev_b64 v[24:25], 9, v[24:25]
	v_lshl_add_u64 v[24:25], v[22:23], 0, v[24:25]
	v_or_b32_e32 v4, 2, v20
	global_store_dword v[24:25], v5, off
	v_ashrrev_i32_e32 v5, 31, v4
	v_lshlrev_b64 v[4:5], 9, v[4:5]
	v_lshl_add_u64 v[4:5], v[22:23], 0, v[4:5]
	global_store_dword v[4:5], v6, off
	v_or_b32_e32 v4, 3, v20
	v_ashrrev_i32_e32 v5, 31, v4
	v_lshlrev_b64 v[4:5], 9, v[4:5]
	v_lshl_add_u64 v[4:5], v[22:23], 0, v[4:5]
	global_store_dword v[4:5], v7, off
	v_or_b32_e32 v4, 8, v20
	v_ashrrev_i32_e32 v5, 31, v4
	v_lshlrev_b64 v[4:5], 9, v[4:5]
	v_lshl_add_u64 v[4:5], v[22:23], 0, v[4:5]
	global_store_dword v[4:5], v8, off
	v_or_b32_e32 v4, 9, v20
	v_ashrrev_i32_e32 v5, 31, v4
	v_lshlrev_b64 v[4:5], 9, v[4:5]
	v_lshl_add_u64 v[4:5], v[22:23], 0, v[4:5]
	global_store_dword v[4:5], v9, off
	v_or_b32_e32 v4, 10, v20
	v_ashrrev_i32_e32 v5, 31, v4
	v_lshlrev_b64 v[4:5], 9, v[4:5]
	v_lshl_add_u64 v[4:5], v[22:23], 0, v[4:5]
	global_store_dword v[4:5], v10, off
	v_or_b32_e32 v4, 11, v20
	v_ashrrev_i32_e32 v5, 31, v4
	v_lshlrev_b64 v[4:5], 9, v[4:5]
	v_lshl_add_u64 v[4:5], v[22:23], 0, v[4:5]
	global_store_dword v[4:5], v11, off
	v_or_b32_e32 v4, 16, v20
	v_ashrrev_i32_e32 v5, 31, v4
	v_lshlrev_b64 v[4:5], 9, v[4:5]
	v_lshl_add_u64 v[4:5], v[22:23], 0, v[4:5]
	global_store_dword v[4:5], v12, off
	v_or_b32_e32 v4, 17, v20
	v_ashrrev_i32_e32 v5, 31, v4
	v_lshlrev_b64 v[4:5], 9, v[4:5]
	v_lshl_add_u64 v[4:5], v[22:23], 0, v[4:5]
	global_store_dword v[4:5], v13, off
	v_or_b32_e32 v4, 18, v20
	v_ashrrev_i32_e32 v5, 31, v4
	v_lshlrev_b64 v[4:5], 9, v[4:5]
	v_lshl_add_u64 v[4:5], v[22:23], 0, v[4:5]
	global_store_dword v[4:5], v14, off
	v_or_b32_e32 v4, 19, v20
	v_ashrrev_i32_e32 v5, 31, v4
	v_lshlrev_b64 v[4:5], 9, v[4:5]
	v_lshl_add_u64 v[4:5], v[22:23], 0, v[4:5]
	global_store_dword v[4:5], v15, off
	v_or_b32_e32 v4, 24, v20
	v_ashrrev_i32_e32 v5, 31, v4
	v_lshlrev_b64 v[4:5], 9, v[4:5]
	v_lshl_add_u64 v[4:5], v[22:23], 0, v[4:5]
	global_store_dword v[4:5], v16, off
	v_or_b32_e32 v4, 25, v20
	v_ashrrev_i32_e32 v5, 31, v4
	v_lshlrev_b64 v[4:5], 9, v[4:5]
	v_lshl_add_u64 v[4:5], v[22:23], 0, v[4:5]
	global_store_dword v[4:5], v17, off
	v_or_b32_e32 v4, 26, v20
	v_ashrrev_i32_e32 v5, 31, v4
	v_lshlrev_b64 v[4:5], 9, v[4:5]
	v_lshl_add_u64 v[4:5], v[22:23], 0, v[4:5]
	global_store_dword v[4:5], v18, off
	v_or_b32_e32 v4, 27, v20
	v_ashrrev_i32_e32 v5, 31, v4
	v_lshlrev_b64 v[4:5], 9, v[4:5]
	v_lshl_add_u64 v[4:5], v[22:23], 0, v[4:5]
	global_store_dword v[4:5], v19, off
	s_mov_b64 s[0:1], 0

; DI uint2 pack4(float a, float b, float c, float d) { return make_uint2(pack2(a, b), pack2(c, d)); }
; DI float siluf_(float x) { return x / (1.0f + __expf(-x)); }
; DI void phase_ffn_up(const Params& P, unsigned char* smem) {
;     ...
;     { const int tid_ = launder_tid(); const int wid = tid_ >> 6, lane = tid_ & 63, wr = wid >> 2, wc = wid & 3, fr = lane & 15, fq = lane >> 4;
; #pragma unroll
;     for (int ai = 0; ai < 2; ++ai)
; #pragma unroll
;     for (int bj = 0; bj < 2; ++bj)
; #pragma unroll
;     for (int n = 0; n < 2; ++n)
; #pragma unroll
;     for (int m = 0; m < 2; ++m) {
;       asm volatile("" ::: "memory");
;       const long token = tt * 256 + bj * 128 + wc * 32 + n * 16 + fr;
;       const int jj = (ft * 4 + ai * 2 + wr) * 32 + m * 16 + fq * 4;
;       f32x4 gt = acc[ai][bj][m][n], up = acc[ai][bj][m + 2][n];
;       *(uint2*)(HM + token * DFF + jj) = pack4(siluf_(gt[0]) * up[0], siluf_(gt[1]) * up[1], siluf_(gt[2]) * up[2], siluf_(gt[3]) * up[3]);
;     }
.LBB0_946:
	v_mov_b32_e32 v130, v142
	v_mov_b64_e32 v[134:135], s[0:1]
	v_lshrrev_b32_e32 v132, 1, v130
	v_and_b32_e32 v131, 15, v130
	v_and_b32_e32 v132, 0x60, v132
	v_or3_b32 v136, v131, v132, s26
	v_lshrrev_b32_e32 v132, 2, v130
	v_ashrrev_i32_e32 v130, 3, v130
	v_and_b32_e32 v133, 0xffffffe0, v130
	v_mul_f32_e32 v130, 0xbfb8aa3b, v122
	v_mul_f32_e32 v131, 0xbfb8aa3b, v123
	v_exp_f32_e32 v130, v130
	v_exp_f32_e32 v131, v131
	v_lshl_add_u32 v133, s46, 7, v133
	v_and_or_b32 v132, v132, 12, v133
	v_pk_add_f32 v[138:139], v[130:131], 1.0 op_sel_hi:[1,0]
	v_mad_i64_i32 v[130:131], s[26:27], v136, s44, v[134:135]
	v_div_scale_f32 v133, s[26:27], v139, v139, v123
	v_rcp_f32_e32 v137, v133
	s_nop 0
	v_fma_f32 v140, -v133, v137, 1.0
	v_fmac_f32_e32 v137, v140, v137
	v_div_scale_f32 v140, vcc, v123, v139, v123
	v_mul_f32_e32 v141, v140, v137
	v_fma_f32 v144, -v133, v141, v140
	v_fmac_f32_e32 v141, v144, v137
	v_fma_f32 v133, -v133, v141, v140
	v_div_scale_f32 v144, s[26:27], v138, v138, v122
	v_rcp_f32_e32 v145, v144
	v_div_fmas_f32 v133, v133, v137, v141
	v_div_fixup_f32 v123, v133, v139, v123
	v_mul_f32_e32 v139, 0xbfb8aa3b, v124
	v_exp_f32_e32 v140, v139
	v_mul_f32_e32 v139, 0xbfb8aa3b, v125
	v_exp_f32_e32 v141, v139
	v_fma_f32 v133, -v144, v145, 1.0
	v_fmac_f32_e32 v145, v133, v145
	v_div_scale_f32 v133, vcc, v122, v138, v122
	v_mul_f32_e32 v137, v133, v145
	v_fma_f32 v139, -v144, v137, v133
	v_pk_add_f32 v[140:141], v[140:141], 1.0 op_sel_hi:[1,0]
	v_fmac_f32_e32 v137, v139, v145
	v_div_scale_f32 v139, s[26:27], v141, v141, v125
	v_fma_f32 v133, -v144, v137, v133
	v_rcp_f32_e32 v144, v139
	v_div_fmas_f32 v133, v133, v145, v137
	v_div_fixup_f32 v122, v133, v138, v122
	v_pk_mul_f32 v[122:123], v[122:123], v[126:127]
	v_fma_f32 v126, -v139, v144, 1.0
	v_fmac_f32_e32 v144, v126, v144
	v_div_scale_f32 v126, vcc, v125, v141, v125
	v_mul_f32_e32 v127, v126, v144
	v_fma_f32 v133, -v139, v127, v126
	v_fmac_f32_e32 v127, v133, v144
	v_div_scale_f32 v133, s[26:27], v140, v140, v124
	v_rcp_f32_e32 v137, v133
	v_fma_f32 v126, -v139, v127, v126
	v_div_fmas_f32 v126, v126, v144, v127
	v_div_fixup_f32 v125, v126, v141, v125
	v_fma_f32 v126, -v133, v137, 1.0
	v_fmac_f32_e32 v137, v126, v137
	v_div_scale_f32 v126, vcc, v124, v140, v124
	v_mul_f32_e32 v127, v126, v137
	v_fma_f32 v138, -v133, v127, v126
	v_fmac_f32_e32 v127, v138, v137
	v_fma_f32 v126, -v133, v127, v126
	v_div_fmas_f32 v126, v126, v137, v127
	v_div_fixup_f32 v124, v126, v140, v124
	v_cvt_pk_bf16_f32 v126, v122, v123
	v_mul_f32_e32 v122, 0xbfb8aa3b, v114
	v_pk_mul_f32 v[124:125], v[124:125], v[128:129]
	v_exp_f32_e32 v128, v122
	v_mul_f32_e32 v122, 0xbfb8aa3b, v115
	v_exp_f32_e32 v129, v122
	v_cvt_pk_bf16_f32 v127, v124, v125
	v_ashrrev_i32_e32 v133, 31, v132
	v_lshlrev_b64 v[122:123], 1, v[132:133]
	v_pk_add_f32 v[124:125], v[128:129], 1.0 op_sel_hi:[1,0]
	v_lshl_add_u64 v[128:129], v[130:131], 0, v[122:123]
	v_div_scale_f32 v133, s[26:27], v125, v125, v115
	v_rcp_f32_e32 v137, v133
	s_waitcnt vmcnt(0)
	global_store_dwordx2 v[128:129], v[126:127], off
	v_fma_f32 v126, -v133, v137, 1.0
	v_fmac_f32_e32 v137, v126, v137
	v_div_scale_f32 v126, vcc, v115, v125, v115
	v_mul_f32_e32 v127, v126, v137
	v_fma_f32 v138, -v133, v127, v126
	v_fmac_f32_e32 v127, v138, v137
	v_fma_f32 v126, -v133, v127, v126
	v_div_scale_f32 v133, s[26:27], v124, v124, v114
	v_rcp_f32_e32 v138, v133
	v_div_fmas_f32 v126, v126, v137, v127
	v_div_fixup_f32 v115, v126, v125, v115
	v_mul_f32_e32 v126, 0xbfb8aa3b, v116
	v_mul_f32_e32 v127, 0xbfb8aa3b, v117
	v_fma_f32 v125, -v133, v138, 1.0
	v_exp_f32_e32 v126, v126
	v_exp_f32_e32 v127, v127
	v_fmac_f32_e32 v138, v125, v138
	v_div_scale_f32 v125, vcc, v114, v124, v114
	v_mul_f32_e32 v137, v125, v138
	v_fma_f32 v139, -v133, v137, v125
	v_fmac_f32_e32 v137, v139, v138
	v_pk_add_f32 v[126:127], v[126:127], 1.0 op_sel_hi:[1,0]
	v_fma_f32 v125, -v133, v137, v125
	v_div_scale_f32 v133, s[26:27], v127, v127, v117
	v_rcp_f32_e32 v139, v133
	v_div_fmas_f32 v125, v125, v138, v137
	v_div_fixup_f32 v114, v125, v124, v114
	v_pk_mul_f32 v[114:115], v[114:115], v[118:119]
	v_fma_f32 v118, -v133, v139, 1.0
	v_fmac_f32_e32 v139, v118, v139
	v_div_scale_f32 v118, vcc, v117, v127, v117
	v_mul_f32_e32 v119, v118, v139
	v_fma_f32 v124, -v133, v119, v118
	v_fmac_f32_e32 v119, v124, v139
	v_div_scale_f32 v124, s[26:27], v126, v126, v116
	v_rcp_f32_e32 v125, v124
	v_fma_f32 v118, -v133, v119, v118
	v_div_fmas_f32 v118, v118, v139, v119
	v_div_fixup_f32 v117, v118, v127, v117
	v_fma_f32 v118, -v124, v125, 1.0
	v_fmac_f32_e32 v125, v118, v125
	v_div_scale_f32 v118, vcc, v116, v126, v116
	v_mul_f32_e32 v119, v118, v125
	v_fma_f32 v127, -v124, v119, v118
	v_fmac_f32_e32 v119, v127, v125
	v_fma_f32 v118, -v124, v119, v118
	v_div_fmas_f32 v118, v118, v125, v119
	v_cvt_pk_bf16_f32 v114, v114, v115
	v_mul_f32_e32 v115, 0xbfb8aa3b, v110
	v_div_fixup_f32 v116, v118, v126, v116
	v_exp_f32_e32 v118, v115
	v_mul_f32_e32 v115, 0xbfb8aa3b, v111
	v_exp_f32_e32 v119, v115
	v_pk_mul_f32 v[116:117], v[116:117], v[120:121]
	s_nop 0
	v_cvt_pk_bf16_f32 v115, v116, v117
	v_pk_add_f32 v[116:117], v[118:119], 1.0 op_sel_hi:[1,0]
	global_store_dwordx2 v[128:129], v[114:115], off offset:32
	v_div_scale_f32 v118, s[26:27], v117, v117, v111
	v_rcp_f32_e32 v119, v118
	v_or_b32_e32 v114, 16, v136
	v_mad_i64_i32 v[114:115], s[26:27], v114, s44, v[134:135]
	v_fma_f32 v120, -v118, v119, 1.0
	v_fmac_f32_e32 v119, v120, v119
	v_div_scale_f32 v120, vcc, v111, v117, v111
	v_mul_f32_e32 v121, v120, v119
	v_fma_f32 v124, -v118, v121, v120
	v_fmac_f32_e32 v121, v124, v119
	v_fma_f32 v118, -v118, v121, v120
	v_div_scale_f32 v120, s[26:27], v116, v116, v110
; DI uint2 pack4(float a, float b, float c, float d) { return make_uint2(pack2(a, b), pack2(c, d)); }
; DI float siluf_(float x) { return x / (1.0f + __expf(-x)); }
; DI void phase_ffn_up(const Params& P, unsigned char* smem) {
;     ...
;     { const int tid_ = launder_tid(); const int wid = tid_ >> 6, lane = tid_ & 63, wr = wid >> 2, wc = wid & 3, fr = lane & 15, fq = lane >> 4;
; #pragma unroll
;     for (int ai = 0; ai < 2; ++ai)
; #pragma unroll
;     for (int bj = 0; bj < 2; ++bj)
; #pragma unroll
;     for (int n = 0; n < 2; ++n)
; #pragma unroll
;     for (int m = 0; m < 2; ++m) {
;       asm volatile("" ::: "memory");
;       const long token = tt * 256 + bj * 128 + wc * 32 + n * 16 + fr;
;       const int jj = (ft * 4 + ai * 2 + wr) * 32 + m * 16 + fq * 4;
;       f32x4 gt = acc[ai][bj][m][n], up = acc[ai][bj][m + 2][n];
;       *(uint2*)(HM + token * DFF + jj) = pack4(siluf_(gt[0]) * up[0], siluf_(gt[1]) * up[1], siluf_(gt[2]) * up[2], siluf_(gt[3]) * up[3]);
;     }
	v_rcp_f32_e32 v124, v120
	v_div_fmas_f32 v118, v118, v119, v121
	v_div_fixup_f32 v111, v118, v117, v111
	v_mul_f32_e32 v118, 0xbfb8aa3b, v112
	v_mul_f32_e32 v119, 0xbfb8aa3b, v113
	v_fma_f32 v117, -v120, v124, 1.0
	v_exp_f32_e32 v118, v118
	v_exp_f32_e32 v119, v119
	v_fmac_f32_e32 v124, v117, v124
	v_div_scale_f32 v117, vcc, v110, v116, v110
	v_mul_f32_e32 v121, v117, v124
	v_fma_f32 v125, -v120, v121, v117
	v_fmac_f32_e32 v121, v125, v124
	v_pk_add_f32 v[118:119], v[118:119], 1.0 op_sel_hi:[1,0]
	v_fma_f32 v117, -v120, v121, v117
	v_div_scale_f32 v120, s[26:27], v119, v119, v113
	v_rcp_f32_e32 v125, v120
	v_div_fmas_f32 v117, v117, v124, v121
	v_div_fixup_f32 v110, v117, v116, v110
	v_pk_mul_f32 v[106:107], v[110:111], v[106:107]
	v_fma_f32 v110, -v120, v125, 1.0
	v_fmac_f32_e32 v125, v110, v125
	v_div_scale_f32 v110, vcc, v113, v119, v113
	v_mul_f32_e32 v111, v110, v125
	v_fma_f32 v116, -v120, v111, v110
	v_fmac_f32_e32 v111, v116, v125
	v_div_scale_f32 v116, s[26:27], v118, v118, v112
	v_rcp_f32_e32 v117, v116
	v_fma_f32 v110, -v120, v111, v110
	v_div_fmas_f32 v110, v110, v125, v111
	v_div_fixup_f32 v111, v110, v119, v113
	v_fma_f32 v110, -v116, v117, 1.0
	v_fmac_f32_e32 v117, v110, v117
	v_div_scale_f32 v110, vcc, v112, v118, v112
	v_mul_f32_e32 v113, v110, v117
	v_fma_f32 v119, -v116, v113, v110
	v_fmac_f32_e32 v113, v119, v117
	v_fma_f32 v110, -v116, v113, v110
	v_div_fmas_f32 v110, v110, v117, v113
	v_div_fixup_f32 v110, v110, v118, v112
	v_mul_f32_e32 v112, 0xbfb8aa3b, v98
	v_mul_f32_e32 v113, 0xbfb8aa3b, v99
	v_exp_f32_e32 v112, v112
	v_exp_f32_e32 v113, v113
	v_pk_mul_f32 v[108:109], v[110:111], v[108:109]
	v_cvt_pk_bf16_f32 v106, v106, v107
	v_cvt_pk_bf16_f32 v107, v108, v109
	v_pk_add_f32 v[108:109], v[112:113], 1.0 op_sel_hi:[1,0]
	v_lshl_add_u64 v[110:111], v[114:115], 0, v[122:123]
	v_div_scale_f32 v112, s[26:27], v109, v109, v99
	v_rcp_f32_e32 v113, v112
	global_store_dwordx2 v[110:111], v[106:107], off
	v_fma_f32 v106, -v112, v113, 1.0
	v_fmac_f32_e32 v113, v106, v113
	v_div_scale_f32 v106, vcc, v99, v109, v99
	v_mul_f32_e32 v107, v106, v113
	v_fma_f32 v116, -v112, v107, v106
	v_fmac_f32_e32 v107, v116, v113
	v_fma_f32 v106, -v112, v107, v106
	v_div_scale_f32 v112, s[26:27], v108, v108, v98
	v_rcp_f32_e32 v116, v112
	v_div_fmas_f32 v106, v106, v113, v107
	v_div_fixup_f32 v99, v106, v109, v99
	v_mul_f32_e32 v107, 0xbfb8aa3b, v101
	v_fma_f32 v106, -v112, v116, 1.0
	v_fmac_f32_e32 v116, v106, v116
	v_mul_f32_e32 v106, 0xbfb8aa3b, v100
	v_exp_f32_e32 v106, v106
	v_exp_f32_e32 v107, v107
	v_div_scale_f32 v109, vcc, v98, v108, v98
	v_mul_f32_e32 v113, v109, v116
	v_fma_f32 v117, -v112, v113, v109
	v_fmac_f32_e32 v113, v117, v116
	v_pk_add_f32 v[106:107], v[106:107], 1.0 op_sel_hi:[1,0]
	v_fma_f32 v109, -v112, v113, v109
	v_div_scale_f32 v112, s[26:27], v107, v107, v101
	v_rcp_f32_e32 v117, v112
	v_div_fmas_f32 v109, v109, v116, v113
	v_div_fixup_f32 v98, v109, v108, v98
	v_pk_mul_f32 v[98:99], v[98:99], v[102:103]
	v_fma_f32 v102, -v112, v117, 1.0
	v_fmac_f32_e32 v117, v102, v117
	v_div_scale_f32 v102, vcc, v101, v107, v101
	v_mul_f32_e32 v103, v102, v117
	v_fma_f32 v108, -v112, v103, v102
	v_fmac_f32_e32 v103, v108, v117
	v_div_scale_f32 v108, s[26:27], v106, v106, v100
	v_rcp_f32_e32 v109, v108
	v_fma_f32 v102, -v112, v103, v102
	v_div_fmas_f32 v102, v102, v117, v103
	v_div_fixup_f32 v101, v102, v107, v101
	v_fma_f32 v102, -v108, v109, 1.0
	v_fmac_f32_e32 v109, v102, v109
	v_div_scale_f32 v102, vcc, v100, v106, v100
	v_mul_f32_e32 v103, v102, v109
	v_fma_f32 v107, -v108, v103, v102
	v_fmac_f32_e32 v103, v107, v109
	v_fma_f32 v102, -v108, v103, v102
	v_div_fmas_f32 v102, v102, v109, v103
	v_cvt_pk_bf16_f32 v98, v98, v99
	v_mul_f32_e32 v99, 0xbfb8aa3b, v94
	v_div_fixup_f32 v100, v102, v106, v100
	v_exp_f32_e32 v102, v99
	v_mul_f32_e32 v99, 0xbfb8aa3b, v95
	v_exp_f32_e32 v103, v99
	v_pk_mul_f32 v[100:101], v[100:101], v[104:105]
	s_nop 0
	v_cvt_pk_bf16_f32 v99, v100, v101
	v_pk_add_f32 v[100:101], v[102:103], 1.0 op_sel_hi:[1,0]
	global_store_dwordx2 v[110:111], v[98:99], off offset:32
	v_div_scale_f32 v102, s[26:27], v101, v101, v95
	v_rcp_f32_e32 v103, v102
	v_or_b32_e32 v98, 0x80, v136
	v_mad_i64_i32 v[98:99], s[26:27], v98, s44, v[134:135]
	v_fma_f32 v104, -v102, v103, 1.0
	v_fmac_f32_e32 v103, v104, v103
	v_div_scale_f32 v104, vcc, v95, v101, v95
	v_mul_f32_e32 v105, v104, v103
	v_fma_f32 v106, -v102, v105, v104
	v_fmac_f32_e32 v105, v106, v103
	v_fma_f32 v102, -v102, v105, v104
	v_div_scale_f32 v104, s[26:27], v100, v100, v94
	v_rcp_f32_e32 v106, v104
	v_div_fmas_f32 v102, v102, v103, v105
	v_div_fixup_f32 v95, v102, v101, v95
	v_mul_f32_e32 v102, 0xbfb8aa3b, v96
	v_mul_f32_e32 v103, 0xbfb8aa3b, v97
	v_fma_f32 v101, -v104, v106, 1.0
	v_exp_f32_e32 v102, v102
	v_exp_f32_e32 v103, v103
	v_fmac_f32_e32 v106, v101, v106
	v_div_scale_f32 v101, vcc, v94, v100, v94
	v_mul_f32_e32 v105, v101, v106
	v_fma_f32 v107, -v104, v105, v101
	v_fmac_f32_e32 v105, v107, v106
	v_pk_add_f32 v[102:103], v[102:103], 1.0 op_sel_hi:[1,0]
	v_fma_f32 v101, -v104, v105, v101
	v_div_scale_f32 v104, s[26:27], v103, v103, v97
	v_rcp_f32_e32 v107, v104
	v_div_fmas_f32 v101, v101, v106, v105
	v_div_fixup_f32 v94, v101, v100, v94
	v_pk_mul_f32 v[90:91], v[94:95], v[90:91]
	v_fma_f32 v94, -v104, v107, 1.0
	v_fmac_f32_e32 v107, v94, v107
	v_div_scale_f32 v94, vcc, v97, v103, v97
	v_mul_f32_e32 v95, v94, v107
	v_fma_f32 v100, -v104, v95, v94
	v_fmac_f32_e32 v95, v100, v107
	v_div_scale_f32 v100, s[26:27], v102, v102, v96
	v_rcp_f32_e32 v101, v100
	v_fma_f32 v94, -v104, v95, v94
	v_div_fmas_f32 v94, v94, v107, v95
	v_div_fixup_f32 v95, v94, v103, v97
; DI uint2 pack4(float a, float b, float c, float d) { return make_uint2(pack2(a, b), pack2(c, d)); }
; DI float siluf_(float x) { return x / (1.0f + __expf(-x)); }
; DI void phase_ffn_up(const Params& P, unsigned char* smem) {
;     ...
;     { const int tid_ = launder_tid(); const int wid = tid_ >> 6, lane = tid_ & 63, wr = wid >> 2, wc = wid & 3, fr = lane & 15, fq = lane >> 4;
; #pragma unroll
;     for (int ai = 0; ai < 2; ++ai)
; #pragma unroll
;     for (int bj = 0; bj < 2; ++bj)
; #pragma unroll
;     for (int n = 0; n < 2; ++n)
; #pragma unroll
;     for (int m = 0; m < 2; ++m) {
;       asm volatile("" ::: "memory");
;       const long token = tt * 256 + bj * 128 + wc * 32 + n * 16 + fr;
;       const int jj = (ft * 4 + ai * 2 + wr) * 32 + m * 16 + fq * 4;
;       f32x4 gt = acc[ai][bj][m][n], up = acc[ai][bj][m + 2][n];
;       *(uint2*)(HM + token * DFF + jj) = pack4(siluf_(gt[0]) * up[0], siluf_(gt[1]) * up[1], siluf_(gt[2]) * up[2], siluf_(gt[3]) * up[3]);
;     }
	v_fma_f32 v94, -v100, v101, 1.0
	v_fmac_f32_e32 v101, v94, v101
	v_div_scale_f32 v94, vcc, v96, v102, v96
	v_mul_f32_e32 v97, v94, v101
	v_fma_f32 v103, -v100, v97, v94
	v_fmac_f32_e32 v97, v103, v101
	v_fma_f32 v94, -v100, v97, v94
	v_div_fmas_f32 v94, v94, v101, v97
	v_div_fixup_f32 v94, v94, v102, v96
	v_mul_f32_e32 v96, 0xbfb8aa3b, v82
	v_mul_f32_e32 v97, 0xbfb8aa3b, v83
	v_exp_f32_e32 v96, v96
	v_exp_f32_e32 v97, v97
	v_pk_mul_f32 v[92:93], v[94:95], v[92:93]
	v_cvt_pk_bf16_f32 v90, v90, v91
	v_cvt_pk_bf16_f32 v91, v92, v93
	v_pk_add_f32 v[92:93], v[96:97], 1.0 op_sel_hi:[1,0]
	v_lshl_add_u64 v[94:95], v[98:99], 0, v[122:123]
	v_div_scale_f32 v96, s[26:27], v93, v93, v83
	v_rcp_f32_e32 v97, v96
	global_store_dwordx2 v[94:95], v[90:91], off
	v_fma_f32 v90, -v96, v97, 1.0
	v_fmac_f32_e32 v97, v90, v97
	v_div_scale_f32 v90, vcc, v83, v93, v83
	v_mul_f32_e32 v91, v90, v97
	v_fma_f32 v100, -v96, v91, v90
	v_fmac_f32_e32 v91, v100, v97
	v_fma_f32 v90, -v96, v91, v90
	v_div_scale_f32 v96, s[26:27], v92, v92, v82
	v_rcp_f32_e32 v100, v96
	v_div_fmas_f32 v90, v90, v97, v91
	v_div_fixup_f32 v83, v90, v93, v83
	v_mul_f32_e32 v91, 0xbfb8aa3b, v85
	v_fma_f32 v90, -v96, v100, 1.0
	v_fmac_f32_e32 v100, v90, v100
	v_mul_f32_e32 v90, 0xbfb8aa3b, v84
	v_exp_f32_e32 v90, v90
	v_exp_f32_e32 v91, v91
	v_div_scale_f32 v93, vcc, v82, v92, v82
	v_mul_f32_e32 v97, v93, v100
	v_fma_f32 v101, -v96, v97, v93
	v_fmac_f32_e32 v97, v101, v100
	v_pk_add_f32 v[90:91], v[90:91], 1.0 op_sel_hi:[1,0]
	v_fma_f32 v93, -v96, v97, v93
	v_div_scale_f32 v96, s[26:27], v91, v91, v85
	v_rcp_f32_e32 v101, v96
	v_div_fmas_f32 v93, v93, v100, v97
	v_div_fixup_f32 v82, v93, v92, v82
	v_pk_mul_f32 v[82:83], v[82:83], v[86:87]
	v_fma_f32 v86, -v96, v101, 1.0
	v_fmac_f32_e32 v101, v86, v101
	v_div_scale_f32 v86, vcc, v85, v91, v85
	v_mul_f32_e32 v87, v86, v101
	v_fma_f32 v92, -v96, v87, v86
	v_fmac_f32_e32 v87, v92, v101
	v_div_scale_f32 v92, s[26:27], v90, v90, v84
	v_rcp_f32_e32 v93, v92
	v_fma_f32 v86, -v96, v87, v86
	v_div_fmas_f32 v86, v86, v101, v87
	v_div_fixup_f32 v85, v86, v91, v85
	v_fma_f32 v86, -v92, v93, 1.0
	v_fmac_f32_e32 v93, v86, v93
	v_div_scale_f32 v86, vcc, v84, v90, v84
	v_mul_f32_e32 v87, v86, v93
	v_fma_f32 v91, -v92, v87, v86
	v_fmac_f32_e32 v87, v91, v93
	v_fma_f32 v86, -v92, v87, v86
	v_div_fmas_f32 v86, v86, v93, v87
	v_cvt_pk_bf16_f32 v82, v82, v83
	v_mul_f32_e32 v83, 0xbfb8aa3b, v78
	v_div_fixup_f32 v84, v86, v90, v84
	v_exp_f32_e32 v86, v83
	v_mul_f32_e32 v83, 0xbfb8aa3b, v79
	v_exp_f32_e32 v87, v83
	v_pk_mul_f32 v[84:85], v[84:85], v[88:89]
	s_nop 0
	v_cvt_pk_bf16_f32 v83, v84, v85
	v_pk_add_f32 v[84:85], v[86:87], 1.0 op_sel_hi:[1,0]
	global_store_dwordx2 v[94:95], v[82:83], off offset:32
	v_div_scale_f32 v86, s[26:27], v85, v85, v79
	v_rcp_f32_e32 v87, v86
	v_or_b32_e32 v82, 0x90, v136
	v_mad_i64_i32 v[82:83], s[26:27], v82, s44, v[134:135]
	v_fma_f32 v88, -v86, v87, 1.0
	v_fmac_f32_e32 v87, v88, v87
	v_div_scale_f32 v88, vcc, v79, v85, v79
	v_mul_f32_e32 v89, v88, v87
	v_fma_f32 v90, -v86, v89, v88
	v_fmac_f32_e32 v89, v90, v87
	v_fma_f32 v86, -v86, v89, v88
	v_div_scale_f32 v88, s[26:27], v84, v84, v78
	v_rcp_f32_e32 v90, v88
	v_div_fmas_f32 v86, v86, v87, v89
	v_div_fixup_f32 v79, v86, v85, v79
	v_mul_f32_e32 v86, 0xbfb8aa3b, v80
	v_mul_f32_e32 v87, 0xbfb8aa3b, v81
	v_fma_f32 v85, -v88, v90, 1.0
	v_exp_f32_e32 v86, v86
	v_exp_f32_e32 v87, v87
	v_fmac_f32_e32 v90, v85, v90
	v_div_scale_f32 v85, vcc, v78, v84, v78
	v_mul_f32_e32 v89, v85, v90
	v_fma_f32 v91, -v88, v89, v85
	v_fmac_f32_e32 v89, v91, v90
	v_pk_add_f32 v[86:87], v[86:87], 1.0 op_sel_hi:[1,0]
	v_fma_f32 v85, -v88, v89, v85
	v_div_scale_f32 v88, s[26:27], v87, v87, v81
	v_rcp_f32_e32 v91, v88
	v_div_fmas_f32 v85, v85, v90, v89
	v_div_fixup_f32 v78, v85, v84, v78
	v_pk_mul_f32 v[74:75], v[78:79], v[74:75]
	v_fma_f32 v78, -v88, v91, 1.0
	v_fmac_f32_e32 v91, v78, v91
	v_div_scale_f32 v78, vcc, v81, v87, v81
	v_mul_f32_e32 v79, v78, v91
	v_fma_f32 v84, -v88, v79, v78
	v_fmac_f32_e32 v79, v84, v91
	v_div_scale_f32 v84, s[26:27], v86, v86, v80
	v_rcp_f32_e32 v85, v84
	v_fma_f32 v78, -v88, v79, v78
	v_div_fmas_f32 v78, v78, v91, v79
	v_div_fixup_f32 v79, v78, v87, v81
	v_fma_f32 v78, -v84, v85, 1.0
	v_fmac_f32_e32 v85, v78, v85
	v_div_scale_f32 v78, vcc, v80, v86, v80
	v_mul_f32_e32 v81, v78, v85
	v_fma_f32 v87, -v84, v81, v78
	v_fmac_f32_e32 v81, v87, v85
	v_fma_f32 v78, -v84, v81, v78
	v_div_fmas_f32 v78, v78, v85, v81
	v_div_fixup_f32 v78, v78, v86, v80
	v_mul_f32_e32 v80, 0xbfb8aa3b, v70
	v_mul_f32_e32 v81, 0xbfb8aa3b, v71
	v_exp_f32_e32 v80, v80
	v_exp_f32_e32 v81, v81
	v_pk_mul_f32 v[76:77], v[78:79], v[76:77]
	v_cvt_pk_bf16_f32 v74, v74, v75
	v_cvt_pk_bf16_f32 v75, v76, v77
	v_pk_add_f32 v[76:77], v[80:81], 1.0 op_sel_hi:[1,0]
	v_lshl_add_u64 v[78:79], v[82:83], 0, v[122:123]
	v_div_scale_f32 v80, s[26:27], v77, v77, v71
	v_rcp_f32_e32 v81, v80
	global_store_dwordx2 v[78:79], v[74:75], off
	v_fma_f32 v74, -v80, v81, 1.0
	v_fmac_f32_e32 v81, v74, v81
	v_div_scale_f32 v74, vcc, v71, v77, v71
	v_mul_f32_e32 v75, v74, v81
	v_fma_f32 v84, -v80, v75, v74
	v_fmac_f32_e32 v75, v84, v81
	v_fma_f32 v74, -v80, v75, v74
	v_div_scale_f32 v80, s[26:27], v76, v76, v70
	v_rcp_f32_e32 v84, v80
	v_div_fmas_f32 v74, v74, v81, v75
	v_div_fixup_f32 v71, v74, v77, v71
	v_mul_f32_e32 v75, 0xbfb8aa3b, v73
	v_fma_f32 v74, -v80, v84, 1.0
	v_fmac_f32_e32 v84, v74, v84
	v_mul_f32_e32 v74, 0xbfb8aa3b, v72
	v_exp_f32_e32 v74, v74
	v_exp_f32_e32 v75, v75
	v_div_scale_f32 v77, vcc, v70, v76, v70
	v_mul_f32_e32 v81, v77, v84
	v_fma_f32 v85, -v80, v81, v77
	v_fmac_f32_e32 v81, v85, v84
	v_pk_add_f32 v[74:75], v[74:75], 1.0 op_sel_hi:[1,0]
; DI uint2 pack4(float a, float b, float c, float d) { return make_uint2(pack2(a, b), pack2(c, d)); }
; DI float siluf_(float x) { return x / (1.0f + __expf(-x)); }
; DI void phase_ffn_up(const Params& P, unsigned char* smem) {
;     ...
;     { const int tid_ = launder_tid(); const int wid = tid_ >> 6, lane = tid_ & 63, wr = wid >> 2, wc = wid & 3, fr = lane & 15, fq = lane >> 4;
; #pragma unroll
;     for (int ai = 0; ai < 2; ++ai)
; #pragma unroll
;     for (int bj = 0; bj < 2; ++bj)
; #pragma unroll
;     for (int n = 0; n < 2; ++n)
; #pragma unroll
;     for (int m = 0; m < 2; ++m) {
;       asm volatile("" ::: "memory");
;       const long token = tt * 256 + bj * 128 + wc * 32 + n * 16 + fr;
;       const int jj = (ft * 4 + ai * 2 + wr) * 32 + m * 16 + fq * 4;
;       f32x4 gt = acc[ai][bj][m][n], up = acc[ai][bj][m + 2][n];
;       *(uint2*)(HM + token * DFF + jj) = pack4(siluf_(gt[0]) * up[0], siluf_(gt[1]) * up[1], siluf_(gt[2]) * up[2], siluf_(gt[3]) * up[3]);
;     }
	v_fma_f32 v77, -v80, v81, v77
	v_div_scale_f32 v80, s[26:27], v75, v75, v73
	v_rcp_f32_e32 v85, v80
	v_div_fmas_f32 v77, v77, v84, v81
	v_div_fixup_f32 v70, v77, v76, v70
	v_pk_mul_f32 v[66:67], v[70:71], v[66:67]
	v_fma_f32 v70, -v80, v85, 1.0
	v_fmac_f32_e32 v85, v70, v85
	v_div_scale_f32 v70, vcc, v73, v75, v73
	v_mul_f32_e32 v71, v70, v85
	v_fma_f32 v76, -v80, v71, v70
	v_fmac_f32_e32 v71, v76, v85
	v_div_scale_f32 v76, s[26:27], v74, v74, v72
	v_rcp_f32_e32 v77, v76
	v_fma_f32 v70, -v80, v71, v70
	v_div_fmas_f32 v70, v70, v85, v71
	v_div_fixup_f32 v71, v70, v75, v73
	v_fma_f32 v70, -v76, v77, 1.0
	v_fmac_f32_e32 v77, v70, v77
	v_div_scale_f32 v70, vcc, v72, v74, v72
	v_mul_f32_e32 v73, v70, v77
	v_fma_f32 v75, -v76, v73, v70
	v_fmac_f32_e32 v73, v75, v77
	v_fma_f32 v70, -v76, v73, v70
	v_div_fmas_f32 v70, v70, v77, v73
	v_div_fixup_f32 v70, v70, v74, v72
	v_mul_f32_e32 v72, 0xbfb8aa3b, v58
	v_mul_f32_e32 v73, 0xbfb8aa3b, v59
	v_exp_f32_e32 v72, v72
	v_exp_f32_e32 v73, v73
	v_pk_mul_f32 v[68:69], v[70:71], v[68:69]
	v_cvt_pk_bf16_f32 v66, v66, v67
	v_cvt_pk_bf16_f32 v67, v68, v69
	v_pk_add_f32 v[68:69], v[72:73], 1.0 op_sel_hi:[1,0]
	global_store_dwordx2 v[78:79], v[66:67], off offset:32
	v_div_scale_f32 v70, s[26:27], v69, v69, v59
	v_rcp_f32_e32 v71, v70
	v_add_u32_e32 v66, 64, v132
	v_fma_f32 v67, -v70, v71, 1.0
	v_fmac_f32_e32 v71, v67, v71
	v_div_scale_f32 v67, vcc, v59, v69, v59
	v_mul_f32_e32 v72, v67, v71
	v_fma_f32 v73, -v70, v72, v67
	v_fmac_f32_e32 v72, v73, v71
	v_div_scale_f32 v73, s[26:27], v68, v68, v58
	v_rcp_f32_e32 v74, v73
	v_fma_f32 v67, -v70, v72, v67
	v_div_fmas_f32 v67, v67, v71, v72
	v_mul_f32_e32 v70, 0xbfb8aa3b, v60
	v_mul_f32_e32 v71, 0xbfb8aa3b, v61
	v_exp_f32_e32 v70, v70
	v_exp_f32_e32 v71, v71
	v_div_fixup_f32 v59, v67, v69, v59
	v_fma_f32 v67, -v73, v74, 1.0
	v_fmac_f32_e32 v74, v67, v74
	v_div_scale_f32 v67, vcc, v58, v68, v58
	v_mul_f32_e32 v69, v67, v74
	v_fma_f32 v72, -v73, v69, v67
	v_pk_add_f32 v[70:71], v[70:71], 1.0 op_sel_hi:[1,0]
	v_fmac_f32_e32 v69, v72, v74
	v_div_scale_f32 v72, s[26:27], v71, v71, v61
	v_fma_f32 v67, -v73, v69, v67
	v_rcp_f32_e32 v73, v72
	v_div_fmas_f32 v67, v67, v74, v69
	v_div_fixup_f32 v58, v67, v68, v58
	v_pk_mul_f32 v[58:59], v[58:59], v[62:63]
	v_fma_f32 v62, -v72, v73, 1.0
	v_fmac_f32_e32 v73, v62, v73
	v_div_scale_f32 v62, vcc, v61, v71, v61
	v_mul_f32_e32 v63, v62, v73
	v_fma_f32 v67, -v72, v63, v62
	v_fmac_f32_e32 v63, v67, v73
	v_div_scale_f32 v67, s[26:27], v70, v70, v60
	v_rcp_f32_e32 v68, v67
	v_fma_f32 v62, -v72, v63, v62
	v_div_fmas_f32 v62, v62, v73, v63
	v_div_fixup_f32 v61, v62, v71, v61
	v_fma_f32 v62, -v67, v68, 1.0
	v_fmac_f32_e32 v68, v62, v68
	v_div_scale_f32 v62, vcc, v60, v70, v60
	v_mul_f32_e32 v63, v62, v68
	v_fma_f32 v69, -v67, v63, v62
	v_fmac_f32_e32 v63, v69, v68
	v_fma_f32 v62, -v67, v63, v62
	v_div_fmas_f32 v62, v62, v68, v63
	v_div_fixup_f32 v60, v62, v70, v60
	v_cvt_pk_bf16_f32 v62, v58, v59
	v_mul_f32_e32 v58, 0xbfb8aa3b, v50
	v_pk_mul_f32 v[60:61], v[60:61], v[64:65]
	v_exp_f32_e32 v64, v58
	v_mul_f32_e32 v58, 0xbfb8aa3b, v51
	v_exp_f32_e32 v65, v58
	v_cvt_pk_bf16_f32 v63, v60, v61
	v_ashrrev_i32_e32 v67, 31, v66
	v_lshlrev_b64 v[58:59], 1, v[66:67]
	v_pk_add_f32 v[60:61], v[64:65], 1.0 op_sel_hi:[1,0]
	v_lshl_add_u64 v[64:65], v[130:131], 0, v[58:59]
	v_div_scale_f32 v66, s[26:27], v61, v61, v51
	v_rcp_f32_e32 v67, v66
	global_store_dwordx2 v[64:65], v[62:63], off
	v_fma_f32 v62, -v66, v67, 1.0
	v_fmac_f32_e32 v67, v62, v67
	v_div_scale_f32 v62, vcc, v51, v61, v51
	v_mul_f32_e32 v63, v62, v67
	v_fma_f32 v68, -v66, v63, v62
	v_fmac_f32_e32 v63, v68, v67
	v_fma_f32 v62, -v66, v63, v62
	v_div_scale_f32 v66, s[26:27], v60, v60, v50
	v_rcp_f32_e32 v68, v66
	v_div_fmas_f32 v62, v62, v67, v63
	v_div_fixup_f32 v51, v62, v61, v51
	v_mul_f32_e32 v62, 0xbfb8aa3b, v52
	v_mul_f32_e32 v63, 0xbfb8aa3b, v53
	v_fma_f32 v61, -v66, v68, 1.0
	v_exp_f32_e32 v62, v62
	v_exp_f32_e32 v63, v63
	v_fmac_f32_e32 v68, v61, v68
	v_div_scale_f32 v61, vcc, v50, v60, v50
	v_mul_f32_e32 v67, v61, v68
	v_fma_f32 v69, -v66, v67, v61
	v_fmac_f32_e32 v67, v69, v68
	v_pk_add_f32 v[62:63], v[62:63], 1.0 op_sel_hi:[1,0]
	v_fma_f32 v61, -v66, v67, v61
	v_div_scale_f32 v66, s[26:27], v63, v63, v53
	v_rcp_f32_e32 v69, v66
	v_div_fmas_f32 v61, v61, v68, v67
	v_div_fixup_f32 v50, v61, v60, v50
	v_pk_mul_f32 v[50:51], v[50:51], v[54:55]
	v_fma_f32 v54, -v66, v69, 1.0
	v_fmac_f32_e32 v69, v54, v69
	v_div_scale_f32 v54, vcc, v53, v63, v53
	v_mul_f32_e32 v55, v54, v69
	v_fma_f32 v60, -v66, v55, v54
	v_fmac_f32_e32 v55, v60, v69
	v_div_scale_f32 v60, s[26:27], v62, v62, v52
	v_rcp_f32_e32 v61, v60
	v_fma_f32 v54, -v66, v55, v54
	v_div_fmas_f32 v54, v54, v69, v55
	v_div_fixup_f32 v53, v54, v63, v53
	v_fma_f32 v54, -v60, v61, 1.0
	v_fmac_f32_e32 v61, v54, v61
	v_div_scale_f32 v54, vcc, v52, v62, v52
	v_mul_f32_e32 v55, v54, v61
	v_fma_f32 v63, -v60, v55, v54
	v_fmac_f32_e32 v55, v63, v61
	v_fma_f32 v54, -v60, v55, v54
	v_div_fmas_f32 v60, v54, v61, v55
	v_mul_f32_e32 v54, 0xbfb8aa3b, v46
	v_mul_f32_e32 v55, 0xbfb8aa3b, v47
	v_exp_f32_e32 v54, v54
	v_exp_f32_e32 v55, v55
	v_div_fixup_f32 v52, v60, v62, v52
	v_pk_mul_f32 v[52:53], v[52:53], v[56:57]
	v_cvt_pk_bf16_f32 v50, v50, v51
	v_pk_add_f32 v[54:55], v[54:55], 1.0 op_sel_hi:[1,0]
	v_cvt_pk_bf16_f32 v51, v52, v53
	v_div_scale_f32 v56, s[26:27], v55, v55, v47
	v_rcp_f32_e32 v57, v56
	global_store_dwordx2 v[64:65], v[50:51], off offset:32
	v_fma_f32 v50, -v56, v57, 1.0
	v_fmac_f32_e32 v57, v50, v57
	v_div_scale_f32 v50, vcc, v47, v55, v47
	v_mul_f32_e32 v51, v50, v57
	v_fma_f32 v52, -v56, v51, v50
	v_fmac_f32_e32 v51, v52, v57
; DI uint2 pack4(float a, float b, float c, float d) { return make_uint2(pack2(a, b), pack2(c, d)); }
; DI float siluf_(float x) { return x / (1.0f + __expf(-x)); }
; DI void phase_ffn_up(const Params& P, unsigned char* smem) {
;     ...
;     { const int tid_ = launder_tid(); const int wid = tid_ >> 6, lane = tid_ & 63, wr = wid >> 2, wc = wid & 3, fr = lane & 15, fq = lane >> 4;
; #pragma unroll
;     for (int ai = 0; ai < 2; ++ai)
; #pragma unroll
;     for (int bj = 0; bj < 2; ++bj)
; #pragma unroll
;     for (int n = 0; n < 2; ++n)
; #pragma unroll
;     for (int m = 0; m < 2; ++m) {
;       asm volatile("" ::: "memory");
;       const long token = tt * 256 + bj * 128 + wc * 32 + n * 16 + fr;
;       const int jj = (ft * 4 + ai * 2 + wr) * 32 + m * 16 + fq * 4;
;       f32x4 gt = acc[ai][bj][m][n], up = acc[ai][bj][m + 2][n];
;       *(uint2*)(HM + token * DFF + jj) = pack4(siluf_(gt[0]) * up[0], siluf_(gt[1]) * up[1], siluf_(gt[2]) * up[2], siluf_(gt[3]) * up[3]);
;     }
	v_div_scale_f32 v52, s[26:27], v54, v54, v46
	v_rcp_f32_e32 v53, v52
	v_fma_f32 v50, -v56, v51, v50
	v_div_fmas_f32 v50, v50, v57, v51
	v_div_fixup_f32 v47, v50, v55, v47
	v_fma_f32 v50, -v52, v53, 1.0
	v_fmac_f32_e32 v53, v50, v53
	v_mul_f32_e32 v50, 0xbfb8aa3b, v48
	v_mul_f32_e32 v51, 0xbfb8aa3b, v49
	v_exp_f32_e32 v50, v50
	v_exp_f32_e32 v51, v51
	v_div_scale_f32 v55, vcc, v46, v54, v46
	v_mul_f32_e32 v56, v55, v53
	v_fma_f32 v57, -v52, v56, v55
	v_fmac_f32_e32 v56, v57, v53
	v_pk_add_f32 v[50:51], v[50:51], 1.0 op_sel_hi:[1,0]
	v_fma_f32 v52, -v52, v56, v55
	v_div_scale_f32 v55, s[26:27], v51, v51, v49
	v_rcp_f32_e32 v57, v55
	v_div_fmas_f32 v52, v52, v53, v56
	v_div_fixup_f32 v46, v52, v54, v46
	v_pk_mul_f32 v[42:43], v[46:47], v[42:43]
	v_fma_f32 v46, -v55, v57, 1.0
	v_fmac_f32_e32 v57, v46, v57
	v_div_scale_f32 v46, vcc, v49, v51, v49
	v_mul_f32_e32 v47, v46, v57
	v_fma_f32 v52, -v55, v47, v46
	v_fmac_f32_e32 v47, v52, v57
	v_div_scale_f32 v52, s[26:27], v50, v50, v48
	v_rcp_f32_e32 v53, v52
	v_fma_f32 v46, -v55, v47, v46
	v_div_fmas_f32 v46, v46, v57, v47
	v_div_fixup_f32 v47, v46, v51, v49
	v_fma_f32 v46, -v52, v53, 1.0
	v_fmac_f32_e32 v53, v46, v53
	v_div_scale_f32 v46, vcc, v48, v50, v48
	v_mul_f32_e32 v49, v46, v53
	v_fma_f32 v51, -v52, v49, v46
	v_fmac_f32_e32 v49, v51, v53
	v_fma_f32 v46, -v52, v49, v46
	v_div_fmas_f32 v46, v46, v53, v49
	v_div_fixup_f32 v46, v46, v50, v48
	v_mul_f32_e32 v48, 0xbfb8aa3b, v34
	v_mul_f32_e32 v49, 0xbfb8aa3b, v35
	v_exp_f32_e32 v48, v48
	v_exp_f32_e32 v49, v49
	v_pk_mul_f32 v[44:45], v[46:47], v[44:45]
	v_cvt_pk_bf16_f32 v42, v42, v43
	v_cvt_pk_bf16_f32 v43, v44, v45
	v_pk_add_f32 v[44:45], v[48:49], 1.0 op_sel_hi:[1,0]
	v_lshl_add_u64 v[46:47], v[114:115], 0, v[58:59]
	v_div_scale_f32 v48, s[26:27], v45, v45, v35
	v_rcp_f32_e32 v49, v48
	global_store_dwordx2 v[46:47], v[42:43], off
	v_fma_f32 v42, -v48, v49, 1.0
	v_fmac_f32_e32 v49, v42, v49
	v_div_scale_f32 v42, vcc, v35, v45, v35
	v_mul_f32_e32 v43, v42, v49
	v_fma_f32 v50, -v48, v43, v42
	v_fmac_f32_e32 v43, v50, v49
	v_fma_f32 v42, -v48, v43, v42
	v_div_scale_f32 v48, s[26:27], v44, v44, v34
	v_rcp_f32_e32 v50, v48
	v_div_fmas_f32 v42, v42, v49, v43
	v_div_fixup_f32 v35, v42, v45, v35
	v_mul_f32_e32 v43, 0xbfb8aa3b, v37
	v_fma_f32 v42, -v48, v50, 1.0
	v_fmac_f32_e32 v50, v42, v50
	v_mul_f32_e32 v42, 0xbfb8aa3b, v36
	v_exp_f32_e32 v42, v42
	v_exp_f32_e32 v43, v43
	v_div_scale_f32 v45, vcc, v34, v44, v34
	v_mul_f32_e32 v49, v45, v50
	v_fma_f32 v51, -v48, v49, v45
	v_fmac_f32_e32 v49, v51, v50
	v_pk_add_f32 v[42:43], v[42:43], 1.0 op_sel_hi:[1,0]
	v_fma_f32 v45, -v48, v49, v45
	v_div_scale_f32 v48, s[26:27], v43, v43, v37
	v_rcp_f32_e32 v51, v48
	v_div_fmas_f32 v45, v45, v50, v49
	v_div_fixup_f32 v34, v45, v44, v34
	v_pk_mul_f32 v[34:35], v[34:35], v[38:39]
	v_fma_f32 v38, -v48, v51, 1.0
	v_fmac_f32_e32 v51, v38, v51
	v_div_scale_f32 v38, vcc, v37, v43, v37
	v_mul_f32_e32 v39, v38, v51
	v_fma_f32 v44, -v48, v39, v38
	v_fmac_f32_e32 v39, v44, v51
	v_div_scale_f32 v44, s[26:27], v42, v42, v36
	v_rcp_f32_e32 v45, v44
	v_fma_f32 v38, -v48, v39, v38
	v_div_fmas_f32 v38, v38, v51, v39
	v_div_fixup_f32 v37, v38, v43, v37
	v_fma_f32 v38, -v44, v45, 1.0
	v_fmac_f32_e32 v45, v38, v45
	v_div_scale_f32 v38, vcc, v36, v42, v36
	v_mul_f32_e32 v39, v38, v45
	v_fma_f32 v43, -v44, v39, v38
	v_fmac_f32_e32 v39, v43, v45
	v_fma_f32 v38, -v44, v39, v38
	v_div_fmas_f32 v43, v38, v45, v39
	v_mul_f32_e32 v38, 0xbfb8aa3b, v30
	v_mul_f32_e32 v39, 0xbfb8aa3b, v31
	v_exp_f32_e32 v38, v38
	v_exp_f32_e32 v39, v39
	v_div_fixup_f32 v36, v43, v42, v36
	v_pk_mul_f32 v[36:37], v[36:37], v[40:41]
	v_cvt_pk_bf16_f32 v34, v34, v35
	v_pk_add_f32 v[38:39], v[38:39], 1.0 op_sel_hi:[1,0]
	v_cvt_pk_bf16_f32 v35, v36, v37
	v_div_scale_f32 v40, s[26:27], v39, v39, v31
	v_rcp_f32_e32 v41, v40
	global_store_dwordx2 v[46:47], v[34:35], off offset:32
	v_fma_f32 v34, -v40, v41, 1.0
	v_fmac_f32_e32 v41, v34, v41
	v_div_scale_f32 v34, vcc, v31, v39, v31
	v_mul_f32_e32 v35, v34, v41
	v_fma_f32 v36, -v40, v35, v34
	v_fmac_f32_e32 v35, v36, v41
	v_div_scale_f32 v36, s[26:27], v38, v38, v30
	v_rcp_f32_e32 v37, v36
	v_fma_f32 v34, -v40, v35, v34
	v_div_fmas_f32 v34, v34, v41, v35
	v_div_fixup_f32 v31, v34, v39, v31
	v_fma_f32 v34, -v36, v37, 1.0
	v_fmac_f32_e32 v37, v34, v37
	v_mul_f32_e32 v34, 0xbfb8aa3b, v32
	v_mul_f32_e32 v35, 0xbfb8aa3b, v33
	v_exp_f32_e32 v34, v34
	v_exp_f32_e32 v35, v35
	v_div_scale_f32 v39, vcc, v30, v38, v30
	v_mul_f32_e32 v40, v39, v37
	v_fma_f32 v41, -v36, v40, v39
	v_fmac_f32_e32 v40, v41, v37
	v_pk_add_f32 v[34:35], v[34:35], 1.0 op_sel_hi:[1,0]
	v_fma_f32 v36, -v36, v40, v39
	v_div_scale_f32 v39, s[26:27], v35, v35, v33
	v_rcp_f32_e32 v41, v39
	v_div_fmas_f32 v36, v36, v37, v40
	v_div_fixup_f32 v30, v36, v38, v30
	v_pk_mul_f32 v[26:27], v[30:31], v[26:27]
	v_fma_f32 v30, -v39, v41, 1.0
	v_fmac_f32_e32 v41, v30, v41
	v_div_scale_f32 v30, vcc, v33, v35, v33
	v_mul_f32_e32 v31, v30, v41
	v_fma_f32 v36, -v39, v31, v30
	v_fmac_f32_e32 v31, v36, v41
	v_div_scale_f32 v36, s[26:27], v34, v34, v32
	v_rcp_f32_e32 v37, v36
	v_fma_f32 v30, -v39, v31, v30
	v_div_fmas_f32 v30, v30, v41, v31
	v_div_fixup_f32 v31, v30, v35, v33
	v_fma_f32 v30, -v36, v37, 1.0
	v_fmac_f32_e32 v37, v30, v37
	v_div_scale_f32 v30, vcc, v32, v34, v32
	v_mul_f32_e32 v33, v30, v37
	v_fma_f32 v35, -v36, v33, v30
	v_fmac_f32_e32 v33, v35, v37
	v_fma_f32 v30, -v36, v33, v30
	v_div_fmas_f32 v30, v30, v37, v33
	v_div_fixup_f32 v30, v30, v34, v32
	v_mul_f32_e32 v32, 0xbfb8aa3b, v18
	v_mul_f32_e32 v33, 0xbfb8aa3b, v19
	v_exp_f32_e32 v32, v32
	v_exp_f32_e32 v33, v33
	v_pk_mul_f32 v[28:29], v[30:31], v[28:29]
; DI uint2 pack4(float a, float b, float c, float d) { return make_uint2(pack2(a, b), pack2(c, d)); }
; DI float siluf_(float x) { return x / (1.0f + __expf(-x)); }
; DI void phase_ffn_up(const Params& P, unsigned char* smem) {
;     ...
;   for (int u = blockIdx.x; u < total; u += gridDim.x) {
;     ...
;     { const int tid_ = launder_tid(); const int wid = tid_ >> 6, lane = tid_ & 63, wr = wid >> 2, wc = wid & 3, fr = lane & 15, fq = lane >> 4;
; #pragma unroll
;     for (int ai = 0; ai < 2; ++ai)
; #pragma unroll
;     for (int bj = 0; bj < 2; ++bj)
; #pragma unroll
;     for (int n = 0; n < 2; ++n)
; #pragma unroll
;     for (int m = 0; m < 2; ++m) {
;       asm volatile("" ::: "memory");
;       const long token = tt * 256 + bj * 128 + wc * 32 + n * 16 + fr;
;       const int jj = (ft * 4 + ai * 2 + wr) * 32 + m * 16 + fq * 4;
;       f32x4 gt = acc[ai][bj][m][n], up = acc[ai][bj][m + 2][n];
;       *(uint2*)(HM + token * DFF + jj) = pack4(siluf_(gt[0]) * up[0], siluf_(gt[1]) * up[1], siluf_(gt[2]) * up[2], siluf_(gt[3]) * up[3]);
;     }
	v_cvt_pk_bf16_f32 v26, v26, v27
	v_cvt_pk_bf16_f32 v27, v28, v29
	v_pk_add_f32 v[28:29], v[32:33], 1.0 op_sel_hi:[1,0]
	v_lshl_add_u64 v[30:31], v[98:99], 0, v[58:59]
	v_div_scale_f32 v32, s[26:27], v29, v29, v19
	v_rcp_f32_e32 v33, v32
	global_store_dwordx2 v[30:31], v[26:27], off
	v_fma_f32 v26, -v32, v33, 1.0
	v_fmac_f32_e32 v33, v26, v33
	v_div_scale_f32 v26, vcc, v19, v29, v19
	v_mul_f32_e32 v27, v26, v33
	v_fma_f32 v34, -v32, v27, v26
	v_fmac_f32_e32 v27, v34, v33
	v_fma_f32 v26, -v32, v27, v26
	v_div_scale_f32 v32, s[26:27], v28, v28, v18
	v_rcp_f32_e32 v34, v32
	v_div_fmas_f32 v26, v26, v33, v27
	v_div_fixup_f32 v19, v26, v29, v19
	v_mul_f32_e32 v27, 0xbfb8aa3b, v21
	v_fma_f32 v26, -v32, v34, 1.0
	v_fmac_f32_e32 v34, v26, v34
	v_mul_f32_e32 v26, 0xbfb8aa3b, v20
	v_exp_f32_e32 v26, v26
	v_exp_f32_e32 v27, v27
	v_div_scale_f32 v29, vcc, v18, v28, v18
	v_mul_f32_e32 v33, v29, v34
	v_fma_f32 v35, -v32, v33, v29
	v_fmac_f32_e32 v33, v35, v34
	v_pk_add_f32 v[26:27], v[26:27], 1.0 op_sel_hi:[1,0]
	v_fma_f32 v29, -v32, v33, v29
	v_div_scale_f32 v32, s[26:27], v27, v27, v21
	v_rcp_f32_e32 v35, v32
	v_div_fmas_f32 v29, v29, v34, v33
	v_div_fixup_f32 v18, v29, v28, v18
	v_pk_mul_f32 v[18:19], v[18:19], v[22:23]
	v_fma_f32 v22, -v32, v35, 1.0
	v_fmac_f32_e32 v35, v22, v35
	v_div_scale_f32 v22, vcc, v21, v27, v21
	v_mul_f32_e32 v23, v22, v35
	v_fma_f32 v28, -v32, v23, v22
	v_fmac_f32_e32 v23, v28, v35
	v_div_scale_f32 v28, s[26:27], v26, v26, v20
	v_rcp_f32_e32 v29, v28
	v_fma_f32 v22, -v32, v23, v22
	v_div_fmas_f32 v22, v22, v35, v23
	v_div_fixup_f32 v21, v22, v27, v21
	v_fma_f32 v22, -v28, v29, 1.0
	v_fmac_f32_e32 v29, v22, v29
	v_div_scale_f32 v22, vcc, v20, v26, v20
	v_mul_f32_e32 v23, v22, v29
	v_fma_f32 v27, -v28, v23, v22
	v_fmac_f32_e32 v23, v27, v29
	v_fma_f32 v22, -v28, v23, v22
	v_div_fmas_f32 v27, v22, v29, v23
	v_mul_f32_e32 v22, 0xbfb8aa3b, v14
	v_mul_f32_e32 v23, 0xbfb8aa3b, v15
	v_exp_f32_e32 v22, v22
	v_exp_f32_e32 v23, v23
	v_div_fixup_f32 v20, v27, v26, v20
	v_pk_mul_f32 v[20:21], v[20:21], v[24:25]
	v_cvt_pk_bf16_f32 v18, v18, v19
	v_pk_add_f32 v[22:23], v[22:23], 1.0 op_sel_hi:[1,0]
	v_cvt_pk_bf16_f32 v19, v20, v21
	v_div_scale_f32 v24, s[26:27], v23, v23, v15
	v_rcp_f32_e32 v25, v24
	global_store_dwordx2 v[30:31], v[18:19], off offset:32
	v_fma_f32 v18, -v24, v25, 1.0
	v_fmac_f32_e32 v25, v18, v25
	v_div_scale_f32 v18, vcc, v15, v23, v15
	v_mul_f32_e32 v19, v18, v25
	v_fma_f32 v20, -v24, v19, v18
	v_fmac_f32_e32 v19, v20, v25
	v_div_scale_f32 v20, s[26:27], v22, v22, v14
	v_rcp_f32_e32 v21, v20
	v_fma_f32 v18, -v24, v19, v18
	v_div_fmas_f32 v18, v18, v25, v19
	v_div_fixup_f32 v15, v18, v23, v15
	v_fma_f32 v18, -v20, v21, 1.0
	v_fmac_f32_e32 v21, v18, v21
	v_mul_f32_e32 v18, 0xbfb8aa3b, v16
	v_mul_f32_e32 v19, 0xbfb8aa3b, v17
	v_exp_f32_e32 v18, v18
	v_exp_f32_e32 v19, v19
	v_div_scale_f32 v23, vcc, v14, v22, v14
	v_mul_f32_e32 v24, v23, v21
	v_fma_f32 v25, -v20, v24, v23
	v_fmac_f32_e32 v24, v25, v21
	v_pk_add_f32 v[18:19], v[18:19], 1.0 op_sel_hi:[1,0]
	v_fma_f32 v20, -v20, v24, v23
	v_div_scale_f32 v23, s[26:27], v19, v19, v17
	v_rcp_f32_e32 v25, v23
	v_div_fmas_f32 v20, v20, v21, v24
	v_div_fixup_f32 v14, v20, v22, v14
	v_pk_mul_f32 v[10:11], v[14:15], v[10:11]
	v_fma_f32 v14, -v23, v25, 1.0
	v_fmac_f32_e32 v25, v14, v25
	v_div_scale_f32 v14, vcc, v17, v19, v17
	v_mul_f32_e32 v15, v14, v25
	v_fma_f32 v20, -v23, v15, v14
	v_fmac_f32_e32 v15, v20, v25
	v_div_scale_f32 v20, s[26:27], v18, v18, v16
	v_rcp_f32_e32 v21, v20
	v_fma_f32 v14, -v23, v15, v14
	v_div_fmas_f32 v14, v14, v25, v15
	v_div_fixup_f32 v15, v14, v19, v17
	v_fma_f32 v14, -v20, v21, 1.0
	v_fmac_f32_e32 v21, v14, v21
	v_div_scale_f32 v14, vcc, v16, v18, v16
	v_mul_f32_e32 v17, v14, v21
	v_fma_f32 v19, -v20, v17, v14
	v_fmac_f32_e32 v17, v19, v21
	v_fma_f32 v14, -v20, v17, v14
	v_div_fmas_f32 v14, v14, v21, v17
	v_div_fixup_f32 v14, v14, v18, v16
	v_mul_f32_e32 v16, 0xbfb8aa3b, v2
	v_mul_f32_e32 v17, 0xbfb8aa3b, v3
	v_exp_f32_e32 v16, v16
	v_exp_f32_e32 v17, v17
	v_pk_mul_f32 v[12:13], v[14:15], v[12:13]
	v_cvt_pk_bf16_f32 v10, v10, v11
	v_cvt_pk_bf16_f32 v11, v12, v13
	v_pk_add_f32 v[12:13], v[16:17], 1.0 op_sel_hi:[1,0]
	v_lshl_add_u64 v[14:15], v[82:83], 0, v[58:59]
	v_div_scale_f32 v16, s[26:27], v13, v13, v3
	v_rcp_f32_e32 v17, v16
	global_store_dwordx2 v[14:15], v[10:11], off
	v_fma_f32 v10, -v16, v17, 1.0
	v_fmac_f32_e32 v17, v10, v17
	v_div_scale_f32 v10, vcc, v3, v13, v3
	v_mul_f32_e32 v11, v10, v17
	v_fma_f32 v18, -v16, v11, v10
	v_fmac_f32_e32 v11, v18, v17
	v_fma_f32 v10, -v16, v11, v10
	v_div_scale_f32 v16, s[26:27], v12, v12, v2
	v_rcp_f32_e32 v18, v16
	v_div_fmas_f32 v10, v10, v17, v11
	v_div_fixup_f32 v3, v10, v13, v3
	v_mul_f32_e32 v11, 0xbfb8aa3b, v5
	v_fma_f32 v10, -v16, v18, 1.0
	v_fmac_f32_e32 v18, v10, v18
	v_mul_f32_e32 v10, 0xbfb8aa3b, v4
	v_exp_f32_e32 v10, v10
	v_exp_f32_e32 v11, v11
	v_div_scale_f32 v13, vcc, v2, v12, v2
	v_mul_f32_e32 v17, v13, v18
	v_fma_f32 v19, -v16, v17, v13
	v_fmac_f32_e32 v17, v19, v18
	v_pk_add_f32 v[10:11], v[10:11], 1.0 op_sel_hi:[1,0]
	v_fma_f32 v13, -v16, v17, v13
	v_div_scale_f32 v16, s[26:27], v11, v11, v5
	v_rcp_f32_e32 v19, v16
	v_div_fmas_f32 v13, v13, v18, v17
	v_div_fixup_f32 v2, v13, v12, v2
	v_pk_mul_f32 v[2:3], v[2:3], v[6:7]
	v_fma_f32 v6, -v16, v19, 1.0
	v_fmac_f32_e32 v19, v6, v19
	v_div_scale_f32 v6, vcc, v5, v11, v5
	v_mul_f32_e32 v7, v6, v19
	v_fma_f32 v12, -v16, v7, v6
	v_fmac_f32_e32 v7, v12, v19
	v_div_scale_f32 v12, s[26:27], v10, v10, v4
	v_rcp_f32_e32 v13, v12
	v_fma_f32 v6, -v16, v7, v6
	v_div_fmas_f32 v6, v6, v19, v7
	v_div_fixup_f32 v5, v6, v11, v5
	v_fma_f32 v6, -v12, v13, 1.0
	v_fmac_f32_e32 v13, v6, v13
	v_div_scale_f32 v6, vcc, v4, v10, v4
	v_mul_f32_e32 v7, v6, v13
	v_fma_f32 v11, -v12, v7, v6
	v_fmac_f32_e32 v7, v11, v13
	v_fma_f32 v6, -v12, v7, v6
	v_div_fmas_f32 v6, v6, v13, v7
	v_div_fixup_f32 v4, v6, v10, v4
	v_readlane_b32 s26, v250, 0
	v_pk_mul_f32 v[4:5], v[4:5], v[8:9]
	s_add_i32 s45, s45, s26
	v_cvt_pk_bf16_f32 v2, v2, v3
	v_cvt_pk_bf16_f32 v3, v4, v5
	s_cmpk_lt_i32 s45, 0x1616
	v_readlane_b32 s27, v250, 1
	global_store_dwordx2 v[14:15], v[2:3], off offset:32
	s_cbranch_scc0 .LBB0_957
